# PEER routing top-16 insertion rewritten as in-place med3 network (16 ops per key instead of 32)
# baseline (speedup 1.0000x reference)
; #define MFMA32(a, b, c) __builtin_amdgcn_mfma_f32_32x32x16_bf16((a), (b), (c), 0, 0, 0)
; DI int crow(int i, int h) { return (i & 3) + 8 * (i >> 2) + 4 * h; }
; DI unsigned f2ord(float f) { unsigned u = __float_as_uint(f); return (u & 0x80000000u) ? ~u : (u | 0x80000000u); }
; #define INS32(T, X) { _Pragma("unroll") for (int jj = 0; jj < 16; ++jj) { unsigned t_ = max(T[jj], X); X = min(T[jj], X); T[jj] = t_; } }
; __device__ __forceinline__ void route_task(const Params& p, int layer, const u16* qg, int rb, int hd, int r, int h) {
;     ...
;     for (int n = 0; n < 4; ++n) {
;       f32x16 acc;
; #pragma unroll
;       for (int e = 0; e < 16; ++e) acc[e] = 0.f;
; #pragma unroll
;       for (int s = 0; s < 8; ++s) {
;         bf16x8 kf = *(const bf16x8*)(kg + (size_t)n * 32 * 128 + 16 * s);
;         acc = MFMA32(kf, qf[s], acc);
;       }
; #pragma unroll
;       for (int e = 0; e < 16; ++e) {
;         unsigned key = (f2ord(acc[e]) & ~127u) | (unsigned)(127 - (n * 32 + crow(e, h)));
;         INS32(tp, key);
;       }
;     }
.LBB0_1873:
	global_load_dwordx4 v[190:193], v[50:51], off offset:-128
	global_load_dwordx4 v[194:197], v[50:51], off offset:-96
	global_load_dwordx4 v[198:201], v[50:51], off offset:-64
	global_load_dwordx4 v[202:205], v[50:51], off offset:-32
	global_load_dwordx4 v[206:209], v[50:51], off
	global_load_dwordx4 v[216:219], v[50:51], off offset:32
	global_load_dwordx4 v[220:223], v[50:51], off offset:64
	global_load_dwordx4 v[224:227], v[50:51], off offset:96
	v_lshl_add_u64 v[50:51], v[50:51], 0, s[16:17]
	s_waitcnt vmcnt(7) lgkmcnt(7)
	v_mfma_f32_32x32x16_bf16 v[0:15], v[190:193], v[16:19], 0
	s_waitcnt vmcnt(6) lgkmcnt(6)
	v_mfma_f32_32x32x16_bf16 v[0:15], v[194:197], v[20:23], v[0:15]
	s_waitcnt vmcnt(5) lgkmcnt(5)
	v_mfma_f32_32x32x16_bf16 v[0:15], v[198:201], v[24:27], v[0:15]
	s_waitcnt vmcnt(4) lgkmcnt(4)
	v_mfma_f32_32x32x16_bf16 v[0:15], v[202:205], v[28:31], v[0:15]
	s_waitcnt vmcnt(3) lgkmcnt(3)
	v_mfma_f32_32x32x16_bf16 v[0:15], v[206:209], v[32:35], v[0:15]
	s_waitcnt vmcnt(2) lgkmcnt(2)
	v_mfma_f32_32x32x16_bf16 v[0:15], v[216:219], v[36:39], v[0:15]
	s_waitcnt vmcnt(1) lgkmcnt(1)
	v_mfma_f32_32x32x16_bf16 v[0:15], v[220:223], v[40:43], v[0:15]
	s_waitcnt vmcnt(0) lgkmcnt(0)
	v_mfma_f32_32x32x16_bf16 v[0:15], v[224:227], v[44:47], v[0:15]
	s_nop 11
	v_cmp_gt_i32_e32 vcc, 0, v0
	v_not_b32_e32 v70, v0
	v_or_b32_e32 v71, 0x80000000, v0
	v_cndmask_b32_e32 v70, v71, v70, vcc
	v_and_b32_e32 v70, 0xffffff80, v70
	v_add_u32_e32 v0, s18, v53
	s_sub_i32 s18, s18, 32
	s_cmpk_lg_i32 s18, 0xff80
	v_add3_u32 v70, v0, v70, s61
	v_med3_u32 v54, v55, v54, v70
	v_med3_u32 v55, v56, v55, v70
	v_med3_u32 v56, v57, v56, v70
	v_med3_u32 v57, v58, v57, v70
	v_med3_u32 v58, v59, v58, v70
	v_med3_u32 v59, v60, v59, v70
	v_med3_u32 v60, v61, v60, v70
	v_med3_u32 v61, v62, v61, v70
	v_med3_u32 v62, v63, v62, v70
	v_med3_u32 v63, v64, v63, v70
	v_med3_u32 v64, v65, v64, v70
	v_med3_u32 v65, v66, v65, v70
	v_med3_u32 v66, v67, v66, v70
	v_med3_u32 v67, v68, v67, v70
	v_med3_u32 v68, v69, v68, v70
	v_max_u32_e32 v69, v69, v70
	v_cmp_gt_i32_e32 vcc, 0, v1
	v_not_b32_e32 v70, v1
	v_or_b32_e32 v71, 0x80000000, v1
	v_cndmask_b32_e32 v70, v71, v70, vcc
	v_and_b32_e32 v70, 0xffffff80, v70
	v_add3_u32 v70, v0, v70, s62
	v_med3_u32 v54, v55, v54, v70
	v_med3_u32 v55, v56, v55, v70
	v_med3_u32 v56, v57, v56, v70
	v_med3_u32 v57, v58, v57, v70
	v_med3_u32 v58, v59, v58, v70
	v_med3_u32 v59, v60, v59, v70
	v_med3_u32 v60, v61, v60, v70
	v_med3_u32 v61, v62, v61, v70
	v_med3_u32 v62, v63, v62, v70
	v_med3_u32 v63, v64, v63, v70
	v_med3_u32 v64, v65, v64, v70
	v_med3_u32 v65, v66, v65, v70
	v_med3_u32 v66, v67, v66, v70
	v_med3_u32 v67, v68, v67, v70
	v_med3_u32 v68, v69, v68, v70
	v_max_u32_e32 v69, v69, v70
	v_cmp_gt_i32_e32 vcc, 0, v2
	v_not_b32_e32 v70, v2
	v_or_b32_e32 v71, 0x80000000, v2
	v_cndmask_b32_e32 v70, v71, v70, vcc
	v_and_b32_e32 v70, 0xffffff80, v70
	v_add3_u32 v70, v0, v70, s63
	v_med3_u32 v54, v55, v54, v70
	v_med3_u32 v55, v56, v55, v70
	v_med3_u32 v56, v57, v56, v70
	v_med3_u32 v57, v58, v57, v70
	v_med3_u32 v58, v59, v58, v70
	v_med3_u32 v59, v60, v59, v70
	v_med3_u32 v60, v61, v60, v70
	v_med3_u32 v61, v62, v61, v70
	v_med3_u32 v62, v63, v62, v70
	v_med3_u32 v63, v64, v63, v70
	v_med3_u32 v64, v65, v64, v70
	v_med3_u32 v65, v66, v65, v70
	v_med3_u32 v66, v67, v66, v70
	v_med3_u32 v67, v68, v67, v70
	v_med3_u32 v68, v69, v68, v70
	v_max_u32_e32 v69, v69, v70
	v_cmp_gt_i32_e32 vcc, 0, v3
	v_not_b32_e32 v70, v3
	v_or_b32_e32 v71, 0x80000000, v3
	v_cndmask_b32_e32 v70, v71, v70, vcc
	v_and_b32_e32 v70, 0xffffff80, v70
	v_add3_u32 v70, v0, v70, s64
	v_med3_u32 v54, v55, v54, v70
	v_med3_u32 v55, v56, v55, v70
	v_med3_u32 v56, v57, v56, v70
	v_med3_u32 v57, v58, v57, v70
	v_med3_u32 v58, v59, v58, v70
	v_med3_u32 v59, v60, v59, v70
	v_med3_u32 v60, v61, v60, v70
	v_med3_u32 v61, v62, v61, v70
	v_med3_u32 v62, v63, v62, v70
	v_med3_u32 v63, v64, v63, v70
	v_med3_u32 v64, v65, v64, v70
	v_med3_u32 v65, v66, v65, v70
	v_med3_u32 v66, v67, v66, v70
	v_med3_u32 v67, v68, v67, v70
	v_med3_u32 v68, v69, v68, v70
	v_max_u32_e32 v69, v69, v70
	v_cmp_gt_i32_e32 vcc, 0, v4
	v_not_b32_e32 v70, v4
	v_or_b32_e32 v71, 0x80000000, v4
	v_cndmask_b32_e32 v70, v71, v70, vcc
	v_and_b32_e32 v70, 0xffffff80, v70
	v_add3_u32 v70, v0, v70, s65
	v_med3_u32 v54, v55, v54, v70
	v_med3_u32 v55, v56, v55, v70
	v_med3_u32 v56, v57, v56, v70
	v_med3_u32 v57, v58, v57, v70
	v_med3_u32 v58, v59, v58, v70
	v_med3_u32 v59, v60, v59, v70
	v_med3_u32 v60, v61, v60, v70
	v_med3_u32 v61, v62, v61, v70
	v_med3_u32 v62, v63, v62, v70
	v_med3_u32 v63, v64, v63, v70
	v_med3_u32 v64, v65, v64, v70
	v_med3_u32 v65, v66, v65, v70
	v_med3_u32 v66, v67, v66, v70
	v_med3_u32 v67, v68, v67, v70
	v_med3_u32 v68, v69, v68, v70
	v_max_u32_e32 v69, v69, v70
	v_cmp_gt_i32_e32 vcc, 0, v5
	v_not_b32_e32 v70, v5
	v_or_b32_e32 v71, 0x80000000, v5
	v_cndmask_b32_e32 v70, v71, v70, vcc
	v_and_b32_e32 v70, 0xffffff80, v70
	v_add3_u32 v70, v0, v70, s66
	v_med3_u32 v54, v55, v54, v70
	v_med3_u32 v55, v56, v55, v70
	v_med3_u32 v56, v57, v56, v70
	v_med3_u32 v57, v58, v57, v70
	v_med3_u32 v58, v59, v58, v70
	v_med3_u32 v59, v60, v59, v70
	v_med3_u32 v60, v61, v60, v70
	v_med3_u32 v61, v62, v61, v70
	v_med3_u32 v62, v63, v62, v70
	v_med3_u32 v63, v64, v63, v70
	v_med3_u32 v64, v65, v64, v70
	v_med3_u32 v65, v66, v65, v70
	v_med3_u32 v66, v67, v66, v70
	v_med3_u32 v67, v68, v67, v70
	v_med3_u32 v68, v69, v68, v70
	v_max_u32_e32 v69, v69, v70
	v_cmp_gt_i32_e32 vcc, 0, v6
	v_not_b32_e32 v70, v6
	v_or_b32_e32 v71, 0x80000000, v6
	v_cndmask_b32_e32 v70, v71, v70, vcc
	v_and_b32_e32 v70, 0xffffff80, v70
; DI int crow(int i, int h) { return (i & 3) + 8 * (i >> 2) + 4 * h; }
; DI unsigned f2ord(float f) { unsigned u = __float_as_uint(f); return (u & 0x80000000u) ? ~u : (u | 0x80000000u); }
; #define INS32(T, X) { _Pragma("unroll") for (int jj = 0; jj < 16; ++jj) { unsigned t_ = max(T[jj], X); X = min(T[jj], X); T[jj] = t_; } }
; __device__ __forceinline__ void route_task(const Params& p, int layer, const u16* qg, int rb, int hd, int r, int h) {
;     ...
; #pragma unroll
;       for (int e = 0; e < 16; ++e) {
;         unsigned key = (f2ord(acc[e]) & ~127u) | (unsigned)(127 - (n * 32 + crow(e, h)));
;         INS32(tp, key);
;       }
;     }
	v_add3_u32 v70, v0, v70, s67
	v_med3_u32 v54, v55, v54, v70
	v_med3_u32 v55, v56, v55, v70
	v_med3_u32 v56, v57, v56, v70
	v_med3_u32 v57, v58, v57, v70
	v_med3_u32 v58, v59, v58, v70
	v_med3_u32 v59, v60, v59, v70
	v_med3_u32 v60, v61, v60, v70
	v_med3_u32 v61, v62, v61, v70
	v_med3_u32 v62, v63, v62, v70
	v_med3_u32 v63, v64, v63, v70
	v_med3_u32 v64, v65, v64, v70
	v_med3_u32 v65, v66, v65, v70
	v_med3_u32 v66, v67, v66, v70
	v_med3_u32 v67, v68, v67, v70
	v_med3_u32 v68, v69, v68, v70
	v_max_u32_e32 v69, v69, v70
	v_cmp_gt_i32_e32 vcc, 0, v7
	v_not_b32_e32 v70, v7
	v_or_b32_e32 v71, 0x80000000, v7
	v_cndmask_b32_e32 v70, v71, v70, vcc
	v_and_b32_e32 v70, 0xffffff80, v70
	v_add3_u32 v70, v0, v70, s68
	v_med3_u32 v54, v55, v54, v70
	v_med3_u32 v55, v56, v55, v70
	v_med3_u32 v56, v57, v56, v70
	v_med3_u32 v57, v58, v57, v70
	v_med3_u32 v58, v59, v58, v70
	v_med3_u32 v59, v60, v59, v70
	v_med3_u32 v60, v61, v60, v70
	v_med3_u32 v61, v62, v61, v70
	v_med3_u32 v62, v63, v62, v70
	v_med3_u32 v63, v64, v63, v70
	v_med3_u32 v64, v65, v64, v70
	v_med3_u32 v65, v66, v65, v70
	v_med3_u32 v66, v67, v66, v70
	v_med3_u32 v67, v68, v67, v70
	v_med3_u32 v68, v69, v68, v70
	v_max_u32_e32 v69, v69, v70
	v_cmp_gt_i32_e32 vcc, 0, v8
	v_not_b32_e32 v70, v8
	v_or_b32_e32 v71, 0x80000000, v8
	v_cndmask_b32_e32 v70, v71, v70, vcc
	v_and_b32_e32 v70, 0xffffff80, v70
	v_add3_u32 v70, v0, v70, s69
	v_med3_u32 v54, v55, v54, v70
	v_med3_u32 v55, v56, v55, v70
	v_med3_u32 v56, v57, v56, v70
	v_med3_u32 v57, v58, v57, v70
	v_med3_u32 v58, v59, v58, v70
	v_med3_u32 v59, v60, v59, v70
	v_med3_u32 v60, v61, v60, v70
	v_med3_u32 v61, v62, v61, v70
	v_med3_u32 v62, v63, v62, v70
	v_med3_u32 v63, v64, v63, v70
	v_med3_u32 v64, v65, v64, v70
	v_med3_u32 v65, v66, v65, v70
	v_med3_u32 v66, v67, v66, v70
	v_med3_u32 v67, v68, v67, v70
	v_med3_u32 v68, v69, v68, v70
	v_max_u32_e32 v69, v69, v70
	v_cmp_gt_i32_e32 vcc, 0, v9
	v_not_b32_e32 v70, v9
	v_or_b32_e32 v71, 0x80000000, v9
	v_cndmask_b32_e32 v70, v71, v70, vcc
	v_and_b32_e32 v70, 0xffffff80, v70
	v_add3_u32 v70, v0, v70, s70
	v_med3_u32 v54, v55, v54, v70
	v_med3_u32 v55, v56, v55, v70
	v_med3_u32 v56, v57, v56, v70
	v_med3_u32 v57, v58, v57, v70
	v_med3_u32 v58, v59, v58, v70
	v_med3_u32 v59, v60, v59, v70
	v_med3_u32 v60, v61, v60, v70
	v_med3_u32 v61, v62, v61, v70
	v_med3_u32 v62, v63, v62, v70
	v_med3_u32 v63, v64, v63, v70
	v_med3_u32 v64, v65, v64, v70
	v_med3_u32 v65, v66, v65, v70
	v_med3_u32 v66, v67, v66, v70
	v_med3_u32 v67, v68, v67, v70
	v_med3_u32 v68, v69, v68, v70
	v_max_u32_e32 v69, v69, v70
	v_cmp_gt_i32_e32 vcc, 0, v10
	v_not_b32_e32 v70, v10
	v_or_b32_e32 v71, 0x80000000, v10
	v_cndmask_b32_e32 v70, v71, v70, vcc
	v_and_b32_e32 v70, 0xffffff80, v70
	v_add3_u32 v70, v0, v70, s71
	v_med3_u32 v54, v55, v54, v70
	v_med3_u32 v55, v56, v55, v70
	v_med3_u32 v56, v57, v56, v70
	v_med3_u32 v57, v58, v57, v70
	v_med3_u32 v58, v59, v58, v70
	v_med3_u32 v59, v60, v59, v70
	v_med3_u32 v60, v61, v60, v70
	v_med3_u32 v61, v62, v61, v70
	v_med3_u32 v62, v63, v62, v70
	v_med3_u32 v63, v64, v63, v70
	v_med3_u32 v64, v65, v64, v70
	v_med3_u32 v65, v66, v65, v70
	v_med3_u32 v66, v67, v66, v70
	v_med3_u32 v67, v68, v67, v70
	v_med3_u32 v68, v69, v68, v70
	v_max_u32_e32 v69, v69, v70
	v_cmp_gt_i32_e32 vcc, 0, v11
	v_not_b32_e32 v70, v11
	v_or_b32_e32 v71, 0x80000000, v11
	v_cndmask_b32_e32 v70, v71, v70, vcc
	v_and_b32_e32 v70, 0xffffff80, v70
	v_add3_u32 v70, v0, v70, s72
	v_med3_u32 v54, v55, v54, v70
	v_med3_u32 v55, v56, v55, v70
	v_med3_u32 v56, v57, v56, v70
	v_med3_u32 v57, v58, v57, v70
	v_med3_u32 v58, v59, v58, v70
	v_med3_u32 v59, v60, v59, v70
	v_med3_u32 v60, v61, v60, v70
	v_med3_u32 v61, v62, v61, v70
	v_med3_u32 v62, v63, v62, v70
	v_med3_u32 v63, v64, v63, v70
	v_med3_u32 v64, v65, v64, v70
	v_med3_u32 v65, v66, v65, v70
	v_med3_u32 v66, v67, v66, v70
	v_med3_u32 v67, v68, v67, v70
	v_med3_u32 v68, v69, v68, v70
	v_max_u32_e32 v69, v69, v70
	v_cmp_gt_i32_e32 vcc, 0, v12
	v_not_b32_e32 v70, v12
	v_or_b32_e32 v71, 0x80000000, v12
	v_cndmask_b32_e32 v70, v71, v70, vcc
	v_and_b32_e32 v70, 0xffffff80, v70
	v_add3_u32 v70, v0, v70, s73
	v_med3_u32 v54, v55, v54, v70
	v_med3_u32 v55, v56, v55, v70
	v_med3_u32 v56, v57, v56, v70
	v_med3_u32 v57, v58, v57, v70
	v_med3_u32 v58, v59, v58, v70
	v_med3_u32 v59, v60, v59, v70
	v_med3_u32 v60, v61, v60, v70
	v_med3_u32 v61, v62, v61, v70
	v_med3_u32 v62, v63, v62, v70
	v_med3_u32 v63, v64, v63, v70
	v_med3_u32 v64, v65, v64, v70
	v_med3_u32 v65, v66, v65, v70
	v_med3_u32 v66, v67, v66, v70
	v_med3_u32 v67, v68, v67, v70
	v_med3_u32 v68, v69, v68, v70
	v_max_u32_e32 v69, v69, v70
	v_cmp_gt_i32_e32 vcc, 0, v13
	v_not_b32_e32 v70, v13
	v_or_b32_e32 v71, 0x80000000, v13
	v_cndmask_b32_e32 v70, v71, v70, vcc
	v_and_b32_e32 v70, 0xffffff80, v70
	v_add3_u32 v70, v0, v70, s77
	v_med3_u32 v54, v55, v54, v70
	v_med3_u32 v55, v56, v55, v70
	v_med3_u32 v56, v57, v56, v70
	v_med3_u32 v57, v58, v57, v70
	v_med3_u32 v58, v59, v58, v70
	v_med3_u32 v59, v60, v59, v70
	v_med3_u32 v60, v61, v60, v70
	v_med3_u32 v61, v62, v61, v70
	v_med3_u32 v62, v63, v62, v70
	v_med3_u32 v63, v64, v63, v70
	v_med3_u32 v64, v65, v64, v70
	v_med3_u32 v65, v66, v65, v70
	v_med3_u32 v66, v67, v66, v70
	v_med3_u32 v67, v68, v67, v70
	v_med3_u32 v68, v69, v68, v70
	v_max_u32_e32 v69, v69, v70
	v_cmp_gt_i32_e32 vcc, 0, v14
	v_not_b32_e32 v70, v14
	v_or_b32_e32 v71, 0x80000000, v14
	v_cndmask_b32_e32 v70, v71, v70, vcc
	v_and_b32_e32 v70, 0xffffff80, v70
	v_add3_u32 v70, v0, v70, s78
	v_med3_u32 v54, v55, v54, v70
	v_med3_u32 v55, v56, v55, v70
	v_med3_u32 v56, v57, v56, v70
	v_med3_u32 v57, v58, v57, v70
	v_med3_u32 v58, v59, v58, v70
	v_med3_u32 v59, v60, v59, v70
	v_med3_u32 v60, v61, v60, v70
	v_med3_u32 v61, v62, v61, v70
	v_med3_u32 v62, v63, v62, v70
	v_med3_u32 v63, v64, v63, v70
	v_med3_u32 v64, v65, v64, v70
	v_med3_u32 v65, v66, v65, v70
	v_med3_u32 v66, v67, v66, v70
	v_med3_u32 v67, v68, v67, v70
	v_med3_u32 v68, v69, v68, v70
	v_max_u32_e32 v69, v69, v70
	v_cmp_gt_i32_e32 vcc, 0, v15
	v_not_b32_e32 v70, v15
	v_or_b32_e32 v71, 0x80000000, v15
	v_cndmask_b32_e32 v70, v71, v70, vcc
	v_and_b32_e32 v70, 0xffffff80, v70
	v_add3_u32 v70, v0, v70, s79
	v_med3_u32 v54, v55, v54, v70
	v_med3_u32 v55, v56, v55, v70
	v_med3_u32 v56, v57, v56, v70
	v_med3_u32 v57, v58, v57, v70
	v_med3_u32 v58, v59, v58, v70
	v_med3_u32 v59, v60, v59, v70
	v_med3_u32 v60, v61, v60, v70
	v_med3_u32 v61, v62, v61, v70
	v_med3_u32 v62, v63, v62, v70
	v_med3_u32 v63, v64, v63, v70
	v_med3_u32 v64, v65, v64, v70
	v_med3_u32 v65, v66, v65, v70
	v_med3_u32 v66, v67, v66, v70
	v_med3_u32 v67, v68, v67, v70
	v_med3_u32 v68, v69, v68, v70
	v_max_u32_e32 v69, v69, v70
	s_cbranch_scc1 .LBB0_1873
; #define MFMA32(a, b, c) __builtin_amdgcn_mfma_f32_32x32x16_bf16((a), (b), (c), 0, 0, 0)
; DI int crow(int i, int h) { return (i & 3) + 8 * (i >> 2) + 4 * h; }
; DI unsigned f2ord(float f) { unsigned u = __float_as_uint(f); return (u & 0x80000000u) ? ~u : (u | 0x80000000u); }
; #define INS32(T, X) { _Pragma("unroll") for (int jj = 0; jj < 16; ++jj) { unsigned t_ = max(T[jj], X); X = min(T[jj], X); T[jj] = t_; } }
; __device__ __forceinline__ void route_task(const Params& p, int layer, const u16* qg, int rb, int hd, int r, int h) {
;     ...
;   for (int ph = 0; ph < 2; ++ph) {
;     bf16x8 qf[8];
; #pragma unroll
;     for (int s = 0; s < 8; ++s) qf[s] = *(const bf16x8*)(qg + ph * 128 + 16 * s);
;     const u16* kg = KY + ((size_t)((layer * 8 + hd) * 2 + ph) * 128 + r) * 128 + 8 * h;
;     unsigned tp[16];
; #pragma unroll
;     for (int jj = 0; jj < 16; ++jj) tp[jj] = 0u;
; #pragma unroll 1
;     for (int n = 0; n < 4; ++n) {
;       f32x16 acc;
; #pragma unroll
;       for (int e = 0; e < 16; ++e) acc[e] = 0.f;
; #pragma unroll
;       for (int s = 0; s < 8; ++s) {
;         bf16x8 kf = *(const bf16x8*)(kg + (size_t)n * 32 * 128 + 16 * s);
;         acc = MFMA32(kf, qf[s], acc);
;       }
; #pragma unroll
;       for (int e = 0; e < 16; ++e) {
;         unsigned key = (f2ord(acc[e]) & ~127u) | (unsigned)(127 - (n * 32 + crow(e, h)));
;         INS32(tp, key);
;       }
;     }
;     unsigned ot[16];
; #pragma unroll
;     for (int jj = 0; jj < 16; ++jj) ot[jj] = (unsigned)__shfl_xor((int)tp[jj], 32);
; #pragma unroll
;     for (int jj = 0; jj < 16; ++jj) { unsigned key = ot[jj]; INS32(tp, key); }
	ds_read_b128 v[16:19], v83 offset:256
	ds_read_b128 v[20:23], v83 offset:288
	ds_read_b128 v[24:27], v83 offset:320
	ds_read_b128 v[28:31], v83 offset:352
	ds_read_b128 v[32:35], v83 offset:384
	ds_read_b128 v[36:39], v83 offset:416
	ds_read_b128 v[40:43], v83 offset:448
	ds_read_b128 v[44:47], v83 offset:480
	v_and_b32_e32 v0, 64, v214
	v_add_u32_e32 v0, 64, v0
	v_xor_b32_e32 v1, 32, v214
	v_cmp_lt_i32_e32 vcc, v1, v0
	s_mov_b32 s18, 0
	v_lshl_add_u64 v[48:49], s[14:15], 0, v[48:49]
	v_cndmask_b32_e32 v0, v214, v1, vcc
	v_lshlrev_b32_e32 v85, 2, v0
	ds_bpermute_b32 v84, v85, v69
	ds_bpermute_b32 v82, v85, v68
	ds_bpermute_b32 v81, v85, v67
	ds_bpermute_b32 v80, v85, v66
	ds_bpermute_b32 v79, v85, v65
	ds_bpermute_b32 v78, v85, v64
	ds_bpermute_b32 v77, v85, v63
	ds_bpermute_b32 v76, v85, v62
	ds_bpermute_b32 v75, v85, v61
	ds_bpermute_b32 v74, v85, v60
	ds_bpermute_b32 v73, v85, v59
	ds_bpermute_b32 v72, v85, v58
	ds_bpermute_b32 v71, v85, v57
	ds_bpermute_b32 v70, v85, v56
	ds_bpermute_b32 v51, v85, v55
	ds_bpermute_b32 v50, v85, v54
	v_mov_b32_e32 v86, 0
	v_mov_b32_e32 v87, 0
	v_mov_b32_e32 v88, 0
	v_mov_b32_e32 v89, 0
	v_mov_b32_e32 v90, 0
	v_mov_b32_e32 v91, 0
	v_mov_b32_e32 v92, 0
	v_mov_b32_e32 v93, 0
	v_mov_b32_e32 v94, 0
	v_mov_b32_e32 v95, 0
	v_mov_b32_e32 v96, 0
	v_mov_b32_e32 v97, 0
	v_mov_b32_e32 v98, 0
	v_mov_b32_e32 v99, 0
	v_mov_b32_e32 v100, 0
	v_mov_b32_e32 v83, 0
.LBB0_1875:
	global_load_dwordx4 v[190:193], v[48:49], off offset:-128
	global_load_dwordx4 v[194:197], v[48:49], off offset:-96
	global_load_dwordx4 v[198:201], v[48:49], off offset:-64
	global_load_dwordx4 v[202:205], v[48:49], off offset:-32
	global_load_dwordx4 v[206:209], v[48:49], off
	global_load_dwordx4 v[216:219], v[48:49], off offset:32
	global_load_dwordx4 v[220:223], v[48:49], off offset:64
	global_load_dwordx4 v[224:227], v[48:49], off offset:96
	v_lshl_add_u64 v[48:49], v[48:49], 0, s[16:17]
	s_waitcnt vmcnt(7) lgkmcnt(14)
	v_mfma_f32_32x32x16_bf16 v[0:15], v[190:193], v[16:19], 0
	s_waitcnt vmcnt(6)
	v_mfma_f32_32x32x16_bf16 v[0:15], v[194:197], v[20:23], v[0:15]
	s_waitcnt vmcnt(5)
	v_mfma_f32_32x32x16_bf16 v[0:15], v[198:201], v[24:27], v[0:15]
	s_waitcnt vmcnt(4)
	v_mfma_f32_32x32x16_bf16 v[0:15], v[202:205], v[28:31], v[0:15]
	s_waitcnt vmcnt(3)
	v_mfma_f32_32x32x16_bf16 v[0:15], v[206:209], v[32:35], v[0:15]
	s_waitcnt vmcnt(2)
	v_mfma_f32_32x32x16_bf16 v[0:15], v[216:219], v[36:39], v[0:15]
	s_waitcnt vmcnt(1)
	v_mfma_f32_32x32x16_bf16 v[0:15], v[220:223], v[40:43], v[0:15]
	s_waitcnt vmcnt(0)
	v_mfma_f32_32x32x16_bf16 v[0:15], v[224:227], v[44:47], v[0:15]
	s_nop 11
	v_cmp_gt_i32_e32 vcc, 0, v0
	v_not_b32_e32 v101, v0
	v_or_b32_e32 v102, 0x80000000, v0
	v_cndmask_b32_e32 v101, v102, v101, vcc
	v_and_b32_e32 v101, 0xffffff80, v101
	v_add_u32_e32 v0, s18, v53
	s_sub_i32 s18, s18, 32
	s_cmpk_lg_i32 s18, 0xff80
	v_add3_u32 v101, v0, v101, s61
	v_med3_u32 v83, v100, v83, v101
	v_med3_u32 v100, v99, v100, v101
	v_med3_u32 v99, v98, v99, v101
	v_med3_u32 v98, v97, v98, v101
	v_med3_u32 v97, v96, v97, v101
	v_med3_u32 v96, v95, v96, v101
	v_med3_u32 v95, v94, v95, v101
	v_med3_u32 v94, v93, v94, v101
	v_med3_u32 v93, v92, v93, v101
	v_med3_u32 v92, v91, v92, v101
	v_med3_u32 v91, v90, v91, v101
	v_med3_u32 v90, v89, v90, v101
	v_med3_u32 v89, v88, v89, v101
	v_med3_u32 v88, v87, v88, v101
	v_med3_u32 v87, v86, v87, v101
	v_max_u32_e32 v86, v86, v101
	v_cmp_gt_i32_e32 vcc, 0, v1
	v_not_b32_e32 v101, v1
	v_or_b32_e32 v102, 0x80000000, v1
	v_cndmask_b32_e32 v101, v102, v101, vcc
	v_and_b32_e32 v101, 0xffffff80, v101
	v_add3_u32 v101, v0, v101, s62
	v_med3_u32 v83, v100, v83, v101
	v_med3_u32 v100, v99, v100, v101
	v_med3_u32 v99, v98, v99, v101
	v_med3_u32 v98, v97, v98, v101
	v_med3_u32 v97, v96, v97, v101
	v_med3_u32 v96, v95, v96, v101
	v_med3_u32 v95, v94, v95, v101
	v_med3_u32 v94, v93, v94, v101
	v_med3_u32 v93, v92, v93, v101
	v_med3_u32 v92, v91, v92, v101
	v_med3_u32 v91, v90, v91, v101
	v_med3_u32 v90, v89, v90, v101
	v_med3_u32 v89, v88, v89, v101
	v_med3_u32 v88, v87, v88, v101
	v_med3_u32 v87, v86, v87, v101
	v_max_u32_e32 v86, v86, v101
	v_cmp_gt_i32_e32 vcc, 0, v2
	v_not_b32_e32 v101, v2
	v_or_b32_e32 v102, 0x80000000, v2
	v_cndmask_b32_e32 v101, v102, v101, vcc
	v_and_b32_e32 v101, 0xffffff80, v101
	v_add3_u32 v101, v0, v101, s63
	v_med3_u32 v83, v100, v83, v101
	v_med3_u32 v100, v99, v100, v101
	v_med3_u32 v99, v98, v99, v101
	v_med3_u32 v98, v97, v98, v101
	v_med3_u32 v97, v96, v97, v101
	v_med3_u32 v96, v95, v96, v101
	v_med3_u32 v95, v94, v95, v101
	v_med3_u32 v94, v93, v94, v101
	v_med3_u32 v93, v92, v93, v101
	v_med3_u32 v92, v91, v92, v101
	v_med3_u32 v91, v90, v91, v101
	v_med3_u32 v90, v89, v90, v101
	v_med3_u32 v89, v88, v89, v101
	v_med3_u32 v88, v87, v88, v101
	v_med3_u32 v87, v86, v87, v101
	v_max_u32_e32 v86, v86, v101
	v_cmp_gt_i32_e32 vcc, 0, v3
	v_not_b32_e32 v101, v3
	v_or_b32_e32 v102, 0x80000000, v3
	v_cndmask_b32_e32 v101, v102, v101, vcc
	v_and_b32_e32 v101, 0xffffff80, v101
	v_add3_u32 v101, v0, v101, s64
	v_med3_u32 v83, v100, v83, v101
	v_med3_u32 v100, v99, v100, v101
	v_med3_u32 v99, v98, v99, v101
	v_med3_u32 v98, v97, v98, v101
	v_med3_u32 v97, v96, v97, v101
	v_med3_u32 v96, v95, v96, v101
	v_med3_u32 v95, v94, v95, v101
	v_med3_u32 v94, v93, v94, v101
	v_med3_u32 v93, v92, v93, v101
	v_med3_u32 v92, v91, v92, v101
	v_med3_u32 v91, v90, v91, v101
	v_med3_u32 v90, v89, v90, v101
	v_med3_u32 v89, v88, v89, v101
	v_med3_u32 v88, v87, v88, v101
	v_med3_u32 v87, v86, v87, v101
	v_max_u32_e32 v86, v86, v101
	v_cmp_gt_i32_e32 vcc, 0, v4
	v_not_b32_e32 v101, v4
	v_or_b32_e32 v102, 0x80000000, v4
; DI int crow(int i, int h) { return (i & 3) + 8 * (i >> 2) + 4 * h; }
; DI unsigned f2ord(float f) { unsigned u = __float_as_uint(f); return (u & 0x80000000u) ? ~u : (u | 0x80000000u); }
; #define INS32(T, X) { _Pragma("unroll") for (int jj = 0; jj < 16; ++jj) { unsigned t_ = max(T[jj], X); X = min(T[jj], X); T[jj] = t_; } }
; __device__ __forceinline__ void route_task(const Params& p, int layer, const u16* qg, int rb, int hd, int r, int h) {
;     ...
; #pragma unroll
;       for (int e = 0; e < 16; ++e) {
;         unsigned key = (f2ord(acc[e]) & ~127u) | (unsigned)(127 - (n * 32 + crow(e, h)));
;         INS32(tp, key);
;       }
;     }
	v_cndmask_b32_e32 v101, v102, v101, vcc
	v_and_b32_e32 v101, 0xffffff80, v101
	v_add3_u32 v101, v0, v101, s65
	v_med3_u32 v83, v100, v83, v101
	v_med3_u32 v100, v99, v100, v101
	v_med3_u32 v99, v98, v99, v101
	v_med3_u32 v98, v97, v98, v101
	v_med3_u32 v97, v96, v97, v101
	v_med3_u32 v96, v95, v96, v101
	v_med3_u32 v95, v94, v95, v101
	v_med3_u32 v94, v93, v94, v101
	v_med3_u32 v93, v92, v93, v101
	v_med3_u32 v92, v91, v92, v101
	v_med3_u32 v91, v90, v91, v101
	v_med3_u32 v90, v89, v90, v101
	v_med3_u32 v89, v88, v89, v101
	v_med3_u32 v88, v87, v88, v101
	v_med3_u32 v87, v86, v87, v101
	v_max_u32_e32 v86, v86, v101
	v_cmp_gt_i32_e32 vcc, 0, v5
	v_not_b32_e32 v101, v5
	v_or_b32_e32 v102, 0x80000000, v5
	v_cndmask_b32_e32 v101, v102, v101, vcc
	v_and_b32_e32 v101, 0xffffff80, v101
	v_add3_u32 v101, v0, v101, s66
	v_med3_u32 v83, v100, v83, v101
	v_med3_u32 v100, v99, v100, v101
	v_med3_u32 v99, v98, v99, v101
	v_med3_u32 v98, v97, v98, v101
	v_med3_u32 v97, v96, v97, v101
	v_med3_u32 v96, v95, v96, v101
	v_med3_u32 v95, v94, v95, v101
	v_med3_u32 v94, v93, v94, v101
	v_med3_u32 v93, v92, v93, v101
	v_med3_u32 v92, v91, v92, v101
	v_med3_u32 v91, v90, v91, v101
	v_med3_u32 v90, v89, v90, v101
	v_med3_u32 v89, v88, v89, v101
	v_med3_u32 v88, v87, v88, v101
	v_med3_u32 v87, v86, v87, v101
	v_max_u32_e32 v86, v86, v101
	v_cmp_gt_i32_e32 vcc, 0, v6
	v_not_b32_e32 v101, v6
	v_or_b32_e32 v102, 0x80000000, v6
	v_cndmask_b32_e32 v101, v102, v101, vcc
	v_and_b32_e32 v101, 0xffffff80, v101
	v_add3_u32 v101, v0, v101, s67
	v_med3_u32 v83, v100, v83, v101
	v_med3_u32 v100, v99, v100, v101
	v_med3_u32 v99, v98, v99, v101
	v_med3_u32 v98, v97, v98, v101
	v_med3_u32 v97, v96, v97, v101
	v_med3_u32 v96, v95, v96, v101
	v_med3_u32 v95, v94, v95, v101
	v_med3_u32 v94, v93, v94, v101
	v_med3_u32 v93, v92, v93, v101
	v_med3_u32 v92, v91, v92, v101
	v_med3_u32 v91, v90, v91, v101
	v_med3_u32 v90, v89, v90, v101
	v_med3_u32 v89, v88, v89, v101
	v_med3_u32 v88, v87, v88, v101
	v_med3_u32 v87, v86, v87, v101
	v_max_u32_e32 v86, v86, v101
	v_cmp_gt_i32_e32 vcc, 0, v7
	v_not_b32_e32 v101, v7
	v_or_b32_e32 v102, 0x80000000, v7
	v_cndmask_b32_e32 v101, v102, v101, vcc
	v_and_b32_e32 v101, 0xffffff80, v101
	v_add3_u32 v101, v0, v101, s68
	v_med3_u32 v83, v100, v83, v101
	v_med3_u32 v100, v99, v100, v101
	v_med3_u32 v99, v98, v99, v101
	v_med3_u32 v98, v97, v98, v101
	v_med3_u32 v97, v96, v97, v101
	v_med3_u32 v96, v95, v96, v101
	v_med3_u32 v95, v94, v95, v101
	v_med3_u32 v94, v93, v94, v101
	v_med3_u32 v93, v92, v93, v101
	v_med3_u32 v92, v91, v92, v101
	v_med3_u32 v91, v90, v91, v101
	v_med3_u32 v90, v89, v90, v101
	v_med3_u32 v89, v88, v89, v101
	v_med3_u32 v88, v87, v88, v101
	v_med3_u32 v87, v86, v87, v101
	v_max_u32_e32 v86, v86, v101
	v_cmp_gt_i32_e32 vcc, 0, v8
	v_not_b32_e32 v101, v8
	v_or_b32_e32 v102, 0x80000000, v8
	v_cndmask_b32_e32 v101, v102, v101, vcc
	v_and_b32_e32 v101, 0xffffff80, v101
	v_add3_u32 v101, v0, v101, s69
	v_med3_u32 v83, v100, v83, v101
	v_med3_u32 v100, v99, v100, v101
	v_med3_u32 v99, v98, v99, v101
	v_med3_u32 v98, v97, v98, v101
	v_med3_u32 v97, v96, v97, v101
	v_med3_u32 v96, v95, v96, v101
	v_med3_u32 v95, v94, v95, v101
	v_med3_u32 v94, v93, v94, v101
	v_med3_u32 v93, v92, v93, v101
	v_med3_u32 v92, v91, v92, v101
	v_med3_u32 v91, v90, v91, v101
	v_med3_u32 v90, v89, v90, v101
	v_med3_u32 v89, v88, v89, v101
	v_med3_u32 v88, v87, v88, v101
	v_med3_u32 v87, v86, v87, v101
	v_max_u32_e32 v86, v86, v101
	v_cmp_gt_i32_e32 vcc, 0, v9
	v_not_b32_e32 v101, v9
	v_or_b32_e32 v102, 0x80000000, v9
	v_cndmask_b32_e32 v101, v102, v101, vcc
	v_and_b32_e32 v101, 0xffffff80, v101
	v_add3_u32 v101, v0, v101, s70
	v_med3_u32 v83, v100, v83, v101
	v_med3_u32 v100, v99, v100, v101
	v_med3_u32 v99, v98, v99, v101
	v_med3_u32 v98, v97, v98, v101
	v_med3_u32 v97, v96, v97, v101
	v_med3_u32 v96, v95, v96, v101
	v_med3_u32 v95, v94, v95, v101
	v_med3_u32 v94, v93, v94, v101
	v_med3_u32 v93, v92, v93, v101
	v_med3_u32 v92, v91, v92, v101
	v_med3_u32 v91, v90, v91, v101
	v_med3_u32 v90, v89, v90, v101
	v_med3_u32 v89, v88, v89, v101
	v_med3_u32 v88, v87, v88, v101
	v_med3_u32 v87, v86, v87, v101
	v_max_u32_e32 v86, v86, v101
	v_cmp_gt_i32_e32 vcc, 0, v10
	v_not_b32_e32 v101, v10
	v_or_b32_e32 v102, 0x80000000, v10
	v_cndmask_b32_e32 v101, v102, v101, vcc
	v_and_b32_e32 v101, 0xffffff80, v101
	v_add3_u32 v101, v0, v101, s71
	v_med3_u32 v83, v100, v83, v101
	v_med3_u32 v100, v99, v100, v101
	v_med3_u32 v99, v98, v99, v101
	v_med3_u32 v98, v97, v98, v101
	v_med3_u32 v97, v96, v97, v101
	v_med3_u32 v96, v95, v96, v101
	v_med3_u32 v95, v94, v95, v101
	v_med3_u32 v94, v93, v94, v101
	v_med3_u32 v93, v92, v93, v101
	v_med3_u32 v92, v91, v92, v101
	v_med3_u32 v91, v90, v91, v101
	v_med3_u32 v90, v89, v90, v101
	v_med3_u32 v89, v88, v89, v101
	v_med3_u32 v88, v87, v88, v101
	v_med3_u32 v87, v86, v87, v101
	v_max_u32_e32 v86, v86, v101
	v_cmp_gt_i32_e32 vcc, 0, v11
	v_not_b32_e32 v101, v11
	v_or_b32_e32 v102, 0x80000000, v11
	v_cndmask_b32_e32 v101, v102, v101, vcc
	v_and_b32_e32 v101, 0xffffff80, v101
	v_add3_u32 v101, v0, v101, s72
	v_med3_u32 v83, v100, v83, v101
	v_med3_u32 v100, v99, v100, v101
	v_med3_u32 v99, v98, v99, v101
	v_med3_u32 v98, v97, v98, v101
	v_med3_u32 v97, v96, v97, v101
	v_med3_u32 v96, v95, v96, v101
	v_med3_u32 v95, v94, v95, v101
	v_med3_u32 v94, v93, v94, v101
	v_med3_u32 v93, v92, v93, v101
	v_med3_u32 v92, v91, v92, v101
	v_med3_u32 v91, v90, v91, v101
	v_med3_u32 v90, v89, v90, v101
	v_med3_u32 v89, v88, v89, v101
	v_med3_u32 v88, v87, v88, v101
	v_med3_u32 v87, v86, v87, v101
	v_max_u32_e32 v86, v86, v101
	v_cmp_gt_i32_e32 vcc, 0, v12
; DI int crow(int i, int h) { return (i & 3) + 8 * (i >> 2) + 4 * h; }
; DI unsigned f2ord(float f) { unsigned u = __float_as_uint(f); return (u & 0x80000000u) ? ~u : (u | 0x80000000u); }
; #define INS32(T, X) { _Pragma("unroll") for (int jj = 0; jj < 16; ++jj) { unsigned t_ = max(T[jj], X); X = min(T[jj], X); T[jj] = t_; } }
; __device__ __forceinline__ void route_task(const Params& p, int layer, const u16* qg, int rb, int hd, int r, int h) {
;     ...
;       for (int e = 0; e < 16; ++e) {
;         unsigned key = (f2ord(acc[e]) & ~127u) | (unsigned)(127 - (n * 32 + crow(e, h)));
;         INS32(tp, key);
;       }
;     }
;     unsigned ot[16];
; #pragma unroll
;     for (int jj = 0; jj < 16; ++jj) ot[jj] = (unsigned)__shfl_xor((int)tp[jj], 32);
; #pragma unroll
;     for (int jj = 0; jj < 16; ++jj) { unsigned key = ot[jj]; INS32(tp, key); }
; #pragma unroll
;     for (int jj = 0; jj < 16; ++jj) top[ph][jj] = tp[jj];
;   }
;   if (h == 0) {
	v_not_b32_e32 v101, v12
	v_or_b32_e32 v102, 0x80000000, v12
	v_cndmask_b32_e32 v101, v102, v101, vcc
	v_and_b32_e32 v101, 0xffffff80, v101
	v_add3_u32 v101, v0, v101, s73
	v_med3_u32 v83, v100, v83, v101
	v_med3_u32 v100, v99, v100, v101
	v_med3_u32 v99, v98, v99, v101
	v_med3_u32 v98, v97, v98, v101
	v_med3_u32 v97, v96, v97, v101
	v_med3_u32 v96, v95, v96, v101
	v_med3_u32 v95, v94, v95, v101
	v_med3_u32 v94, v93, v94, v101
	v_med3_u32 v93, v92, v93, v101
	v_med3_u32 v92, v91, v92, v101
	v_med3_u32 v91, v90, v91, v101
	v_med3_u32 v90, v89, v90, v101
	v_med3_u32 v89, v88, v89, v101
	v_med3_u32 v88, v87, v88, v101
	v_med3_u32 v87, v86, v87, v101
	v_max_u32_e32 v86, v86, v101
	v_cmp_gt_i32_e32 vcc, 0, v13
	v_not_b32_e32 v101, v13
	v_or_b32_e32 v102, 0x80000000, v13
	v_cndmask_b32_e32 v101, v102, v101, vcc
	v_and_b32_e32 v101, 0xffffff80, v101
	v_add3_u32 v101, v0, v101, s77
	v_med3_u32 v83, v100, v83, v101
	v_med3_u32 v100, v99, v100, v101
	v_med3_u32 v99, v98, v99, v101
	v_med3_u32 v98, v97, v98, v101
	v_med3_u32 v97, v96, v97, v101
	v_med3_u32 v96, v95, v96, v101
	v_med3_u32 v95, v94, v95, v101
	v_med3_u32 v94, v93, v94, v101
	v_med3_u32 v93, v92, v93, v101
	v_med3_u32 v92, v91, v92, v101
	v_med3_u32 v91, v90, v91, v101
	v_med3_u32 v90, v89, v90, v101
	v_med3_u32 v89, v88, v89, v101
	v_med3_u32 v88, v87, v88, v101
	v_med3_u32 v87, v86, v87, v101
	v_max_u32_e32 v86, v86, v101
	v_cmp_gt_i32_e32 vcc, 0, v14
	v_not_b32_e32 v101, v14
	v_or_b32_e32 v102, 0x80000000, v14
	v_cndmask_b32_e32 v101, v102, v101, vcc
	v_and_b32_e32 v101, 0xffffff80, v101
	v_add3_u32 v101, v0, v101, s78
	v_med3_u32 v83, v100, v83, v101
	v_med3_u32 v100, v99, v100, v101
	v_med3_u32 v99, v98, v99, v101
	v_med3_u32 v98, v97, v98, v101
	v_med3_u32 v97, v96, v97, v101
	v_med3_u32 v96, v95, v96, v101
	v_med3_u32 v95, v94, v95, v101
	v_med3_u32 v94, v93, v94, v101
	v_med3_u32 v93, v92, v93, v101
	v_med3_u32 v92, v91, v92, v101
	v_med3_u32 v91, v90, v91, v101
	v_med3_u32 v90, v89, v90, v101
	v_med3_u32 v89, v88, v89, v101
	v_med3_u32 v88, v87, v88, v101
	v_med3_u32 v87, v86, v87, v101
	v_max_u32_e32 v86, v86, v101
	v_cmp_gt_i32_e32 vcc, 0, v15
	v_not_b32_e32 v101, v15
	v_or_b32_e32 v102, 0x80000000, v15
	v_cndmask_b32_e32 v101, v102, v101, vcc
	v_and_b32_e32 v101, 0xffffff80, v101
	v_add3_u32 v101, v0, v101, s79
	v_med3_u32 v83, v100, v83, v101
	v_med3_u32 v100, v99, v100, v101
	v_med3_u32 v99, v98, v99, v101
	v_med3_u32 v98, v97, v98, v101
	v_med3_u32 v97, v96, v97, v101
	v_med3_u32 v96, v95, v96, v101
	v_med3_u32 v95, v94, v95, v101
	v_med3_u32 v94, v93, v94, v101
	v_med3_u32 v93, v92, v93, v101
	v_med3_u32 v92, v91, v92, v101
	v_med3_u32 v91, v90, v91, v101
	v_med3_u32 v90, v89, v90, v101
	v_med3_u32 v89, v88, v89, v101
	v_med3_u32 v88, v87, v88, v101
	v_med3_u32 v87, v86, v87, v101
	v_max_u32_e32 v86, v86, v101
	s_cbranch_scc1 .LBB0_1875
	ds_bpermute_b32 v17, v85, v86
	ds_bpermute_b32 v16, v85, v87
	ds_bpermute_b32 v13, v85, v88
	ds_bpermute_b32 v12, v85, v89
	ds_bpermute_b32 v11, v85, v90
	ds_bpermute_b32 v10, v85, v91
	ds_bpermute_b32 v9, v85, v92
	ds_bpermute_b32 v8, v85, v93
	ds_bpermute_b32 v7, v85, v94
	ds_bpermute_b32 v6, v85, v95
	ds_bpermute_b32 v5, v85, v96
	ds_bpermute_b32 v4, v85, v97
	ds_bpermute_b32 v3, v85, v98
	ds_bpermute_b32 v2, v85, v99
	ds_bpermute_b32 v1, v85, v100
	ds_bpermute_b32 v0, v85, v83
	v_cmp_eq_u32_e32 vcc, 0, v139
	s_and_saveexec_b64 s[18:19], vcc
	s_cbranch_execz .LBB0_1867
	v_max_u32_e32 v14, v69, v84
	v_min_u32_e32 v15, v69, v84
	v_max_u32_e32 v18, v68, v15
	v_min_u32_e32 v15, v68, v15
	v_max_u32_e32 v31, v14, v82
	v_min_u32_e32 v14, v14, v82
	v_max_u32_e32 v19, v67, v15
	v_min_u32_e32 v15, v67, v15
	v_max_u32_e32 v32, v18, v14
	v_min_u32_e32 v14, v18, v14
	v_max_u32_e32 v20, v66, v15
	v_min_u32_e32 v15, v66, v15
	v_max_u32_e32 v18, v19, v14
	v_min_u32_e32 v14, v19, v14
	v_max_u32_e32 v21, v65, v15
	v_min_u32_e32 v15, v65, v15
	v_max_u32_e32 v19, v20, v14
	v_min_u32_e32 v14, v20, v14
	v_max_u32_e32 v22, v64, v15
	v_min_u32_e32 v15, v64, v15
	v_max_u32_e32 v20, v21, v14
	v_min_u32_e32 v14, v21, v14
	v_max_u32_e32 v23, v63, v15
	v_min_u32_e32 v15, v63, v15
	v_max_u32_e32 v21, v22, v14
	v_min_u32_e32 v14, v22, v14
	v_max_u32_e32 v24, v62, v15
	v_min_u32_e32 v15, v62, v15
	v_max_u32_e32 v22, v23, v14
	v_min_u32_e32 v14, v23, v14
	v_max_u32_e32 v25, v61, v15
	v_min_u32_e32 v15, v61, v15
	v_max_u32_e32 v23, v24, v14
	v_min_u32_e32 v14, v24, v14
	v_max_u32_e32 v26, v60, v15
	v_min_u32_e32 v15, v60, v15
	v_max_u32_e32 v24, v25, v14
	v_min_u32_e32 v14, v25, v14
	v_max_u32_e32 v27, v59, v15
	v_min_u32_e32 v15, v59, v15
	v_max_u32_e32 v25, v26, v14
	v_min_u32_e32 v14, v26, v14
	v_max_u32_e32 v28, v58, v15
	v_min_u32_e32 v15, v58, v15
	v_max_u32_e32 v26, v27, v14
	v_min_u32_e32 v14, v27, v14
	v_max_u32_e32 v29, v57, v15
	v_min_u32_e32 v15, v57, v15
	v_max_u32_e32 v27, v28, v14
	v_min_u32_e32 v14, v28, v14
	v_max_u32_e32 v30, v56, v15
	v_max_u32_e32 v28, v29, v14
	v_min_u32_e32 v14, v29, v14
	v_max_u32_e32 v29, v30, v14
	v_min_u32_e32 v30, v30, v14
	s_waitcnt lgkmcnt(14)
; #define INS32(T, X) { _Pragma("unroll") for (int jj = 0; jj < 16; ++jj) { unsigned t_ = max(T[jj], X); X = min(T[jj], X); T[jj] = t_; } }
; __device__ __forceinline__ void route_task(const Params& p, int layer, const u16* qg, int rb, int hd, int r, int h) {
;     ...
;     for (int jj = 0; jj < 16; ++jj) ot[jj] = (unsigned)__shfl_xor((int)tp[jj], 32);
; #pragma unroll
;     for (int jj = 0; jj < 16; ++jj) { unsigned key = ot[jj]; INS32(tp, key); }
	v_max_u32_e32 v14, v31, v81
	v_min_u32_e32 v31, v31, v81
	v_max_u32_e32 v33, v32, v31
	v_min_u32_e32 v31, v32, v31
	v_max_u32_e32 v32, v18, v31
	v_min_u32_e32 v18, v18, v31
	v_max_u32_e32 v31, v19, v18
	v_min_u32_e32 v18, v19, v18
	v_max_u32_e32 v19, v20, v18
	v_min_u32_e32 v18, v20, v18
	v_max_u32_e32 v20, v21, v18
	v_min_u32_e32 v18, v21, v18
	v_max_u32_e32 v21, v22, v18
	v_min_u32_e32 v18, v22, v18
	v_max_u32_e32 v22, v23, v18
	v_min_u32_e32 v18, v23, v18
	v_max_u32_e32 v23, v24, v18
	v_min_u32_e32 v18, v24, v18
	v_max_u32_e32 v24, v25, v18
	v_min_u32_e32 v18, v25, v18
	v_max_u32_e32 v25, v26, v18
	v_min_u32_e32 v18, v26, v18
	v_max_u32_e32 v26, v27, v18
	v_min_u32_e32 v18, v27, v18
	v_max_u32_e32 v27, v28, v18
	v_min_u32_e32 v18, v28, v18
	v_max_u32_e32 v28, v29, v18
	v_min_u32_e32 v18, v29, v18
	v_max_u32_e32 v29, v14, v80
	v_min_u32_e32 v14, v14, v80
	v_max_u32_e32 v34, v33, v14
	v_min_u32_e32 v14, v33, v14
	v_max_u32_e32 v33, v32, v14
	v_min_u32_e32 v14, v32, v14
	v_max_u32_e32 v32, v31, v14
	v_min_u32_e32 v14, v31, v14
	v_max_u32_e32 v31, v19, v14
	v_min_u32_e32 v14, v19, v14
	v_max_u32_e32 v19, v20, v14
	v_min_u32_e32 v14, v20, v14
	v_max_u32_e32 v20, v21, v14
	v_min_u32_e32 v14, v21, v14
	v_max_u32_e32 v21, v22, v14
	v_min_u32_e32 v14, v22, v14
	v_max_u32_e32 v22, v23, v14
	v_min_u32_e32 v14, v23, v14
	v_max_u32_e32 v23, v24, v14
	v_min_u32_e32 v14, v24, v14
	v_max_u32_e32 v24, v25, v14
	v_min_u32_e32 v14, v25, v14
	v_max_u32_e32 v25, v26, v14
	v_min_u32_e32 v14, v26, v14
	v_max_u32_e32 v26, v27, v14
	v_min_u32_e32 v14, v27, v14
	v_max_u32_e32 v27, v28, v14
	v_min_u32_e32 v28, v28, v14
	v_max_u32_e32 v14, v29, v79
	v_min_u32_e32 v29, v29, v79
	v_max_u32_e32 v35, v34, v29
	v_min_u32_e32 v29, v34, v29
	v_max_u32_e32 v34, v33, v29
	v_min_u32_e32 v29, v33, v29
	v_max_u32_e32 v33, v32, v29
	v_min_u32_e32 v29, v32, v29
	v_max_u32_e32 v32, v31, v29
	v_min_u32_e32 v29, v31, v29
	v_max_u32_e32 v31, v19, v29
	v_min_u32_e32 v19, v19, v29
	v_max_u32_e32 v29, v20, v19
	v_min_u32_e32 v19, v20, v19
	v_max_u32_e32 v20, v21, v19
	v_min_u32_e32 v19, v21, v19
	v_max_u32_e32 v21, v22, v19
	v_min_u32_e32 v19, v22, v19
	v_max_u32_e32 v22, v23, v19
	v_min_u32_e32 v19, v23, v19
	v_max_u32_e32 v23, v24, v19
	v_min_u32_e32 v19, v24, v19
	v_max_u32_e32 v24, v25, v19
	v_min_u32_e32 v19, v25, v19
	v_max_u32_e32 v25, v26, v19
	v_min_u32_e32 v19, v26, v19
	v_max_u32_e32 v26, v27, v19
	v_min_u32_e32 v19, v27, v19
	v_max_u32_e32 v27, v14, v78
	v_min_u32_e32 v14, v14, v78
	v_max_u32_e32 v36, v35, v14
	v_min_u32_e32 v14, v35, v14
	v_max_u32_e32 v35, v34, v14
	v_min_u32_e32 v14, v34, v14
	v_max_u32_e32 v34, v33, v14
	v_min_u32_e32 v14, v33, v14
	v_max_u32_e32 v33, v32, v14
	v_min_u32_e32 v14, v32, v14
	v_max_u32_e32 v32, v31, v14
	v_min_u32_e32 v14, v31, v14
	v_max_u32_e32 v31, v29, v14
	v_min_u32_e32 v14, v29, v14
	v_max_u32_e32 v29, v20, v14
	v_min_u32_e32 v14, v20, v14
	v_max_u32_e32 v20, v21, v14
	v_min_u32_e32 v14, v21, v14
	v_max_u32_e32 v21, v22, v14
	v_min_u32_e32 v14, v22, v14
	v_max_u32_e32 v22, v23, v14
	v_min_u32_e32 v14, v23, v14
	v_max_u32_e32 v23, v24, v14
	v_min_u32_e32 v14, v24, v14
	v_max_u32_e32 v24, v25, v14
	v_min_u32_e32 v14, v25, v14
	v_max_u32_e32 v25, v26, v14
	v_min_u32_e32 v26, v26, v14
	v_max_u32_e32 v14, v27, v77
	v_min_u32_e32 v27, v27, v77
	v_max_u32_e32 v37, v36, v27
	v_min_u32_e32 v27, v36, v27
	v_max_u32_e32 v36, v35, v27
	v_min_u32_e32 v27, v35, v27
	v_max_u32_e32 v35, v34, v27
	v_min_u32_e32 v27, v34, v27
	v_max_u32_e32 v34, v33, v27
	v_min_u32_e32 v27, v33, v27
	v_max_u32_e32 v33, v32, v27
	v_min_u32_e32 v27, v32, v27
	v_max_u32_e32 v32, v31, v27
	v_min_u32_e32 v27, v31, v27
	v_max_u32_e32 v31, v29, v27
	v_min_u32_e32 v27, v29, v27
	v_max_u32_e32 v29, v20, v27
	v_min_u32_e32 v20, v20, v27
	v_max_u32_e32 v27, v21, v20
	v_min_u32_e32 v20, v21, v20
	v_max_u32_e32 v21, v22, v20
	v_min_u32_e32 v20, v22, v20
	v_max_u32_e32 v22, v23, v20
	v_min_u32_e32 v20, v23, v20
	v_max_u32_e32 v23, v24, v20
	v_min_u32_e32 v20, v24, v20
	v_max_u32_e32 v24, v25, v20
	v_min_u32_e32 v20, v25, v20
	v_max_u32_e32 v25, v14, v76
	v_min_u32_e32 v14, v14, v76
	v_max_u32_e32 v38, v37, v14
	v_min_u32_e32 v14, v37, v14
	v_max_u32_e32 v37, v36, v14
	v_min_u32_e32 v14, v36, v14
	v_max_u32_e32 v36, v35, v14
	v_min_u32_e32 v14, v35, v14
	v_max_u32_e32 v35, v34, v14
	v_min_u32_e32 v14, v34, v14
	v_max_u32_e32 v34, v33, v14
	v_min_u32_e32 v14, v33, v14
	v_max_u32_e32 v33, v32, v14
	v_min_u32_e32 v14, v32, v14
	v_max_u32_e32 v32, v31, v14
	v_min_u32_e32 v14, v31, v14
	v_max_u32_e32 v31, v29, v14
	v_min_u32_e32 v14, v29, v14
	v_max_u32_e32 v29, v27, v14
	v_min_u32_e32 v14, v27, v14
	v_max_u32_e32 v27, v21, v14
	v_min_u32_e32 v14, v21, v14
	v_max_u32_e32 v21, v22, v14
	v_min_u32_e32 v14, v22, v14
	v_max_u32_e32 v22, v23, v14
	v_min_u32_e32 v14, v23, v14
	v_max_u32_e32 v23, v24, v14
	v_min_u32_e32 v24, v24, v14
	v_max_u32_e32 v14, v25, v75
	v_min_u32_e32 v25, v25, v75
	v_max_u32_e32 v39, v38, v25
	v_min_u32_e32 v25, v38, v25
	v_max_u32_e32 v38, v37, v25
	v_min_u32_e32 v25, v37, v25
	v_max_u32_e32 v37, v36, v25
	v_min_u32_e32 v25, v36, v25
	v_max_u32_e32 v36, v35, v25
	v_min_u32_e32 v25, v35, v25
	v_max_u32_e32 v35, v34, v25
	v_min_u32_e32 v25, v34, v25
	v_max_u32_e32 v34, v33, v25
	v_min_u32_e32 v25, v33, v25
	v_max_u32_e32 v33, v32, v25
	v_min_u32_e32 v25, v32, v25
	v_max_u32_e32 v32, v31, v25
	v_min_u32_e32 v25, v31, v25
	v_max_u32_e32 v31, v29, v25
	v_min_u32_e32 v25, v29, v25
	v_max_u32_e32 v29, v27, v25
	v_min_u32_e32 v25, v27, v25
	v_max_u32_e32 v27, v21, v25
	v_min_u32_e32 v21, v21, v25
	v_max_u32_e32 v25, v22, v21
	v_min_u32_e32 v21, v22, v21
; #define INS32(T, X) { _Pragma("unroll") for (int jj = 0; jj < 16; ++jj) { unsigned t_ = max(T[jj], X); X = min(T[jj], X); T[jj] = t_; } }
; __device__ __forceinline__ void route_task(const Params& p, int layer, const u16* qg, int rb, int hd, int r, int h) {
;     ...
;     for (int jj = 0; jj < 16; ++jj) ot[jj] = (unsigned)__shfl_xor((int)tp[jj], 32);
; #pragma unroll
;     for (int jj = 0; jj < 16; ++jj) { unsigned key = ot[jj]; INS32(tp, key); }
	v_max_u32_e32 v22, v23, v21
	v_min_u32_e32 v21, v23, v21
	v_max_u32_e32 v23, v14, v74
	v_min_u32_e32 v14, v14, v74
	v_max_u32_e32 v40, v39, v14
	v_min_u32_e32 v14, v39, v14
	v_max_u32_e32 v39, v38, v14
	v_min_u32_e32 v14, v38, v14
	v_max_u32_e32 v38, v37, v14
	v_min_u32_e32 v14, v37, v14
	v_max_u32_e32 v37, v36, v14
	v_min_u32_e32 v14, v36, v14
	v_max_u32_e32 v36, v35, v14
	v_min_u32_e32 v14, v35, v14
	v_max_u32_e32 v35, v34, v14
	v_min_u32_e32 v14, v34, v14
	v_max_u32_e32 v34, v33, v14
	v_min_u32_e32 v14, v33, v14
	v_max_u32_e32 v33, v32, v14
	v_min_u32_e32 v14, v32, v14
	v_max_u32_e32 v32, v31, v14
	v_min_u32_e32 v14, v31, v14
	v_max_u32_e32 v31, v29, v14
	v_min_u32_e32 v14, v29, v14
	v_max_u32_e32 v29, v27, v14
	v_min_u32_e32 v14, v27, v14
	v_max_u32_e32 v27, v25, v14
	v_min_u32_e32 v14, v25, v14
	v_max_u32_e32 v25, v22, v14
	v_min_u32_e32 v22, v22, v14
	v_max_u32_e32 v14, v23, v73
	v_min_u32_e32 v23, v23, v73
	v_max_u32_e32 v41, v40, v23
	v_min_u32_e32 v23, v40, v23
	v_max_u32_e32 v40, v39, v23
	v_min_u32_e32 v23, v39, v23
	v_max_u32_e32 v39, v38, v23
	v_min_u32_e32 v23, v38, v23
	v_max_u32_e32 v38, v37, v23
	v_min_u32_e32 v23, v37, v23
	v_max_u32_e32 v37, v36, v23
	v_min_u32_e32 v23, v36, v23
	v_max_u32_e32 v36, v35, v23
	v_min_u32_e32 v23, v35, v23
	v_max_u32_e32 v35, v34, v23
	v_min_u32_e32 v23, v34, v23
	v_max_u32_e32 v34, v33, v23
	v_min_u32_e32 v23, v33, v23
	v_max_u32_e32 v33, v32, v23
	v_min_u32_e32 v23, v32, v23
	v_max_u32_e32 v32, v31, v23
	v_min_u32_e32 v23, v31, v23
	v_max_u32_e32 v31, v29, v23
	v_min_u32_e32 v23, v29, v23
	v_max_u32_e32 v29, v27, v23
	v_min_u32_e32 v23, v27, v23
	v_max_u32_e32 v27, v25, v23
	v_min_u32_e32 v23, v25, v23
	v_max_u32_e32 v25, v14, v72
	v_min_u32_e32 v14, v14, v72
	v_max_u32_e32 v42, v41, v14
	v_min_u32_e32 v14, v41, v14
	v_max_u32_e32 v41, v40, v14
	v_min_u32_e32 v14, v40, v14
	v_max_u32_e32 v40, v39, v14
	v_min_u32_e32 v14, v39, v14
	v_max_u32_e32 v39, v38, v14
	v_min_u32_e32 v14, v38, v14
	v_max_u32_e32 v38, v37, v14
	v_min_u32_e32 v14, v37, v14
	v_max_u32_e32 v37, v36, v14
	v_min_u32_e32 v14, v36, v14
	v_max_u32_e32 v36, v35, v14
	v_min_u32_e32 v14, v35, v14
	v_max_u32_e32 v35, v34, v14
	v_min_u32_e32 v14, v34, v14
	v_max_u32_e32 v34, v33, v14
	v_min_u32_e32 v14, v33, v14
	v_max_u32_e32 v33, v32, v14
	v_min_u32_e32 v14, v32, v14
	v_max_u32_e32 v32, v31, v14
	v_min_u32_e32 v14, v31, v14
	v_max_u32_e32 v31, v29, v14
	v_min_u32_e32 v14, v29, v14
	v_max_u32_e32 v29, v27, v14
	v_min_u32_e32 v27, v27, v14
	v_max_u32_e32 v14, v25, v71
	v_min_u32_e32 v25, v25, v71
	v_max_u32_e32 v43, v42, v25
	v_min_u32_e32 v25, v42, v25
	v_max_u32_e32 v42, v41, v25
	v_min_u32_e32 v25, v41, v25
	v_max_u32_e32 v41, v40, v25
	v_min_u32_e32 v25, v40, v25
	v_max_u32_e32 v40, v39, v25
	v_min_u32_e32 v25, v39, v25
	v_max_u32_e32 v39, v38, v25
	v_min_u32_e32 v25, v38, v25
	v_max_u32_e32 v38, v37, v25
	v_min_u32_e32 v25, v37, v25
	v_max_u32_e32 v37, v36, v25
	v_min_u32_e32 v25, v36, v25
	v_max_u32_e32 v36, v35, v25
	v_min_u32_e32 v25, v35, v25
	v_max_u32_e32 v35, v34, v25
	v_min_u32_e32 v25, v34, v25
	v_max_u32_e32 v34, v33, v25
	v_min_u32_e32 v25, v33, v25
	v_max_u32_e32 v33, v32, v25
	v_min_u32_e32 v25, v32, v25
	v_max_u32_e32 v32, v31, v25
	v_min_u32_e32 v25, v31, v25
	v_max_u32_e32 v31, v29, v25
	v_min_u32_e32 v25, v29, v25
	v_max_u32_e32 v29, v14, v70
	v_min_u32_e32 v14, v14, v70
	v_max_u32_e32 v44, v43, v14
	v_min_u32_e32 v14, v43, v14
	v_max_u32_e32 v43, v42, v14
	v_min_u32_e32 v14, v42, v14
	v_max_u32_e32 v42, v41, v14
	v_min_u32_e32 v14, v41, v14
	v_max_u32_e32 v41, v40, v14
	v_min_u32_e32 v14, v40, v14
	v_max_u32_e32 v40, v39, v14
	v_min_u32_e32 v14, v39, v14
	v_max_u32_e32 v39, v38, v14
	v_min_u32_e32 v14, v38, v14
	v_max_u32_e32 v38, v37, v14
	v_min_u32_e32 v14, v37, v14
	v_max_u32_e32 v37, v36, v14
	v_min_u32_e32 v14, v36, v14
	v_max_u32_e32 v36, v35, v14
	v_min_u32_e32 v14, v35, v14
	v_max_u32_e32 v35, v34, v14
	v_min_u32_e32 v14, v34, v14
	v_max_u32_e32 v34, v33, v14
	v_min_u32_e32 v14, v33, v14
	v_min_u32_e32 v15, v56, v15
	v_max_u32_e32 v33, v32, v14
	v_min_u32_e32 v14, v32, v14
	v_max_u32_e32 v32, v31, v14
	v_min_u32_e32 v31, v31, v14
	v_max_u32_e32 v14, v29, v51
	v_min_u32_e32 v29, v29, v51
	v_max_u32_e32 v63, v55, v15
	v_max_u32_e32 v46, v44, v29
	v_min_u32_e32 v29, v44, v29
	v_min_u32_e32 v47, v14, v50
	v_max_u32_e32 v64, v63, v30
	v_max_u32_e32 v45, v43, v29
	v_min_u32_e32 v29, v43, v29
	v_min_u32_e32 v48, v46, v47
	v_max_u32_e32 v65, v64, v18
	v_max_u32_e32 v44, v42, v29
	v_min_u32_e32 v29, v42, v29
	v_min_u32_e32 v49, v45, v48
	v_max_u32_e32 v66, v65, v28
	v_max_u32_e32 v43, v41, v29
	v_min_u32_e32 v29, v41, v29
	v_min_u32_e32 v51, v44, v49
	v_max_u32_e32 v67, v66, v19
	v_max_u32_e32 v42, v40, v29
	v_min_u32_e32 v29, v40, v29
	v_min_u32_e32 v53, v43, v51
	v_max_u32_e32 v68, v67, v26
	v_max_u32_e32 v41, v39, v29
	v_min_u32_e32 v29, v39, v29
	v_min_u32_e32 v56, v42, v53
	v_max_u32_e32 v69, v68, v20
	v_max_u32_e32 v40, v38, v29
	v_min_u32_e32 v29, v38, v29
	v_min_u32_e32 v57, v41, v56
	v_max_u32_e32 v70, v69, v24
	v_max_u32_e32 v39, v37, v29
	v_min_u32_e32 v29, v37, v29
	v_min_u32_e32 v58, v40, v57
	v_max_u32_e32 v71, v70, v21
	v_min_u32_e32 v30, v63, v30
	v_min_u32_e32 v15, v55, v15
	v_max_u32_e32 v38, v36, v29
	v_min_u32_e32 v29, v36, v29
	v_min_u32_e32 v59, v39, v58
	v_max_u32_e32 v72, v71, v22
	v_min_u32_e32 v28, v65, v28
	v_min_u32_e32 v18, v64, v18
	v_max3_u32 v15, v54, v15, v30
	v_max_u32_e32 v37, v35, v29
	v_min_u32_e32 v29, v35, v29
	v_min_u32_e32 v60, v38, v59
	v_max_u32_e32 v73, v72, v23
	v_min_u32_e32 v26, v67, v26
	v_min_u32_e32 v19, v66, v19
	v_max3_u32 v15, v15, v18, v28
	v_max_u32_e32 v36, v34, v29
	v_min_u32_e32 v29, v34, v29
	v_min_u32_e32 v61, v37, v60
	v_max_u32_e32 v74, v73, v27
	v_min_u32_e32 v24, v69, v24
	v_min_u32_e32 v20, v68, v20
	v_max3_u32 v15, v15, v19, v26
	v_max_u32_e32 v35, v33, v29
	v_min_u32_e32 v29, v33, v29
	v_min_u32_e32 v62, v36, v61
	v_max_u32_e32 v75, v74, v25
	v_min_u32_e32 v22, v71, v22
	v_min_u32_e32 v21, v70, v21
	v_max3_u32 v15, v15, v20, v24
	v_min_u32_e32 v18, v86, v17
	v_max_u32_e32 v17, v86, v17
	v_min_u32_e32 v33, v32, v29
	v_min_u32_e32 v34, v35, v62
	v_max_u32_e32 v29, v32, v29
	v_max_u32_e32 v76, v75, v31
	v_min_u32_e32 v27, v73, v27
	v_min_u32_e32 v23, v72, v23
	v_max3_u32 v15, v15, v21, v22
	v_max_u32_e32 v45, v45, v48
	v_min_u32_e32 v19, v87, v18
	v_max_u32_e32 v18, v87, v18
	v_min_u32_e32 v48, v17, v16
	v_max_u32_e32 v16, v17, v16
	v_min_u32_e32 v32, v29, v34
	v_max_u32_e32 v77, v76, v33
	v_min_u32_e32 v31, v75, v31
	v_min_u32_e32 v25, v74, v25
	v_max3_u32 v15, v15, v23, v27
	v_max_u32_e32 v44, v44, v49
	v_min_u32_e32 v20, v88, v19
	v_max_u32_e32 v19, v88, v19
	v_min_u32_e32 v49, v18, v48
	v_max_u32_e32 v18, v18, v48
	s_waitcnt lgkmcnt(13)
; #define INS32(T, X) { _Pragma("unroll") for (int jj = 0; jj < 16; ++jj) { unsigned t_ = max(T[jj], X); X = min(T[jj], X); T[jj] = t_; } }
; __device__ __forceinline__ void route_task(const Params& p, int layer, const u16* qg, int rb, int hd, int r, int h) {
;     ...
;     for (int jj = 0; jj < 16; ++jj) ot[jj] = (unsigned)__shfl_xor((int)tp[jj], 32);
; #pragma unroll
;     for (int jj = 0; jj < 16; ++jj) { unsigned key = ot[jj]; INS32(tp, key); }
	v_min_u32_e32 v17, v16, v13
	v_max_u32_e32 v13, v16, v13
	v_min_u32_e32 v78, v77, v32
	v_min_u32_e32 v33, v76, v33
	v_max3_u32 v15, v15, v25, v31
	v_max_u32_e32 v43, v43, v51
	v_min_u32_e32 v21, v89, v20
	v_max_u32_e32 v20, v89, v20
	v_min_u32_e32 v51, v19, v49
	v_max_u32_e32 v19, v19, v49
	v_min_u32_e32 v48, v18, v17
	v_max_u32_e32 v17, v18, v17
	s_waitcnt lgkmcnt(12)
	v_min_u32_e32 v16, v13, v12
	v_max3_u32 v15, v15, v33, v78
	v_max_u32_e32 v33, v77, v32
	v_add_u32_e32 v32, s34, v52
	v_min_u32_e32 v22, v90, v21
	v_max_u32_e32 v21, v90, v21
	v_min_u32_e32 v52, v20, v51
	v_max_u32_e32 v20, v20, v51
	v_min_u32_e32 v49, v19, v48
	v_max_u32_e32 v19, v19, v48
	v_min_u32_e32 v18, v17, v16
	v_max_u32_e32 v42, v42, v53
	v_min_u32_e32 v23, v91, v22
	v_max_u32_e32 v22, v91, v22
	v_min_u32_e32 v53, v21, v52
	v_max_u32_e32 v21, v21, v52
	v_min_u32_e32 v51, v20, v49
	v_max_u32_e32 v20, v20, v49
	v_min_u32_e32 v48, v19, v18
	v_max_u32_e32 v12, v13, v12
	v_min_u32_e32 v24, v92, v23
	v_max_u32_e32 v23, v92, v23
	v_min_u32_e32 v54, v22, v53
	v_max_u32_e32 v22, v22, v53
	v_min_u32_e32 v52, v21, v51
	v_max_u32_e32 v21, v21, v51
	v_min_u32_e32 v49, v20, v48
	v_max_u32_e32 v16, v17, v16
	s_waitcnt lgkmcnt(11)
	v_min_u32_e32 v13, v12, v11
	v_max_u32_e32 v11, v12, v11
	v_min_u32_e32 v25, v93, v24
	v_max_u32_e32 v24, v93, v24
	v_min_u32_e32 v55, v23, v54
	v_max_u32_e32 v23, v23, v54
	v_min_u32_e32 v53, v22, v52
	v_max_u32_e32 v22, v22, v52
	v_min_u32_e32 v51, v21, v49
	v_min_u32_e32 v17, v16, v13
	v_max_u32_e32 v13, v16, v13
	s_waitcnt lgkmcnt(10)
	v_min_u32_e32 v12, v11, v10
	v_max_u32_e32 v10, v11, v10
	v_max_u32_e32 v41, v41, v56
	v_min_u32_e32 v26, v94, v25
	v_max_u32_e32 v25, v94, v25
	v_min_u32_e32 v56, v24, v55
	v_max_u32_e32 v24, v24, v55
	v_min_u32_e32 v54, v23, v53
	v_max_u32_e32 v23, v23, v53
	v_min_u32_e32 v52, v22, v51
	v_max_u32_e32 v18, v19, v18
	v_min_u32_e32 v16, v13, v12
	v_max_u32_e32 v12, v13, v12
	s_waitcnt lgkmcnt(9)
	v_min_u32_e32 v11, v10, v9
	v_max_u32_e32 v9, v10, v9
	v_max_u32_e32 v40, v40, v57
	v_min_u32_e32 v27, v95, v26
	v_max_u32_e32 v26, v95, v26
	v_min_u32_e32 v57, v25, v56
	v_max_u32_e32 v25, v25, v56
	v_min_u32_e32 v55, v24, v54
	v_max_u32_e32 v24, v24, v54
	v_min_u32_e32 v53, v23, v52
	v_max_u32_e32 v20, v20, v48
	v_min_u32_e32 v19, v18, v17
	v_max_u32_e32 v17, v18, v17
	v_min_u32_e32 v13, v12, v11
	v_max_u32_e32 v11, v12, v11
	s_waitcnt lgkmcnt(8)
	v_min_u32_e32 v10, v9, v8
	v_max_u32_e32 v8, v9, v8
	v_max_u32_e32 v39, v39, v58
	v_min_u32_e32 v28, v96, v27
	v_max_u32_e32 v27, v96, v27
	v_min_u32_e32 v58, v26, v57
	v_max_u32_e32 v26, v26, v57
	v_min_u32_e32 v56, v25, v55
	v_max_u32_e32 v25, v25, v55
	v_min_u32_e32 v54, v24, v53
	v_max_u32_e32 v21, v21, v49
	v_min_u32_e32 v48, v20, v19
	v_max_u32_e32 v19, v20, v19
	v_min_u32_e32 v18, v17, v16
	v_min_u32_e32 v12, v11, v10
	v_max_u32_e32 v10, v11, v10
	s_waitcnt lgkmcnt(7)
	v_min_u32_e32 v9, v8, v7
	v_max_u32_e32 v7, v8, v7
	v_max_u32_e32 v34, v29, v34
	v_max_u32_e32 v38, v38, v59
	v_min_u32_e32 v29, v97, v28
	v_max_u32_e32 v28, v97, v28
	v_min_u32_e32 v59, v27, v58
	v_max_u32_e32 v27, v27, v58
	v_min_u32_e32 v57, v26, v56
	v_max_u32_e32 v26, v26, v56
	v_min_u32_e32 v55, v25, v54
	v_max_u32_e32 v22, v22, v51
	v_min_u32_e32 v49, v21, v48
	v_max_u32_e32 v21, v21, v48
	v_min_u32_e32 v20, v19, v18
	v_min_u32_e32 v11, v10, v9
	v_max_u32_e32 v9, v10, v9
	s_waitcnt lgkmcnt(6)
	v_min_u32_e32 v8, v7, v6
	v_max_u32_e32 v6, v7, v6
	v_max_u32_e32 v37, v37, v60
	v_min_u32_e32 v30, v98, v29
	v_max_u32_e32 v29, v98, v29
	v_min_u32_e32 v60, v28, v59
	v_max_u32_e32 v28, v28, v59
	v_min_u32_e32 v58, v27, v57
	v_max_u32_e32 v27, v27, v57
	v_min_u32_e32 v56, v26, v55
	v_max_u32_e32 v23, v23, v52
	v_min_u32_e32 v51, v22, v49
	v_max_u32_e32 v22, v22, v49
	v_min_u32_e32 v48, v21, v20
	v_max_u32_e32 v16, v17, v16
	v_min_u32_e32 v10, v9, v8
	v_max_u32_e32 v8, v9, v8
	s_waitcnt lgkmcnt(5)
	v_min_u32_e32 v7, v6, v5
	v_max_u32_e32 v5, v6, v5
	v_max_u32_e32 v36, v36, v61
	v_min_u32_e32 v31, v99, v30
	v_max_u32_e32 v30, v99, v30
	v_min_u32_e32 v61, v29, v60
	v_max_u32_e32 v29, v29, v60
	v_min_u32_e32 v59, v28, v58
	v_max_u32_e32 v28, v28, v58
	v_min_u32_e32 v57, v27, v56
	v_max_u32_e32 v24, v24, v53
	v_min_u32_e32 v52, v23, v51
	v_max_u32_e32 v23, v23, v51
	v_min_u32_e32 v49, v22, v48
	v_max_u32_e32 v18, v19, v18
	v_min_u32_e32 v17, v16, v13
	v_max_u32_e32 v13, v16, v13
	v_min_u32_e32 v9, v8, v7
	v_max_u32_e32 v7, v8, v7
	s_waitcnt lgkmcnt(4)
	v_min_u32_e32 v6, v5, v4
	v_max_u32_e32 v4, v5, v4
	v_max_u32_e32 v35, v35, v62
	v_max_u32_e32 v46, v46, v47
	v_min_u32_e32 v47, v100, v31
	v_max_u32_e32 v31, v100, v31
	v_min_u32_e32 v62, v30, v61
	v_max_u32_e32 v30, v30, v61
	v_min_u32_e32 v60, v29, v59
	v_max_u32_e32 v29, v29, v59
	v_min_u32_e32 v58, v28, v57
	v_max_u32_e32 v25, v25, v54
	v_min_u32_e32 v53, v24, v52
	v_max_u32_e32 v24, v24, v52
	v_min_u32_e32 v51, v23, v49
	v_min_u32_e32 v19, v18, v17
	v_max_u32_e32 v17, v18, v17
	v_min_u32_e32 v16, v13, v12
	v_max_u32_e32 v12, v13, v12
	v_min_u32_e32 v8, v7, v6
	v_max_u32_e32 v6, v7, v6
	s_waitcnt lgkmcnt(3)
	v_min_u32_e32 v5, v4, v3
	v_max_u32_e32 v3, v4, v3
	v_min_u32_e32 v63, v31, v62
	v_max_u32_e32 v31, v31, v62
	v_min_u32_e32 v61, v30, v60
	v_max_u32_e32 v30, v30, v60
	v_min_u32_e32 v59, v29, v58
	v_max_u32_e32 v26, v26, v55
	v_min_u32_e32 v54, v25, v53
	v_max_u32_e32 v25, v25, v53
	v_min_u32_e32 v52, v24, v51
	v_min_u32_e32 v18, v17, v16
	v_max_u32_e32 v16, v17, v16
	v_min_u32_e32 v13, v12, v11
	v_max_u32_e32 v11, v12, v11
	v_min_u32_e32 v7, v6, v5
	v_max_u32_e32 v5, v6, v5
	s_waitcnt lgkmcnt(2)
; DI unsigned f2ord(float f) { unsigned u = __float_as_uint(f); return (u & 0x80000000u) ? ~u : (u | 0x80000000u); }
; DI float ord2f(unsigned u) { return __uint_as_float((u & 0x80000000u) ? (u & 0x7fffffffu) : ~u); }
; #define INS32(T, X) { _Pragma("unroll") for (int jj = 0; jj < 16; ++jj) { unsigned t_ = max(T[jj], X); X = min(T[jj], X); T[jj] = t_; } }
; __device__ __forceinline__ void route_task(const Params& p, int layer, const u16* qg, int rb, int hd, int r, int h) {
;     ...
;     for (int jj = 0; jj < 16; ++jj) ot[jj] = (unsigned)__shfl_xor((int)tp[jj], 32);
; #pragma unroll
;     for (int jj = 0; jj < 16; ++jj) { unsigned key = ot[jj]; INS32(tp, key); }
; #pragma unroll
;     for (int jj = 0; jj < 16; ++jj) top[ph][jj] = tp[jj];
;   }
;   if (h == 0) {
;     unsigned ct[16];
; #pragma unroll
;     for (int jj = 0; jj < 16; ++jj) ct[jj] = 0u;
; #pragma unroll
;     for (int a = 0; a < 16; ++a) {
;       const float va = ord2f(top[0][a] & ~127u);
; #pragma unroll
;       for (int b = 0; b < 16; ++b) {
;         if ((a + 1) * (b + 1) <= 16) {
;           const float vb = ord2f(top[1][b] & ~127u);
;           unsigned key = (f2ord(va + vb) & ~255u) | (unsigned)(255 - (a * 16 + b));
;           INS32(ct, key);
;         }
;       }
;     }
	v_min_u32_e32 v4, v3, v2
	v_max_u32_e32 v2, v3, v2
	v_min_u32_e32 v62, v31, v61
	v_max_u32_e32 v31, v31, v61
	v_min_u32_e32 v60, v30, v59
	v_max_u32_e32 v27, v27, v56
	v_min_u32_e32 v55, v26, v54
	v_max_u32_e32 v26, v26, v54
	v_min_u32_e32 v53, v25, v52
	v_min_u32_e32 v17, v16, v13
	v_max_u32_e32 v13, v16, v13
	v_min_u32_e32 v12, v11, v10
	v_max_u32_e32 v10, v11, v10
	v_min_u32_e32 v6, v5, v4
	v_max_u32_e32 v4, v5, v4
	s_waitcnt lgkmcnt(1)
	v_min_u32_e32 v3, v2, v1
	v_max_u32_e32 v1, v2, v1
	v_max3_u32 v47, v83, v47, v63
	v_min_u32_e32 v61, v31, v60
	v_max_u32_e32 v28, v28, v57
	v_min_u32_e32 v56, v27, v55
	v_max_u32_e32 v27, v27, v55
	v_min_u32_e32 v54, v26, v53
	v_min_u32_e32 v16, v13, v12
	v_max_u32_e32 v12, v13, v12
	v_min_u32_e32 v11, v10, v9
	v_max_u32_e32 v9, v10, v9
	v_min_u32_e32 v5, v4, v3
	v_max_u32_e32 v3, v4, v3
	s_waitcnt lgkmcnt(0)
	v_min_u32_e32 v2, v1, v0
	v_max_u32_e32 v63, v1, v0
	v_max3_u32 v47, v47, v62, v61
	v_max_u32_e32 v29, v29, v58
	v_min_u32_e32 v57, v28, v56
	v_max_u32_e32 v28, v28, v56
	v_min_u32_e32 v55, v27, v54
	v_max_u32_e32 v20, v21, v20
	v_min_u32_e32 v13, v12, v11
	v_max_u32_e32 v11, v12, v11
	v_min_u32_e32 v10, v9, v8
	v_max_u32_e32 v8, v9, v8
	v_max_u32_e32 v62, v3, v2
	v_and_b32_e32 v0, 0x7fffff80, v63
	v_bitop3_b32 v1, v63, s61, v63 bitop3:0xcf
	v_cmp_gt_i32_e32 vcc, 0, v63
	v_max_u32_e32 v30, v30, v59
	v_min_u32_e32 v58, v29, v57
	v_max_u32_e32 v29, v29, v57
	v_min_u32_e32 v56, v28, v55
	v_max_u32_e32 v22, v22, v48
	v_min_u32_e32 v21, v20, v19
	v_max_u32_e32 v19, v20, v19
	v_min_u32_e32 v12, v11, v10
	v_max_u32_e32 v10, v11, v10
	v_min_u32_e32 v9, v8, v7
	v_max_u32_e32 v7, v8, v7
	v_min_u32_e32 v4, v3, v2
	v_max_u32_e32 v50, v14, v50
	v_cndmask_b32_e32 v1, v1, v0, vcc
	v_and_b32_e32 v0, 0x7fffff80, v62
	v_bitop3_b32 v2, v62, s61, v62 bitop3:0xcf
	v_cmp_gt_i32_e32 vcc, 0, v62
	v_max_u32_e32 v31, v31, v60
	v_min_u32_e32 v59, v30, v58
	v_max_u32_e32 v30, v30, v58
	v_min_u32_e32 v57, v29, v56
	v_max_u32_e32 v23, v23, v49
	v_min_u32_e32 v48, v22, v21
	v_max_u32_e32 v21, v22, v21
	v_min_u32_e32 v20, v19, v18
	v_max_u32_e32 v18, v19, v18
	v_min_u32_e32 v11, v10, v9
	v_max_u32_e32 v9, v10, v9
	v_min_u32_e32 v8, v7, v6
	v_max_u32_e32 v6, v7, v6
	v_cndmask_b32_e32 v0, v2, v0, vcc
	v_and_b32_e32 v2, 0x7fffff80, v50
	v_bitop3_b32 v3, v50, s61, v50 bitop3:0xcf
	v_cmp_gt_i32_e32 vcc, 0, v50
	v_min_u32_e32 v60, v31, v59
	v_max_u32_e32 v31, v31, v59
	v_min_u32_e32 v58, v30, v57
	v_max_u32_e32 v24, v24, v51
	v_min_u32_e32 v49, v23, v48
	v_max_u32_e32 v23, v23, v48
	v_min_u32_e32 v22, v21, v20
	v_min_u32_e32 v19, v18, v17
	v_max_u32_e32 v17, v18, v17
	v_min_u32_e32 v10, v9, v8
	v_max_u32_e32 v8, v9, v8
	v_min_u32_e32 v7, v6, v5
	v_max_u32_e32 v5, v6, v5
	v_cndmask_b32_e32 v2, v3, v2, vcc
	v_min_u32_e32 v59, v31, v58
	v_max_u32_e32 v25, v25, v52
	v_min_u32_e32 v51, v24, v49
	v_max_u32_e32 v24, v24, v49
	v_min_u32_e32 v48, v23, v22
	v_min_u32_e32 v18, v17, v16
	v_max_u32_e32 v16, v17, v16
	v_min_u32_e32 v9, v8, v7
	v_max_u32_e32 v7, v8, v7
	v_min_u32_e32 v6, v5, v4
	v_max_u32_e32 v61, v5, v4
	v_pk_add_f32 v[4:5], v[2:3], v[0:1] op_sel_hi:[0,1]
	v_max3_u32 v47, v47, v60, v59
	v_max_u32_e32 v26, v26, v53
	v_min_u32_e32 v52, v25, v51
	v_max_u32_e32 v25, v25, v51
	v_min_u32_e32 v49, v24, v48
	v_max_u32_e32 v20, v21, v20
	v_min_u32_e32 v17, v16, v13
	v_max_u32_e32 v13, v16, v13
	v_min_u32_e32 v8, v7, v6
	v_max_u32_e32 v60, v7, v6
	v_not_b32_e32 v3, v5
	v_or_b32_e32 v6, 0x80000000, v5
	v_cmp_gt_i32_e32 vcc, 0, v5
	v_max_u32_e32 v27, v27, v54
	v_min_u32_e32 v53, v26, v52
	v_max_u32_e32 v26, v26, v52
	v_min_u32_e32 v51, v25, v49
	v_min_u32_e32 v21, v20, v19
	v_max_u32_e32 v19, v20, v19
	v_min_u32_e32 v16, v13, v12
	v_max_u32_e32 v12, v13, v12
	v_cndmask_b32_e32 v3, v6, v3, vcc
	v_max_u32_e32 v28, v28, v55
	v_min_u32_e32 v54, v27, v53
	v_max_u32_e32 v27, v27, v53
	v_min_u32_e32 v52, v26, v51
	v_min_u32_e32 v20, v19, v18
	v_max_u32_e32 v18, v19, v18
	v_min_u32_e32 v13, v12, v11
	v_max_u32_e32 v11, v12, v11
	v_or_b32_e32 v5, 0xff, v3
	v_not_b32_e32 v3, v4
	v_or_b32_e32 v6, 0x80000000, v4
	v_cmp_gt_i32_e32 vcc, 0, v4
	v_max_u32_e32 v29, v29, v56
	v_min_u32_e32 v55, v28, v54
	v_max_u32_e32 v28, v28, v54
	v_min_u32_e32 v53, v27, v52
	v_min_u32_e32 v19, v18, v17
	v_max_u32_e32 v17, v18, v17
	v_min_u32_e32 v12, v11, v10
	v_max_u32_e32 v10, v11, v10
	v_cndmask_b32_e32 v3, v6, v3, vcc
	v_max_u32_e32 v30, v30, v57
	v_min_u32_e32 v56, v29, v55
	v_max_u32_e32 v29, v29, v55
	v_min_u32_e32 v54, v28, v53
	v_min_u32_e32 v18, v17, v16
	v_max_u32_e32 v16, v17, v16
	v_min_u32_e32 v11, v10, v9
	v_max_u32_e32 v9, v10, v9
	v_and_b32_e32 v3, 0xffffff00, v3
	v_max_u32_e32 v31, v31, v58
	v_min_u32_e32 v57, v30, v56
	v_max_u32_e32 v30, v30, v56
	v_min_u32_e32 v55, v29, v54
	v_min_u32_e32 v17, v16, v13
	v_max_u32_e32 v13, v16, v13
	v_min_u32_e32 v10, v9, v8
	v_max_u32_e32 v59, v9, v8
	v_or_b32_e32 v4, 0xfe, v3
	v_and_b32_e32 v3, 0x7fffff80, v61
	v_bitop3_b32 v8, v61, s61, v61 bitop3:0xcf
	v_cmp_gt_i32_e32 vcc, 0, v61
	v_min_u32_e32 v58, v31, v57
	v_max_u32_e32 v31, v31, v57
	v_min_u32_e32 v56, v30, v55
	v_min_u32_e32 v16, v13, v12
	v_max_u32_e32 v12, v13, v12
	v_cndmask_b32_e32 v3, v8, v3, vcc
	v_min_u32_e32 v57, v31, v56
	v_max_u32_e32 v22, v23, v22
	v_min_u32_e32 v13, v12, v11
	v_max_u32_e32 v11, v12, v11
	v_add_f32_e32 v8, v2, v3
	v_max3_u32 v47, v47, v58, v57
	v_min_u32_e32 v23, v22, v21
	v_max_u32_e32 v21, v22, v21
	v_min_u32_e32 v12, v11, v10
	v_max_u32_e32 v58, v11, v10
	v_not_b32_e32 v9, v8
	v_or_b32_e32 v10, 0x80000000, v8
	v_cmp_gt_i32_e32 vcc, 0, v8
	v_min_u32_e32 v22, v21, v20
	v_max_u32_e32 v20, v21, v20
	v_cndmask_b32_e32 v8, v10, v9, vcc
; DI unsigned f2ord(float f) { unsigned u = __float_as_uint(f); return (u & 0x80000000u) ? ~u : (u | 0x80000000u); }
; DI float ord2f(unsigned u) { return __uint_as_float((u & 0x80000000u) ? (u & 0x7fffffffu) : ~u); }
; #define INS32(T, X) { _Pragma("unroll") for (int jj = 0; jj < 16; ++jj) { unsigned t_ = max(T[jj], X); X = min(T[jj], X); T[jj] = t_; } }
; __device__ __forceinline__ void route_task(const Params& p, int layer, const u16* qg, int rb, int hd, int r, int h) {
;     ...
;     for (int a = 0; a < 16; ++a) {
;       const float va = ord2f(top[0][a] & ~127u);
; #pragma unroll
;       for (int b = 0; b < 16; ++b) {
;         if ((a + 1) * (b + 1) <= 16) {
;           const float vb = ord2f(top[1][b] & ~127u);
;           unsigned key = (f2ord(va + vb) & ~255u) | (unsigned)(255 - (a * 16 + b));
;           INS32(ct, key);
;         }
;       }
;     }
	v_min_u32_e32 v21, v20, v19
	v_max_u32_e32 v19, v20, v19
	v_and_b32_e32 v8, 0xffffff00, v8
	v_min_u32_e32 v20, v19, v18
	v_max_u32_e32 v18, v19, v18
	v_max_u32_e32 v7, v5, v4
	v_or_b32_e32 v8, 0xfd, v8
	v_min_u32_e32 v19, v18, v17
	v_max_u32_e32 v17, v18, v17
	v_min_u32_e32 v6, v5, v4
	v_min_u32_e32 v9, v7, v8
	v_med3_u32 v5, v5, v4, v8
	v_max_u32_e32 v7, v7, v8
	v_and_b32_e32 v4, 0x7fffff80, v60
	v_bitop3_b32 v8, v60, s61, v60 bitop3:0xcf
	v_cmp_gt_i32_e32 vcc, 0, v60
	v_min_u32_e32 v18, v17, v16
	v_max_u32_e32 v16, v17, v16
	v_cndmask_b32_e32 v4, v8, v4, vcc
	v_min_u32_e32 v17, v16, v13
	v_max_u32_e32 v13, v16, v13
	v_add_f32_e32 v8, v2, v4
	v_min_u32_e32 v16, v13, v12
	v_max_u32_e32 v57, v13, v12
	v_not_b32_e32 v11, v8
	v_or_b32_e32 v12, 0x80000000, v8
	v_cmp_gt_i32_e32 vcc, 0, v8
	v_min_u32_e32 v10, v6, v9
	v_max_u32_e32 v24, v24, v48
	v_cndmask_b32_e32 v8, v12, v11, vcc
	v_and_b32_e32 v8, 0xffffff00, v8
	v_or_b32_e32 v8, 0xfc, v8
	v_min_u32_e32 v11, v7, v8
	v_min_u32_e32 v12, v5, v11
	v_med3_u32 v6, v6, v9, v11
	v_max_u32_e32 v9, v5, v11
	v_max_u32_e32 v7, v7, v8
	v_and_b32_e32 v5, 0x7fffff80, v59
	v_bitop3_b32 v8, v59, s61, v59 bitop3:0xcf
	v_cmp_gt_i32_e32 vcc, 0, v59
	v_max_u32_e32 v25, v25, v49
	v_min_u32_e32 v48, v24, v23
	v_cndmask_b32_e32 v5, v8, v5, vcc
	v_max_u32_e32 v23, v24, v23
	v_add_f32_e32 v8, v2, v5
	v_max_u32_e32 v26, v26, v51
	v_min_u32_e32 v49, v25, v48
	v_max_u32_e32 v25, v25, v48
	v_min_u32_e32 v24, v23, v22
	v_not_b32_e32 v11, v8
	v_or_b32_e32 v14, 0x80000000, v8
	v_cmp_gt_i32_e32 vcc, 0, v8
	v_max_u32_e32 v27, v27, v52
	v_min_u32_e32 v51, v26, v49
	v_max_u32_e32 v26, v26, v49
	v_min_u32_e32 v48, v25, v24
	v_cndmask_b32_e32 v8, v14, v11, vcc
	v_max_u32_e32 v28, v28, v53
	v_min_u32_e32 v52, v27, v51
	v_max_u32_e32 v27, v27, v51
	v_min_u32_e32 v49, v26, v48
	v_max_u32_e32 v22, v23, v22
	v_and_b32_e32 v8, 0xffffff00, v8
	v_max_u32_e32 v29, v29, v54
	v_min_u32_e32 v53, v28, v52
	v_max_u32_e32 v28, v28, v52
	v_min_u32_e32 v51, v27, v49
	v_min_u32_e32 v23, v22, v21
	v_max_u32_e32 v21, v22, v21
	v_or_b32_e32 v8, 0xfb, v8
	v_max_u32_e32 v30, v30, v55
	v_min_u32_e32 v54, v29, v53
	v_max_u32_e32 v29, v29, v53
	v_min_u32_e32 v52, v28, v51
	v_min_u32_e32 v22, v21, v20
	v_max_u32_e32 v20, v21, v20
	v_min_u32_e32 v11, v7, v8
	v_max_u32_e32 v31, v31, v56
	v_min_u32_e32 v55, v30, v54
	v_max_u32_e32 v30, v30, v54
	v_min_u32_e32 v53, v29, v52
	v_min_u32_e32 v21, v20, v19
	v_max_u32_e32 v19, v20, v19
	v_min_u32_e32 v14, v9, v11
	v_max_u32_e32 v9, v9, v11
	v_max_u32_e32 v7, v7, v8
	v_and_b32_e32 v8, 0x7fffff80, v58
	v_bitop3_b32 v11, v58, s61, v58 bitop3:0xcf
	v_cmp_gt_i32_e32 vcc, 0, v58
	v_min_u32_e32 v56, v31, v55
	v_max_u32_e32 v31, v31, v55
	v_min_u32_e32 v54, v30, v53
	v_min_u32_e32 v20, v19, v18
	v_max_u32_e32 v18, v19, v18
	v_cndmask_b32_e32 v8, v11, v8, vcc
	v_min_u32_e32 v55, v31, v54
	v_min_u32_e32 v19, v18, v17
	v_max_u32_e32 v17, v18, v17
	v_add_f32_e32 v11, v2, v8
	v_max3_u32 v47, v47, v56, v55
	v_min_u32_e32 v18, v17, v16
	v_max_u32_e32 v56, v17, v16
	v_min_u32_e32 v13, v10, v12
	v_min_u32_e32 v16, v6, v14
	v_med3_u32 v10, v10, v12, v14
	v_max_u32_e32 v6, v6, v14
	v_not_b32_e32 v12, v11
	v_or_b32_e32 v14, 0x80000000, v11
	v_cmp_gt_i32_e32 vcc, 0, v11
	v_max_u32_e32 v24, v25, v24
	v_min_u32_e32 v25, v24, v23
	v_cndmask_b32_e32 v11, v14, v12, vcc
	v_max_u32_e32 v23, v24, v23
	v_and_b32_e32 v11, 0xffffff00, v11
	v_min_u32_e32 v24, v23, v22
	v_max_u32_e32 v22, v23, v22
	v_or_b32_e32 v11, 0xfa, v11
	v_min_u32_e32 v23, v22, v21
	v_max_u32_e32 v21, v22, v21
	v_min_u32_e32 v12, v7, v11
	v_min_u32_e32 v22, v21, v20
	v_max_u32_e32 v20, v21, v20
	v_min_u32_e32 v14, v9, v12
	v_max_u32_e32 v9, v9, v12
	v_max_u32_e32 v11, v7, v11
	v_and_b32_e32 v7, 0x7fffff80, v57
	v_bitop3_b32 v12, v57, s61, v57 bitop3:0xcf
	v_cmp_gt_i32_e32 vcc, 0, v57
	v_min_u32_e32 v21, v20, v19
	v_max_u32_e32 v19, v20, v19
	v_cndmask_b32_e32 v7, v12, v7, vcc
	v_min_u32_e32 v20, v19, v18
	v_max_u32_e32 v55, v19, v18
	v_min_u32_e32 v18, v6, v14
	v_add_f32_e32 v12, v2, v7
	v_min_u32_e32 v17, v13, v16
	v_med3_u32 v13, v13, v16, v18
	v_max_u32_e32 v6, v6, v14
	v_not_b32_e32 v14, v12
	v_or_b32_e32 v16, 0x80000000, v12
	v_cmp_gt_i32_e32 vcc, 0, v12
	v_max_u32_e32 v26, v26, v48
	v_max_u32_e32 v27, v27, v49
	v_cndmask_b32_e32 v12, v16, v14, vcc
	v_min_u32_e32 v48, v26, v25
	v_max_u32_e32 v25, v26, v25
	v_and_b32_e32 v12, 0xffffff00, v12
	v_max_u32_e32 v28, v28, v51
	v_min_u32_e32 v49, v27, v48
	v_max_u32_e32 v27, v27, v48
	v_min_u32_e32 v26, v25, v24
	v_or_b32_e32 v12, 0xf9, v12
	v_max_u32_e32 v29, v29, v52
	v_min_u32_e32 v51, v28, v49
	v_max_u32_e32 v28, v28, v49
	v_min_u32_e32 v48, v27, v26
	v_min_u32_e32 v14, v11, v12
	v_max_u32_e32 v30, v30, v53
	v_min_u32_e32 v52, v29, v51
	v_max_u32_e32 v29, v29, v51
	v_min_u32_e32 v49, v28, v48
	v_max_u32_e32 v24, v25, v24
	v_min_u32_e32 v16, v9, v14
	v_max_u32_e32 v31, v31, v54
	v_min_u32_e32 v53, v30, v52
	v_max_u32_e32 v30, v30, v52
	v_min_u32_e32 v51, v29, v49
	v_min_u32_e32 v25, v24, v23
	v_max_u32_e32 v23, v24, v23
	v_min_u32_e32 v19, v10, v18
	v_max_u32_e32 v10, v10, v18
	v_min_u32_e32 v18, v6, v16
	v_max_u32_e32 v16, v6, v16
	v_max_u32_e32 v11, v11, v12
	v_and_b32_e32 v6, 0x7fffff80, v56
	v_bitop3_b32 v12, v56, s61, v56 bitop3:0xcf
	v_cmp_gt_i32_e32 vcc, 0, v56
	v_min_u32_e32 v54, v31, v53
	v_max_u32_e32 v31, v31, v53
	v_min_u32_e32 v52, v30, v51
	v_min_u32_e32 v24, v23, v22
	v_max_u32_e32 v22, v23, v22
	v_cndmask_b32_e32 v6, v12, v6, vcc
	v_min_u32_e32 v53, v31, v52
	v_min_u32_e32 v23, v22, v21
	v_max_u32_e32 v21, v22, v21
	v_add_f32_e32 v12, v2, v6
	v_max3_u32 v47, v47, v54, v53
	v_min_u32_e32 v22, v21, v20
; DI unsigned f2ord(float f) { unsigned u = __float_as_uint(f); return (u & 0x80000000u) ? ~u : (u | 0x80000000u); }
; DI float ord2f(unsigned u) { return __uint_as_float((u & 0x80000000u) ? (u & 0x7fffffffu) : ~u); }
; #define INS32(T, X) { _Pragma("unroll") for (int jj = 0; jj < 16; ++jj) { unsigned t_ = max(T[jj], X); X = min(T[jj], X); T[jj] = t_; } }
; __device__ __forceinline__ void route_task(const Params& p, int layer, const u16* qg, int rb, int hd, int r, int h) {
;     ...
;     for (int a = 0; a < 16; ++a) {
;       const float va = ord2f(top[0][a] & ~127u);
; #pragma unroll
;       for (int b = 0; b < 16; ++b) {
;         if ((a + 1) * (b + 1) <= 16) {
;           const float vb = ord2f(top[1][b] & ~127u);
;           unsigned key = (f2ord(va + vb) & ~255u) | (unsigned)(255 - (a * 16 + b));
;           INS32(ct, key);
;         }
;       }
;     }
	v_max_u32_e32 v54, v21, v20
	v_min_u32_e32 v21, v10, v18
	v_max_u32_e32 v10, v10, v18
	v_max_u32_e32 v9, v9, v14
	v_not_b32_e32 v14, v12
	v_or_b32_e32 v18, 0x80000000, v12
	v_cmp_gt_i32_e32 vcc, 0, v12
	v_min_u32_e32 v20, v17, v19
	v_med3_u32 v17, v17, v19, v21
	v_cndmask_b32_e32 v12, v18, v14, vcc
	v_and_b32_e32 v12, 0xffffff00, v12
	v_or_b32_e32 v12, 0xf8, v12
	v_min_u32_e32 v14, v11, v12
	v_min_u32_e32 v18, v9, v14
	v_max_u32_e32 v9, v9, v14
	v_max_u32_e32 v11, v11, v12
	v_and_b32_e32 v12, 0x7fffff80, v55
	v_bitop3_b32 v14, v55, s61, v55 bitop3:0xcf
	v_cmp_gt_i32_e32 vcc, 0, v55
	v_min_u32_e32 v19, v16, v18
	v_max_u32_e32 v16, v16, v18
	v_cndmask_b32_e32 v12, v14, v12, vcc
	v_add_f32_e32 v12, v2, v12
	v_not_b32_e32 v14, v12
	v_or_b32_e32 v18, 0x80000000, v12
	v_cmp_gt_i32_e32 vcc, 0, v12
	v_max_u32_e32 v26, v27, v26
	v_min_u32_e32 v27, v26, v25
	v_cndmask_b32_e32 v12, v18, v14, vcc
	v_and_b32_e32 v12, 0xffffff00, v12
	v_or_b32_e32 v12, 0xf7, v12
	v_min_u32_e32 v14, v11, v12
	v_max_u32_e32 v25, v26, v25
	v_min_u32_e32 v18, v9, v14
	v_max_u32_e32 v9, v9, v14
	v_max_u32_e32 v11, v11, v12
	v_and_b32_e32 v12, 0x7fffff80, v54
	v_bitop3_b32 v14, v54, s61, v54 bitop3:0xcf
	v_cmp_gt_i32_e32 vcc, 0, v54
	v_min_u32_e32 v26, v25, v24
	v_max_u32_e32 v24, v25, v24
	v_cndmask_b32_e32 v12, v14, v12, vcc
	v_min_u32_e32 v25, v24, v23
	v_max_u32_e32 v23, v24, v23
	v_add_f32_e32 v12, v2, v12
	v_min_u32_e32 v24, v23, v22
	v_max_u32_e32 v53, v23, v22
	v_min_u32_e32 v22, v13, v21
	v_max_u32_e32 v13, v13, v21
	v_min_u32_e32 v21, v10, v19
	v_max_u32_e32 v10, v10, v19
	v_min_u32_e32 v19, v16, v18
	v_max_u32_e32 v16, v16, v18
	v_not_b32_e32 v14, v12
	v_or_b32_e32 v18, 0x80000000, v12
	v_cmp_gt_i32_e32 vcc, 0, v12
	v_max_u32_e32 v28, v28, v48
	v_max_u32_e32 v29, v29, v49
	v_cndmask_b32_e32 v12, v18, v14, vcc
	v_and_b32_e32 v12, 0xffffff00, v12
	v_min_u32_e32 v48, v28, v27
	v_max_u32_e32 v27, v28, v27
	v_or_b32_e32 v12, 0xf6, v12
	v_max_u32_e32 v30, v30, v51
	v_min_u32_e32 v49, v29, v48
	v_max_u32_e32 v29, v29, v48
	v_min_u32_e32 v28, v27, v26
	v_min_u32_e32 v14, v11, v12
	v_max_u32_e32 v31, v31, v52
	v_min_u32_e32 v51, v30, v49
	v_max_u32_e32 v30, v30, v49
	v_min_u32_e32 v48, v29, v28
	v_min_u32_e32 v18, v9, v14
	v_max_u32_e32 v9, v9, v14
	v_max_u32_e32 v11, v11, v12
	v_and_b32_e32 v12, 0x7fffff80, v53
	v_bitop3_b32 v14, v53, s61, v53 bitop3:0xcf
	v_cmp_gt_i32_e32 vcc, 0, v53
	v_min_u32_e32 v52, v31, v51
	v_max_u32_e32 v31, v31, v51
	v_min_u32_e32 v49, v30, v48
	v_max_u32_e32 v26, v27, v26
	v_cndmask_b32_e32 v12, v14, v12, vcc
	v_min_u32_e32 v51, v31, v49
	v_min_u32_e32 v27, v26, v25
	v_max_u32_e32 v25, v26, v25
	v_add_f32_e32 v12, v2, v12
	v_max3_u32 v47, v47, v52, v51
	v_min_u32_e32 v26, v25, v24
	v_max_u32_e32 v52, v25, v24
	v_min_u32_e32 v24, v13, v21
	v_max_u32_e32 v13, v13, v21
	v_min_u32_e32 v21, v10, v19
	v_max_u32_e32 v10, v10, v19
	v_min_u32_e32 v19, v16, v18
	v_max_u32_e32 v16, v16, v18
	v_not_b32_e32 v14, v12
	v_or_b32_e32 v18, 0x80000000, v12
	v_cmp_gt_i32_e32 vcc, 0, v12
	v_min_u32_e32 v23, v20, v22
	v_med3_u32 v20, v20, v22, v24
	v_cndmask_b32_e32 v12, v18, v14, vcc
	v_and_b32_e32 v12, 0xffffff00, v12
	v_or_b32_e32 v12, 0xf5, v12
	v_min_u32_e32 v14, v11, v12
	v_min_u32_e32 v18, v9, v14
	v_max_u32_e32 v9, v9, v14
	v_max_u32_e32 v11, v11, v12
	v_and_b32_e32 v12, 0x7fffff80, v52
	v_bitop3_b32 v14, v52, s61, v52 bitop3:0xcf
	v_cmp_gt_i32_e32 vcc, 0, v52
	v_min_u32_e32 v22, v13, v21
	v_max_u32_e32 v13, v13, v21
	v_cndmask_b32_e32 v12, v14, v12, vcc
	v_add_f32_e32 v12, v2, v12
	v_min_u32_e32 v21, v10, v19
	v_max_u32_e32 v10, v10, v19
	v_min_u32_e32 v19, v16, v18
	v_max_u32_e32 v16, v16, v18
	v_not_b32_e32 v14, v12
	v_or_b32_e32 v18, 0x80000000, v12
	v_cmp_gt_i32_e32 vcc, 0, v12
	v_max_u32_e32 v28, v29, v28
	v_min_u32_e32 v29, v28, v27
	v_cndmask_b32_e32 v12, v18, v14, vcc
	v_and_b32_e32 v12, 0xffffff00, v12
	v_max_u32_e32 v27, v28, v27
	v_or_b32_e32 v12, 0xf4, v12
	v_max_u32_e32 v51, v27, v26
	v_min_u32_e32 v14, v11, v12
	v_min_u32_e32 v18, v9, v14
	v_max_u32_e32 v9, v9, v14
	v_max_u32_e32 v11, v11, v12
	v_and_b32_e32 v12, 0x7fffff80, v51
	v_bitop3_b32 v14, v51, s61, v51 bitop3:0xcf
	v_cmp_gt_i32_e32 vcc, 0, v51
	v_min_u32_e32 v25, v17, v24
	v_max_u32_e32 v17, v17, v24
	v_cndmask_b32_e32 v12, v14, v12, vcc
	v_add_f32_e32 v12, v2, v12
	v_max_u32_e32 v30, v30, v48
	v_min_u32_e32 v24, v17, v22
	v_max_u32_e32 v17, v17, v22
	v_min_u32_e32 v22, v13, v21
	v_max_u32_e32 v13, v13, v21
	v_min_u32_e32 v21, v10, v19
	v_max_u32_e32 v10, v10, v19
	v_min_u32_e32 v19, v16, v18
	v_max_u32_e32 v16, v16, v18
	v_not_b32_e32 v14, v12
	v_or_b32_e32 v18, 0x80000000, v12
	v_cmp_gt_i32_e32 vcc, 0, v12
	v_max_u32_e32 v31, v31, v49
	v_min_u32_e32 v48, v30, v29
	v_max_u32_e32 v29, v30, v29
	v_min_u32_e32 v28, v27, v26
	v_cndmask_b32_e32 v12, v18, v14, vcc
	v_min_u32_e32 v49, v31, v48
	v_max_u32_e32 v31, v31, v48
	v_min_u32_e32 v30, v29, v28
	v_and_b32_e32 v12, 0xffffff00, v12
	v_min_u32_e32 v48, v31, v30
	v_or_b32_e32 v12, 0xf3, v12
	v_max3_u32 v47, v47, v49, v48
	v_max_u32_e32 v49, v29, v28
	v_min_u32_e32 v14, v11, v12
	v_min_u32_e32 v18, v9, v14
	v_max_u32_e32 v9, v9, v14
	v_max_u32_e32 v11, v11, v12
	v_and_b32_e32 v12, 0x7fffff80, v49
	v_bitop3_b32 v14, v49, s61, v49 bitop3:0xcf
	v_cmp_gt_i32_e32 vcc, 0, v49
	v_min_u32_e32 v26, v23, v25
	v_min_u32_e32 v27, v20, v24
	v_cndmask_b32_e32 v12, v14, v12, vcc
	v_add_f32_e32 v12, v2, v12
	v_med3_u32 v23, v23, v25, v24
	v_max_u32_e32 v20, v20, v24
	v_min_u32_e32 v24, v17, v22
	v_max_u32_e32 v17, v17, v22
	v_min_u32_e32 v22, v13, v21
	v_max_u32_e32 v13, v13, v21
	v_min_u32_e32 v21, v10, v19
	v_max_u32_e32 v10, v10, v19
; DI unsigned f2ord(float f) { unsigned u = __float_as_uint(f); return (u & 0x80000000u) ? ~u : (u | 0x80000000u); }
; DI float ord2f(unsigned u) { return __uint_as_float((u & 0x80000000u) ? (u & 0x7fffffffu) : ~u); }
; #define INS32(T, X) { _Pragma("unroll") for (int jj = 0; jj < 16; ++jj) { unsigned t_ = max(T[jj], X); X = min(T[jj], X); T[jj] = t_; } }
; __device__ __forceinline__ void route_task(const Params& p, int layer, const u16* qg, int rb, int hd, int r, int h) {
;     ...
;     for (int a = 0; a < 16; ++a) {
;       const float va = ord2f(top[0][a] & ~127u);
; #pragma unroll
;       for (int b = 0; b < 16; ++b) {
;         if ((a + 1) * (b + 1) <= 16) {
;           const float vb = ord2f(top[1][b] & ~127u);
;           unsigned key = (f2ord(va + vb) & ~255u) | (unsigned)(255 - (a * 16 + b));
;           INS32(ct, key);
;         }
;       }
;     }
	v_min_u32_e32 v19, v16, v18
	v_max_u32_e32 v16, v16, v18
	v_not_b32_e32 v14, v12
	v_or_b32_e32 v18, 0x80000000, v12
	v_cmp_gt_i32_e32 vcc, 0, v12
	v_max_u32_e32 v48, v31, v30
	v_min_u32_e32 v25, v20, v24
	v_cndmask_b32_e32 v12, v18, v14, vcc
	v_and_b32_e32 v12, 0xffffff00, v12
	v_or_b32_e32 v12, 0xf2, v12
	v_min_u32_e32 v14, v11, v12
	v_min_u32_e32 v18, v9, v14
	v_max_u32_e32 v9, v9, v14
	v_max_u32_e32 v11, v11, v12
	v_and_b32_e32 v12, 0x7fffff80, v48
	v_bitop3_b32 v14, v48, s61, v48 bitop3:0xcf
	v_cmp_gt_i32_e32 vcc, 0, v48
	v_max_u32_e32 v20, v20, v24
	v_min_u32_e32 v24, v17, v22
	v_cndmask_b32_e32 v12, v14, v12, vcc
	v_add_f32_e32 v12, v2, v12
	v_max_u32_e32 v17, v17, v22
	v_min_u32_e32 v22, v13, v21
	v_max_u32_e32 v13, v13, v21
	v_min_u32_e32 v21, v10, v19
	v_max_u32_e32 v10, v10, v19
	v_min_u32_e32 v19, v16, v18
	v_max_u32_e32 v16, v16, v18
	v_not_b32_e32 v14, v12
	v_or_b32_e32 v18, 0x80000000, v12
	v_cmp_gt_i32_e32 vcc, 0, v12
	v_min_u32_e32 v28, v26, v27
	v_min_u32_e32 v29, v23, v25
	v_cndmask_b32_e32 v12, v18, v14, vcc
	v_and_b32_e32 v12, 0xffffff00, v12
	v_or_b32_e32 v12, 0xf1, v12
	v_min_u32_e32 v14, v11, v12
	v_min_u32_e32 v18, v9, v14
	v_max_u32_e32 v9, v9, v14
	v_max_u32_e32 v11, v11, v12
	v_and_b32_e32 v12, 0x7fffff80, v47
	v_bitop3_b32 v14, v47, s61, v47 bitop3:0xcf
	v_cmp_gt_i32_e32 vcc, 0, v47
	v_med3_u32 v26, v26, v27, v25
	v_max_u32_e32 v23, v23, v25
	v_cndmask_b32_e32 v12, v14, v12, vcc
	v_add_f32_e32 v2, v2, v12
	v_not_b32_e32 v12, v2
	v_or_b32_e32 v14, 0x80000000, v2
	v_cmp_gt_i32_e32 vcc, 0, v2
	v_min_u32_e32 v25, v20, v24
	v_max_u32_e32 v20, v20, v24
	v_cndmask_b32_e32 v2, v14, v12, vcc
	v_and_b32_e32 v2, 0xffffff00, v2
	v_or_b32_e32 v2, 0xf0, v2
	v_min_u32_e32 v12, v11, v2
	v_min_u32_e32 v14, v9, v12
	v_max_u32_e32 v9, v9, v12
	v_max_u32_e32 v2, v11, v2
	v_and_b32_e32 v11, 0x7fffff80, v46
	v_bitop3_b32 v12, v46, s61, v46 bitop3:0xcf
	v_cmp_gt_i32_e32 vcc, 0, v46
	v_min_u32_e32 v24, v17, v22
	v_max_u32_e32 v17, v17, v22
	v_min_u32_e32 v22, v13, v21
	v_max_u32_e32 v13, v13, v21
	v_min_u32_e32 v21, v10, v19
	v_max_u32_e32 v10, v10, v19
	v_min_u32_e32 v19, v16, v18
	v_max_u32_e32 v16, v16, v18
	v_cndmask_b32_e32 v11, v12, v11, vcc
	v_min_u32_e32 v27, v23, v25
	v_max_u32_e32 v23, v23, v25
	v_min_u32_e32 v25, v20, v24
	v_max_u32_e32 v20, v20, v24
	v_min_u32_e32 v24, v17, v22
	v_max_u32_e32 v17, v17, v22
	v_min_u32_e32 v22, v13, v21
	v_max_u32_e32 v13, v13, v21
	v_min_u32_e32 v21, v10, v19
	v_max_u32_e32 v10, v10, v19
	v_min_u32_e32 v18, v16, v14
	v_add_f32_e32 v12, v11, v1
	v_min_u32_e32 v19, v10, v18
	v_max_u32_e32 v10, v10, v18
	v_max_u32_e32 v14, v16, v14
	v_not_b32_e32 v16, v12
	v_or_b32_e32 v18, 0x80000000, v12
	v_cmp_gt_i32_e32 vcc, 0, v12
	v_min_u32_e32 v30, v28, v29
	v_min_u32_e32 v31, v26, v27
	v_cndmask_b32_e32 v12, v18, v16, vcc
	v_and_b32_e32 v12, 0xffffff00, v12
	v_or_b32_e32 v12, 0xef, v12
	v_min_u32_e32 v16, v2, v12
	v_med3_u32 v28, v28, v29, v27
	v_max_u32_e32 v26, v26, v27
	v_min_u32_e32 v27, v23, v25
	v_max_u32_e32 v23, v23, v25
	v_min_u32_e32 v25, v20, v24
	v_max_u32_e32 v20, v20, v24
	v_min_u32_e32 v24, v17, v22
	v_max_u32_e32 v17, v17, v22
	v_min_u32_e32 v22, v13, v21
	v_max_u32_e32 v13, v13, v21
	v_min_u32_e32 v18, v9, v16
	v_max_u32_e32 v2, v2, v12
	v_add_f32_e32 v12, v11, v0
	v_min_u32_e32 v21, v13, v19
	v_max_u32_e32 v13, v13, v19
	v_min_u32_e32 v19, v14, v18
	v_max_u32_e32 v14, v14, v18
	v_max_u32_e32 v9, v9, v16
	v_not_b32_e32 v16, v12
	v_or_b32_e32 v18, 0x80000000, v12
	v_cmp_gt_i32_e32 vcc, 0, v12
	v_min_u32_e32 v29, v26, v27
	v_max_u32_e32 v26, v26, v27
	v_cndmask_b32_e32 v12, v18, v16, vcc
	v_and_b32_e32 v12, 0xffffff00, v12
	v_or_b32_e32 v12, 0xee, v12
	v_min_u32_e32 v16, v2, v12
	v_min_u32_e32 v27, v23, v25
	v_max_u32_e32 v23, v23, v25
	v_min_u32_e32 v25, v20, v24
	v_max_u32_e32 v20, v20, v24
	v_min_u32_e32 v24, v17, v22
	v_max_u32_e32 v17, v17, v22
	v_min_u32_e32 v18, v9, v16
	v_max_u32_e32 v2, v2, v12
	v_add_f32_e32 v12, v11, v3
	v_min_u32_e32 v22, v17, v21
	v_max_u32_e32 v17, v17, v21
	v_min_u32_e32 v21, v10, v19
	v_max_u32_e32 v10, v10, v19
	v_min_u32_e32 v19, v14, v18
	v_max_u32_e32 v14, v14, v18
	v_max_u32_e32 v9, v9, v16
	v_not_b32_e32 v16, v12
	v_or_b32_e32 v18, 0x80000000, v12
	v_cmp_gt_i32_e32 vcc, 0, v12
	v_min_u32_e32 v64, v30, v31
	v_min_u32_e32 v65, v28, v29
	v_cndmask_b32_e32 v12, v18, v16, vcc
	v_and_b32_e32 v12, 0xffffff00, v12
	v_or_b32_e32 v12, 0xed, v12
	v_min_u32_e32 v16, v2, v12
	v_med3_u32 v30, v30, v31, v29
	v_max_u32_e32 v28, v28, v29
	v_min_u32_e32 v29, v26, v27
	v_max_u32_e32 v26, v26, v27
	v_min_u32_e32 v27, v23, v25
	v_max_u32_e32 v23, v23, v25
	v_min_u32_e32 v25, v20, v24
	v_max_u32_e32 v20, v20, v24
	v_min_u32_e32 v18, v9, v16
	v_max_u32_e32 v2, v2, v12
	v_add_f32_e32 v12, v11, v4
	v_min_u32_e32 v24, v20, v22
	v_max_u32_e32 v20, v20, v22
	v_min_u32_e32 v22, v13, v21
	v_max_u32_e32 v13, v13, v21
	v_min_u32_e32 v21, v10, v19
	v_max_u32_e32 v10, v10, v19
	v_min_u32_e32 v19, v14, v18
	v_max_u32_e32 v14, v14, v18
	v_max_u32_e32 v9, v9, v16
	v_not_b32_e32 v16, v12
	v_or_b32_e32 v18, 0x80000000, v12
	v_cmp_gt_i32_e32 vcc, 0, v12
	v_min_u32_e32 v31, v28, v29
	v_max_u32_e32 v28, v28, v29
	v_cndmask_b32_e32 v12, v18, v16, vcc
	v_and_b32_e32 v12, 0xffffff00, v12
	v_or_b32_e32 v12, 0xec, v12
	v_min_u32_e32 v16, v2, v12
	v_min_u32_e32 v29, v26, v27
	v_max_u32_e32 v26, v26, v27
	v_min_u32_e32 v27, v23, v25
	v_max_u32_e32 v23, v23, v25
	v_min_u32_e32 v18, v9, v16
	v_max_u32_e32 v2, v2, v12
	v_add_f32_e32 v12, v11, v5
	v_min_u32_e32 v25, v23, v24
	v_max_u32_e32 v23, v23, v24
	v_min_u32_e32 v24, v17, v22
	v_max_u32_e32 v17, v17, v22
	v_min_u32_e32 v22, v13, v21
; DI unsigned f2ord(float f) { unsigned u = __float_as_uint(f); return (u & 0x80000000u) ? ~u : (u | 0x80000000u); }
; DI float ord2f(unsigned u) { return __uint_as_float((u & 0x80000000u) ? (u & 0x7fffffffu) : ~u); }
; #define INS32(T, X) { _Pragma("unroll") for (int jj = 0; jj < 16; ++jj) { unsigned t_ = max(T[jj], X); X = min(T[jj], X); T[jj] = t_; } }
; __device__ __forceinline__ void route_task(const Params& p, int layer, const u16* qg, int rb, int hd, int r, int h) {
;     ...
;     for (int a = 0; a < 16; ++a) {
;       const float va = ord2f(top[0][a] & ~127u);
; #pragma unroll
;       for (int b = 0; b < 16; ++b) {
;         if ((a + 1) * (b + 1) <= 16) {
;           const float vb = ord2f(top[1][b] & ~127u);
;           unsigned key = (f2ord(va + vb) & ~255u) | (unsigned)(255 - (a * 16 + b));
;           INS32(ct, key);
;         }
;       }
;     }
	v_max_u32_e32 v13, v13, v21
	v_min_u32_e32 v21, v10, v19
	v_max_u32_e32 v10, v10, v19
	v_min_u32_e32 v19, v14, v18
	v_max_u32_e32 v14, v14, v18
	v_max_u32_e32 v9, v9, v16
	v_not_b32_e32 v16, v12
	v_or_b32_e32 v18, 0x80000000, v12
	v_cmp_gt_i32_e32 vcc, 0, v12
	v_add_f32_e32 v8, v11, v8
	v_add_f32_e32 v7, v11, v7
	v_cndmask_b32_e32 v12, v18, v16, vcc
	v_and_b32_e32 v12, 0xffffff00, v12
	v_or_b32_e32 v12, 0xeb, v12
	v_min_u32_e32 v16, v2, v12
	v_min_u32_e32 v18, v9, v16
	v_max_u32_e32 v9, v9, v16
	v_max_u32_e32 v2, v2, v12
	v_not_b32_e32 v12, v8
	v_or_b32_e32 v16, 0x80000000, v8
	v_cmp_gt_i32_e32 vcc, 0, v8
	v_add_f32_e32 v6, v11, v6
	v_min_u32_e32 v66, v64, v65
	v_cndmask_b32_e32 v8, v16, v12, vcc
	v_and_b32_e32 v8, 0xffffff00, v8
	v_or_b32_e32 v8, 0xea, v8
	v_min_u32_e32 v12, v2, v8
	v_min_u32_e32 v16, v9, v12
	v_max_u32_e32 v9, v9, v12
	v_max_u32_e32 v2, v2, v8
	v_not_b32_e32 v8, v7
	v_or_b32_e32 v12, 0x80000000, v7
	v_cmp_gt_i32_e32 vcc, 0, v7
	v_min_u32_e32 v67, v30, v31
	v_med3_u32 v64, v64, v65, v31
	v_cndmask_b32_e32 v7, v12, v8, vcc
	v_and_b32_e32 v7, 0xffffff00, v7
	v_or_b32_e32 v7, 0xe9, v7
	v_min_u32_e32 v8, v2, v7
	v_min_u32_e32 v12, v9, v8
	v_max_u32_e32 v8, v9, v8
	v_max_u32_e32 v2, v2, v7
	v_not_b32_e32 v7, v6
	v_or_b32_e32 v9, 0x80000000, v6
	v_cmp_gt_i32_e32 vcc, 0, v6
	v_max_u32_e32 v30, v30, v31
	v_min_u32_e32 v31, v28, v29
	v_cndmask_b32_e32 v6, v9, v7, vcc
	v_and_b32_e32 v6, 0xffffff00, v6
	v_max_u32_e32 v28, v28, v29
	v_min_u32_e32 v29, v26, v27
	v_max_u32_e32 v26, v26, v27
	v_or_b32_e32 v6, 0xe8, v6
	v_min_u32_e32 v65, v30, v31
	v_max_u32_e32 v30, v30, v31
	v_min_u32_e32 v31, v28, v29
	v_max_u32_e32 v28, v28, v29
	v_min_u32_e32 v27, v26, v25
	v_max_u32_e32 v25, v26, v25
	v_min_u32_e32 v26, v20, v24
	v_max_u32_e32 v20, v20, v24
	v_min_u32_e32 v24, v17, v22
	v_max_u32_e32 v17, v17, v22
	v_min_u32_e32 v22, v13, v21
	v_max_u32_e32 v13, v13, v21
	v_min_u32_e32 v21, v10, v19
	v_max_u32_e32 v10, v10, v19
	v_min_u32_e32 v19, v14, v18
	v_max_u32_e32 v14, v14, v18
	v_min_u32_e32 v7, v2, v6
	v_min_u32_e32 v29, v28, v27
	v_max_u32_e32 v27, v28, v27
	v_min_u32_e32 v28, v23, v26
	v_max_u32_e32 v23, v23, v26
	v_min_u32_e32 v26, v20, v24
	v_max_u32_e32 v20, v20, v24
	v_min_u32_e32 v24, v17, v22
	v_max_u32_e32 v17, v17, v22
	v_min_u32_e32 v22, v13, v21
	v_max_u32_e32 v13, v13, v21
	v_min_u32_e32 v21, v10, v19
	v_max_u32_e32 v10, v10, v19
	v_min_u32_e32 v18, v14, v16
	v_max_u32_e32 v14, v14, v16
	v_min_u32_e32 v9, v8, v7
	v_max_u32_e32 v7, v8, v7
	v_max_u32_e32 v2, v2, v6
	v_and_b32_e32 v6, 0x7fffff80, v45
	v_bitop3_b32 v8, v45, s61, v45 bitop3:0xcf
	v_cmp_gt_i32_e32 vcc, 0, v45
	v_min_u32_e32 v19, v10, v18
	v_max_u32_e32 v10, v10, v18
	v_min_u32_e32 v16, v14, v12
	v_max_u32_e32 v12, v14, v12
	v_cndmask_b32_e32 v6, v8, v6, vcc
	v_min_u32_e32 v18, v10, v16
	v_max_u32_e32 v10, v10, v16
	v_min_u32_e32 v11, v12, v9
	v_add_f32_e32 v8, v6, v1
	v_min_u32_e32 v14, v10, v11
	v_max_u32_e32 v10, v10, v11
	v_max_u32_e32 v9, v12, v9
	v_not_b32_e32 v11, v8
	v_or_b32_e32 v12, 0x80000000, v8
	v_cmp_gt_i32_e32 vcc, 0, v8
	v_min_u32_e32 v68, v66, v67
	v_min_u32_e32 v69, v64, v65
	v_cndmask_b32_e32 v8, v12, v11, vcc
	v_med3_u32 v66, v66, v67, v65
	v_max_u32_e32 v64, v64, v65
	v_min_u32_e32 v65, v30, v31
	v_max_u32_e32 v30, v30, v31
	v_and_b32_e32 v8, 0xffffff00, v8
	v_min_u32_e32 v31, v30, v29
	v_max_u32_e32 v29, v30, v29
	v_min_u32_e32 v30, v25, v28
	v_max_u32_e32 v25, v25, v28
	v_min_u32_e32 v28, v23, v26
	v_max_u32_e32 v23, v23, v26
	v_min_u32_e32 v26, v20, v24
	v_max_u32_e32 v20, v20, v24
	v_min_u32_e32 v24, v17, v22
	v_max_u32_e32 v17, v17, v22
	v_min_u32_e32 v22, v13, v21
	v_max_u32_e32 v13, v13, v21
	v_or_b32_e32 v8, 0xdf, v8
	v_min_u32_e32 v21, v13, v19
	v_max_u32_e32 v13, v13, v19
	v_min_u32_e32 v11, v2, v8
	v_min_u32_e32 v19, v13, v18
	v_max_u32_e32 v13, v13, v18
	v_min_u32_e32 v12, v7, v11
	v_max_u32_e32 v2, v2, v8
	v_add_f32_e32 v8, v6, v0
	v_min_u32_e32 v16, v13, v14
	v_max_u32_e32 v13, v13, v14
	v_min_u32_e32 v14, v9, v12
	v_max_u32_e32 v9, v9, v12
	v_max_u32_e32 v7, v7, v11
	v_not_b32_e32 v11, v8
	v_or_b32_e32 v12, 0x80000000, v8
	v_cmp_gt_i32_e32 vcc, 0, v8
	v_min_u32_e32 v67, v64, v65
	v_max_u32_e32 v64, v64, v65
	v_cndmask_b32_e32 v8, v12, v11, vcc
	v_and_b32_e32 v8, 0xffffff00, v8
	v_min_u32_e32 v65, v64, v31
	v_max_u32_e32 v31, v64, v31
	v_min_u32_e32 v64, v27, v30
	v_max_u32_e32 v27, v27, v30
	v_min_u32_e32 v30, v25, v28
	v_max_u32_e32 v25, v25, v28
	v_min_u32_e32 v28, v23, v26
	v_max_u32_e32 v23, v23, v26
	v_min_u32_e32 v26, v20, v24
	v_max_u32_e32 v20, v20, v24
	v_min_u32_e32 v24, v17, v22
	v_max_u32_e32 v17, v17, v22
	v_or_b32_e32 v8, 0xde, v8
	v_min_u32_e32 v22, v17, v21
	v_max_u32_e32 v17, v17, v21
	v_min_u32_e32 v11, v2, v8
	v_min_u32_e32 v21, v17, v19
	v_max_u32_e32 v17, v17, v19
	v_min_u32_e32 v12, v7, v11
	v_max_u32_e32 v2, v2, v8
	v_add_f32_e32 v8, v6, v3
	v_min_u32_e32 v18, v17, v16
	v_max_u32_e32 v16, v17, v16
	v_min_u32_e32 v17, v10, v14
	v_max_u32_e32 v10, v10, v14
	v_min_u32_e32 v14, v9, v12
	v_max_u32_e32 v9, v9, v12
	v_max_u32_e32 v7, v7, v11
	v_not_b32_e32 v11, v8
	v_or_b32_e32 v12, 0x80000000, v8
	v_cmp_gt_i32_e32 vcc, 0, v8
	v_min_u32_e32 v71, v66, v67
	v_max_u32_e32 v66, v66, v67
	v_cndmask_b32_e32 v8, v12, v11, vcc
	v_and_b32_e32 v8, 0xffffff00, v8
	v_min_u32_e32 v70, v68, v69
	v_med3_u32 v68, v68, v69, v67
	v_min_u32_e32 v67, v66, v65
	v_max_u32_e32 v65, v66, v65
	v_min_u32_e32 v66, v29, v64
	v_max_u32_e32 v29, v29, v64
	v_min_u32_e32 v64, v27, v30
	v_max_u32_e32 v27, v27, v30
	v_min_u32_e32 v30, v25, v28
	v_max_u32_e32 v25, v25, v28
	v_min_u32_e32 v28, v23, v26
	v_max_u32_e32 v23, v23, v26
; DI unsigned f2ord(float f) { unsigned u = __float_as_uint(f); return (u & 0x80000000u) ? ~u : (u | 0x80000000u); }
; DI float ord2f(unsigned u) { return __uint_as_float((u & 0x80000000u) ? (u & 0x7fffffffu) : ~u); }
; #define INS32(T, X) { _Pragma("unroll") for (int jj = 0; jj < 16; ++jj) { unsigned t_ = max(T[jj], X); X = min(T[jj], X); T[jj] = t_; } }
; __device__ __forceinline__ void route_task(const Params& p, int layer, const u16* qg, int rb, int hd, int r, int h) {
;     ...
; #pragma unroll
;     for (int jj = 0; jj < 16; ++jj) ct[jj] = 0u;
; #pragma unroll
;     for (int a = 0; a < 16; ++a) {
;       const float va = ord2f(top[0][a] & ~127u);
; #pragma unroll
;       for (int b = 0; b < 16; ++b) {
;         if ((a + 1) * (b + 1) <= 16) {
;           const float vb = ord2f(top[1][b] & ~127u);
;           unsigned key = (f2ord(va + vb) & ~255u) | (unsigned)(255 - (a * 16 + b));
;           INS32(ct, key);
;         }
;       }
;     }
	v_min_u32_e32 v26, v20, v24
	v_max_u32_e32 v20, v20, v24
	v_or_b32_e32 v8, 0xdd, v8
	v_min_u32_e32 v24, v20, v22
	v_max_u32_e32 v20, v20, v22
	v_min_u32_e32 v11, v2, v8
	v_min_u32_e32 v22, v20, v21
	v_max_u32_e32 v20, v20, v21
	v_min_u32_e32 v12, v7, v11
	v_max_u32_e32 v2, v2, v8
	v_add_f32_e32 v8, v6, v4
	v_min_u32_e32 v19, v20, v18
	v_max_u32_e32 v18, v20, v18
	v_min_u32_e32 v20, v13, v17
	v_max_u32_e32 v13, v13, v17
	v_min_u32_e32 v17, v10, v14
	v_max_u32_e32 v10, v10, v14
	v_min_u32_e32 v14, v9, v12
	v_max_u32_e32 v9, v9, v12
	v_max_u32_e32 v7, v7, v11
	v_not_b32_e32 v11, v8
	v_or_b32_e32 v12, 0x80000000, v8
	v_cmp_gt_i32_e32 vcc, 0, v8
	v_add_f32_e32 v5, v6, v5
	v_not_b32_e32 v6, v5
	v_cndmask_b32_e32 v8, v12, v11, vcc
	v_and_b32_e32 v8, 0xffffff00, v8
	v_or_b32_e32 v8, 0xdc, v8
	v_min_u32_e32 v11, v2, v8
	v_max_u32_e32 v2, v2, v8
	v_or_b32_e32 v8, 0x80000000, v5
	v_cmp_gt_i32_e32 vcc, 0, v5
	v_min_u32_e32 v72, v70, v71
	v_min_u32_e32 v69, v68, v67
	v_cndmask_b32_e32 v5, v8, v6, vcc
	v_and_b32_e32 v5, 0xffffff00, v5
	v_med3_u32 v70, v70, v71, v67
	v_max_u32_e32 v67, v68, v67
	v_min_u32_e32 v68, v31, v66
	v_max_u32_e32 v31, v31, v66
	v_min_u32_e32 v66, v29, v64
	v_max_u32_e32 v29, v29, v64
	v_min_u32_e32 v64, v27, v30
	v_max_u32_e32 v27, v27, v30
	v_min_u32_e32 v30, v25, v28
	v_max_u32_e32 v25, v25, v28
	v_min_u32_e32 v28, v23, v26
	v_max_u32_e32 v23, v23, v26
	v_or_b32_e32 v5, 0xdb, v5
	v_min_u32_e32 v71, v65, v68
	v_max_u32_e32 v65, v65, v68
	v_min_u32_e32 v68, v31, v66
	v_max_u32_e32 v31, v31, v66
	v_min_u32_e32 v66, v29, v64
	v_max_u32_e32 v29, v29, v64
	v_min_u32_e32 v64, v27, v30
	v_max_u32_e32 v27, v27, v30
	v_min_u32_e32 v30, v25, v28
	v_max_u32_e32 v25, v25, v28
	v_min_u32_e32 v26, v23, v24
	v_max_u32_e32 v23, v23, v24
	v_min_u32_e32 v12, v7, v11
	v_max_u32_e32 v7, v7, v11
	v_min_u32_e32 v6, v2, v5
	v_min_u32_e32 v28, v25, v26
	v_max_u32_e32 v25, v25, v26
	v_min_u32_e32 v24, v23, v22
	v_max_u32_e32 v22, v23, v22
	v_min_u32_e32 v8, v7, v6
	v_max_u32_e32 v6, v7, v6
	v_max_u32_e32 v2, v2, v5
	v_and_b32_e32 v5, 0x7fffff80, v44
	v_bitop3_b32 v7, v44, s61, v44 bitop3:0xcf
	v_cmp_gt_i32_e32 vcc, 0, v44
	v_min_u32_e32 v26, v25, v24
	v_max_u32_e32 v24, v25, v24
	v_min_u32_e32 v21, v22, v19
	v_max_u32_e32 v19, v22, v19
	v_min_u32_e32 v22, v16, v20
	v_max_u32_e32 v16, v16, v20
	v_min_u32_e32 v20, v13, v17
	v_max_u32_e32 v13, v13, v17
	v_min_u32_e32 v17, v10, v14
	v_max_u32_e32 v10, v10, v14
	v_min_u32_e32 v14, v9, v12
	v_max_u32_e32 v9, v9, v12
	v_cndmask_b32_e32 v5, v7, v5, vcc
	v_min_u32_e32 v23, v24, v21
	v_max_u32_e32 v21, v24, v21
	v_min_u32_e32 v24, v18, v22
	v_max_u32_e32 v18, v18, v22
	v_min_u32_e32 v22, v16, v20
	v_max_u32_e32 v16, v16, v20
	v_min_u32_e32 v20, v13, v17
	v_max_u32_e32 v13, v13, v17
	v_min_u32_e32 v17, v10, v14
	v_max_u32_e32 v10, v10, v14
	v_min_u32_e32 v11, v9, v8
	v_add_f32_e32 v7, v5, v1
	v_min_u32_e32 v12, v10, v11
	v_max_u32_e32 v10, v10, v11
	v_max_u32_e32 v8, v9, v8
	v_not_b32_e32 v9, v7
	v_or_b32_e32 v11, 0x80000000, v7
	v_cmp_gt_i32_e32 vcc, 0, v7
	v_min_u32_e32 v69, v72, v69
	v_min_u32_e32 v72, v67, v71
	v_cndmask_b32_e32 v7, v11, v9, vcc
	v_max_u32_e32 v67, v67, v71
	v_min_u32_e32 v71, v65, v68
	v_max_u32_e32 v65, v65, v68
	v_min_u32_e32 v68, v31, v66
	v_max_u32_e32 v31, v31, v66
	v_min_u32_e32 v66, v29, v64
	v_max_u32_e32 v29, v29, v64
	v_min_u32_e32 v64, v27, v30
	v_max_u32_e32 v27, v27, v30
	v_and_b32_e32 v7, 0xffffff00, v7
	v_min_u32_e32 v30, v27, v28
	v_max_u32_e32 v27, v27, v28
	v_or_b32_e32 v7, 0xcf, v7
	v_min_u32_e32 v28, v27, v26
	v_max_u32_e32 v26, v27, v26
	v_min_u32_e32 v9, v2, v7
	v_min_u32_e32 v25, v26, v23
	v_max_u32_e32 v23, v26, v23
	v_min_u32_e32 v26, v19, v24
	v_max_u32_e32 v19, v19, v24
	v_min_u32_e32 v24, v18, v22
	v_max_u32_e32 v18, v18, v22
	v_min_u32_e32 v22, v16, v20
	v_max_u32_e32 v16, v16, v20
	v_min_u32_e32 v20, v13, v17
	v_max_u32_e32 v13, v13, v17
	v_min_u32_e32 v11, v6, v9
	v_max_u32_e32 v2, v2, v7
	v_add_f32_e32 v7, v5, v0
	v_min_u32_e32 v14, v13, v12
	v_max_u32_e32 v12, v13, v12
	v_min_u32_e32 v13, v8, v11
	v_max_u32_e32 v8, v8, v11
	v_max_u32_e32 v6, v6, v9
	v_not_b32_e32 v9, v7
	v_or_b32_e32 v11, 0x80000000, v7
	v_cmp_gt_i32_e32 vcc, 0, v7
	v_min_u32_e32 v73, v70, v72
	v_max_u32_e32 v70, v70, v72
	v_cndmask_b32_e32 v7, v11, v9, vcc
	v_min_u32_e32 v72, v67, v71
	v_max_u32_e32 v67, v67, v71
	v_min_u32_e32 v71, v65, v68
	v_max_u32_e32 v65, v65, v68
	v_min_u32_e32 v68, v31, v66
	v_max_u32_e32 v31, v31, v66
	v_min_u32_e32 v66, v29, v64
	v_max_u32_e32 v29, v29, v64
	v_and_b32_e32 v7, 0xffffff00, v7
	v_min_u32_e32 v64, v29, v30
	v_max_u32_e32 v29, v29, v30
	v_or_b32_e32 v7, 0xce, v7
	v_min_u32_e32 v30, v29, v28
	v_max_u32_e32 v28, v29, v28
	v_min_u32_e32 v9, v2, v7
	v_min_u32_e32 v27, v28, v25
	v_max_u32_e32 v25, v28, v25
	v_min_u32_e32 v28, v21, v26
	v_max_u32_e32 v21, v21, v26
	v_min_u32_e32 v26, v19, v24
	v_max_u32_e32 v19, v19, v24
	v_min_u32_e32 v24, v18, v22
	v_max_u32_e32 v18, v18, v22
	v_min_u32_e32 v22, v16, v20
	v_max_u32_e32 v16, v16, v20
	v_min_u32_e32 v11, v6, v9
	v_max_u32_e32 v2, v2, v7
	v_add_f32_e32 v7, v5, v3
	v_min_u32_e32 v17, v16, v14
	v_max_u32_e32 v14, v16, v14
	v_min_u32_e32 v16, v10, v13
	v_max_u32_e32 v10, v10, v13
	v_min_u32_e32 v13, v8, v11
	v_max_u32_e32 v8, v8, v11
	v_max_u32_e32 v6, v6, v9
	v_not_b32_e32 v9, v7
	v_or_b32_e32 v11, 0x80000000, v7
	v_cmp_gt_i32_e32 vcc, 0, v7
	v_add_f32_e32 v4, v5, v4
	v_not_b32_e32 v5, v4
	v_cndmask_b32_e32 v7, v11, v9, vcc
	v_and_b32_e32 v7, 0xffffff00, v7
	v_or_b32_e32 v7, 0xcd, v7
	v_min_u32_e32 v9, v2, v7
	v_max_u32_e32 v2, v2, v7
	v_or_b32_e32 v7, 0x80000000, v4
	v_cmp_gt_i32_e32 vcc, 0, v4
; DI unsigned f2ord(float f) { unsigned u = __float_as_uint(f); return (u & 0x80000000u) ? ~u : (u | 0x80000000u); }
; DI float ord2f(unsigned u) { return __uint_as_float((u & 0x80000000u) ? (u & 0x7fffffffu) : ~u); }
; #define INS32(T, X) { _Pragma("unroll") for (int jj = 0; jj < 16; ++jj) { unsigned t_ = max(T[jj], X); X = min(T[jj], X); T[jj] = t_; } }
; __device__ __forceinline__ void route_task(const Params& p, int layer, const u16* qg, int rb, int hd, int r, int h) {
;     ...
; #pragma unroll
;     for (int jj = 0; jj < 16; ++jj) ct[jj] = 0u;
; #pragma unroll
;     for (int a = 0; a < 16; ++a) {
;       const float va = ord2f(top[0][a] & ~127u);
; #pragma unroll
;       for (int b = 0; b < 16; ++b) {
;         if ((a + 1) * (b + 1) <= 16) {
;           const float vb = ord2f(top[1][b] & ~127u);
;           unsigned key = (f2ord(va + vb) & ~255u) | (unsigned)(255 - (a * 16 + b));
;           INS32(ct, key);
;         }
;       }
;     }
	v_min_u32_e32 v74, v70, v72
	v_max_u32_e32 v70, v70, v72
	v_cndmask_b32_e32 v4, v7, v5, vcc
	v_min_u32_e32 v72, v67, v71
	v_max_u32_e32 v67, v67, v71
	v_min_u32_e32 v71, v65, v68
	v_max_u32_e32 v65, v65, v68
	v_min_u32_e32 v68, v31, v66
	v_max_u32_e32 v31, v31, v66
	v_and_b32_e32 v4, 0xffffff00, v4
	v_max3_u32 v69, v69, v73, v74
	v_min_u32_e32 v73, v70, v72
	v_max_u32_e32 v70, v70, v72
	v_min_u32_e32 v72, v67, v71
	v_max_u32_e32 v67, v67, v71
	v_min_u32_e32 v71, v65, v68
	v_max_u32_e32 v65, v65, v68
	v_min_u32_e32 v66, v31, v64
	v_max_u32_e32 v31, v31, v64
	v_or_b32_e32 v4, 0xcc, v4
	v_min_u32_e32 v68, v65, v66
	v_max_u32_e32 v65, v65, v66
	v_min_u32_e32 v64, v31, v30
	v_max_u32_e32 v30, v31, v30
	v_min_u32_e32 v11, v6, v9
	v_max_u32_e32 v6, v6, v9
	v_min_u32_e32 v5, v2, v4
	v_min_u32_e32 v66, v65, v64
	v_max_u32_e32 v64, v65, v64
	v_min_u32_e32 v29, v30, v27
	v_max_u32_e32 v27, v30, v27
	v_min_u32_e32 v30, v23, v28
	v_max_u32_e32 v23, v23, v28
	v_min_u32_e32 v28, v21, v26
	v_max_u32_e32 v21, v21, v26
	v_min_u32_e32 v26, v19, v24
	v_max_u32_e32 v19, v19, v24
	v_min_u32_e32 v24, v18, v22
	v_max_u32_e32 v18, v18, v22
	v_min_u32_e32 v7, v6, v5
	v_max_u32_e32 v5, v6, v5
	v_max_u32_e32 v2, v2, v4
	v_and_b32_e32 v4, 0x7fffff80, v43
	v_bitop3_b32 v6, v43, s61, v43 bitop3:0xcf
	v_cmp_gt_i32_e32 vcc, 0, v43
	v_min_u32_e32 v31, v64, v29
	v_max_u32_e32 v29, v64, v29
	v_min_u32_e32 v64, v25, v30
	v_max_u32_e32 v25, v25, v30
	v_min_u32_e32 v30, v23, v28
	v_max_u32_e32 v23, v23, v28
	v_min_u32_e32 v28, v21, v26
	v_max_u32_e32 v21, v21, v26
	v_min_u32_e32 v26, v19, v24
	v_max_u32_e32 v19, v19, v24
	v_min_u32_e32 v20, v18, v17
	v_max_u32_e32 v17, v18, v17
	v_min_u32_e32 v18, v12, v16
	v_max_u32_e32 v12, v12, v16
	v_min_u32_e32 v16, v10, v13
	v_max_u32_e32 v10, v10, v13
	v_min_u32_e32 v13, v8, v11
	v_max_u32_e32 v8, v8, v11
	v_cndmask_b32_e32 v4, v6, v4, vcc
	v_min_u32_e32 v22, v19, v20
	v_max_u32_e32 v19, v19, v20
	v_min_u32_e32 v20, v14, v18
	v_max_u32_e32 v14, v14, v18
	v_min_u32_e32 v18, v12, v16
	v_max_u32_e32 v12, v12, v16
	v_min_u32_e32 v16, v10, v13
	v_max_u32_e32 v10, v10, v13
	v_min_u32_e32 v9, v8, v7
	v_add_f32_e32 v6, v4, v1
	v_min_u32_e32 v11, v10, v9
	v_max_u32_e32 v9, v10, v9
	v_max_u32_e32 v7, v8, v7
	v_not_b32_e32 v8, v6
	v_or_b32_e32 v10, 0x80000000, v6
	v_cmp_gt_i32_e32 vcc, 0, v6
	v_min_u32_e32 v74, v70, v72
	v_max_u32_e32 v70, v70, v72
	v_min_u32_e32 v72, v67, v71
	v_max_u32_e32 v67, v67, v71
	v_cndmask_b32_e32 v6, v10, v8, vcc
	v_min_u32_e32 v71, v67, v68
	v_max_u32_e32 v67, v67, v68
	v_and_b32_e32 v6, 0xffffff00, v6
	v_min_u32_e32 v68, v67, v66
	v_max_u32_e32 v66, v67, v66
	v_or_b32_e32 v6, 0xbf, v6
	v_min_u32_e32 v65, v66, v31
	v_max_u32_e32 v31, v66, v31
	v_min_u32_e32 v66, v27, v64
	v_max_u32_e32 v27, v27, v64
	v_min_u32_e32 v64, v25, v30
	v_max_u32_e32 v25, v25, v30
	v_min_u32_e32 v30, v23, v28
	v_max_u32_e32 v23, v23, v28
	v_min_u32_e32 v28, v21, v26
	v_max_u32_e32 v21, v21, v26
	v_min_u32_e32 v8, v2, v6
	v_min_u32_e32 v24, v21, v22
	v_max_u32_e32 v21, v21, v22
	v_min_u32_e32 v22, v17, v20
	v_max_u32_e32 v17, v17, v20
	v_min_u32_e32 v20, v14, v18
	v_max_u32_e32 v14, v14, v18
	v_min_u32_e32 v18, v12, v16
	v_max_u32_e32 v12, v12, v16
	v_min_u32_e32 v10, v5, v8
	v_max_u32_e32 v2, v2, v6
	v_add_f32_e32 v6, v4, v0
	v_min_u32_e32 v13, v12, v11
	v_max_u32_e32 v11, v12, v11
	v_min_u32_e32 v12, v7, v10
	v_max_u32_e32 v7, v7, v10
	v_max_u32_e32 v5, v5, v8
	v_not_b32_e32 v8, v6
	v_or_b32_e32 v10, 0x80000000, v6
	v_cmp_gt_i32_e32 vcc, 0, v6
	v_add_f32_e32 v3, v4, v3
	v_not_b32_e32 v4, v3
	v_cndmask_b32_e32 v6, v10, v8, vcc
	v_and_b32_e32 v6, 0xffffff00, v6
	v_or_b32_e32 v6, 0xbe, v6
	v_min_u32_e32 v8, v2, v6
	v_max_u32_e32 v2, v2, v6
	v_or_b32_e32 v6, 0x80000000, v3
	v_cmp_gt_i32_e32 vcc, 0, v3
	v_max3_u32 v69, v69, v73, v74
	v_min_u32_e32 v73, v70, v72
	v_max_u32_e32 v70, v70, v72
	v_cndmask_b32_e32 v3, v6, v4, vcc
	v_min_u32_e32 v72, v70, v71
	v_max_u32_e32 v70, v70, v71
	v_and_b32_e32 v3, 0xffffff00, v3
	v_min_u32_e32 v71, v70, v68
	v_max_u32_e32 v68, v70, v68
	v_or_b32_e32 v3, 0xbd, v3
	v_max3_u32 v69, v69, v73, v72
	v_min_u32_e32 v67, v68, v65
	v_max_u32_e32 v65, v68, v65
	v_min_u32_e32 v68, v29, v66
	v_max_u32_e32 v29, v29, v66
	v_min_u32_e32 v66, v27, v64
	v_max_u32_e32 v27, v27, v64
	v_min_u32_e32 v64, v25, v30
	v_max_u32_e32 v25, v25, v30
	v_min_u32_e32 v30, v23, v28
	v_max_u32_e32 v23, v23, v28
	v_min_u32_e32 v10, v5, v8
	v_max_u32_e32 v5, v5, v8
	v_min_u32_e32 v4, v2, v3
	v_max3_u32 v67, v69, v71, v67
	v_min_u32_e32 v69, v31, v68
	v_max_u32_e32 v31, v31, v68
	v_min_u32_e32 v68, v29, v66
	v_max_u32_e32 v29, v29, v66
	v_min_u32_e32 v66, v27, v64
	v_max_u32_e32 v27, v27, v64
	v_min_u32_e32 v64, v25, v30
	v_max_u32_e32 v25, v25, v30
	v_min_u32_e32 v26, v23, v24
	v_max_u32_e32 v23, v23, v24
	v_min_u32_e32 v24, v19, v22
	v_max_u32_e32 v19, v19, v22
	v_min_u32_e32 v22, v17, v20
	v_max_u32_e32 v17, v17, v20
	v_min_u32_e32 v20, v14, v18
	v_max_u32_e32 v14, v14, v18
	v_min_u32_e32 v6, v5, v4
	v_max_u32_e32 v4, v5, v4
	v_max_u32_e32 v2, v2, v3
	v_and_b32_e32 v3, 0x7fffff80, v42
	v_bitop3_b32 v5, v42, s61, v42 bitop3:0xcf
	v_cmp_gt_i32_e32 vcc, 0, v42
	v_min_u32_e32 v28, v25, v26
	v_max_u32_e32 v25, v25, v26
	v_min_u32_e32 v26, v21, v24
	v_max_u32_e32 v21, v21, v24
	v_min_u32_e32 v24, v19, v22
	v_max_u32_e32 v19, v19, v22
	v_min_u32_e32 v22, v17, v20
	v_max_u32_e32 v17, v17, v20
	v_min_u32_e32 v16, v14, v13
	v_max_u32_e32 v13, v14, v13
	v_min_u32_e32 v14, v9, v12
	v_max_u32_e32 v9, v9, v12
	v_min_u32_e32 v12, v7, v10
	v_max_u32_e32 v7, v7, v10
	v_cndmask_b32_e32 v3, v5, v3, vcc
	v_min_u32_e32 v18, v17, v16
	v_max_u32_e32 v16, v17, v16
; DI unsigned f2ord(float f) { unsigned u = __float_as_uint(f); return (u & 0x80000000u) ? ~u : (u | 0x80000000u); }
; DI float ord2f(unsigned u) { return __uint_as_float((u & 0x80000000u) ? (u & 0x7fffffffu) : ~u); }
; #define INS32(T, X) { _Pragma("unroll") for (int jj = 0; jj < 16; ++jj) { unsigned t_ = max(T[jj], X); X = min(T[jj], X); T[jj] = t_; } }
; __device__ __forceinline__ void route_task(const Params& p, int layer, const u16* qg, int rb, int hd, int r, int h) {
;     ...
; #pragma unroll
;     for (int jj = 0; jj < 16; ++jj) ct[jj] = 0u;
; #pragma unroll
;     for (int a = 0; a < 16; ++a) {
;       const float va = ord2f(top[0][a] & ~127u);
; #pragma unroll
;       for (int b = 0; b < 16; ++b) {
;         if ((a + 1) * (b + 1) <= 16) {
;           const float vb = ord2f(top[1][b] & ~127u);
;           unsigned key = (f2ord(va + vb) & ~255u) | (unsigned)(255 - (a * 16 + b));
;           INS32(ct, key);
;         }
;       }
;     }
	v_min_u32_e32 v17, v11, v14
	v_max_u32_e32 v11, v11, v14
	v_min_u32_e32 v14, v9, v12
	v_max_u32_e32 v9, v9, v12
	v_min_u32_e32 v8, v7, v6
	v_add_f32_e32 v5, v3, v1
	v_min_u32_e32 v10, v9, v8
	v_max_u32_e32 v8, v9, v8
	v_max_u32_e32 v6, v7, v6
	v_not_b32_e32 v7, v5
	v_or_b32_e32 v9, 0x80000000, v5
	v_cmp_gt_i32_e32 vcc, 0, v5
	v_add_f32_e32 v3, v3, v0
	v_min_u32_e32 v70, v65, v69
	v_cndmask_b32_e32 v5, v9, v7, vcc
	v_and_b32_e32 v5, 0xffffff00, v5
	v_or_b32_e32 v5, 0xaf, v5
	v_min_u32_e32 v7, v2, v5
	v_min_u32_e32 v9, v4, v7
	v_max_u32_e32 v4, v4, v7
	v_max_u32_e32 v2, v2, v5
	v_not_b32_e32 v5, v3
	v_or_b32_e32 v7, 0x80000000, v3
	v_cmp_gt_i32_e32 vcc, 0, v3
	v_max_u32_e32 v65, v65, v69
	v_min_u32_e32 v69, v31, v68
	v_cndmask_b32_e32 v3, v7, v5, vcc
	v_and_b32_e32 v3, 0xffffff00, v3
	v_max_u32_e32 v31, v31, v68
	v_min_u32_e32 v68, v29, v66
	v_max_u32_e32 v29, v29, v66
	v_min_u32_e32 v66, v27, v64
	v_max_u32_e32 v27, v27, v64
	v_or_b32_e32 v3, 0xae, v3
	v_min_u32_e32 v71, v65, v69
	v_max_u32_e32 v65, v65, v69
	v_min_u32_e32 v69, v31, v68
	v_max_u32_e32 v31, v31, v68
	v_min_u32_e32 v68, v29, v66
	v_max_u32_e32 v29, v29, v66
	v_min_u32_e32 v30, v27, v28
	v_max_u32_e32 v27, v27, v28
	v_min_u32_e32 v28, v23, v26
	v_max_u32_e32 v23, v23, v26
	v_min_u32_e32 v26, v21, v24
	v_max_u32_e32 v21, v21, v24
	v_min_u32_e32 v24, v19, v22
	v_max_u32_e32 v19, v19, v22
	v_min_u32_e32 v5, v2, v3
	v_min_u32_e32 v64, v29, v30
	v_max_u32_e32 v29, v29, v30
	v_min_u32_e32 v30, v25, v28
	v_max_u32_e32 v25, v25, v28
	v_min_u32_e32 v28, v23, v26
	v_max_u32_e32 v23, v23, v26
	v_min_u32_e32 v26, v21, v24
	v_max_u32_e32 v21, v21, v24
	v_min_u32_e32 v20, v19, v18
	v_max_u32_e32 v18, v19, v18
	v_min_u32_e32 v19, v13, v17
	v_max_u32_e32 v13, v13, v17
	v_min_u32_e32 v17, v11, v14
	v_max_u32_e32 v11, v11, v14
	v_min_u32_e32 v7, v4, v5
	v_max_u32_e32 v4, v4, v5
	v_max_u32_e32 v2, v2, v3
	v_and_b32_e32 v3, 0x7fffff80, v41
	v_bitop3_b32 v5, v41, s61, v41 bitop3:0xcf
	v_cmp_gt_i32_e32 vcc, 0, v41
	v_min_u32_e32 v22, v21, v20
	v_max_u32_e32 v20, v21, v20
	v_min_u32_e32 v21, v16, v19
	v_max_u32_e32 v16, v16, v19
	v_min_u32_e32 v19, v13, v17
	v_max_u32_e32 v13, v13, v17
	v_min_u32_e32 v12, v11, v10
	v_max_u32_e32 v10, v11, v10
	v_min_u32_e32 v11, v6, v9
	v_max_u32_e32 v6, v6, v9
	v_cndmask_b32_e32 v3, v5, v3, vcc
	v_min_u32_e32 v14, v13, v12
	v_max_u32_e32 v12, v13, v12
	v_min_u32_e32 v13, v8, v11
	v_max_u32_e32 v8, v8, v11
	v_min_u32_e32 v9, v6, v7
	v_add_f32_e32 v5, v3, v1
	v_min_u32_e32 v11, v8, v9
	v_max_u32_e32 v8, v8, v9
	v_max_u32_e32 v6, v6, v7
	v_not_b32_e32 v7, v5
	v_or_b32_e32 v9, 0x80000000, v5
	v_cmp_gt_i32_e32 vcc, 0, v5
	v_add_f32_e32 v3, v3, v0
	v_max3_u32 v67, v67, v70, v71
	v_cndmask_b32_e32 v5, v9, v7, vcc
	v_and_b32_e32 v5, 0xffffff00, v5
	v_or_b32_e32 v5, 0x9f, v5
	v_min_u32_e32 v7, v2, v5
	v_min_u32_e32 v9, v4, v7
	v_max_u32_e32 v4, v4, v7
	v_max_u32_e32 v2, v2, v5
	v_not_b32_e32 v5, v3
	v_or_b32_e32 v7, 0x80000000, v3
	v_cmp_gt_i32_e32 vcc, 0, v3
	v_min_u32_e32 v70, v65, v69
	v_max_u32_e32 v65, v65, v69
	v_cndmask_b32_e32 v3, v7, v5, vcc
	v_min_u32_e32 v69, v31, v68
	v_max_u32_e32 v31, v31, v68
	v_and_b32_e32 v3, 0xffffff00, v3
	v_min_u32_e32 v71, v65, v69
	v_max_u32_e32 v65, v65, v69
	v_min_u32_e32 v66, v31, v64
	v_max_u32_e32 v31, v31, v64
	v_min_u32_e32 v64, v27, v30
	v_max_u32_e32 v27, v27, v30
	v_min_u32_e32 v30, v25, v28
	v_max_u32_e32 v25, v25, v28
	v_min_u32_e32 v28, v23, v26
	v_max_u32_e32 v23, v23, v26
	v_or_b32_e32 v3, 0x9e, v3
	v_min_u32_e32 v68, v65, v66
	v_max_u32_e32 v65, v65, v66
	v_min_u32_e32 v66, v29, v64
	v_max_u32_e32 v29, v29, v64
	v_min_u32_e32 v64, v27, v30
	v_max_u32_e32 v27, v27, v30
	v_min_u32_e32 v30, v25, v28
	v_max_u32_e32 v25, v25, v28
	v_min_u32_e32 v24, v23, v22
	v_max_u32_e32 v22, v23, v22
	v_min_u32_e32 v23, v18, v21
	v_max_u32_e32 v18, v18, v21
	v_min_u32_e32 v21, v16, v19
	v_max_u32_e32 v16, v16, v19
	v_min_u32_e32 v5, v2, v3
	v_min_u32_e32 v26, v25, v24
	v_max_u32_e32 v24, v25, v24
	v_min_u32_e32 v25, v20, v23
	v_max_u32_e32 v20, v20, v23
	v_min_u32_e32 v23, v18, v21
	v_max_u32_e32 v18, v18, v21
	v_min_u32_e32 v17, v16, v14
	v_max_u32_e32 v14, v16, v14
	v_min_u32_e32 v16, v10, v13
	v_max_u32_e32 v10, v10, v13
	v_min_u32_e32 v7, v4, v5
	v_max_u32_e32 v4, v4, v5
	v_max_u32_e32 v2, v2, v3
	v_and_b32_e32 v3, 0x7fffff80, v40
	v_bitop3_b32 v5, v40, s61, v40 bitop3:0xcf
	v_cmp_gt_i32_e32 vcc, 0, v40
	v_min_u32_e32 v19, v18, v17
	v_max_u32_e32 v17, v18, v17
	v_min_u32_e32 v18, v12, v16
	v_max_u32_e32 v12, v12, v16
	v_min_u32_e32 v13, v10, v11
	v_max_u32_e32 v10, v10, v11
	v_min_u32_e32 v11, v6, v9
	v_max_u32_e32 v6, v6, v9
	v_cndmask_b32_e32 v3, v5, v3, vcc
	v_min_u32_e32 v16, v12, v13
	v_max_u32_e32 v12, v12, v13
	v_min_u32_e32 v13, v8, v11
	v_max_u32_e32 v8, v8, v11
	v_min_u32_e32 v9, v6, v7
	v_add_f32_e32 v5, v3, v1
	v_min_u32_e32 v11, v8, v9
	v_max_u32_e32 v8, v8, v9
	v_max_u32_e32 v6, v6, v7
	v_not_b32_e32 v7, v5
	v_or_b32_e32 v9, 0x80000000, v5
	v_cmp_gt_i32_e32 vcc, 0, v5
	v_add_f32_e32 v0, v3, v0
	v_not_b32_e32 v3, v0
	v_cndmask_b32_e32 v5, v9, v7, vcc
	v_and_b32_e32 v5, 0xffffff00, v5
	v_or_b32_e32 v5, 0x8f, v5
	v_min_u32_e32 v7, v2, v5
	v_max_u32_e32 v2, v2, v5
	v_or_b32_e32 v5, 0x80000000, v0
	v_cmp_gt_i32_e32 vcc, 0, v0
	v_min_u32_e32 v69, v31, v66
	v_max_u32_e32 v31, v31, v66
	v_cndmask_b32_e32 v0, v5, v3, vcc
	v_and_b32_e32 v0, 0xffffff00, v0
	v_min_u32_e32 v66, v29, v64
	v_max_u32_e32 v29, v29, v64
	v_min_u32_e32 v64, v27, v30
	v_max_u32_e32 v27, v27, v30
	v_or_b32_e32 v0, 0x8e, v0
	v_min_u32_e32 v28, v27, v26
	v_max_u32_e32 v26, v27, v26
	v_min_u32_e32 v27, v22, v25
	v_max_u32_e32 v22, v22, v25
	v_min_u32_e32 v25, v20, v23
; DI unsigned f2ord(float f) { unsigned u = __float_as_uint(f); return (u & 0x80000000u) ? ~u : (u | 0x80000000u); }
; DI float ord2f(unsigned u) { return __uint_as_float((u & 0x80000000u) ? (u & 0x7fffffffu) : ~u); }
; #define INS32(T, X) { _Pragma("unroll") for (int jj = 0; jj < 16; ++jj) { unsigned t_ = max(T[jj], X); X = min(T[jj], X); T[jj] = t_; } }
; __device__ __forceinline__ void route_task(const Params& p, int layer, const u16* qg, int rb, int hd, int r, int h) {
;     ...
; #pragma unroll
;     for (int jj = 0; jj < 16; ++jj) ct[jj] = 0u;
; #pragma unroll
;     for (int a = 0; a < 16; ++a) {
;       const float va = ord2f(top[0][a] & ~127u);
; #pragma unroll
;       for (int b = 0; b < 16; ++b) {
;         if ((a + 1) * (b + 1) <= 16) {
;           const float vb = ord2f(top[1][b] & ~127u);
;           unsigned key = (f2ord(va + vb) & ~255u) | (unsigned)(255 - (a * 16 + b));
;           INS32(ct, key);
;         }
;       }
;     }
	v_max_u32_e32 v20, v20, v23
	v_min_u32_e32 v9, v4, v7
	v_max_u32_e32 v4, v4, v7
	v_min_u32_e32 v3, v2, v0
	v_min_u32_e32 v21, v20, v19
	v_max_u32_e32 v19, v20, v19
	v_min_u32_e32 v20, v14, v18
	v_max_u32_e32 v14, v14, v18
	v_min_u32_e32 v5, v4, v3
	v_max_u32_e32 v3, v4, v3
	v_max_u32_e32 v0, v2, v0
	v_and_b32_e32 v2, 0x7fffff80, v39
	v_bitop3_b32 v4, v39, s61, v39 bitop3:0xcf
	v_cmp_gt_i32_e32 vcc, 0, v39
	v_min_u32_e32 v18, v14, v16
	v_max_u32_e32 v14, v14, v16
	v_min_u32_e32 v16, v10, v13
	v_max_u32_e32 v10, v10, v13
	v_cndmask_b32_e32 v2, v4, v2, vcc
	v_min_u32_e32 v13, v10, v11
	v_max_u32_e32 v10, v10, v11
	v_min_u32_e32 v11, v6, v9
	v_max_u32_e32 v6, v6, v9
	v_add_f32_e32 v2, v2, v1
	v_min_u32_e32 v7, v6, v5
	v_max_u32_e32 v5, v6, v5
	v_not_b32_e32 v4, v2
	v_or_b32_e32 v6, 0x80000000, v2
	v_cmp_gt_i32_e32 vcc, 0, v2
	v_max3_u32 v67, v67, v70, v71
	v_min_u32_e32 v70, v65, v69
	v_cndmask_b32_e32 v2, v6, v4, vcc
	v_and_b32_e32 v2, 0xffffff00, v2
	v_max3_u32 v67, v67, v68, v70
	v_min_u32_e32 v68, v31, v66
	v_max_u32_e32 v31, v31, v66
	v_min_u32_e32 v66, v29, v64
	v_max_u32_e32 v29, v29, v64
	v_or_b32_e32 v2, 0x7f, v2
	v_min_u32_e32 v30, v29, v28
	v_max_u32_e32 v28, v29, v28
	v_min_u32_e32 v29, v24, v27
	v_max_u32_e32 v24, v24, v27
	v_min_u32_e32 v27, v22, v25
	v_max_u32_e32 v22, v22, v25
	v_min_u32_e32 v4, v0, v2
	v_min_u32_e32 v23, v22, v21
	v_max_u32_e32 v21, v22, v21
	v_min_u32_e32 v22, v17, v20
	v_max_u32_e32 v17, v17, v20
	v_min_u32_e32 v6, v3, v4
	v_max_u32_e32 v3, v3, v4
	v_max_u32_e32 v0, v0, v2
	v_and_b32_e32 v2, 0x7fffff80, v38
	v_bitop3_b32 v4, v38, s61, v38 bitop3:0xcf
	v_cmp_gt_i32_e32 vcc, 0, v38
	v_min_u32_e32 v20, v17, v18
	v_max_u32_e32 v17, v17, v18
	v_min_u32_e32 v18, v12, v16
	v_max_u32_e32 v12, v12, v16
	v_cndmask_b32_e32 v2, v4, v2, vcc
	v_min_u32_e32 v16, v12, v13
	v_max_u32_e32 v12, v12, v13
	v_min_u32_e32 v13, v8, v11
	v_max_u32_e32 v8, v8, v11
	v_add_f32_e32 v2, v2, v1
	v_min_u32_e32 v9, v8, v7
	v_max_u32_e32 v7, v8, v7
	v_min_u32_e32 v8, v5, v6
	v_max_u32_e32 v5, v5, v6
	v_not_b32_e32 v4, v2
	v_or_b32_e32 v6, 0x80000000, v2
	v_cmp_gt_i32_e32 vcc, 0, v2
	v_max_u32_e32 v65, v65, v69
	v_min_u32_e32 v69, v65, v68
	v_cndmask_b32_e32 v2, v6, v4, vcc
	v_and_b32_e32 v2, 0xffffff00, v2
	v_max_u32_e32 v65, v65, v68
	v_min_u32_e32 v68, v31, v66
	v_max_u32_e32 v31, v31, v66
	v_or_b32_e32 v2, 0x6f, v2
	v_min_u32_e32 v64, v31, v30
	v_max_u32_e32 v30, v31, v30
	v_min_u32_e32 v31, v26, v29
	v_max_u32_e32 v26, v26, v29
	v_min_u32_e32 v29, v24, v27
	v_max_u32_e32 v24, v24, v27
	v_min_u32_e32 v4, v0, v2
	v_min_u32_e32 v25, v24, v23
	v_max_u32_e32 v23, v24, v23
	v_min_u32_e32 v24, v19, v22
	v_max_u32_e32 v19, v19, v22
	v_min_u32_e32 v6, v3, v4
	v_max_u32_e32 v3, v3, v4
	v_max_u32_e32 v0, v0, v2
	v_and_b32_e32 v2, 0x7fffff80, v37
	v_bitop3_b32 v4, v37, s61, v37 bitop3:0xcf
	v_cmp_gt_i32_e32 vcc, 0, v37
	v_min_u32_e32 v22, v19, v20
	v_max_u32_e32 v19, v19, v20
	v_min_u32_e32 v20, v14, v18
	v_max_u32_e32 v14, v14, v18
	v_cndmask_b32_e32 v2, v4, v2, vcc
	v_min_u32_e32 v18, v14, v16
	v_max_u32_e32 v14, v14, v16
	v_min_u32_e32 v16, v10, v13
	v_max_u32_e32 v10, v10, v13
	v_add_f32_e32 v2, v2, v1
	v_min_u32_e32 v11, v10, v9
	v_max_u32_e32 v9, v10, v9
	v_min_u32_e32 v10, v7, v8
	v_max_u32_e32 v7, v7, v8
	v_min_u32_e32 v8, v5, v6
	v_max_u32_e32 v5, v5, v6
	v_not_b32_e32 v4, v2
	v_or_b32_e32 v6, 0x80000000, v2
	v_cmp_gt_i32_e32 vcc, 0, v2
	v_min_u32_e32 v70, v65, v68
	v_max_u32_e32 v65, v65, v68
	v_cndmask_b32_e32 v2, v6, v4, vcc
	v_and_b32_e32 v2, 0xffffff00, v2
	v_or_b32_e32 v2, 0x5f, v2
	v_min_u32_e32 v66, v65, v64
	v_max_u32_e32 v64, v65, v64
	v_min_u32_e32 v65, v28, v31
	v_max_u32_e32 v28, v28, v31
	v_min_u32_e32 v31, v26, v29
	v_max_u32_e32 v26, v26, v29
	v_min_u32_e32 v4, v0, v2
	v_min_u32_e32 v27, v26, v25
	v_max_u32_e32 v25, v26, v25
	v_min_u32_e32 v26, v21, v24
	v_max_u32_e32 v21, v21, v24
	v_min_u32_e32 v6, v3, v4
	v_max_u32_e32 v3, v3, v4
	v_max_u32_e32 v0, v0, v2
	v_and_b32_e32 v2, 0x7fffff80, v36
	v_bitop3_b32 v4, v36, s61, v36 bitop3:0xcf
	v_cmp_gt_i32_e32 vcc, 0, v36
	v_min_u32_e32 v24, v21, v22
	v_max_u32_e32 v21, v21, v22
	v_min_u32_e32 v22, v17, v20
	v_max_u32_e32 v17, v17, v20
	v_cndmask_b32_e32 v2, v4, v2, vcc
	v_min_u32_e32 v20, v17, v18
	v_max_u32_e32 v17, v17, v18
	v_min_u32_e32 v18, v12, v16
	v_max_u32_e32 v12, v12, v16
	v_add_f32_e32 v2, v2, v1
	v_min_u32_e32 v13, v12, v11
	v_max_u32_e32 v11, v12, v11
	v_min_u32_e32 v12, v9, v10
	v_max_u32_e32 v9, v9, v10
	v_min_u32_e32 v10, v7, v8
	v_max_u32_e32 v7, v7, v8
	v_min_u32_e32 v8, v5, v6
	v_max_u32_e32 v5, v5, v6
	v_not_b32_e32 v4, v2
	v_or_b32_e32 v6, 0x80000000, v2
	v_cmp_gt_i32_e32 vcc, 0, v2
	v_min_u32_e32 v68, v30, v65
	v_max_u32_e32 v30, v30, v65
	v_cndmask_b32_e32 v2, v6, v4, vcc
	v_and_b32_e32 v2, 0xffffff00, v2
	v_or_b32_e32 v2, 0x4f, v2
	v_min_u32_e32 v65, v28, v31
	v_max_u32_e32 v28, v28, v31
	v_min_u32_e32 v4, v0, v2
	v_min_u32_e32 v29, v28, v27
	v_max_u32_e32 v27, v28, v27
	v_min_u32_e32 v28, v23, v26
	v_max_u32_e32 v23, v23, v26
	v_min_u32_e32 v6, v3, v4
	v_max_u32_e32 v3, v3, v4
	v_max_u32_e32 v0, v0, v2
	v_and_b32_e32 v2, 0x7fffff80, v35
	v_bitop3_b32 v4, v35, s61, v35 bitop3:0xcf
	v_cmp_gt_i32_e32 vcc, 0, v35
	v_min_u32_e32 v26, v23, v24
	v_max_u32_e32 v23, v23, v24
	v_min_u32_e32 v24, v19, v22
	v_max_u32_e32 v19, v19, v22
	v_cndmask_b32_e32 v2, v4, v2, vcc
	v_min_u32_e32 v22, v19, v20
	v_max_u32_e32 v19, v19, v20
	v_min_u32_e32 v20, v14, v18
	v_max_u32_e32 v14, v14, v18
	v_add_f32_e32 v2, v2, v1
	v_min_u32_e32 v16, v14, v13
	v_max_u32_e32 v13, v14, v13
	v_min_u32_e32 v14, v11, v12
	v_max_u32_e32 v11, v11, v12
	v_min_u32_e32 v12, v9, v10
; DI unsigned f2ord(float f) { unsigned u = __float_as_uint(f); return (u & 0x80000000u) ? ~u : (u | 0x80000000u); }
; DI float ord2f(unsigned u) { return __uint_as_float((u & 0x80000000u) ? (u & 0x7fffffffu) : ~u); }
; #define INS32(T, X) { _Pragma("unroll") for (int jj = 0; jj < 16; ++jj) { unsigned t_ = max(T[jj], X); X = min(T[jj], X); T[jj] = t_; } }
; __device__ __forceinline__ void route_task(const Params& p, int layer, const u16* qg, int rb, int hd, int r, int h) {
;     ...
; #pragma unroll
;     for (int jj = 0; jj < 16; ++jj) ct[jj] = 0u;
; #pragma unroll
;     for (int a = 0; a < 16; ++a) {
;       const float va = ord2f(top[0][a] & ~127u);
; #pragma unroll
;       for (int b = 0; b < 16; ++b) {
;         if ((a + 1) * (b + 1) <= 16) {
;           const float vb = ord2f(top[1][b] & ~127u);
;           unsigned key = (f2ord(va + vb) & ~255u) | (unsigned)(255 - (a * 16 + b));
;           INS32(ct, key);
;         }
;       }
;     }
	v_max_u32_e32 v9, v9, v10
	v_min_u32_e32 v10, v7, v8
	v_max_u32_e32 v7, v7, v8
	v_min_u32_e32 v8, v5, v6
	v_max_u32_e32 v5, v5, v6
	v_not_b32_e32 v4, v2
	v_or_b32_e32 v6, 0x80000000, v2
	v_cmp_gt_i32_e32 vcc, 0, v2
	v_max3_u32 v67, v67, v69, v70
	v_min_u32_e32 v69, v64, v68
	v_cndmask_b32_e32 v2, v6, v4, vcc
	v_and_or_b32 v2, v2, s81, 63
	v_max3_u32 v66, v67, v66, v69
	v_min_u32_e32 v67, v30, v65
	v_max_u32_e32 v30, v30, v65
	v_min_u32_e32 v4, v0, v2
	v_min_u32_e32 v31, v30, v29
	v_max_u32_e32 v29, v30, v29
	v_min_u32_e32 v30, v25, v28
	v_max_u32_e32 v25, v25, v28
	v_min_u32_e32 v6, v3, v4
	v_max_u32_e32 v3, v3, v4
	v_max_u32_e32 v0, v0, v2
	v_and_b32_e32 v2, 0x7fffff80, v34
	v_bitop3_b32 v4, v34, s61, v34 bitop3:0xcf
	v_cmp_gt_i32_e32 vcc, 0, v34
	v_min_u32_e32 v28, v25, v26
	v_max_u32_e32 v25, v25, v26
	v_min_u32_e32 v26, v21, v24
	v_max_u32_e32 v21, v21, v24
	v_cndmask_b32_e32 v2, v4, v2, vcc
	v_min_u32_e32 v24, v21, v22
	v_max_u32_e32 v21, v21, v22
	v_min_u32_e32 v22, v17, v20
	v_max_u32_e32 v17, v17, v20
	v_add_f32_e32 v2, v2, v1
	v_min_u32_e32 v18, v17, v16
	v_max_u32_e32 v16, v17, v16
	v_min_u32_e32 v17, v13, v14
	v_max_u32_e32 v13, v13, v14
	v_min_u32_e32 v14, v11, v12
	v_max_u32_e32 v11, v11, v12
	v_min_u32_e32 v12, v9, v10
	v_max_u32_e32 v9, v9, v10
	v_min_u32_e32 v10, v7, v8
	v_max_u32_e32 v7, v7, v8
	v_min_u32_e32 v8, v5, v6
	v_max_u32_e32 v5, v5, v6
	v_not_b32_e32 v4, v2
	v_or_b32_e32 v6, 0x80000000, v2
	v_cmp_gt_i32_e32 vcc, 0, v2
	v_max_u32_e32 v64, v64, v68
	v_min_u32_e32 v68, v64, v67
	v_cndmask_b32_e32 v2, v6, v4, vcc
	v_and_or_b32 v2, v2, s81, 47
	v_max_u32_e32 v64, v64, v67
	v_min_u32_e32 v4, v0, v2
	v_min_u32_e32 v65, v64, v31
	v_max_u32_e32 v31, v64, v31
	v_min_u32_e32 v64, v27, v30
	v_max_u32_e32 v27, v27, v30
	v_min_u32_e32 v6, v3, v4
	v_max_u32_e32 v3, v3, v4
	v_max_u32_e32 v0, v0, v2
	v_and_b32_e32 v2, 0x7fffff80, v33
	v_bitop3_b32 v4, v33, s61, v33 bitop3:0xcf
	v_cmp_gt_i32_e32 vcc, 0, v33
	v_min_u32_e32 v30, v27, v28
	v_max_u32_e32 v27, v27, v28
	v_min_u32_e32 v28, v23, v26
	v_max_u32_e32 v23, v23, v26
	v_cndmask_b32_e32 v2, v4, v2, vcc
	v_min_u32_e32 v26, v23, v24
	v_max_u32_e32 v23, v23, v24
	v_min_u32_e32 v24, v19, v22
	v_max_u32_e32 v19, v19, v22
	v_add_f32_e32 v2, v2, v1
	v_min_u32_e32 v20, v19, v18
	v_max_u32_e32 v18, v19, v18
	v_min_u32_e32 v19, v16, v17
	v_max_u32_e32 v16, v16, v17
	v_min_u32_e32 v17, v13, v14
	v_max_u32_e32 v13, v13, v14
	v_min_u32_e32 v14, v11, v12
	v_max_u32_e32 v11, v11, v12
	v_min_u32_e32 v12, v9, v10
	v_max_u32_e32 v9, v9, v10
	v_min_u32_e32 v10, v7, v8
	v_max_u32_e32 v7, v7, v8
	v_min_u32_e32 v8, v5, v6
	v_max_u32_e32 v5, v5, v6
	v_not_b32_e32 v4, v2
	v_or_b32_e32 v6, 0x80000000, v2
	v_cmp_gt_i32_e32 vcc, 0, v2
	v_max3_u32 v65, v66, v68, v65
	v_min_u32_e32 v66, v29, v64
	v_cndmask_b32_e32 v2, v6, v4, vcc
	v_max_u32_e32 v29, v29, v64
	v_and_or_b32 v2, v2, s81, 31
	v_min_u32_e32 v67, v31, v66
	v_max_u32_e32 v31, v31, v66
	v_min_u32_e32 v64, v29, v30
	v_max_u32_e32 v29, v29, v30
	v_min_u32_e32 v30, v25, v28
	v_max_u32_e32 v25, v25, v28
	v_min_u32_e32 v4, v0, v2
	v_min_u32_e32 v66, v31, v64
	v_max_u32_e32 v31, v31, v64
	v_min_u32_e32 v64, v27, v30
	v_max_u32_e32 v27, v27, v30
	v_min_u32_e32 v28, v25, v26
	v_max_u32_e32 v25, v25, v26
	v_min_u32_e32 v26, v21, v24
	v_max_u32_e32 v21, v21, v24
	v_min_u32_e32 v6, v3, v4
	v_max3_u32 v65, v65, v67, v66
	v_min_u32_e32 v66, v29, v64
	v_max_u32_e32 v29, v29, v64
	v_min_u32_e32 v30, v27, v28
	v_max_u32_e32 v27, v27, v28
	v_min_u32_e32 v28, v23, v26
	v_max_u32_e32 v23, v23, v26
	v_min_u32_e32 v22, v21, v20
	v_max_u32_e32 v20, v21, v20
	v_min_u32_e32 v21, v18, v19
	v_max_u32_e32 v18, v18, v19
	v_min_u32_e32 v19, v16, v17
	v_max_u32_e32 v16, v16, v17
	v_min_u32_e32 v17, v13, v14
	v_max_u32_e32 v13, v13, v14
	v_min_u32_e32 v14, v11, v12
	v_max_u32_e32 v11, v11, v12
	v_min_u32_e32 v12, v9, v10
	v_max_u32_e32 v9, v9, v10
	v_min_u32_e32 v10, v7, v8
	v_max_u32_e32 v7, v7, v8
	v_min_u32_e32 v8, v5, v6
	v_min_u32_e32 v67, v31, v66
	v_max_u32_e32 v31, v31, v66
	v_min_u32_e32 v64, v29, v30
	v_max_u32_e32 v29, v29, v30
	v_min_u32_e32 v30, v25, v28
	v_max_u32_e32 v25, v25, v28
	v_min_u32_e32 v24, v23, v22
	v_max_u32_e32 v22, v23, v22
	v_min_u32_e32 v23, v20, v21
	v_max_u32_e32 v20, v20, v21
	v_min_u32_e32 v21, v18, v19
	v_max_u32_e32 v18, v18, v19
	v_min_u32_e32 v19, v16, v17
	v_max_u32_e32 v16, v16, v17
	v_min_u32_e32 v17, v13, v14
	v_max_u32_e32 v13, v13, v14
	v_min_u32_e32 v14, v11, v12
	v_max_u32_e32 v11, v11, v12
	v_min_u32_e32 v12, v9, v10
	v_max_u32_e32 v9, v9, v10
	v_min_u32_e32 v10, v7, v8
	v_max_u32_e32 v3, v3, v4
	v_max_u32_e32 v0, v0, v2
	v_and_b32_e32 v2, 0x7fffff80, v15
	v_bitop3_b32 v4, v15, s61, v15 bitop3:0xcf
	v_cmp_gt_i32_e32 vcc, 0, v15
	v_min_u32_e32 v66, v31, v64
	v_max_u32_e32 v31, v31, v64
	v_min_u32_e32 v64, v27, v30
	v_max_u32_e32 v27, v27, v30
	v_min_u32_e32 v26, v25, v24
	v_max_u32_e32 v24, v25, v24
	v_min_u32_e32 v25, v22, v23
	v_max_u32_e32 v22, v22, v23
	v_min_u32_e32 v23, v20, v21
	v_max_u32_e32 v20, v20, v21
	v_min_u32_e32 v21, v18, v19
	v_max_u32_e32 v18, v18, v19
	v_min_u32_e32 v19, v16, v17
	v_max_u32_e32 v16, v16, v17
	v_min_u32_e32 v17, v13, v14
	v_max_u32_e32 v13, v13, v14
	v_min_u32_e32 v14, v11, v12
	v_max_u32_e32 v11, v11, v12
	v_min_u32_e32 v12, v9, v10
	v_cndmask_b32_e32 v2, v4, v2, vcc
	v_max3_u32 v65, v65, v67, v66
	v_min_u32_e32 v66, v29, v64
	v_max_u32_e32 v29, v29, v64
	v_min_u32_e32 v28, v27, v26
	v_max_u32_e32 v26, v27, v26
	v_min_u32_e32 v27, v24, v25
	v_max_u32_e32 v24, v24, v25
	v_min_u32_e32 v25, v22, v23
	v_max_u32_e32 v22, v22, v23
	v_min_u32_e32 v23, v20, v21
	v_max_u32_e32 v20, v20, v21
; DI float ord2f(unsigned u) { return __uint_as_float((u & 0x80000000u) ? (u & 0x7fffffffu) : ~u); }
; #define INS32(T, X) { _Pragma("unroll") for (int jj = 0; jj < 16; ++jj) { unsigned t_ = max(T[jj], X); X = min(T[jj], X); T[jj] = t_; } }
; __device__ __forceinline__ void route_task(const Params& p, int layer, const u16* qg, int rb, int hd, int r, int h) {
;     ...
;           INS32(ct, key);
;         }
;       }
;     }
;     const float v0 = ord2f(ct[0] & ~255u);
;     float vs[16];
;     float den = 0.f;
; #pragma unroll
;     for (int jj = 0; jj < 16; ++jj) { vs[jj] = __expf(ord2f(ct[jj] & ~255u) - v0); den += vs[jj]; }
	v_min_u32_e32 v21, v18, v19
	v_max_u32_e32 v18, v18, v19
	v_min_u32_e32 v19, v16, v17
	v_max_u32_e32 v16, v16, v17
	v_min_u32_e32 v17, v13, v14
	v_max_u32_e32 v13, v13, v14
	v_min_u32_e32 v14, v11, v12
	v_add_f32_e32 v1, v2, v1
	v_min_u32_e32 v67, v31, v66
	v_max_u32_e32 v31, v31, v66
	v_min_u32_e32 v30, v29, v28
	v_max_u32_e32 v28, v29, v28
	v_min_u32_e32 v29, v26, v27
	v_max_u32_e32 v26, v26, v27
	v_min_u32_e32 v27, v24, v25
	v_max_u32_e32 v24, v24, v25
	v_min_u32_e32 v25, v22, v23
	v_max_u32_e32 v22, v22, v23
	v_min_u32_e32 v23, v20, v21
	v_max_u32_e32 v20, v20, v21
	v_min_u32_e32 v21, v18, v19
	v_max_u32_e32 v18, v18, v19
	v_min_u32_e32 v19, v16, v17
	v_max_u32_e32 v16, v16, v17
	v_min_u32_e32 v17, v13, v14
	v_not_b32_e32 v2, v1
	v_or_b32_e32 v4, 0x80000000, v1
	v_cmp_gt_i32_e32 vcc, 0, v1
	v_min_u32_e32 v64, v31, v30
	v_max_u32_e32 v30, v31, v30
	v_min_u32_e32 v31, v28, v29
	v_max_u32_e32 v28, v28, v29
	v_min_u32_e32 v29, v26, v27
	v_max_u32_e32 v26, v26, v27
	v_min_u32_e32 v27, v24, v25
	v_max_u32_e32 v24, v24, v25
	v_min_u32_e32 v25, v22, v23
	v_max_u32_e32 v22, v22, v23
	v_min_u32_e32 v23, v20, v21
	v_max_u32_e32 v20, v20, v21
	v_min_u32_e32 v21, v18, v19
	v_max_u32_e32 v18, v18, v19
	v_min_u32_e32 v19, v16, v17
	v_cndmask_b32_e32 v1, v4, v2, vcc
	v_max3_u32 v64, v65, v67, v64
	v_min_u32_e32 v65, v30, v31
	v_max_u32_e32 v30, v30, v31
	v_min_u32_e32 v31, v28, v29
	v_max_u32_e32 v28, v28, v29
	v_min_u32_e32 v29, v26, v27
	v_max_u32_e32 v26, v26, v27
	v_min_u32_e32 v27, v24, v25
	v_max_u32_e32 v24, v24, v25
	v_min_u32_e32 v25, v22, v23
	v_max_u32_e32 v22, v22, v23
	v_min_u32_e32 v23, v20, v21
	v_max_u32_e32 v20, v20, v21
	v_min_u32_e32 v21, v18, v19
	v_and_or_b32 v1, v1, s81, 15
	v_min_u32_e32 v66, v30, v31
	v_max_u32_e32 v30, v30, v31
	v_min_u32_e32 v31, v28, v29
	v_max_u32_e32 v28, v28, v29
	v_min_u32_e32 v29, v26, v27
	v_max_u32_e32 v26, v26, v27
	v_min_u32_e32 v27, v24, v25
	v_max_u32_e32 v24, v24, v25
	v_min_u32_e32 v25, v22, v23
	v_max_u32_e32 v22, v22, v23
	v_min_u32_e32 v23, v20, v21
	v_min_u32_e32 v2, v0, v1
	v_max3_u32 v64, v64, v65, v66
	v_min_u32_e32 v65, v30, v31
	v_max_u32_e32 v30, v30, v31
	v_min_u32_e32 v31, v28, v29
	v_max_u32_e32 v28, v28, v29
	v_min_u32_e32 v29, v26, v27
	v_max_u32_e32 v26, v26, v27
	v_min_u32_e32 v27, v24, v25
	v_max_u32_e32 v24, v24, v25
	v_min_u32_e32 v25, v22, v23
	v_max_u32_e32 v5, v5, v6
	v_min_u32_e32 v4, v3, v2
	v_min_u32_e32 v66, v30, v31
	v_max_u32_e32 v30, v30, v31
	v_min_u32_e32 v31, v28, v29
	v_max_u32_e32 v28, v28, v29
	v_min_u32_e32 v29, v26, v27
	v_max_u32_e32 v26, v26, v27
	v_min_u32_e32 v27, v24, v25
	v_max_u32_e32 v24, v24, v25
	v_max_u32_e32 v22, v22, v23
	v_max_u32_e32 v23, v7, v8
	v_min_u32_e32 v25, v5, v4
	v_max3_u32 v64, v64, v65, v66
	v_min_u32_e32 v65, v30, v31
	v_max_u32_e32 v30, v30, v31
	v_min_u32_e32 v31, v28, v29
	v_max_u32_e32 v28, v28, v29
	v_min_u32_e32 v29, v26, v27
	v_max_u32_e32 v26, v26, v27
	v_max_u32_e32 v20, v20, v21
	v_max_u32_e32 v21, v9, v10
	v_min_u32_e32 v27, v23, v25
	v_min_u32_e32 v66, v30, v31
	v_max_u32_e32 v30, v30, v31
	v_min_u32_e32 v31, v28, v29
	v_max_u32_e32 v28, v28, v29
	v_max_u32_e32 v18, v18, v19
	v_max_u32_e32 v19, v11, v12
	v_min_u32_e32 v29, v21, v27
	v_max_u32_e32 v16, v16, v17
	v_max_u32_e32 v17, v13, v14
	v_min_u32_e32 v6, v19, v29
	v_min_u32_e32 v7, v17, v6
	v_min_u32_e32 v8, v16, v7
	v_min_u32_e32 v9, v18, v8
	v_min_u32_e32 v10, v20, v9
	v_min_u32_e32 v11, v22, v10
	v_min_u32_e32 v12, v24, v11
	v_min_u32_e32 v13, v26, v12
	v_max3_u32 v64, v64, v65, v66
	v_min_u32_e32 v65, v30, v31
	v_max_u32_e32 v30, v30, v31
	v_min_u32_e32 v14, v28, v13
	v_max_u32_e32 v0, v0, v1
	v_min_u32_e32 v31, v30, v14
	v_max_u32_e32 v7, v16, v7
	v_max_u32_e32 v6, v17, v6
	v_max_u32_e32 v2, v3, v2
	v_and_b32_e32 v16, 0x7fffff00, v0
	v_bitop3_b32 v17, v0, s80, v0 bitop3:0xcf
	v_cmp_gt_i32_e32 vcc, 0, v0
	v_max3_u32 v64, v64, v65, v31
	v_max_u32_e32 v8, v18, v8
	v_max_u32_e32 v4, v5, v4
	v_cndmask_b32_e32 v31, v17, v16, vcc
	v_and_b32_e32 v17, 0x7fffff00, v2
	v_bitop3_b32 v18, v2, s80, v2 bitop3:0xcf
	v_cmp_gt_i32_e32 vcc, 0, v2
	v_max_u32_e32 v76, v19, v29
	v_max_u32_e32 v80, v23, v25
	v_sub_f32_e32 v16, v31, v31
	v_cndmask_b32_e32 v17, v18, v17, vcc
	v_and_b32_e32 v18, 0x7fffff00, v4
	v_bitop3_b32 v19, v4, s80, v4 bitop3:0xcf
	v_cmp_gt_i32_e32 vcc, 0, v4
	v_max_u32_e32 v9, v20, v9
	v_mul_f32_e32 v16, 0x3fb8aa3b, v16
	v_sub_f32_e32 v17, v17, v31
	v_cndmask_b32_e32 v18, v19, v18, vcc
	v_and_b32_e32 v19, 0x7fffff00, v80
	v_bitop3_b32 v20, v80, s80, v80 bitop3:0xcf
	v_cmp_gt_i32_e32 vcc, 0, v80
	v_exp_f32_e32 v16, v16
	v_mul_f32_e32 v17, 0x3fb8aa3b, v17
	v_sub_f32_e32 v18, v18, v31
	v_cndmask_b32_e32 v19, v20, v19, vcc
	v_exp_f32_e32 v17, v17
	v_mul_f32_e32 v18, 0x3fb8aa3b, v18
	v_sub_f32_e32 v19, v19, v31
	v_exp_f32_e32 v18, v18
	v_mul_f32_e32 v19, 0x3fb8aa3b, v19
	v_exp_f32_e32 v19, v19
	v_add_f32_e32 v20, 0, v16
	v_add_f32_e32 v20, v17, v20
	v_max_u32_e32 v78, v21, v27
	v_add_f32_e32 v20, v18, v20
	v_max_u32_e32 v11, v24, v11
	v_add_f32_e32 v24, v19, v20
	v_and_b32_e32 v20, 0x7fffff00, v78
	v_bitop3_b32 v21, v78, s80, v78 bitop3:0xcf
	v_cmp_gt_i32_e32 vcc, 0, v78
	v_max_u32_e32 v10, v22, v10
	v_bitop3_b32 v22, v76, s80, v76 bitop3:0xcf
	v_cndmask_b32_e32 v20, v21, v20, vcc
	v_and_b32_e32 v21, 0x7fffff00, v76
	v_cmp_gt_i32_e32 vcc, 0, v76
	v_sub_f32_e32 v20, v20, v31
	v_bitop3_b32 v23, v6, s80, v6 bitop3:0xcf
	v_cndmask_b32_e32 v21, v22, v21, vcc
	v_and_b32_e32 v22, 0x7fffff00, v6
	v_cmp_gt_i32_e32 vcc, 0, v6
	v_mul_f32_e32 v20, 0x3fb8aa3b, v20
	v_sub_f32_e32 v21, v21, v31
	v_cndmask_b32_e32 v22, v23, v22, vcc
	v_and_b32_e32 v23, 0x7fffff00, v7
; DI float ord2f(unsigned u) { return __uint_as_float((u & 0x80000000u) ? (u & 0x7fffffffu) : ~u); }
; __device__ __forceinline__ void route_task(const Params& p, int layer, const u16* qg, int rb, int hd, int r, int h) {
;     ...
;     for (int jj = 0; jj < 16; ++jj) { vs[jj] = __expf(ord2f(ct[jj] & ~255u) - v0); den += vs[jj]; }
;     const float inv = 1.f / den;
;     unsigned eo[16];
; #pragma unroll
;     for (int jj = 0; jj < 16; ++jj) {
;       const unsigned flat = 255u - (ct[jj] & 255u);
;       const unsigned a = flat >> 4, b = flat & 15u;
;       unsigned ka = top[0][0], kb = top[1][0];
; #pragma unroll
;       for (int k = 1; k < 16; ++k) { ka = (a == (unsigned)k) ? top[0][k] : ka; kb = (b == (unsigned)k) ? top[1][k] : kb; }
;       eo[jj] = (127u - (ka & 127u)) * 128u + (127u - (kb & 127u));
	v_bitop3_b32 v25, v7, s80, v7 bitop3:0xcf
	v_cmp_gt_i32_e32 vcc, 0, v7
	v_exp_f32_e32 v20, v20
	v_mul_f32_e32 v21, 0x3fb8aa3b, v21
	v_sub_f32_e32 v22, v22, v31
	v_cndmask_b32_e32 v23, v25, v23, vcc
	v_exp_f32_e32 v21, v21
	v_mul_f32_e32 v22, 0x3fb8aa3b, v22
	v_sub_f32_e32 v23, v23, v31
	v_exp_f32_e32 v22, v22
	v_mul_f32_e32 v23, 0x3fb8aa3b, v23
	v_exp_f32_e32 v23, v23
	v_add_f32_e32 v24, v20, v24
	v_add_f32_e32 v24, v21, v24
	v_add_f32_e32 v24, v22, v24
	v_max_u32_e32 v13, v28, v13
	v_add_f32_e32 v28, v23, v24
	v_and_b32_e32 v24, 0x7fffff00, v8
	v_bitop3_b32 v25, v8, s80, v8 bitop3:0xcf
	v_cmp_gt_i32_e32 vcc, 0, v8
	v_max_u32_e32 v12, v26, v12
	v_bitop3_b32 v26, v9, s80, v9 bitop3:0xcf
	v_cndmask_b32_e32 v24, v25, v24, vcc
	v_and_b32_e32 v25, 0x7fffff00, v9
	v_cmp_gt_i32_e32 vcc, 0, v9
	v_sub_f32_e32 v24, v24, v31
	v_bitop3_b32 v27, v10, s80, v10 bitop3:0xcf
	v_cndmask_b32_e32 v25, v26, v25, vcc
	v_and_b32_e32 v26, 0x7fffff00, v10
	v_cmp_gt_i32_e32 vcc, 0, v10
	v_mul_f32_e32 v24, 0x3fb8aa3b, v24
	v_sub_f32_e32 v25, v25, v31
	v_cndmask_b32_e32 v26, v27, v26, vcc
	v_and_b32_e32 v27, 0x7fffff00, v11
	v_bitop3_b32 v29, v11, s80, v11 bitop3:0xcf
	v_cmp_gt_i32_e32 vcc, 0, v11
	v_exp_f32_e32 v24, v24
	v_mul_f32_e32 v25, 0x3fb8aa3b, v25
	v_sub_f32_e32 v26, v26, v31
	v_cndmask_b32_e32 v27, v29, v27, vcc
	v_exp_f32_e32 v25, v25
	v_mul_f32_e32 v26, 0x3fb8aa3b, v26
	v_sub_f32_e32 v27, v27, v31
	v_exp_f32_e32 v26, v26
	v_mul_f32_e32 v27, 0x3fb8aa3b, v27
	v_exp_f32_e32 v27, v27
	v_add_f32_e32 v28, v24, v28
	v_add_f32_e32 v28, v25, v28
	v_add_f32_e32 v28, v26, v28
	v_add_f32_e32 v67, v27, v28
	v_and_b32_e32 v28, 0x7fffff00, v12
	v_bitop3_b32 v29, v12, s80, v12 bitop3:0xcf
	v_cmp_gt_i32_e32 vcc, 0, v12
	v_max_u32_e32 v14, v30, v14
	v_bitop3_b32 v30, v13, s80, v13 bitop3:0xcf
	v_cndmask_b32_e32 v28, v29, v28, vcc
	v_and_b32_e32 v29, 0x7fffff00, v13
	v_cmp_gt_i32_e32 vcc, 0, v13
	v_not_b32_e32 v1, v0
	v_bitop3_b32 v82, v14, s80, v14 bitop3:0xcf
	v_cndmask_b32_e32 v29, v30, v29, vcc
	v_and_b32_e32 v30, 0x7fffff00, v14
	v_cmp_gt_i32_e32 vcc, 0, v14
	v_bitop3_b32 v83, v64, s80, v64 bitop3:0xcf
	v_bfe_u32 v1, v1, 4, 4
	v_cndmask_b32_e32 v30, v82, v30, vcc
	v_and_b32_e32 v82, 0x7fffff00, v64
	v_cmp_gt_i32_e32 vcc, 0, v64
	v_bitop3_b32 v0, v0, 15, v0 bitop3:0xc
	v_sub_f32_e32 v28, v28, v31
	v_cndmask_b32_e32 v82, v83, v82, vcc
	v_cmp_eq_u32_e32 vcc, 1, v1
	v_sub_f32_e32 v29, v29, v31
	v_sub_f32_e32 v30, v30, v31
	v_sub_f32_e32 v31, v82, v31
	v_cndmask_b32_e32 v82, v50, v46, vcc
	v_cmp_eq_u32_e32 vcc, 1, v0
	v_not_b32_e32 v3, v2
	v_bitop3_b32 v2, v2, 15, v2 bitop3:0xc
	v_cndmask_b32_e32 v83, v63, v62, vcc
	v_cmp_eq_u32_e32 vcc, 2, v1
	v_not_b32_e32 v5, v4
	v_not_b32_e32 v81, v80
	v_cndmask_b32_e32 v82, v82, v45, vcc
	v_cmp_eq_u32_e32 vcc, 2, v0
	v_not_b32_e32 v79, v78
	v_not_b32_e32 v77, v76
	v_cndmask_b32_e32 v83, v83, v61, vcc
	v_cmp_eq_u32_e32 vcc, 3, v1
	v_bitop3_b32 v76, v76, 15, v76 bitop3:0xc
	v_not_b32_e32 v75, v6
	v_cndmask_b32_e32 v82, v82, v44, vcc
	v_cmp_eq_u32_e32 vcc, 3, v0
	v_bfe_u32 v75, v75, 4, 4
	v_bitop3_b32 v6, v6, 15, v6 bitop3:0xc
	v_cndmask_b32_e32 v83, v83, v60, vcc
	v_cmp_eq_u32_e32 vcc, 4, v1
	v_not_b32_e32 v74, v7
	v_bfe_u32 v74, v74, 4, 4
	v_cndmask_b32_e32 v82, v82, v43, vcc
	v_cmp_eq_u32_e32 vcc, 4, v0
	v_bitop3_b32 v7, v7, 15, v7 bitop3:0xc
	v_not_b32_e32 v73, v8
	v_cndmask_b32_e32 v83, v83, v59, vcc
	v_cmp_eq_u32_e32 vcc, 5, v1
	v_bfe_u32 v73, v73, 4, 4
	v_bitop3_b32 v8, v8, 15, v8 bitop3:0xc
	v_cndmask_b32_e32 v82, v82, v42, vcc
	v_cmp_eq_u32_e32 vcc, 5, v0
	v_not_b32_e32 v72, v9
	v_bfe_u32 v72, v72, 4, 4
	v_cndmask_b32_e32 v83, v83, v58, vcc
	v_cmp_eq_u32_e32 vcc, 6, v1
	v_bitop3_b32 v9, v9, 15, v9 bitop3:0xc
	v_not_b32_e32 v71, v10
	v_cndmask_b32_e32 v82, v82, v41, vcc
	v_cmp_eq_u32_e32 vcc, 6, v0
	v_bfe_u32 v71, v71, 4, 4
	v_bitop3_b32 v10, v10, 15, v10 bitop3:0xc
	v_cndmask_b32_e32 v83, v83, v57, vcc
	v_cmp_eq_u32_e32 vcc, 7, v1
	v_not_b32_e32 v70, v11
	v_bfe_u32 v70, v70, 4, 4
	v_cndmask_b32_e32 v82, v82, v40, vcc
	v_cmp_eq_u32_e32 vcc, 7, v0
	v_bitop3_b32 v11, v11, 15, v11 bitop3:0xc
	v_not_b32_e32 v69, v12
	v_cndmask_b32_e32 v83, v83, v56, vcc
	v_cmp_eq_u32_e32 vcc, 8, v1
	v_bfe_u32 v69, v69, 4, 4
	v_bitop3_b32 v12, v12, 15, v12 bitop3:0xc
	v_cndmask_b32_e32 v82, v82, v39, vcc
	v_cmp_eq_u32_e32 vcc, 8, v0
	v_not_b32_e32 v68, v13
	v_bfe_u32 v68, v68, 4, 4
	v_cndmask_b32_e32 v83, v83, v55, vcc
	v_cmp_eq_u32_e32 vcc, 9, v1
	v_bitop3_b32 v13, v13, 15, v13 bitop3:0xc
	v_not_b32_e32 v66, v14
	v_cndmask_b32_e32 v82, v82, v38, vcc
	v_cmp_eq_u32_e32 vcc, 9, v0
	v_bfe_u32 v66, v66, 4, 4
	v_bitop3_b32 v14, v14, 15, v14 bitop3:0xc
	v_cndmask_b32_e32 v83, v83, v54, vcc
	v_cmp_eq_u32_e32 vcc, 10, v1
	v_not_b32_e32 v65, v64
	v_bfe_u32 v65, v65, 4, 4
	v_cndmask_b32_e32 v82, v82, v37, vcc
	v_cmp_eq_u32_e32 vcc, 10, v0
	v_bitop3_b32 v64, v64, 15, v64 bitop3:0xc
	v_mul_f32_e32 v28, 0x3fb8aa3b, v28
	v_cndmask_b32_e32 v83, v83, v53, vcc
	v_cmp_eq_u32_e32 vcc, 11, v1
	v_exp_f32_e32 v28, v28
	v_mul_f32_e32 v29, 0x3fb8aa3b, v29
	v_cndmask_b32_e32 v82, v82, v36, vcc
	v_cmp_eq_u32_e32 vcc, 11, v0
	v_exp_f32_e32 v29, v29
	v_mul_f32_e32 v30, 0x3fb8aa3b, v30
	v_cndmask_b32_e32 v83, v83, v52, vcc
	v_cmp_eq_u32_e32 vcc, 12, v1
	v_exp_f32_e32 v30, v30
	v_mul_f32_e32 v31, 0x3fb8aa3b, v31
	v_cndmask_b32_e32 v82, v82, v35, vcc
	v_cmp_eq_u32_e32 vcc, 12, v0
	v_exp_f32_e32 v31, v31
	v_add_f32_e32 v67, v28, v67
	v_cndmask_b32_e32 v83, v83, v51, vcc
	v_cmp_eq_u32_e32 vcc, 13, v1
	v_add_f32_e32 v67, v29, v67
	v_add_f32_e32 v67, v30, v67
	v_cndmask_b32_e32 v82, v82, v34, vcc
	v_cmp_eq_u32_e32 vcc, 13, v0
	v_add_f32_e32 v67, v31, v67
	v_or_b32_e32 v32, v32, v138
; __device__ __forceinline__ void route_task(const Params& p, int layer, const u16* qg, int rb, int hd, int r, int h) {
;     ...
;     for (int jj = 0; jj < 16; ++jj) {
;       const unsigned flat = 255u - (ct[jj] & 255u);
;       const unsigned a = flat >> 4, b = flat & 15u;
;       unsigned ka = top[0][0], kb = top[1][0];
; #pragma unroll
;       for (int k = 1; k < 16; ++k) { ka = (a == (unsigned)k) ? top[0][k] : ka; kb = (b == (unsigned)k) ? top[1][k] : kb; }
;       eo[jj] = (127u - (ka & 127u)) * 128u + (127u - (kb & 127u));
;     }
	v_cndmask_b32_e32 v83, v83, v49, vcc
	v_cmp_eq_u32_e32 vcc, 14, v1
	s_nop 1
	v_cndmask_b32_e32 v82, v82, v33, vcc
	v_cmp_eq_u32_e32 vcc, 14, v0
	s_nop 1
	v_cndmask_b32_e32 v83, v83, v48, vcc
	v_cmp_eq_u32_e32 vcc, 15, v1
	s_nop 1
	v_cndmask_b32_e32 v1, v82, v15, vcc
	v_cmp_eq_u32_e32 vcc, 15, v0
	v_lshlrev_b32_e32 v1, 7, v1
	v_and_b32_e32 v1, 0x3f80, v1
	v_cndmask_b32_e32 v0, v83, v47, vcc
	v_and_b32_e32 v0, 0x7f, v0
	v_bitop3_b32 v0, v1, s82, v0 bitop3:0x36
	v_bfe_u32 v1, v3, 4, 4
	v_cmp_eq_u32_e32 vcc, 1, v1
	s_nop 1
	v_cndmask_b32_e32 v3, v50, v46, vcc
	v_cmp_eq_u32_e32 vcc, 1, v2
	s_nop 1
	v_cndmask_b32_e32 v82, v63, v62, vcc
	v_cmp_eq_u32_e32 vcc, 2, v1
	s_nop 1
	v_cndmask_b32_e32 v3, v3, v45, vcc
	v_cmp_eq_u32_e32 vcc, 2, v2
	s_nop 1
	v_cndmask_b32_e32 v82, v82, v61, vcc
	v_cmp_eq_u32_e32 vcc, 3, v1
	s_nop 1
	v_cndmask_b32_e32 v3, v3, v44, vcc
	v_cmp_eq_u32_e32 vcc, 3, v2
	s_nop 1
	v_cndmask_b32_e32 v82, v82, v60, vcc
	v_cmp_eq_u32_e32 vcc, 4, v1
	s_nop 1
	v_cndmask_b32_e32 v3, v3, v43, vcc
	v_cmp_eq_u32_e32 vcc, 4, v2
	s_nop 1
	v_cndmask_b32_e32 v82, v82, v59, vcc
	v_cmp_eq_u32_e32 vcc, 5, v1
	s_nop 1
	v_cndmask_b32_e32 v3, v3, v42, vcc
	v_cmp_eq_u32_e32 vcc, 5, v2
	s_nop 1
	v_cndmask_b32_e32 v82, v82, v58, vcc
	v_cmp_eq_u32_e32 vcc, 6, v1
	s_nop 1
	v_cndmask_b32_e32 v3, v3, v41, vcc
	v_cmp_eq_u32_e32 vcc, 6, v2
	s_nop 1
	v_cndmask_b32_e32 v82, v82, v57, vcc
	v_cmp_eq_u32_e32 vcc, 7, v1
	s_nop 1
	v_cndmask_b32_e32 v3, v3, v40, vcc
	v_cmp_eq_u32_e32 vcc, 7, v2
	s_nop 1
	v_cndmask_b32_e32 v82, v82, v56, vcc
	v_cmp_eq_u32_e32 vcc, 8, v1
	s_nop 1
	v_cndmask_b32_e32 v3, v3, v39, vcc
	v_cmp_eq_u32_e32 vcc, 8, v2
	s_nop 1
	v_cndmask_b32_e32 v82, v82, v55, vcc
	v_cmp_eq_u32_e32 vcc, 9, v1
	s_nop 1
	v_cndmask_b32_e32 v3, v3, v38, vcc
	v_cmp_eq_u32_e32 vcc, 9, v2
	s_nop 1
	v_cndmask_b32_e32 v82, v82, v54, vcc
	v_cmp_eq_u32_e32 vcc, 10, v1
	s_nop 1
	v_cndmask_b32_e32 v3, v3, v37, vcc
	v_cmp_eq_u32_e32 vcc, 10, v2
	s_nop 1
	v_cndmask_b32_e32 v82, v82, v53, vcc
	v_cmp_eq_u32_e32 vcc, 11, v1
	s_nop 1
	v_cndmask_b32_e32 v3, v3, v36, vcc
	v_cmp_eq_u32_e32 vcc, 11, v2
	s_nop 1
	v_cndmask_b32_e32 v82, v82, v52, vcc
	v_cmp_eq_u32_e32 vcc, 12, v1
	s_nop 1
	v_cndmask_b32_e32 v3, v3, v35, vcc
	v_cmp_eq_u32_e32 vcc, 12, v2
	s_nop 1
	v_cndmask_b32_e32 v82, v82, v51, vcc
	v_cmp_eq_u32_e32 vcc, 13, v1
	s_nop 1
	v_cndmask_b32_e32 v3, v3, v34, vcc
	v_cmp_eq_u32_e32 vcc, 13, v2
	s_nop 1
	v_cndmask_b32_e32 v82, v82, v49, vcc
	v_cmp_eq_u32_e32 vcc, 14, v1
	s_nop 1
	v_cndmask_b32_e32 v3, v3, v33, vcc
	v_cmp_eq_u32_e32 vcc, 14, v2
	s_nop 1
	v_cndmask_b32_e32 v82, v82, v48, vcc
	v_cmp_eq_u32_e32 vcc, 15, v1
	s_nop 1
	v_cndmask_b32_e32 v1, v3, v15, vcc
	v_cmp_eq_u32_e32 vcc, 15, v2
	v_lshlrev_b32_e32 v1, 7, v1
	v_and_b32_e32 v1, 0x3f80, v1
	v_cndmask_b32_e32 v2, v82, v47, vcc
	v_and_b32_e32 v2, 0x7f, v2
	v_bitop3_b32 v1, v1, s82, v2 bitop3:0x36
	v_bfe_u32 v2, v5, 4, 4
	v_bitop3_b32 v3, v4, 15, v4 bitop3:0xc
	v_cmp_eq_u32_e32 vcc, 1, v2
	s_nop 1
	v_cndmask_b32_e32 v4, v50, v46, vcc
	v_cmp_eq_u32_e32 vcc, 1, v3
	s_nop 1
	v_cndmask_b32_e32 v5, v63, v62, vcc
	v_cmp_eq_u32_e32 vcc, 2, v2
	s_nop 1
	v_cndmask_b32_e32 v4, v4, v45, vcc
	v_cmp_eq_u32_e32 vcc, 2, v3
	s_nop 1
	v_cndmask_b32_e32 v5, v5, v61, vcc
	v_cmp_eq_u32_e32 vcc, 3, v2
	s_nop 1
	v_cndmask_b32_e32 v4, v4, v44, vcc
	v_cmp_eq_u32_e32 vcc, 3, v3
	s_nop 1
	v_cndmask_b32_e32 v5, v5, v60, vcc
	v_cmp_eq_u32_e32 vcc, 4, v2
	s_nop 1
	v_cndmask_b32_e32 v4, v4, v43, vcc
	v_cmp_eq_u32_e32 vcc, 4, v3
	s_nop 1
	v_cndmask_b32_e32 v5, v5, v59, vcc
	v_cmp_eq_u32_e32 vcc, 5, v2
	s_nop 1
	v_cndmask_b32_e32 v4, v4, v42, vcc
	v_cmp_eq_u32_e32 vcc, 5, v3
	s_nop 1
	v_cndmask_b32_e32 v5, v5, v58, vcc
	v_cmp_eq_u32_e32 vcc, 6, v2
	s_nop 1
	v_cndmask_b32_e32 v4, v4, v41, vcc
	v_cmp_eq_u32_e32 vcc, 6, v3
	s_nop 1
	v_cndmask_b32_e32 v5, v5, v57, vcc
	v_cmp_eq_u32_e32 vcc, 7, v2
	s_nop 1
	v_cndmask_b32_e32 v4, v4, v40, vcc
	v_cmp_eq_u32_e32 vcc, 7, v3
	s_nop 1
	v_cndmask_b32_e32 v5, v5, v56, vcc
	v_cmp_eq_u32_e32 vcc, 8, v2
	s_nop 1
	v_cndmask_b32_e32 v4, v4, v39, vcc
	v_cmp_eq_u32_e32 vcc, 8, v3
	s_nop 1
	v_cndmask_b32_e32 v5, v5, v55, vcc
	v_cmp_eq_u32_e32 vcc, 9, v2
	s_nop 1
	v_cndmask_b32_e32 v4, v4, v38, vcc
	v_cmp_eq_u32_e32 vcc, 9, v3
	s_nop 1
	v_cndmask_b32_e32 v5, v5, v54, vcc
	v_cmp_eq_u32_e32 vcc, 10, v2
	s_nop 1
	v_cndmask_b32_e32 v4, v4, v37, vcc
	v_cmp_eq_u32_e32 vcc, 10, v3
	s_nop 1
	v_cndmask_b32_e32 v5, v5, v53, vcc
	v_cmp_eq_u32_e32 vcc, 11, v2
	s_nop 1
	v_cndmask_b32_e32 v4, v4, v36, vcc
	v_cmp_eq_u32_e32 vcc, 11, v3
	s_nop 1
	v_cndmask_b32_e32 v5, v5, v52, vcc
	v_cmp_eq_u32_e32 vcc, 12, v2
	s_nop 1
	v_cndmask_b32_e32 v4, v4, v35, vcc
	v_cmp_eq_u32_e32 vcc, 12, v3
	s_nop 1
	v_cndmask_b32_e32 v5, v5, v51, vcc
	v_cmp_eq_u32_e32 vcc, 13, v2
	s_nop 1
	v_cndmask_b32_e32 v4, v4, v34, vcc
	v_cmp_eq_u32_e32 vcc, 13, v3
	s_nop 1
	v_cndmask_b32_e32 v5, v5, v49, vcc
	v_cmp_eq_u32_e32 vcc, 14, v2
	s_nop 1
	v_cndmask_b32_e32 v4, v4, v33, vcc
	v_cmp_eq_u32_e32 vcc, 14, v3
	s_nop 1
	v_cndmask_b32_e32 v5, v5, v48, vcc
	v_cmp_eq_u32_e32 vcc, 15, v2
	s_nop 1
	v_cndmask_b32_e32 v2, v4, v15, vcc
	v_cmp_eq_u32_e32 vcc, 15, v3
	v_lshlrev_b32_e32 v2, 7, v2
	v_and_b32_e32 v2, 0x3f80, v2
	v_cndmask_b32_e32 v3, v5, v47, vcc
	v_and_b32_e32 v3, 0x7f, v3
	v_bitop3_b32 v2, v2, s82, v3 bitop3:0x36
	v_bfe_u32 v3, v81, 4, 4
	v_bitop3_b32 v4, v80, 15, v80 bitop3:0xc
	v_cmp_eq_u32_e32 vcc, 1, v3
	s_nop 1
	v_cndmask_b32_e32 v5, v50, v46, vcc
	v_cmp_eq_u32_e32 vcc, 1, v4
	s_nop 1
	v_cndmask_b32_e32 v80, v63, v62, vcc
	v_cmp_eq_u32_e32 vcc, 2, v3
	s_nop 1
	v_cndmask_b32_e32 v5, v5, v45, vcc
	v_cmp_eq_u32_e32 vcc, 2, v4
	s_nop 1
	v_cndmask_b32_e32 v80, v80, v61, vcc
; __device__ __forceinline__ void route_task(const Params& p, int layer, const u16* qg, int rb, int hd, int r, int h) {
;     ...
;     for (int jj = 0; jj < 16; ++jj) {
;       const unsigned flat = 255u - (ct[jj] & 255u);
;       const unsigned a = flat >> 4, b = flat & 15u;
;       unsigned ka = top[0][0], kb = top[1][0];
; #pragma unroll
;       for (int k = 1; k < 16; ++k) { ka = (a == (unsigned)k) ? top[0][k] : ka; kb = (b == (unsigned)k) ? top[1][k] : kb; }
;       eo[jj] = (127u - (ka & 127u)) * 128u + (127u - (kb & 127u));
;     }
	v_cmp_eq_u32_e32 vcc, 3, v3
	s_nop 1
	v_cndmask_b32_e32 v5, v5, v44, vcc
	v_cmp_eq_u32_e32 vcc, 3, v4
	s_nop 1
	v_cndmask_b32_e32 v80, v80, v60, vcc
	v_cmp_eq_u32_e32 vcc, 4, v3
	s_nop 1
	v_cndmask_b32_e32 v5, v5, v43, vcc
	v_cmp_eq_u32_e32 vcc, 4, v4
	s_nop 1
	v_cndmask_b32_e32 v80, v80, v59, vcc
	v_cmp_eq_u32_e32 vcc, 5, v3
	s_nop 1
	v_cndmask_b32_e32 v5, v5, v42, vcc
	v_cmp_eq_u32_e32 vcc, 5, v4
	s_nop 1
	v_cndmask_b32_e32 v80, v80, v58, vcc
	v_cmp_eq_u32_e32 vcc, 6, v3
	s_nop 1
	v_cndmask_b32_e32 v5, v5, v41, vcc
	v_cmp_eq_u32_e32 vcc, 6, v4
	s_nop 1
	v_cndmask_b32_e32 v80, v80, v57, vcc
	v_cmp_eq_u32_e32 vcc, 7, v3
	s_nop 1
	v_cndmask_b32_e32 v5, v5, v40, vcc
	v_cmp_eq_u32_e32 vcc, 7, v4
	s_nop 1
	v_cndmask_b32_e32 v80, v80, v56, vcc
	v_cmp_eq_u32_e32 vcc, 8, v3
	s_nop 1
	v_cndmask_b32_e32 v5, v5, v39, vcc
	v_cmp_eq_u32_e32 vcc, 8, v4
	s_nop 1
	v_cndmask_b32_e32 v80, v80, v55, vcc
	v_cmp_eq_u32_e32 vcc, 9, v3
	s_nop 1
	v_cndmask_b32_e32 v5, v5, v38, vcc
	v_cmp_eq_u32_e32 vcc, 9, v4
	s_nop 1
	v_cndmask_b32_e32 v80, v80, v54, vcc
	v_cmp_eq_u32_e32 vcc, 10, v3
	s_nop 1
	v_cndmask_b32_e32 v5, v5, v37, vcc
	v_cmp_eq_u32_e32 vcc, 10, v4
	s_nop 1
	v_cndmask_b32_e32 v80, v80, v53, vcc
	v_cmp_eq_u32_e32 vcc, 11, v3
	s_nop 1
	v_cndmask_b32_e32 v5, v5, v36, vcc
	v_cmp_eq_u32_e32 vcc, 11, v4
	s_nop 1
	v_cndmask_b32_e32 v80, v80, v52, vcc
	v_cmp_eq_u32_e32 vcc, 12, v3
	s_nop 1
	v_cndmask_b32_e32 v5, v5, v35, vcc
	v_cmp_eq_u32_e32 vcc, 12, v4
	s_nop 1
	v_cndmask_b32_e32 v80, v80, v51, vcc
	v_cmp_eq_u32_e32 vcc, 13, v3
	s_nop 1
	v_cndmask_b32_e32 v5, v5, v34, vcc
	v_cmp_eq_u32_e32 vcc, 13, v4
	s_nop 1
	v_cndmask_b32_e32 v80, v80, v49, vcc
	v_cmp_eq_u32_e32 vcc, 14, v3
	s_nop 1
	v_cndmask_b32_e32 v5, v5, v33, vcc
	v_cmp_eq_u32_e32 vcc, 14, v4
	s_nop 1
	v_cndmask_b32_e32 v80, v80, v48, vcc
	v_cmp_eq_u32_e32 vcc, 15, v3
	s_nop 1
	v_cndmask_b32_e32 v3, v5, v15, vcc
	v_cmp_eq_u32_e32 vcc, 15, v4
	v_lshlrev_b32_e32 v3, 7, v3
	v_and_b32_e32 v3, 0x3f80, v3
	v_cndmask_b32_e32 v4, v80, v47, vcc
	v_and_b32_e32 v4, 0x7f, v4
	v_bitop3_b32 v3, v3, s82, v4 bitop3:0x36
	v_bfe_u32 v4, v79, 4, 4
	v_bitop3_b32 v5, v78, 15, v78 bitop3:0xc
	v_cmp_eq_u32_e32 vcc, 1, v4
	s_nop 1
	v_cndmask_b32_e32 v78, v50, v46, vcc
	v_cmp_eq_u32_e32 vcc, 1, v5
	s_nop 1
	v_cndmask_b32_e32 v79, v63, v62, vcc
	v_cmp_eq_u32_e32 vcc, 2, v4
	s_nop 1
	v_cndmask_b32_e32 v78, v78, v45, vcc
	v_cmp_eq_u32_e32 vcc, 2, v5
	s_nop 1
	v_cndmask_b32_e32 v79, v79, v61, vcc
	v_cmp_eq_u32_e32 vcc, 3, v4
	s_nop 1
	v_cndmask_b32_e32 v78, v78, v44, vcc
	v_cmp_eq_u32_e32 vcc, 3, v5
	s_nop 1
	v_cndmask_b32_e32 v79, v79, v60, vcc
	v_cmp_eq_u32_e32 vcc, 4, v4
	s_nop 1
	v_cndmask_b32_e32 v78, v78, v43, vcc
	v_cmp_eq_u32_e32 vcc, 4, v5
	s_nop 1
	v_cndmask_b32_e32 v79, v79, v59, vcc
	v_cmp_eq_u32_e32 vcc, 5, v4
	s_nop 1
	v_cndmask_b32_e32 v78, v78, v42, vcc
	v_cmp_eq_u32_e32 vcc, 5, v5
	s_nop 1
	v_cndmask_b32_e32 v79, v79, v58, vcc
	v_cmp_eq_u32_e32 vcc, 6, v4
	s_nop 1
	v_cndmask_b32_e32 v78, v78, v41, vcc
	v_cmp_eq_u32_e32 vcc, 6, v5
	s_nop 1
	v_cndmask_b32_e32 v79, v79, v57, vcc
	v_cmp_eq_u32_e32 vcc, 7, v4
	s_nop 1
	v_cndmask_b32_e32 v78, v78, v40, vcc
	v_cmp_eq_u32_e32 vcc, 7, v5
	s_nop 1
	v_cndmask_b32_e32 v79, v79, v56, vcc
	v_cmp_eq_u32_e32 vcc, 8, v4
	s_nop 1
	v_cndmask_b32_e32 v78, v78, v39, vcc
	v_cmp_eq_u32_e32 vcc, 8, v5
	s_nop 1
	v_cndmask_b32_e32 v79, v79, v55, vcc
	v_cmp_eq_u32_e32 vcc, 9, v4
	s_nop 1
	v_cndmask_b32_e32 v78, v78, v38, vcc
	v_cmp_eq_u32_e32 vcc, 9, v5
	s_nop 1
	v_cndmask_b32_e32 v79, v79, v54, vcc
	v_cmp_eq_u32_e32 vcc, 10, v4
	s_nop 1
	v_cndmask_b32_e32 v78, v78, v37, vcc
	v_cmp_eq_u32_e32 vcc, 10, v5
	s_nop 1
	v_cndmask_b32_e32 v79, v79, v53, vcc
	v_cmp_eq_u32_e32 vcc, 11, v4
	s_nop 1
	v_cndmask_b32_e32 v78, v78, v36, vcc
	v_cmp_eq_u32_e32 vcc, 11, v5
	s_nop 1
	v_cndmask_b32_e32 v79, v79, v52, vcc
	v_cmp_eq_u32_e32 vcc, 12, v4
	s_nop 1
	v_cndmask_b32_e32 v78, v78, v35, vcc
	v_cmp_eq_u32_e32 vcc, 12, v5
	s_nop 1
	v_cndmask_b32_e32 v79, v79, v51, vcc
	v_cmp_eq_u32_e32 vcc, 13, v4
	s_nop 1
	v_cndmask_b32_e32 v78, v78, v34, vcc
	v_cmp_eq_u32_e32 vcc, 13, v5
	s_nop 1
	v_cndmask_b32_e32 v79, v79, v49, vcc
	v_cmp_eq_u32_e32 vcc, 14, v4
	s_nop 1
	v_cndmask_b32_e32 v78, v78, v33, vcc
	v_cmp_eq_u32_e32 vcc, 14, v5
	s_nop 1
	v_cndmask_b32_e32 v79, v79, v48, vcc
	v_cmp_eq_u32_e32 vcc, 15, v4
	s_nop 1
	v_cndmask_b32_e32 v4, v78, v15, vcc
	v_cmp_eq_u32_e32 vcc, 15, v5
	v_lshlrev_b32_e32 v4, 7, v4
	v_and_b32_e32 v4, 0x3f80, v4
	v_cndmask_b32_e32 v5, v79, v47, vcc
	v_and_b32_e32 v5, 0x7f, v5
	v_bitop3_b32 v4, v4, s82, v5 bitop3:0x36
	v_bfe_u32 v5, v77, 4, 4
	v_cmp_eq_u32_e32 vcc, 1, v5
	s_nop 1
	v_cndmask_b32_e32 v77, v50, v46, vcc
	v_cmp_eq_u32_e32 vcc, 1, v76
	s_nop 1
	v_cndmask_b32_e32 v78, v63, v62, vcc
	v_cmp_eq_u32_e32 vcc, 2, v5
	s_nop 1
	v_cndmask_b32_e32 v77, v77, v45, vcc
	v_cmp_eq_u32_e32 vcc, 2, v76
	s_nop 1
	v_cndmask_b32_e32 v78, v78, v61, vcc
	v_cmp_eq_u32_e32 vcc, 3, v5
	s_nop 1
	v_cndmask_b32_e32 v77, v77, v44, vcc
	v_cmp_eq_u32_e32 vcc, 3, v76
	s_nop 1
	v_cndmask_b32_e32 v78, v78, v60, vcc
	v_cmp_eq_u32_e32 vcc, 4, v5
	s_nop 1
	v_cndmask_b32_e32 v77, v77, v43, vcc
	v_cmp_eq_u32_e32 vcc, 4, v76
	s_nop 1
	v_cndmask_b32_e32 v78, v78, v59, vcc
	v_cmp_eq_u32_e32 vcc, 5, v5
	s_nop 1
	v_cndmask_b32_e32 v77, v77, v42, vcc
	v_cmp_eq_u32_e32 vcc, 5, v76
	s_nop 1
	v_cndmask_b32_e32 v78, v78, v58, vcc
	v_cmp_eq_u32_e32 vcc, 6, v5
	s_nop 1
	v_cndmask_b32_e32 v77, v77, v41, vcc
	v_cmp_eq_u32_e32 vcc, 6, v76
	s_nop 1
	v_cndmask_b32_e32 v78, v78, v57, vcc
	v_cmp_eq_u32_e32 vcc, 7, v5
	s_nop 1
	v_cndmask_b32_e32 v77, v77, v40, vcc
	v_cmp_eq_u32_e32 vcc, 7, v76
	s_nop 1
	v_cndmask_b32_e32 v78, v78, v56, vcc
; __device__ __forceinline__ void route_task(const Params& p, int layer, const u16* qg, int rb, int hd, int r, int h) {
;     ...
;     for (int jj = 0; jj < 16; ++jj) {
;       const unsigned flat = 255u - (ct[jj] & 255u);
;       const unsigned a = flat >> 4, b = flat & 15u;
;       unsigned ka = top[0][0], kb = top[1][0];
; #pragma unroll
;       for (int k = 1; k < 16; ++k) { ka = (a == (unsigned)k) ? top[0][k] : ka; kb = (b == (unsigned)k) ? top[1][k] : kb; }
;       eo[jj] = (127u - (ka & 127u)) * 128u + (127u - (kb & 127u));
;     }
	v_cmp_eq_u32_e32 vcc, 8, v5
	s_nop 1
	v_cndmask_b32_e32 v77, v77, v39, vcc
	v_cmp_eq_u32_e32 vcc, 8, v76
	s_nop 1
	v_cndmask_b32_e32 v78, v78, v55, vcc
	v_cmp_eq_u32_e32 vcc, 9, v5
	s_nop 1
	v_cndmask_b32_e32 v77, v77, v38, vcc
	v_cmp_eq_u32_e32 vcc, 9, v76
	s_nop 1
	v_cndmask_b32_e32 v78, v78, v54, vcc
	v_cmp_eq_u32_e32 vcc, 10, v5
	s_nop 1
	v_cndmask_b32_e32 v77, v77, v37, vcc
	v_cmp_eq_u32_e32 vcc, 10, v76
	s_nop 1
	v_cndmask_b32_e32 v78, v78, v53, vcc
	v_cmp_eq_u32_e32 vcc, 11, v5
	s_nop 1
	v_cndmask_b32_e32 v77, v77, v36, vcc
	v_cmp_eq_u32_e32 vcc, 11, v76
	s_nop 1
	v_cndmask_b32_e32 v78, v78, v52, vcc
	v_cmp_eq_u32_e32 vcc, 12, v5
	s_nop 1
	v_cndmask_b32_e32 v77, v77, v35, vcc
	v_cmp_eq_u32_e32 vcc, 12, v76
	s_nop 1
	v_cndmask_b32_e32 v78, v78, v51, vcc
	v_cmp_eq_u32_e32 vcc, 13, v5
	s_nop 1
	v_cndmask_b32_e32 v77, v77, v34, vcc
	v_cmp_eq_u32_e32 vcc, 13, v76
	s_nop 1
	v_cndmask_b32_e32 v78, v78, v49, vcc
	v_cmp_eq_u32_e32 vcc, 14, v5
	s_nop 1
	v_cndmask_b32_e32 v77, v77, v33, vcc
	v_cmp_eq_u32_e32 vcc, 14, v76
	s_nop 1
	v_cndmask_b32_e32 v78, v78, v48, vcc
	v_cmp_eq_u32_e32 vcc, 15, v5
	s_nop 1
	v_cndmask_b32_e32 v5, v77, v15, vcc
	v_cmp_eq_u32_e32 vcc, 15, v76
	v_lshlrev_b32_e32 v5, 7, v5
	v_and_b32_e32 v5, 0x3f80, v5
	v_cndmask_b32_e32 v76, v78, v47, vcc
	v_and_b32_e32 v76, 0x7f, v76
	v_cmp_eq_u32_e32 vcc, 1, v75
	v_bitop3_b32 v5, v5, s82, v76 bitop3:0x36
	s_nop 0
	v_cndmask_b32_e32 v76, v50, v46, vcc
	v_cmp_eq_u32_e32 vcc, 1, v6
	s_nop 1
	v_cndmask_b32_e32 v77, v63, v62, vcc
	v_cmp_eq_u32_e32 vcc, 2, v75
	s_nop 1
	v_cndmask_b32_e32 v76, v76, v45, vcc
	v_cmp_eq_u32_e32 vcc, 2, v6
	s_nop 1
	v_cndmask_b32_e32 v77, v77, v61, vcc
	v_cmp_eq_u32_e32 vcc, 3, v75
	s_nop 1
	v_cndmask_b32_e32 v76, v76, v44, vcc
	v_cmp_eq_u32_e32 vcc, 3, v6
	s_nop 1
	v_cndmask_b32_e32 v77, v77, v60, vcc
	v_cmp_eq_u32_e32 vcc, 4, v75
	s_nop 1
	v_cndmask_b32_e32 v76, v76, v43, vcc
	v_cmp_eq_u32_e32 vcc, 4, v6
	s_nop 1
	v_cndmask_b32_e32 v77, v77, v59, vcc
	v_cmp_eq_u32_e32 vcc, 5, v75
	s_nop 1
	v_cndmask_b32_e32 v76, v76, v42, vcc
	v_cmp_eq_u32_e32 vcc, 5, v6
	s_nop 1
	v_cndmask_b32_e32 v77, v77, v58, vcc
	v_cmp_eq_u32_e32 vcc, 6, v75
	s_nop 1
	v_cndmask_b32_e32 v76, v76, v41, vcc
	v_cmp_eq_u32_e32 vcc, 6, v6
	s_nop 1
	v_cndmask_b32_e32 v77, v77, v57, vcc
	v_cmp_eq_u32_e32 vcc, 7, v75
	s_nop 1
	v_cndmask_b32_e32 v76, v76, v40, vcc
	v_cmp_eq_u32_e32 vcc, 7, v6
	s_nop 1
	v_cndmask_b32_e32 v77, v77, v56, vcc
	v_cmp_eq_u32_e32 vcc, 8, v75
	s_nop 1
	v_cndmask_b32_e32 v76, v76, v39, vcc
	v_cmp_eq_u32_e32 vcc, 8, v6
	s_nop 1
	v_cndmask_b32_e32 v77, v77, v55, vcc
	v_cmp_eq_u32_e32 vcc, 9, v75
	s_nop 1
	v_cndmask_b32_e32 v76, v76, v38, vcc
	v_cmp_eq_u32_e32 vcc, 9, v6
	s_nop 1
	v_cndmask_b32_e32 v77, v77, v54, vcc
	v_cmp_eq_u32_e32 vcc, 10, v75
	s_nop 1
	v_cndmask_b32_e32 v76, v76, v37, vcc
	v_cmp_eq_u32_e32 vcc, 10, v6
	s_nop 1
	v_cndmask_b32_e32 v77, v77, v53, vcc
	v_cmp_eq_u32_e32 vcc, 11, v75
	s_nop 1
	v_cndmask_b32_e32 v76, v76, v36, vcc
	v_cmp_eq_u32_e32 vcc, 11, v6
	s_nop 1
	v_cndmask_b32_e32 v77, v77, v52, vcc
	v_cmp_eq_u32_e32 vcc, 12, v75
	s_nop 1
	v_cndmask_b32_e32 v76, v76, v35, vcc
	v_cmp_eq_u32_e32 vcc, 12, v6
	s_nop 1
	v_cndmask_b32_e32 v77, v77, v51, vcc
	v_cmp_eq_u32_e32 vcc, 13, v75
	s_nop 1
	v_cndmask_b32_e32 v76, v76, v34, vcc
	v_cmp_eq_u32_e32 vcc, 13, v6
	s_nop 1
	v_cndmask_b32_e32 v77, v77, v49, vcc
	v_cmp_eq_u32_e32 vcc, 14, v75
	s_nop 1
	v_cndmask_b32_e32 v76, v76, v33, vcc
	v_cmp_eq_u32_e32 vcc, 14, v6
	s_nop 1
	v_cndmask_b32_e32 v77, v77, v48, vcc
	v_cmp_eq_u32_e32 vcc, 15, v75
	s_nop 1
	v_cndmask_b32_e32 v75, v76, v15, vcc
	v_cmp_eq_u32_e32 vcc, 15, v6
	v_lshlrev_b32_e32 v75, 7, v75
	v_and_b32_e32 v75, 0x3f80, v75
	v_cndmask_b32_e32 v6, v77, v47, vcc
	v_and_b32_e32 v6, 0x7f, v6
	v_cmp_eq_u32_e32 vcc, 1, v74
	v_bitop3_b32 v6, v75, s82, v6 bitop3:0x36
	s_nop 0
	v_cndmask_b32_e32 v75, v50, v46, vcc
	v_cmp_eq_u32_e32 vcc, 1, v7
	s_nop 1
	v_cndmask_b32_e32 v76, v63, v62, vcc
	v_cmp_eq_u32_e32 vcc, 2, v74
	s_nop 1
	v_cndmask_b32_e32 v75, v75, v45, vcc
	v_cmp_eq_u32_e32 vcc, 2, v7
	s_nop 1
	v_cndmask_b32_e32 v76, v76, v61, vcc
	v_cmp_eq_u32_e32 vcc, 3, v74
	s_nop 1
	v_cndmask_b32_e32 v75, v75, v44, vcc
	v_cmp_eq_u32_e32 vcc, 3, v7
	s_nop 1
	v_cndmask_b32_e32 v76, v76, v60, vcc
	v_cmp_eq_u32_e32 vcc, 4, v74
	s_nop 1
	v_cndmask_b32_e32 v75, v75, v43, vcc
	v_cmp_eq_u32_e32 vcc, 4, v7
	s_nop 1
	v_cndmask_b32_e32 v76, v76, v59, vcc
	v_cmp_eq_u32_e32 vcc, 5, v74
	s_nop 1
	v_cndmask_b32_e32 v75, v75, v42, vcc
	v_cmp_eq_u32_e32 vcc, 5, v7
	s_nop 1
	v_cndmask_b32_e32 v76, v76, v58, vcc
	v_cmp_eq_u32_e32 vcc, 6, v74
	s_nop 1
	v_cndmask_b32_e32 v75, v75, v41, vcc
	v_cmp_eq_u32_e32 vcc, 6, v7
	s_nop 1
	v_cndmask_b32_e32 v76, v76, v57, vcc
	v_cmp_eq_u32_e32 vcc, 7, v74
	s_nop 1
	v_cndmask_b32_e32 v75, v75, v40, vcc
	v_cmp_eq_u32_e32 vcc, 7, v7
	s_nop 1
	v_cndmask_b32_e32 v76, v76, v56, vcc
	v_cmp_eq_u32_e32 vcc, 8, v74
	s_nop 1
	v_cndmask_b32_e32 v75, v75, v39, vcc
	v_cmp_eq_u32_e32 vcc, 8, v7
	s_nop 1
	v_cndmask_b32_e32 v76, v76, v55, vcc
	v_cmp_eq_u32_e32 vcc, 9, v74
	s_nop 1
	v_cndmask_b32_e32 v75, v75, v38, vcc
	v_cmp_eq_u32_e32 vcc, 9, v7
	s_nop 1
	v_cndmask_b32_e32 v76, v76, v54, vcc
	v_cmp_eq_u32_e32 vcc, 10, v74
	s_nop 1
	v_cndmask_b32_e32 v75, v75, v37, vcc
	v_cmp_eq_u32_e32 vcc, 10, v7
	s_nop 1
	v_cndmask_b32_e32 v76, v76, v53, vcc
	v_cmp_eq_u32_e32 vcc, 11, v74
	s_nop 1
	v_cndmask_b32_e32 v75, v75, v36, vcc
	v_cmp_eq_u32_e32 vcc, 11, v7
	s_nop 1
	v_cndmask_b32_e32 v76, v76, v52, vcc
	v_cmp_eq_u32_e32 vcc, 12, v74
	s_nop 1
	v_cndmask_b32_e32 v75, v75, v35, vcc
	v_cmp_eq_u32_e32 vcc, 12, v7
	s_nop 1
	v_cndmask_b32_e32 v76, v76, v51, vcc
; __device__ __forceinline__ void route_task(const Params& p, int layer, const u16* qg, int rb, int hd, int r, int h) {
;     ...
;     for (int jj = 0; jj < 16; ++jj) {
;       const unsigned flat = 255u - (ct[jj] & 255u);
;       const unsigned a = flat >> 4, b = flat & 15u;
;       unsigned ka = top[0][0], kb = top[1][0];
; #pragma unroll
;       for (int k = 1; k < 16; ++k) { ka = (a == (unsigned)k) ? top[0][k] : ka; kb = (b == (unsigned)k) ? top[1][k] : kb; }
;       eo[jj] = (127u - (ka & 127u)) * 128u + (127u - (kb & 127u));
;     }
	v_cmp_eq_u32_e32 vcc, 13, v74
	s_nop 1
	v_cndmask_b32_e32 v75, v75, v34, vcc
	v_cmp_eq_u32_e32 vcc, 13, v7
	s_nop 1
	v_cndmask_b32_e32 v76, v76, v49, vcc
	v_cmp_eq_u32_e32 vcc, 14, v74
	s_nop 1
	v_cndmask_b32_e32 v75, v75, v33, vcc
	v_cmp_eq_u32_e32 vcc, 14, v7
	s_nop 1
	v_cndmask_b32_e32 v76, v76, v48, vcc
	v_cmp_eq_u32_e32 vcc, 15, v74
	s_nop 1
	v_cndmask_b32_e32 v74, v75, v15, vcc
	v_cmp_eq_u32_e32 vcc, 15, v7
	v_lshlrev_b32_e32 v74, 7, v74
	v_and_b32_e32 v74, 0x3f80, v74
	v_cndmask_b32_e32 v7, v76, v47, vcc
	v_and_b32_e32 v7, 0x7f, v7
	v_cmp_eq_u32_e32 vcc, 1, v73
	v_bitop3_b32 v7, v74, s82, v7 bitop3:0x36
	s_nop 0
	v_cndmask_b32_e32 v74, v50, v46, vcc
	v_cmp_eq_u32_e32 vcc, 1, v8
	s_nop 1
	v_cndmask_b32_e32 v75, v63, v62, vcc
	v_cmp_eq_u32_e32 vcc, 2, v73
	s_nop 1
	v_cndmask_b32_e32 v74, v74, v45, vcc
	v_cmp_eq_u32_e32 vcc, 2, v8
	s_nop 1
	v_cndmask_b32_e32 v75, v75, v61, vcc
	v_cmp_eq_u32_e32 vcc, 3, v73
	s_nop 1
	v_cndmask_b32_e32 v74, v74, v44, vcc
	v_cmp_eq_u32_e32 vcc, 3, v8
	s_nop 1
	v_cndmask_b32_e32 v75, v75, v60, vcc
	v_cmp_eq_u32_e32 vcc, 4, v73
	s_nop 1
	v_cndmask_b32_e32 v74, v74, v43, vcc
	v_cmp_eq_u32_e32 vcc, 4, v8
	s_nop 1
	v_cndmask_b32_e32 v75, v75, v59, vcc
	v_cmp_eq_u32_e32 vcc, 5, v73
	s_nop 1
	v_cndmask_b32_e32 v74, v74, v42, vcc
	v_cmp_eq_u32_e32 vcc, 5, v8
	s_nop 1
	v_cndmask_b32_e32 v75, v75, v58, vcc
	v_cmp_eq_u32_e32 vcc, 6, v73
	s_nop 1
	v_cndmask_b32_e32 v74, v74, v41, vcc
	v_cmp_eq_u32_e32 vcc, 6, v8
	s_nop 1
	v_cndmask_b32_e32 v75, v75, v57, vcc
	v_cmp_eq_u32_e32 vcc, 7, v73
	s_nop 1
	v_cndmask_b32_e32 v74, v74, v40, vcc
	v_cmp_eq_u32_e32 vcc, 7, v8
	s_nop 1
	v_cndmask_b32_e32 v75, v75, v56, vcc
	v_cmp_eq_u32_e32 vcc, 8, v73
	s_nop 1
	v_cndmask_b32_e32 v74, v74, v39, vcc
	v_cmp_eq_u32_e32 vcc, 8, v8
	s_nop 1
	v_cndmask_b32_e32 v75, v75, v55, vcc
	v_cmp_eq_u32_e32 vcc, 9, v73
	s_nop 1
	v_cndmask_b32_e32 v74, v74, v38, vcc
	v_cmp_eq_u32_e32 vcc, 9, v8
	s_nop 1
	v_cndmask_b32_e32 v75, v75, v54, vcc
	v_cmp_eq_u32_e32 vcc, 10, v73
	s_nop 1
	v_cndmask_b32_e32 v74, v74, v37, vcc
	v_cmp_eq_u32_e32 vcc, 10, v8
	s_nop 1
	v_cndmask_b32_e32 v75, v75, v53, vcc
	v_cmp_eq_u32_e32 vcc, 11, v73
	s_nop 1
	v_cndmask_b32_e32 v74, v74, v36, vcc
	v_cmp_eq_u32_e32 vcc, 11, v8
	s_nop 1
	v_cndmask_b32_e32 v75, v75, v52, vcc
	v_cmp_eq_u32_e32 vcc, 12, v73
	s_nop 1
	v_cndmask_b32_e32 v74, v74, v35, vcc
	v_cmp_eq_u32_e32 vcc, 12, v8
	s_nop 1
	v_cndmask_b32_e32 v75, v75, v51, vcc
	v_cmp_eq_u32_e32 vcc, 13, v73
	s_nop 1
	v_cndmask_b32_e32 v74, v74, v34, vcc
	v_cmp_eq_u32_e32 vcc, 13, v8
	s_nop 1
	v_cndmask_b32_e32 v75, v75, v49, vcc
	v_cmp_eq_u32_e32 vcc, 14, v73
	s_nop 1
	v_cndmask_b32_e32 v74, v74, v33, vcc
	v_cmp_eq_u32_e32 vcc, 14, v8
	s_nop 1
	v_cndmask_b32_e32 v75, v75, v48, vcc
	v_cmp_eq_u32_e32 vcc, 15, v73
	s_nop 1
	v_cndmask_b32_e32 v73, v74, v15, vcc
	v_cmp_eq_u32_e32 vcc, 15, v8
	v_lshlrev_b32_e32 v73, 7, v73
	v_and_b32_e32 v73, 0x3f80, v73
	v_cndmask_b32_e32 v8, v75, v47, vcc
	v_and_b32_e32 v8, 0x7f, v8
	v_cmp_eq_u32_e32 vcc, 1, v72
	v_bitop3_b32 v8, v73, s82, v8 bitop3:0x36
	s_nop 0
	v_cndmask_b32_e32 v73, v50, v46, vcc
	v_cmp_eq_u32_e32 vcc, 1, v9
	s_nop 1
	v_cndmask_b32_e32 v74, v63, v62, vcc
	v_cmp_eq_u32_e32 vcc, 2, v72
	s_nop 1
	v_cndmask_b32_e32 v73, v73, v45, vcc
	v_cmp_eq_u32_e32 vcc, 2, v9
	s_nop 1
	v_cndmask_b32_e32 v74, v74, v61, vcc
	v_cmp_eq_u32_e32 vcc, 3, v72
	s_nop 1
	v_cndmask_b32_e32 v73, v73, v44, vcc
	v_cmp_eq_u32_e32 vcc, 3, v9
	s_nop 1
	v_cndmask_b32_e32 v74, v74, v60, vcc
	v_cmp_eq_u32_e32 vcc, 4, v72
	s_nop 1
	v_cndmask_b32_e32 v73, v73, v43, vcc
	v_cmp_eq_u32_e32 vcc, 4, v9
	s_nop 1
	v_cndmask_b32_e32 v74, v74, v59, vcc
	v_cmp_eq_u32_e32 vcc, 5, v72
	s_nop 1
	v_cndmask_b32_e32 v73, v73, v42, vcc
	v_cmp_eq_u32_e32 vcc, 5, v9
	s_nop 1
	v_cndmask_b32_e32 v74, v74, v58, vcc
	v_cmp_eq_u32_e32 vcc, 6, v72
	s_nop 1
	v_cndmask_b32_e32 v73, v73, v41, vcc
	v_cmp_eq_u32_e32 vcc, 6, v9
	s_nop 1
	v_cndmask_b32_e32 v74, v74, v57, vcc
	v_cmp_eq_u32_e32 vcc, 7, v72
	s_nop 1
	v_cndmask_b32_e32 v73, v73, v40, vcc
	v_cmp_eq_u32_e32 vcc, 7, v9
	s_nop 1
	v_cndmask_b32_e32 v74, v74, v56, vcc
	v_cmp_eq_u32_e32 vcc, 8, v72
	s_nop 1
	v_cndmask_b32_e32 v73, v73, v39, vcc
	v_cmp_eq_u32_e32 vcc, 8, v9
	s_nop 1
	v_cndmask_b32_e32 v74, v74, v55, vcc
	v_cmp_eq_u32_e32 vcc, 9, v72
	s_nop 1
	v_cndmask_b32_e32 v73, v73, v38, vcc
	v_cmp_eq_u32_e32 vcc, 9, v9
	s_nop 1
	v_cndmask_b32_e32 v74, v74, v54, vcc
	v_cmp_eq_u32_e32 vcc, 10, v72
	s_nop 1
	v_cndmask_b32_e32 v73, v73, v37, vcc
	v_cmp_eq_u32_e32 vcc, 10, v9
	s_nop 1
	v_cndmask_b32_e32 v74, v74, v53, vcc
	v_cmp_eq_u32_e32 vcc, 11, v72
	s_nop 1
	v_cndmask_b32_e32 v73, v73, v36, vcc
	v_cmp_eq_u32_e32 vcc, 11, v9
	s_nop 1
	v_cndmask_b32_e32 v74, v74, v52, vcc
	v_cmp_eq_u32_e32 vcc, 12, v72
	s_nop 1
	v_cndmask_b32_e32 v73, v73, v35, vcc
	v_cmp_eq_u32_e32 vcc, 12, v9
	s_nop 1
	v_cndmask_b32_e32 v74, v74, v51, vcc
	v_cmp_eq_u32_e32 vcc, 13, v72
	s_nop 1
	v_cndmask_b32_e32 v73, v73, v34, vcc
	v_cmp_eq_u32_e32 vcc, 13, v9
	s_nop 1
	v_cndmask_b32_e32 v74, v74, v49, vcc
	v_cmp_eq_u32_e32 vcc, 14, v72
	s_nop 1
	v_cndmask_b32_e32 v73, v73, v33, vcc
	v_cmp_eq_u32_e32 vcc, 14, v9
	s_nop 1
	v_cndmask_b32_e32 v74, v74, v48, vcc
	v_cmp_eq_u32_e32 vcc, 15, v72
	s_nop 1
	v_cndmask_b32_e32 v72, v73, v15, vcc
	v_cmp_eq_u32_e32 vcc, 15, v9
	v_lshlrev_b32_e32 v72, 7, v72
	v_and_b32_e32 v72, 0x3f80, v72
	v_cndmask_b32_e32 v9, v74, v47, vcc
	v_and_b32_e32 v9, 0x7f, v9
	v_cmp_eq_u32_e32 vcc, 1, v71
	v_bitop3_b32 v9, v72, s82, v9 bitop3:0x36
	s_nop 0
	v_cndmask_b32_e32 v72, v50, v46, vcc
	v_cmp_eq_u32_e32 vcc, 1, v10
	s_nop 1
	v_cndmask_b32_e32 v73, v63, v62, vcc
	v_cmp_eq_u32_e32 vcc, 2, v71
	s_nop 1
; __device__ __forceinline__ void route_task(const Params& p, int layer, const u16* qg, int rb, int hd, int r, int h) {
;     ...
;     for (int jj = 0; jj < 16; ++jj) {
;       const unsigned flat = 255u - (ct[jj] & 255u);
;       const unsigned a = flat >> 4, b = flat & 15u;
;       unsigned ka = top[0][0], kb = top[1][0];
; #pragma unroll
;       for (int k = 1; k < 16; ++k) { ka = (a == (unsigned)k) ? top[0][k] : ka; kb = (b == (unsigned)k) ? top[1][k] : kb; }
;       eo[jj] = (127u - (ka & 127u)) * 128u + (127u - (kb & 127u));
;     }
	v_cndmask_b32_e32 v72, v72, v45, vcc
	v_cmp_eq_u32_e32 vcc, 2, v10
	s_nop 1
	v_cndmask_b32_e32 v73, v73, v61, vcc
	v_cmp_eq_u32_e32 vcc, 3, v71
	s_nop 1
	v_cndmask_b32_e32 v72, v72, v44, vcc
	v_cmp_eq_u32_e32 vcc, 3, v10
	s_nop 1
	v_cndmask_b32_e32 v73, v73, v60, vcc
	v_cmp_eq_u32_e32 vcc, 4, v71
	s_nop 1
	v_cndmask_b32_e32 v72, v72, v43, vcc
	v_cmp_eq_u32_e32 vcc, 4, v10
	s_nop 1
	v_cndmask_b32_e32 v73, v73, v59, vcc
	v_cmp_eq_u32_e32 vcc, 5, v71
	s_nop 1
	v_cndmask_b32_e32 v72, v72, v42, vcc
	v_cmp_eq_u32_e32 vcc, 5, v10
	s_nop 1
	v_cndmask_b32_e32 v73, v73, v58, vcc
	v_cmp_eq_u32_e32 vcc, 6, v71
	s_nop 1
	v_cndmask_b32_e32 v72, v72, v41, vcc
	v_cmp_eq_u32_e32 vcc, 6, v10
	s_nop 1
	v_cndmask_b32_e32 v73, v73, v57, vcc
	v_cmp_eq_u32_e32 vcc, 7, v71
	s_nop 1
	v_cndmask_b32_e32 v72, v72, v40, vcc
	v_cmp_eq_u32_e32 vcc, 7, v10
	s_nop 1
	v_cndmask_b32_e32 v73, v73, v56, vcc
	v_cmp_eq_u32_e32 vcc, 8, v71
	s_nop 1
	v_cndmask_b32_e32 v72, v72, v39, vcc
	v_cmp_eq_u32_e32 vcc, 8, v10
	s_nop 1
	v_cndmask_b32_e32 v73, v73, v55, vcc
	v_cmp_eq_u32_e32 vcc, 9, v71
	s_nop 1
	v_cndmask_b32_e32 v72, v72, v38, vcc
	v_cmp_eq_u32_e32 vcc, 9, v10
	s_nop 1
	v_cndmask_b32_e32 v73, v73, v54, vcc
	v_cmp_eq_u32_e32 vcc, 10, v71
	s_nop 1
	v_cndmask_b32_e32 v72, v72, v37, vcc
	v_cmp_eq_u32_e32 vcc, 10, v10
	s_nop 1
	v_cndmask_b32_e32 v73, v73, v53, vcc
	v_cmp_eq_u32_e32 vcc, 11, v71
	s_nop 1
	v_cndmask_b32_e32 v72, v72, v36, vcc
	v_cmp_eq_u32_e32 vcc, 11, v10
	s_nop 1
	v_cndmask_b32_e32 v73, v73, v52, vcc
	v_cmp_eq_u32_e32 vcc, 12, v71
	s_nop 1
	v_cndmask_b32_e32 v72, v72, v35, vcc
	v_cmp_eq_u32_e32 vcc, 12, v10
	s_nop 1
	v_cndmask_b32_e32 v73, v73, v51, vcc
	v_cmp_eq_u32_e32 vcc, 13, v71
	s_nop 1
	v_cndmask_b32_e32 v72, v72, v34, vcc
	v_cmp_eq_u32_e32 vcc, 13, v10
	s_nop 1
	v_cndmask_b32_e32 v73, v73, v49, vcc
	v_cmp_eq_u32_e32 vcc, 14, v71
	s_nop 1
	v_cndmask_b32_e32 v72, v72, v33, vcc
	v_cmp_eq_u32_e32 vcc, 14, v10
	s_nop 1
	v_cndmask_b32_e32 v73, v73, v48, vcc
	v_cmp_eq_u32_e32 vcc, 15, v71
	s_nop 1
	v_cndmask_b32_e32 v71, v72, v15, vcc
	v_cmp_eq_u32_e32 vcc, 15, v10
	v_lshlrev_b32_e32 v71, 7, v71
	v_and_b32_e32 v71, 0x3f80, v71
	v_cndmask_b32_e32 v10, v73, v47, vcc
	v_and_b32_e32 v10, 0x7f, v10
	v_cmp_eq_u32_e32 vcc, 1, v70
	v_bitop3_b32 v10, v71, s82, v10 bitop3:0x36
	s_nop 0
	v_cndmask_b32_e32 v71, v50, v46, vcc
	v_cmp_eq_u32_e32 vcc, 1, v11
	s_nop 1
	v_cndmask_b32_e32 v72, v63, v62, vcc
	v_cmp_eq_u32_e32 vcc, 2, v70
	s_nop 1
	v_cndmask_b32_e32 v71, v71, v45, vcc
	v_cmp_eq_u32_e32 vcc, 2, v11
	s_nop 1
	v_cndmask_b32_e32 v72, v72, v61, vcc
	v_cmp_eq_u32_e32 vcc, 3, v70
	s_nop 1
	v_cndmask_b32_e32 v71, v71, v44, vcc
	v_cmp_eq_u32_e32 vcc, 3, v11
	s_nop 1
	v_cndmask_b32_e32 v72, v72, v60, vcc
	v_cmp_eq_u32_e32 vcc, 4, v70
	s_nop 1
	v_cndmask_b32_e32 v71, v71, v43, vcc
	v_cmp_eq_u32_e32 vcc, 4, v11
	s_nop 1
	v_cndmask_b32_e32 v72, v72, v59, vcc
	v_cmp_eq_u32_e32 vcc, 5, v70
	s_nop 1
	v_cndmask_b32_e32 v71, v71, v42, vcc
	v_cmp_eq_u32_e32 vcc, 5, v11
	s_nop 1
	v_cndmask_b32_e32 v72, v72, v58, vcc
	v_cmp_eq_u32_e32 vcc, 6, v70
	s_nop 1
	v_cndmask_b32_e32 v71, v71, v41, vcc
	v_cmp_eq_u32_e32 vcc, 6, v11
	s_nop 1
	v_cndmask_b32_e32 v72, v72, v57, vcc
	v_cmp_eq_u32_e32 vcc, 7, v70
	s_nop 1
	v_cndmask_b32_e32 v71, v71, v40, vcc
	v_cmp_eq_u32_e32 vcc, 7, v11
	s_nop 1
	v_cndmask_b32_e32 v72, v72, v56, vcc
	v_cmp_eq_u32_e32 vcc, 8, v70
	s_nop 1
	v_cndmask_b32_e32 v71, v71, v39, vcc
	v_cmp_eq_u32_e32 vcc, 8, v11
	s_nop 1
	v_cndmask_b32_e32 v72, v72, v55, vcc
	v_cmp_eq_u32_e32 vcc, 9, v70
	s_nop 1
	v_cndmask_b32_e32 v71, v71, v38, vcc
	v_cmp_eq_u32_e32 vcc, 9, v11
	s_nop 1
	v_cndmask_b32_e32 v72, v72, v54, vcc
	v_cmp_eq_u32_e32 vcc, 10, v70
	s_nop 1
	v_cndmask_b32_e32 v71, v71, v37, vcc
	v_cmp_eq_u32_e32 vcc, 10, v11
	s_nop 1
	v_cndmask_b32_e32 v72, v72, v53, vcc
	v_cmp_eq_u32_e32 vcc, 11, v70
	s_nop 1
	v_cndmask_b32_e32 v71, v71, v36, vcc
	v_cmp_eq_u32_e32 vcc, 11, v11
	s_nop 1
	v_cndmask_b32_e32 v72, v72, v52, vcc
	v_cmp_eq_u32_e32 vcc, 12, v70
	s_nop 1
	v_cndmask_b32_e32 v71, v71, v35, vcc
	v_cmp_eq_u32_e32 vcc, 12, v11
	s_nop 1
	v_cndmask_b32_e32 v72, v72, v51, vcc
	v_cmp_eq_u32_e32 vcc, 13, v70
	s_nop 1
	v_cndmask_b32_e32 v71, v71, v34, vcc
	v_cmp_eq_u32_e32 vcc, 13, v11
	s_nop 1
	v_cndmask_b32_e32 v72, v72, v49, vcc
	v_cmp_eq_u32_e32 vcc, 14, v70
	s_nop 1
	v_cndmask_b32_e32 v71, v71, v33, vcc
	v_cmp_eq_u32_e32 vcc, 14, v11
	s_nop 1
	v_cndmask_b32_e32 v72, v72, v48, vcc
	v_cmp_eq_u32_e32 vcc, 15, v70
	s_nop 1
	v_cndmask_b32_e32 v70, v71, v15, vcc
	v_cmp_eq_u32_e32 vcc, 15, v11
	v_lshlrev_b32_e32 v70, 7, v70
	v_and_b32_e32 v70, 0x3f80, v70
	v_cndmask_b32_e32 v11, v72, v47, vcc
	v_and_b32_e32 v11, 0x7f, v11
	v_cmp_eq_u32_e32 vcc, 1, v69
	v_bitop3_b32 v11, v70, s82, v11 bitop3:0x36
	s_nop 0
	v_cndmask_b32_e32 v70, v50, v46, vcc
	v_cmp_eq_u32_e32 vcc, 1, v12
	s_nop 1
	v_cndmask_b32_e32 v71, v63, v62, vcc
	v_cmp_eq_u32_e32 vcc, 2, v69
	s_nop 1
	v_cndmask_b32_e32 v70, v70, v45, vcc
	v_cmp_eq_u32_e32 vcc, 2, v12
	s_nop 1
	v_cndmask_b32_e32 v71, v71, v61, vcc
	v_cmp_eq_u32_e32 vcc, 3, v69
	s_nop 1
	v_cndmask_b32_e32 v70, v70, v44, vcc
	v_cmp_eq_u32_e32 vcc, 3, v12
	s_nop 1
	v_cndmask_b32_e32 v71, v71, v60, vcc
	v_cmp_eq_u32_e32 vcc, 4, v69
	s_nop 1
	v_cndmask_b32_e32 v70, v70, v43, vcc
	v_cmp_eq_u32_e32 vcc, 4, v12
	s_nop 1
	v_cndmask_b32_e32 v71, v71, v59, vcc
	v_cmp_eq_u32_e32 vcc, 5, v69
	s_nop 1
	v_cndmask_b32_e32 v70, v70, v42, vcc
	v_cmp_eq_u32_e32 vcc, 5, v12
	s_nop 1
	v_cndmask_b32_e32 v71, v71, v58, vcc
	v_cmp_eq_u32_e32 vcc, 6, v69
	s_nop 1
	v_cndmask_b32_e32 v70, v70, v41, vcc
	v_cmp_eq_u32_e32 vcc, 6, v12
	s_nop 1
	v_cndmask_b32_e32 v71, v71, v57, vcc
; __device__ __forceinline__ void route_task(const Params& p, int layer, const u16* qg, int rb, int hd, int r, int h) {
;     ...
;     for (int jj = 0; jj < 16; ++jj) {
;       const unsigned flat = 255u - (ct[jj] & 255u);
;       const unsigned a = flat >> 4, b = flat & 15u;
;       unsigned ka = top[0][0], kb = top[1][0];
; #pragma unroll
;       for (int k = 1; k < 16; ++k) { ka = (a == (unsigned)k) ? top[0][k] : ka; kb = (b == (unsigned)k) ? top[1][k] : kb; }
;       eo[jj] = (127u - (ka & 127u)) * 128u + (127u - (kb & 127u));
;     }
	v_cmp_eq_u32_e32 vcc, 7, v69
	s_nop 1
	v_cndmask_b32_e32 v70, v70, v40, vcc
	v_cmp_eq_u32_e32 vcc, 7, v12
	s_nop 1
	v_cndmask_b32_e32 v71, v71, v56, vcc
	v_cmp_eq_u32_e32 vcc, 8, v69
	s_nop 1
	v_cndmask_b32_e32 v70, v70, v39, vcc
	v_cmp_eq_u32_e32 vcc, 8, v12
	s_nop 1
	v_cndmask_b32_e32 v71, v71, v55, vcc
	v_cmp_eq_u32_e32 vcc, 9, v69
	s_nop 1
	v_cndmask_b32_e32 v70, v70, v38, vcc
	v_cmp_eq_u32_e32 vcc, 9, v12
	s_nop 1
	v_cndmask_b32_e32 v71, v71, v54, vcc
	v_cmp_eq_u32_e32 vcc, 10, v69
	s_nop 1
	v_cndmask_b32_e32 v70, v70, v37, vcc
	v_cmp_eq_u32_e32 vcc, 10, v12
	s_nop 1
	v_cndmask_b32_e32 v71, v71, v53, vcc
	v_cmp_eq_u32_e32 vcc, 11, v69
	s_nop 1
	v_cndmask_b32_e32 v70, v70, v36, vcc
	v_cmp_eq_u32_e32 vcc, 11, v12
	s_nop 1
	v_cndmask_b32_e32 v71, v71, v52, vcc
	v_cmp_eq_u32_e32 vcc, 12, v69
	s_nop 1
	v_cndmask_b32_e32 v70, v70, v35, vcc
	v_cmp_eq_u32_e32 vcc, 12, v12
	s_nop 1
	v_cndmask_b32_e32 v71, v71, v51, vcc
	v_cmp_eq_u32_e32 vcc, 13, v69
	s_nop 1
	v_cndmask_b32_e32 v70, v70, v34, vcc
	v_cmp_eq_u32_e32 vcc, 13, v12
	s_nop 1
	v_cndmask_b32_e32 v71, v71, v49, vcc
	v_cmp_eq_u32_e32 vcc, 14, v69
	s_nop 1
	v_cndmask_b32_e32 v70, v70, v33, vcc
	v_cmp_eq_u32_e32 vcc, 14, v12
	s_nop 1
	v_cndmask_b32_e32 v71, v71, v48, vcc
	v_cmp_eq_u32_e32 vcc, 15, v69
	s_nop 1
	v_cndmask_b32_e32 v69, v70, v15, vcc
	v_cmp_eq_u32_e32 vcc, 15, v12
	v_lshlrev_b32_e32 v69, 7, v69
	v_and_b32_e32 v69, 0x3f80, v69
	v_cndmask_b32_e32 v12, v71, v47, vcc
	v_and_b32_e32 v12, 0x7f, v12
	v_cmp_eq_u32_e32 vcc, 1, v68
	v_bitop3_b32 v12, v69, s82, v12 bitop3:0x36
	s_nop 0
	v_cndmask_b32_e32 v69, v50, v46, vcc
	v_cmp_eq_u32_e32 vcc, 1, v13
	s_nop 1
	v_cndmask_b32_e32 v70, v63, v62, vcc
	v_cmp_eq_u32_e32 vcc, 2, v68
	s_nop 1
	v_cndmask_b32_e32 v69, v69, v45, vcc
	v_cmp_eq_u32_e32 vcc, 2, v13
	s_nop 1
	v_cndmask_b32_e32 v70, v70, v61, vcc
	v_cmp_eq_u32_e32 vcc, 3, v68
	s_nop 1
	v_cndmask_b32_e32 v69, v69, v44, vcc
	v_cmp_eq_u32_e32 vcc, 3, v13
	s_nop 1
	v_cndmask_b32_e32 v70, v70, v60, vcc
	v_cmp_eq_u32_e32 vcc, 4, v68
	s_nop 1
	v_cndmask_b32_e32 v69, v69, v43, vcc
	v_cmp_eq_u32_e32 vcc, 4, v13
	s_nop 1
	v_cndmask_b32_e32 v70, v70, v59, vcc
	v_cmp_eq_u32_e32 vcc, 5, v68
	s_nop 1
	v_cndmask_b32_e32 v69, v69, v42, vcc
	v_cmp_eq_u32_e32 vcc, 5, v13
	s_nop 1
	v_cndmask_b32_e32 v70, v70, v58, vcc
	v_cmp_eq_u32_e32 vcc, 6, v68
	s_nop 1
	v_cndmask_b32_e32 v69, v69, v41, vcc
	v_cmp_eq_u32_e32 vcc, 6, v13
	s_nop 1
	v_cndmask_b32_e32 v70, v70, v57, vcc
	v_cmp_eq_u32_e32 vcc, 7, v68
	s_nop 1
	v_cndmask_b32_e32 v69, v69, v40, vcc
	v_cmp_eq_u32_e32 vcc, 7, v13
	s_nop 1
	v_cndmask_b32_e32 v70, v70, v56, vcc
	v_cmp_eq_u32_e32 vcc, 8, v68
	s_nop 1
	v_cndmask_b32_e32 v69, v69, v39, vcc
	v_cmp_eq_u32_e32 vcc, 8, v13
	s_nop 1
	v_cndmask_b32_e32 v70, v70, v55, vcc
	v_cmp_eq_u32_e32 vcc, 9, v68
	s_nop 1
	v_cndmask_b32_e32 v69, v69, v38, vcc
	v_cmp_eq_u32_e32 vcc, 9, v13
	s_nop 1
	v_cndmask_b32_e32 v70, v70, v54, vcc
	v_cmp_eq_u32_e32 vcc, 10, v68
	s_nop 1
	v_cndmask_b32_e32 v69, v69, v37, vcc
	v_cmp_eq_u32_e32 vcc, 10, v13
	s_nop 1
	v_cndmask_b32_e32 v70, v70, v53, vcc
	v_cmp_eq_u32_e32 vcc, 11, v68
	s_nop 1
	v_cndmask_b32_e32 v69, v69, v36, vcc
	v_cmp_eq_u32_e32 vcc, 11, v13
	s_nop 1
	v_cndmask_b32_e32 v70, v70, v52, vcc
	v_cmp_eq_u32_e32 vcc, 12, v68
	s_nop 1
	v_cndmask_b32_e32 v69, v69, v35, vcc
	v_cmp_eq_u32_e32 vcc, 12, v13
	s_nop 1
	v_cndmask_b32_e32 v70, v70, v51, vcc
	v_cmp_eq_u32_e32 vcc, 13, v68
	s_nop 1
	v_cndmask_b32_e32 v69, v69, v34, vcc
	v_cmp_eq_u32_e32 vcc, 13, v13
	s_nop 1
	v_cndmask_b32_e32 v70, v70, v49, vcc
	v_cmp_eq_u32_e32 vcc, 14, v68
	s_nop 1
	v_cndmask_b32_e32 v69, v69, v33, vcc
	v_cmp_eq_u32_e32 vcc, 14, v13
	s_nop 1
	v_cndmask_b32_e32 v70, v70, v48, vcc
	v_cmp_eq_u32_e32 vcc, 15, v68
	s_nop 1
	v_cndmask_b32_e32 v68, v69, v15, vcc
	v_cmp_eq_u32_e32 vcc, 15, v13
	v_lshlrev_b32_e32 v68, 7, v68
	v_and_b32_e32 v68, 0x3f80, v68
	v_cndmask_b32_e32 v13, v70, v47, vcc
	v_and_b32_e32 v13, 0x7f, v13
	v_cmp_eq_u32_e32 vcc, 1, v66
	v_bitop3_b32 v13, v68, s82, v13 bitop3:0x36
	s_nop 0
	v_cndmask_b32_e32 v68, v50, v46, vcc
	v_cmp_eq_u32_e32 vcc, 1, v14
	s_nop 1
	v_cndmask_b32_e32 v69, v63, v62, vcc
	v_cmp_eq_u32_e32 vcc, 2, v66
	s_nop 1
	v_cndmask_b32_e32 v68, v68, v45, vcc
	v_cmp_eq_u32_e32 vcc, 2, v14
	s_nop 1
	v_cndmask_b32_e32 v69, v69, v61, vcc
	v_cmp_eq_u32_e32 vcc, 3, v66
	s_nop 1
	v_cndmask_b32_e32 v68, v68, v44, vcc
	v_cmp_eq_u32_e32 vcc, 3, v14
	s_nop 1
	v_cndmask_b32_e32 v69, v69, v60, vcc
	v_cmp_eq_u32_e32 vcc, 4, v66
	s_nop 1
	v_cndmask_b32_e32 v68, v68, v43, vcc
	v_cmp_eq_u32_e32 vcc, 4, v14
	s_nop 1
	v_cndmask_b32_e32 v69, v69, v59, vcc
	v_cmp_eq_u32_e32 vcc, 5, v66
	s_nop 1
	v_cndmask_b32_e32 v68, v68, v42, vcc
	v_cmp_eq_u32_e32 vcc, 5, v14
	s_nop 1
	v_cndmask_b32_e32 v69, v69, v58, vcc
	v_cmp_eq_u32_e32 vcc, 6, v66
	s_nop 1
	v_cndmask_b32_e32 v68, v68, v41, vcc
	v_cmp_eq_u32_e32 vcc, 6, v14
	s_nop 1
	v_cndmask_b32_e32 v69, v69, v57, vcc
	v_cmp_eq_u32_e32 vcc, 7, v66
	s_nop 1
	v_cndmask_b32_e32 v68, v68, v40, vcc
	v_cmp_eq_u32_e32 vcc, 7, v14
	s_nop 1
	v_cndmask_b32_e32 v69, v69, v56, vcc
	v_cmp_eq_u32_e32 vcc, 8, v66
	s_nop 1
	v_cndmask_b32_e32 v68, v68, v39, vcc
	v_cmp_eq_u32_e32 vcc, 8, v14
	s_nop 1
	v_cndmask_b32_e32 v69, v69, v55, vcc
	v_cmp_eq_u32_e32 vcc, 9, v66
; __device__ __forceinline__ void route_task(const Params& p, int layer, const u16* qg, int rb, int hd, int r, int h) {
;     ...
;     const float inv = 1.f / den;
;     unsigned eo[16];
; #pragma unroll
;     for (int jj = 0; jj < 16; ++jj) {
;       const unsigned flat = 255u - (ct[jj] & 255u);
;       const unsigned a = flat >> 4, b = flat & 15u;
;       unsigned ka = top[0][0], kb = top[1][0];
; #pragma unroll
;       for (int k = 1; k < 16; ++k) { ka = (a == (unsigned)k) ? top[0][k] : ka; kb = (b == (unsigned)k) ? top[1][k] : kb; }
;       eo[jj] = (127u - (ka & 127u)) * 128u + (127u - (kb & 127u));
;     }
;     const size_t ob = (size_t)(rb + r) * 128 + hd * 16;
; #pragma unroll
;     for (int g4 = 0; g4 < 4; ++g4) {
;       *(u32x4*)(EX + ob + g4 * 4) = u32x4{eo[g4 * 4], eo[g4 * 4 + 1], eo[g4 * 4 + 2], eo[g4 * 4 + 3]};
;       *(f32x4*)(GT + ob + g4 * 4) = f32x4{vs[g4 * 4] * inv, vs[g4 * 4 + 1] * inv, vs[g4 * 4 + 2] * inv, vs[g4 * 4 + 3] * inv};
;     }
	s_nop 1
	v_cndmask_b32_e32 v68, v68, v38, vcc
	v_cmp_eq_u32_e32 vcc, 9, v14
	s_nop 1
	v_cndmask_b32_e32 v69, v69, v54, vcc
	v_cmp_eq_u32_e32 vcc, 10, v66
	s_nop 1
	v_cndmask_b32_e32 v68, v68, v37, vcc
	v_cmp_eq_u32_e32 vcc, 10, v14
	s_nop 1
	v_cndmask_b32_e32 v69, v69, v53, vcc
	v_cmp_eq_u32_e32 vcc, 11, v66
	s_nop 1
	v_cndmask_b32_e32 v68, v68, v36, vcc
	v_cmp_eq_u32_e32 vcc, 11, v14
	s_nop 1
	v_cndmask_b32_e32 v69, v69, v52, vcc
	v_cmp_eq_u32_e32 vcc, 12, v66
	s_nop 1
	v_cndmask_b32_e32 v68, v68, v35, vcc
	v_cmp_eq_u32_e32 vcc, 12, v14
	s_nop 1
	v_cndmask_b32_e32 v69, v69, v51, vcc
	v_cmp_eq_u32_e32 vcc, 13, v66
	s_nop 1
	v_cndmask_b32_e32 v68, v68, v34, vcc
	v_cmp_eq_u32_e32 vcc, 13, v14
	s_nop 1
	v_cndmask_b32_e32 v69, v69, v49, vcc
	v_cmp_eq_u32_e32 vcc, 14, v66
	s_nop 1
	v_cndmask_b32_e32 v68, v68, v33, vcc
	v_cmp_eq_u32_e32 vcc, 14, v14
	s_nop 1
	v_cndmask_b32_e32 v69, v69, v48, vcc
	v_cmp_eq_u32_e32 vcc, 15, v66
	s_nop 1
	v_cndmask_b32_e32 v66, v68, v15, vcc
	v_cmp_eq_u32_e32 vcc, 15, v14
	v_lshlrev_b32_e32 v66, 7, v66
	v_and_b32_e32 v66, 0x3f80, v66
	v_cndmask_b32_e32 v14, v69, v47, vcc
	v_cmp_eq_u32_e32 vcc, 1, v65
	v_and_b32_e32 v14, 0x7f, v14
	v_bitop3_b32 v14, v66, s82, v14 bitop3:0x36
	v_cndmask_b32_e32 v46, v50, v46, vcc
	v_cmp_eq_u32_e32 vcc, 1, v64
	s_nop 1
	v_cndmask_b32_e32 v50, v63, v62, vcc
	v_cmp_eq_u32_e32 vcc, 2, v65
	s_nop 1
	v_cndmask_b32_e32 v45, v46, v45, vcc
	v_cmp_eq_u32_e32 vcc, 2, v64
	s_nop 1
	v_cndmask_b32_e32 v46, v50, v61, vcc
	v_cmp_eq_u32_e32 vcc, 3, v65
	s_nop 1
	v_cndmask_b32_e32 v44, v45, v44, vcc
	v_cmp_eq_u32_e32 vcc, 3, v64
	s_nop 1
	v_cndmask_b32_e32 v45, v46, v60, vcc
	v_cmp_eq_u32_e32 vcc, 4, v65
	s_nop 1
	v_cndmask_b32_e32 v43, v44, v43, vcc
	v_cmp_eq_u32_e32 vcc, 4, v64
	s_nop 1
	v_cndmask_b32_e32 v44, v45, v59, vcc
	v_cmp_eq_u32_e32 vcc, 5, v65
	s_nop 1
	v_cndmask_b32_e32 v42, v43, v42, vcc
	v_cmp_eq_u32_e32 vcc, 5, v64
	s_nop 1
	v_cndmask_b32_e32 v43, v44, v58, vcc
	v_cmp_eq_u32_e32 vcc, 6, v65
	s_nop 1
	v_cndmask_b32_e32 v41, v42, v41, vcc
	v_cmp_eq_u32_e32 vcc, 6, v64
	s_nop 1
	v_cndmask_b32_e32 v42, v43, v57, vcc
	v_cmp_eq_u32_e32 vcc, 7, v65
	s_nop 1
	v_cndmask_b32_e32 v40, v41, v40, vcc
	v_cmp_eq_u32_e32 vcc, 7, v64
	s_nop 1
	v_cndmask_b32_e32 v41, v42, v56, vcc
	v_cmp_eq_u32_e32 vcc, 8, v65
	s_nop 1
	v_cndmask_b32_e32 v39, v40, v39, vcc
	v_cmp_eq_u32_e32 vcc, 8, v64
	s_nop 1
	v_cndmask_b32_e32 v40, v41, v55, vcc
	v_cmp_eq_u32_e32 vcc, 9, v65
	s_nop 1
	v_cndmask_b32_e32 v38, v39, v38, vcc
	v_cmp_eq_u32_e32 vcc, 9, v64
	s_nop 1
	v_cndmask_b32_e32 v39, v40, v54, vcc
	v_cmp_eq_u32_e32 vcc, 10, v65
	s_nop 1
	v_cndmask_b32_e32 v37, v38, v37, vcc
	v_cmp_eq_u32_e32 vcc, 10, v64
	s_nop 1
	v_cndmask_b32_e32 v38, v39, v53, vcc
	v_cmp_eq_u32_e32 vcc, 11, v65
	s_nop 1
	v_cndmask_b32_e32 v36, v37, v36, vcc
	v_cmp_eq_u32_e32 vcc, 11, v64
	s_nop 1
	v_cndmask_b32_e32 v37, v38, v52, vcc
	v_cmp_eq_u32_e32 vcc, 12, v65
	s_nop 1
	v_cndmask_b32_e32 v35, v36, v35, vcc
	v_cmp_eq_u32_e32 vcc, 12, v64
	s_nop 1
	v_cndmask_b32_e32 v36, v37, v51, vcc
	v_cmp_eq_u32_e32 vcc, 13, v65
	s_nop 1
	v_cndmask_b32_e32 v34, v35, v34, vcc
	v_cmp_eq_u32_e32 vcc, 13, v64
	s_nop 1
	v_cndmask_b32_e32 v35, v36, v49, vcc
	v_cmp_eq_u32_e32 vcc, 14, v65
	s_nop 1
	v_cndmask_b32_e32 v33, v34, v33, vcc
	v_cmp_eq_u32_e32 vcc, 14, v64
	s_nop 1
	v_cndmask_b32_e32 v34, v35, v48, vcc
	v_cmp_eq_u32_e32 vcc, 15, v65
	s_nop 1
	v_cndmask_b32_e32 v15, v33, v15, vcc
	v_cmp_eq_u32_e32 vcc, 15, v64
	v_lshlrev_b32_e32 v15, 7, v15
	v_and_b32_e32 v15, 0x3f80, v15
	v_cndmask_b32_e32 v33, v34, v47, vcc
	v_div_scale_f32 v34, s[34:35], v67, v67, 1.0
	v_rcp_f32_e32 v35, v34
	v_and_b32_e32 v33, 0x7f, v33
	v_bitop3_b32 v15, v15, s82, v33 bitop3:0x36
	s_lshl_b32 s34, s83, 4
	v_fma_f32 v33, -v34, v35, 1.0
	v_fmac_f32_e32 v35, v33, v35
	v_div_scale_f32 v33, vcc, 1.0, v67, 1.0
	v_mul_f32_e32 v36, v33, v35
	v_fma_f32 v37, -v34, v36, v33
	v_fmac_f32_e32 v36, v37, v35
	v_fma_f32 v33, -v34, v36, v33
	v_div_fmas_f32 v33, v33, v35, v36
	v_div_fixup_f32 v34, v33, v67, 1.0
	v_ashrrev_i32_e32 v33, 31, v32
	v_lshlrev_b64 v[32:33], 7, v[32:33]
	s_ashr_i32 s35, s34, 31
	v_lshl_add_u64 v[32:33], v[32:33], 0, s[34:35]
	v_lshlrev_b64 v[32:33], 2, v[32:33]
	v_lshl_add_u64 v[36:37], s[10:11], 0, v[32:33]
	v_lshl_add_u64 v[32:33], s[8:9], 0, v[32:33]
	global_store_dwordx4 v[36:37], v[0:3], off
	s_nop 1
	v_pk_mul_f32 v[2:3], v[18:19], v[34:35] op_sel_hi:[1,0]
	v_pk_mul_f32 v[0:1], v[16:17], v[34:35] op_sel_hi:[1,0]
	global_store_dwordx4 v[32:33], v[0:3], off
	global_store_dwordx4 v[36:37], v[4:7], off offset:16
	s_nop 0
	v_pk_mul_f32 v[2:3], v[22:23], v[34:35] op_sel_hi:[1,0]
	v_pk_mul_f32 v[0:1], v[20:21], v[34:35] op_sel_hi:[1,0]
	global_store_dwordx4 v[32:33], v[0:3], off offset:16
	global_store_dwordx4 v[36:37], v[8:11], off offset:32
	s_nop 0
	v_pk_mul_f32 v[2:3], v[26:27], v[34:35] op_sel_hi:[1,0]
	v_pk_mul_f32 v[0:1], v[24:25], v[34:35] op_sel_hi:[1,0]
	global_store_dwordx4 v[32:33], v[0:3], off offset:32
	global_store_dwordx4 v[36:37], v[12:15], off offset:48
	s_nop 0
	v_pk_mul_f32 v[2:3], v[30:31], v[34:35] op_sel_hi:[1,0]
	v_pk_mul_f32 v[0:1], v[28:29], v[34:35] op_sel_hi:[1,0]
	global_store_dwordx4 v[32:33], v[0:3], off offset:48
	s_branch .LBB0_1867

; #define MFMA32(a, b, c) __builtin_amdgcn_mfma_f32_32x32x16_bf16((a), (b), (c), 0, 0, 0)
; DI int crow(int i, int h) { return (i & 3) + 8 * (i >> 2) + 4 * h; }
; DI unsigned f2ord(float f) { unsigned u = __float_as_uint(f); return (u & 0x80000000u) ? ~u : (u | 0x80000000u); }
; #define INS32(T, X) { _Pragma("unroll") for (int jj = 0; jj < 16; ++jj) { unsigned t_ = max(T[jj], X); X = min(T[jj], X); T[jj] = t_; } }
; __device__ __forceinline__ void route_task(const Params& p, int layer, const u16* qg, int rb, int hd, int r, int h) {
;     ...
;     for (int n = 0; n < 4; ++n) {
;       f32x16 acc;
; #pragma unroll
;       for (int e = 0; e < 16; ++e) acc[e] = 0.f;
; #pragma unroll
;       for (int s = 0; s < 8; ++s) {
;         bf16x8 kf = *(const bf16x8*)(kg + (size_t)n * 32 * 128 + 16 * s);
;         acc = MFMA32(kf, qf[s], acc);
;       }
; #pragma unroll
;       for (int e = 0; e < 16; ++e) {
;         unsigned key = (f2ord(acc[e]) & ~127u) | (unsigned)(127 - (n * 32 + crow(e, h)));
;         INS32(tp, key);
;       }
;     }
.LBB0_2501:
	global_load_dwordx4 v[190:193], v[50:51], off offset:-128
	global_load_dwordx4 v[194:197], v[50:51], off offset:-96
	global_load_dwordx4 v[198:201], v[50:51], off offset:-64
	global_load_dwordx4 v[202:205], v[50:51], off offset:-32
	global_load_dwordx4 v[206:209], v[50:51], off
	global_load_dwordx4 v[216:219], v[50:51], off offset:32
	global_load_dwordx4 v[220:223], v[50:51], off offset:64
	global_load_dwordx4 v[224:227], v[50:51], off offset:96
	v_lshl_add_u64 v[50:51], v[50:51], 0, s[16:17]
	s_waitcnt vmcnt(7) lgkmcnt(7)
	v_mfma_f32_32x32x16_bf16 v[0:15], v[190:193], v[16:19], 0
	s_waitcnt vmcnt(6) lgkmcnt(6)
	v_mfma_f32_32x32x16_bf16 v[0:15], v[194:197], v[20:23], v[0:15]
	s_waitcnt vmcnt(5) lgkmcnt(5)
	v_mfma_f32_32x32x16_bf16 v[0:15], v[198:201], v[24:27], v[0:15]
	s_waitcnt vmcnt(4) lgkmcnt(4)
	v_mfma_f32_32x32x16_bf16 v[0:15], v[202:205], v[28:31], v[0:15]
	s_waitcnt vmcnt(3) lgkmcnt(3)
	v_mfma_f32_32x32x16_bf16 v[0:15], v[206:209], v[32:35], v[0:15]
	s_waitcnt vmcnt(2) lgkmcnt(2)
	v_mfma_f32_32x32x16_bf16 v[0:15], v[216:219], v[36:39], v[0:15]
	s_waitcnt vmcnt(1) lgkmcnt(1)
	v_mfma_f32_32x32x16_bf16 v[0:15], v[220:223], v[40:43], v[0:15]
	s_waitcnt vmcnt(0) lgkmcnt(0)
	v_mfma_f32_32x32x16_bf16 v[0:15], v[224:227], v[44:47], v[0:15]
	s_nop 11
	v_cmp_gt_i32_e32 vcc, 0, v0
	v_not_b32_e32 v70, v0
	v_or_b32_e32 v71, 0x80000000, v0
	v_cndmask_b32_e32 v70, v71, v70, vcc
	v_and_b32_e32 v70, 0xffffff80, v70
	v_add_u32_e32 v0, s18, v53
	s_sub_i32 s18, s18, 32
	s_cmpk_lg_i32 s18, 0xff80
	v_add3_u32 v70, v0, v70, s52
	v_med3_u32 v54, v55, v54, v70
	v_med3_u32 v55, v56, v55, v70
	v_med3_u32 v56, v57, v56, v70
	v_med3_u32 v57, v58, v57, v70
	v_med3_u32 v58, v59, v58, v70
	v_med3_u32 v59, v60, v59, v70
	v_med3_u32 v60, v61, v60, v70
	v_med3_u32 v61, v62, v61, v70
	v_med3_u32 v62, v63, v62, v70
	v_med3_u32 v63, v64, v63, v70
	v_med3_u32 v64, v65, v64, v70
	v_med3_u32 v65, v66, v65, v70
	v_med3_u32 v66, v67, v66, v70
	v_med3_u32 v67, v68, v67, v70
	v_med3_u32 v68, v69, v68, v70
	v_max_u32_e32 v69, v69, v70
	v_cmp_gt_i32_e32 vcc, 0, v1
	v_not_b32_e32 v70, v1
	v_or_b32_e32 v71, 0x80000000, v1
	v_cndmask_b32_e32 v70, v71, v70, vcc
	v_and_b32_e32 v70, 0xffffff80, v70
	v_add3_u32 v70, v0, v70, s53
	v_med3_u32 v54, v55, v54, v70
	v_med3_u32 v55, v56, v55, v70
	v_med3_u32 v56, v57, v56, v70
	v_med3_u32 v57, v58, v57, v70
	v_med3_u32 v58, v59, v58, v70
	v_med3_u32 v59, v60, v59, v70
	v_med3_u32 v60, v61, v60, v70
	v_med3_u32 v61, v62, v61, v70
	v_med3_u32 v62, v63, v62, v70
	v_med3_u32 v63, v64, v63, v70
	v_med3_u32 v64, v65, v64, v70
	v_med3_u32 v65, v66, v65, v70
	v_med3_u32 v66, v67, v66, v70
	v_med3_u32 v67, v68, v67, v70
	v_med3_u32 v68, v69, v68, v70
	v_max_u32_e32 v69, v69, v70
	v_cmp_gt_i32_e32 vcc, 0, v2
	v_not_b32_e32 v70, v2
	v_or_b32_e32 v71, 0x80000000, v2
	v_cndmask_b32_e32 v70, v71, v70, vcc
	v_and_b32_e32 v70, 0xffffff80, v70
	v_add3_u32 v70, v0, v70, s54
	v_med3_u32 v54, v55, v54, v70
	v_med3_u32 v55, v56, v55, v70
	v_med3_u32 v56, v57, v56, v70
	v_med3_u32 v57, v58, v57, v70
	v_med3_u32 v58, v59, v58, v70
	v_med3_u32 v59, v60, v59, v70
	v_med3_u32 v60, v61, v60, v70
	v_med3_u32 v61, v62, v61, v70
	v_med3_u32 v62, v63, v62, v70
	v_med3_u32 v63, v64, v63, v70
	v_med3_u32 v64, v65, v64, v70
	v_med3_u32 v65, v66, v65, v70
	v_med3_u32 v66, v67, v66, v70
	v_med3_u32 v67, v68, v67, v70
	v_med3_u32 v68, v69, v68, v70
	v_max_u32_e32 v69, v69, v70
	v_cmp_gt_i32_e32 vcc, 0, v3
	v_not_b32_e32 v70, v3
	v_or_b32_e32 v71, 0x80000000, v3
	v_cndmask_b32_e32 v70, v71, v70, vcc
	v_and_b32_e32 v70, 0xffffff80, v70
	v_add3_u32 v70, v0, v70, s55
	v_med3_u32 v54, v55, v54, v70
	v_med3_u32 v55, v56, v55, v70
	v_med3_u32 v56, v57, v56, v70
	v_med3_u32 v57, v58, v57, v70
	v_med3_u32 v58, v59, v58, v70
	v_med3_u32 v59, v60, v59, v70
	v_med3_u32 v60, v61, v60, v70
	v_med3_u32 v61, v62, v61, v70
	v_med3_u32 v62, v63, v62, v70
	v_med3_u32 v63, v64, v63, v70
	v_med3_u32 v64, v65, v64, v70
	v_med3_u32 v65, v66, v65, v70
	v_med3_u32 v66, v67, v66, v70
	v_med3_u32 v67, v68, v67, v70
	v_med3_u32 v68, v69, v68, v70
	v_max_u32_e32 v69, v69, v70
	v_cmp_gt_i32_e32 vcc, 0, v4
	v_not_b32_e32 v70, v4
	v_or_b32_e32 v71, 0x80000000, v4
	v_cndmask_b32_e32 v70, v71, v70, vcc
	v_and_b32_e32 v70, 0xffffff80, v70
	v_add3_u32 v70, v0, v70, s56
	v_med3_u32 v54, v55, v54, v70
	v_med3_u32 v55, v56, v55, v70
	v_med3_u32 v56, v57, v56, v70
	v_med3_u32 v57, v58, v57, v70
	v_med3_u32 v58, v59, v58, v70
	v_med3_u32 v59, v60, v59, v70
	v_med3_u32 v60, v61, v60, v70
	v_med3_u32 v61, v62, v61, v70
	v_med3_u32 v62, v63, v62, v70
	v_med3_u32 v63, v64, v63, v70
	v_med3_u32 v64, v65, v64, v70
	v_med3_u32 v65, v66, v65, v70
	v_med3_u32 v66, v67, v66, v70
	v_med3_u32 v67, v68, v67, v70
	v_med3_u32 v68, v69, v68, v70
	v_max_u32_e32 v69, v69, v70
	v_cmp_gt_i32_e32 vcc, 0, v5
	v_not_b32_e32 v70, v5
	v_or_b32_e32 v71, 0x80000000, v5
	v_cndmask_b32_e32 v70, v71, v70, vcc
	v_and_b32_e32 v70, 0xffffff80, v70
	v_add3_u32 v70, v0, v70, s57
	v_med3_u32 v54, v55, v54, v70
	v_med3_u32 v55, v56, v55, v70
	v_med3_u32 v56, v57, v56, v70
	v_med3_u32 v57, v58, v57, v70
	v_med3_u32 v58, v59, v58, v70
	v_med3_u32 v59, v60, v59, v70
	v_med3_u32 v60, v61, v60, v70
	v_med3_u32 v61, v62, v61, v70
	v_med3_u32 v62, v63, v62, v70
	v_med3_u32 v63, v64, v63, v70
	v_med3_u32 v64, v65, v64, v70
	v_med3_u32 v65, v66, v65, v70
	v_med3_u32 v66, v67, v66, v70
	v_med3_u32 v67, v68, v67, v70
	v_med3_u32 v68, v69, v68, v70
	v_max_u32_e32 v69, v69, v70
	v_cmp_gt_i32_e32 vcc, 0, v6
	v_not_b32_e32 v70, v6
	v_or_b32_e32 v71, 0x80000000, v6
	v_cndmask_b32_e32 v70, v71, v70, vcc
	v_and_b32_e32 v70, 0xffffff80, v70
; #define MFMA32(a, b, c) __builtin_amdgcn_mfma_f32_32x32x16_bf16((a), (b), (c), 0, 0, 0)
; DI int crow(int i, int h) { return (i & 3) + 8 * (i >> 2) + 4 * h; }
; DI unsigned f2ord(float f) { unsigned u = __float_as_uint(f); return (u & 0x80000000u) ? ~u : (u | 0x80000000u); }
; #define INS32(T, X) { _Pragma("unroll") for (int jj = 0; jj < 16; ++jj) { unsigned t_ = max(T[jj], X); X = min(T[jj], X); T[jj] = t_; } }
; __device__ __forceinline__ void route_task(const Params& p, int layer, const u16* qg, int rb, int hd, int r, int h) {
;     ...
;     for (int n = 0; n < 4; ++n) {
;       f32x16 acc;
; #pragma unroll
;       for (int e = 0; e < 16; ++e) acc[e] = 0.f;
; #pragma unroll
;       for (int s = 0; s < 8; ++s) {
;         bf16x8 kf = *(const bf16x8*)(kg + (size_t)n * 32 * 128 + 16 * s);
;         acc = MFMA32(kf, qf[s], acc);
;       }
; #pragma unroll
;       for (int e = 0; e < 16; ++e) {
;         unsigned key = (f2ord(acc[e]) & ~127u) | (unsigned)(127 - (n * 32 + crow(e, h)));
;         INS32(tp, key);
;       }
;     }
	v_add3_u32 v70, v0, v70, s58
	v_med3_u32 v54, v55, v54, v70
	v_med3_u32 v55, v56, v55, v70
	v_med3_u32 v56, v57, v56, v70
	v_med3_u32 v57, v58, v57, v70
	v_med3_u32 v58, v59, v58, v70
	v_med3_u32 v59, v60, v59, v70
	v_med3_u32 v60, v61, v60, v70
	v_med3_u32 v61, v62, v61, v70
	v_med3_u32 v62, v63, v62, v70
	v_med3_u32 v63, v64, v63, v70
	v_med3_u32 v64, v65, v64, v70
	v_med3_u32 v65, v66, v65, v70
	v_med3_u32 v66, v67, v66, v70
	v_med3_u32 v67, v68, v67, v70
	v_med3_u32 v68, v69, v68, v70
	v_max_u32_e32 v69, v69, v70
	v_cmp_gt_i32_e32 vcc, 0, v7
	v_not_b32_e32 v70, v7
	v_or_b32_e32 v71, 0x80000000, v7
	v_cndmask_b32_e32 v70, v71, v70, vcc
	v_and_b32_e32 v70, 0xffffff80, v70
	v_add3_u32 v70, v0, v70, s59
	v_med3_u32 v54, v55, v54, v70
	v_med3_u32 v55, v56, v55, v70
	v_med3_u32 v56, v57, v56, v70
	v_med3_u32 v57, v58, v57, v70
	v_med3_u32 v58, v59, v58, v70
	v_med3_u32 v59, v60, v59, v70
	v_med3_u32 v60, v61, v60, v70
	v_med3_u32 v61, v62, v61, v70
	v_med3_u32 v62, v63, v62, v70
	v_med3_u32 v63, v64, v63, v70
	v_med3_u32 v64, v65, v64, v70
	v_med3_u32 v65, v66, v65, v70
	v_med3_u32 v66, v67, v66, v70
	v_med3_u32 v67, v68, v67, v70
	v_med3_u32 v68, v69, v68, v70
	v_max_u32_e32 v69, v69, v70
	v_cmp_gt_i32_e32 vcc, 0, v8
	v_not_b32_e32 v70, v8
	v_or_b32_e32 v71, 0x80000000, v8
	v_cndmask_b32_e32 v70, v71, v70, vcc
	v_and_b32_e32 v70, 0xffffff80, v70
	v_add3_u32 v70, v0, v70, s60
	v_med3_u32 v54, v55, v54, v70
	v_med3_u32 v55, v56, v55, v70
	v_med3_u32 v56, v57, v56, v70
	v_med3_u32 v57, v58, v57, v70
	v_med3_u32 v58, v59, v58, v70
	v_med3_u32 v59, v60, v59, v70
	v_med3_u32 v60, v61, v60, v70
	v_med3_u32 v61, v62, v61, v70
	v_med3_u32 v62, v63, v62, v70
	v_med3_u32 v63, v64, v63, v70
	v_med3_u32 v64, v65, v64, v70
	v_med3_u32 v65, v66, v65, v70
	v_med3_u32 v66, v67, v66, v70
	v_med3_u32 v67, v68, v67, v70
	v_med3_u32 v68, v69, v68, v70
	v_max_u32_e32 v69, v69, v70
	v_cmp_gt_i32_e32 vcc, 0, v9
	v_not_b32_e32 v70, v9
	v_or_b32_e32 v71, 0x80000000, v9
	v_cndmask_b32_e32 v70, v71, v70, vcc
	v_and_b32_e32 v70, 0xffffff80, v70
	v_add3_u32 v70, v0, v70, s61
	v_med3_u32 v54, v55, v54, v70
	v_med3_u32 v55, v56, v55, v70
	v_med3_u32 v56, v57, v56, v70
	v_med3_u32 v57, v58, v57, v70
	v_med3_u32 v58, v59, v58, v70
	v_med3_u32 v59, v60, v59, v70
	v_med3_u32 v60, v61, v60, v70
	v_med3_u32 v61, v62, v61, v70
	v_med3_u32 v62, v63, v62, v70
	v_med3_u32 v63, v64, v63, v70
	v_med3_u32 v64, v65, v64, v70
	v_med3_u32 v65, v66, v65, v70
	v_med3_u32 v66, v67, v66, v70
	v_med3_u32 v67, v68, v67, v70
	v_med3_u32 v68, v69, v68, v70
	v_max_u32_e32 v69, v69, v70
	v_cmp_gt_i32_e32 vcc, 0, v10
	v_not_b32_e32 v70, v10
	v_or_b32_e32 v71, 0x80000000, v10
	v_cndmask_b32_e32 v70, v71, v70, vcc
	v_and_b32_e32 v70, 0xffffff80, v70
	v_add3_u32 v70, v0, v70, s62
	v_med3_u32 v54, v55, v54, v70
	v_med3_u32 v55, v56, v55, v70
	v_med3_u32 v56, v57, v56, v70
	v_med3_u32 v57, v58, v57, v70
	v_med3_u32 v58, v59, v58, v70
	v_med3_u32 v59, v60, v59, v70
	v_med3_u32 v60, v61, v60, v70
	v_med3_u32 v61, v62, v61, v70
	v_med3_u32 v62, v63, v62, v70
	v_med3_u32 v63, v64, v63, v70
	v_med3_u32 v64, v65, v64, v70
	v_med3_u32 v65, v66, v65, v70
	v_med3_u32 v66, v67, v66, v70
	v_med3_u32 v67, v68, v67, v70
	v_med3_u32 v68, v69, v68, v70
	v_max_u32_e32 v69, v69, v70
	v_cmp_gt_i32_e32 vcc, 0, v11
	v_not_b32_e32 v70, v11
	v_or_b32_e32 v71, 0x80000000, v11
	v_cndmask_b32_e32 v70, v71, v70, vcc
	v_and_b32_e32 v70, 0xffffff80, v70
	v_add3_u32 v70, v0, v70, s63
	v_med3_u32 v54, v55, v54, v70
	v_med3_u32 v55, v56, v55, v70
	v_med3_u32 v56, v57, v56, v70
	v_med3_u32 v57, v58, v57, v70
	v_med3_u32 v58, v59, v58, v70
	v_med3_u32 v59, v60, v59, v70
	v_med3_u32 v60, v61, v60, v70
	v_med3_u32 v61, v62, v61, v70
	v_med3_u32 v62, v63, v62, v70
	v_med3_u32 v63, v64, v63, v70
	v_med3_u32 v64, v65, v64, v70
	v_med3_u32 v65, v66, v65, v70
	v_med3_u32 v66, v67, v66, v70
	v_med3_u32 v67, v68, v67, v70
	v_med3_u32 v68, v69, v68, v70
	v_max_u32_e32 v69, v69, v70
	v_cmp_gt_i32_e32 vcc, 0, v12
	v_not_b32_e32 v70, v12
	v_or_b32_e32 v71, 0x80000000, v12
	v_cndmask_b32_e32 v70, v71, v70, vcc
	v_and_b32_e32 v70, 0xffffff80, v70
	v_add3_u32 v70, v0, v70, s64
	v_med3_u32 v54, v55, v54, v70
	v_med3_u32 v55, v56, v55, v70
	v_med3_u32 v56, v57, v56, v70
	v_med3_u32 v57, v58, v57, v70
	v_med3_u32 v58, v59, v58, v70
	v_med3_u32 v59, v60, v59, v70
	v_med3_u32 v60, v61, v60, v70
	v_med3_u32 v61, v62, v61, v70
	v_med3_u32 v62, v63, v62, v70
	v_med3_u32 v63, v64, v63, v70
	v_med3_u32 v64, v65, v64, v70
	v_med3_u32 v65, v66, v65, v70
	v_med3_u32 v66, v67, v66, v70
	v_med3_u32 v67, v68, v67, v70
	v_med3_u32 v68, v69, v68, v70
	v_max_u32_e32 v69, v69, v70
	v_cmp_gt_i32_e32 vcc, 0, v13
	v_not_b32_e32 v70, v13
	v_or_b32_e32 v71, 0x80000000, v13
	v_cndmask_b32_e32 v70, v71, v70, vcc
	v_and_b32_e32 v70, 0xffffff80, v70
	v_add3_u32 v70, v0, v70, s65
	v_med3_u32 v54, v55, v54, v70
	v_med3_u32 v55, v56, v55, v70
	v_med3_u32 v56, v57, v56, v70
	v_med3_u32 v57, v58, v57, v70
	v_med3_u32 v58, v59, v58, v70
	v_med3_u32 v59, v60, v59, v70
	v_med3_u32 v60, v61, v60, v70
	v_med3_u32 v61, v62, v61, v70
	v_med3_u32 v62, v63, v62, v70
	v_med3_u32 v63, v64, v63, v70
	v_med3_u32 v64, v65, v64, v70
	v_med3_u32 v65, v66, v65, v70
	v_med3_u32 v66, v67, v66, v70
	v_med3_u32 v67, v68, v67, v70
	v_med3_u32 v68, v69, v68, v70
	v_max_u32_e32 v69, v69, v70
	v_cmp_gt_i32_e32 vcc, 0, v14
	v_not_b32_e32 v70, v14
	v_or_b32_e32 v71, 0x80000000, v14
	v_cndmask_b32_e32 v70, v71, v70, vcc
	v_and_b32_e32 v70, 0xffffff80, v70
	v_add3_u32 v70, v0, v70, s66
	v_med3_u32 v54, v55, v54, v70
	v_med3_u32 v55, v56, v55, v70
	v_med3_u32 v56, v57, v56, v70
	v_med3_u32 v57, v58, v57, v70
	v_med3_u32 v58, v59, v58, v70
	v_med3_u32 v59, v60, v59, v70
	v_med3_u32 v60, v61, v60, v70
	v_med3_u32 v61, v62, v61, v70
	v_med3_u32 v62, v63, v62, v70
	v_med3_u32 v63, v64, v63, v70
	v_med3_u32 v64, v65, v64, v70
	v_med3_u32 v65, v66, v65, v70
	v_med3_u32 v66, v67, v66, v70
	v_med3_u32 v67, v68, v67, v70
	v_med3_u32 v68, v69, v68, v70
	v_max_u32_e32 v69, v69, v70
	v_cmp_gt_i32_e32 vcc, 0, v15
	v_not_b32_e32 v70, v15
	v_or_b32_e32 v71, 0x80000000, v15
	v_cndmask_b32_e32 v70, v71, v70, vcc
	v_and_b32_e32 v70, 0xffffff80, v70
	v_add3_u32 v70, v0, v70, s67
	v_med3_u32 v54, v55, v54, v70
	v_med3_u32 v55, v56, v55, v70
	v_med3_u32 v56, v57, v56, v70
	v_med3_u32 v57, v58, v57, v70
	v_med3_u32 v58, v59, v58, v70
	v_med3_u32 v59, v60, v59, v70
	v_med3_u32 v60, v61, v60, v70
	v_med3_u32 v61, v62, v61, v70
	v_med3_u32 v62, v63, v62, v70
	v_med3_u32 v63, v64, v63, v70
	v_med3_u32 v64, v65, v64, v70
	v_med3_u32 v65, v66, v65, v70
	v_med3_u32 v66, v67, v66, v70
	v_med3_u32 v67, v68, v67, v70
	v_med3_u32 v68, v69, v68, v70
	v_max_u32_e32 v69, v69, v70
	s_cbranch_scc1 .LBB0_2501
; #define MFMA32(a, b, c) __builtin_amdgcn_mfma_f32_32x32x16_bf16((a), (b), (c), 0, 0, 0)
; DI int crow(int i, int h) { return (i & 3) + 8 * (i >> 2) + 4 * h; }
; DI unsigned f2ord(float f) { unsigned u = __float_as_uint(f); return (u & 0x80000000u) ? ~u : (u | 0x80000000u); }
; #define INS32(T, X) { _Pragma("unroll") for (int jj = 0; jj < 16; ++jj) { unsigned t_ = max(T[jj], X); X = min(T[jj], X); T[jj] = t_; } }
; __device__ __forceinline__ void route_task(const Params& p, int layer, const u16* qg, int rb, int hd, int r, int h) {
;     ...
;   for (int ph = 0; ph < 2; ++ph) {
;     bf16x8 qf[8];
; #pragma unroll
;     for (int s = 0; s < 8; ++s) qf[s] = *(const bf16x8*)(qg + ph * 128 + 16 * s);
;     const u16* kg = KY + ((size_t)((layer * 8 + hd) * 2 + ph) * 128 + r) * 128 + 8 * h;
;     unsigned tp[16];
; #pragma unroll
;     for (int jj = 0; jj < 16; ++jj) tp[jj] = 0u;
; #pragma unroll 1
;     for (int n = 0; n < 4; ++n) {
;       f32x16 acc;
; #pragma unroll
;       for (int e = 0; e < 16; ++e) acc[e] = 0.f;
; #pragma unroll
;       for (int s = 0; s < 8; ++s) {
;         bf16x8 kf = *(const bf16x8*)(kg + (size_t)n * 32 * 128 + 16 * s);
;         acc = MFMA32(kf, qf[s], acc);
;       }
; #pragma unroll
;       for (int e = 0; e < 16; ++e) {
;         unsigned key = (f2ord(acc[e]) & ~127u) | (unsigned)(127 - (n * 32 + crow(e, h)));
;         INS32(tp, key);
;       }
;     }
;     unsigned ot[16];
; #pragma unroll
;     for (int jj = 0; jj < 16; ++jj) ot[jj] = (unsigned)__shfl_xor((int)tp[jj], 32);
; #pragma unroll
;     for (int jj = 0; jj < 16; ++jj) { unsigned key = ot[jj]; INS32(tp, key); }
	ds_read_b128 v[16:19], v83 offset:256
	ds_read_b128 v[20:23], v83 offset:288
	ds_read_b128 v[24:27], v83 offset:320
	ds_read_b128 v[28:31], v83 offset:352
	ds_read_b128 v[32:35], v83 offset:384
	ds_read_b128 v[36:39], v83 offset:416
	ds_read_b128 v[40:43], v83 offset:448
	ds_read_b128 v[44:47], v83 offset:480
	v_and_b32_e32 v0, 64, v214
	v_add_u32_e32 v0, 64, v0
	v_xor_b32_e32 v1, 32, v214
	v_cmp_lt_i32_e32 vcc, v1, v0
	s_mov_b32 s14, 0
	v_lshl_add_u64 v[48:49], s[12:13], 0, v[48:49]
	v_cndmask_b32_e32 v0, v214, v1, vcc
	v_lshlrev_b32_e32 v85, 2, v0
	ds_bpermute_b32 v84, v85, v69
	ds_bpermute_b32 v82, v85, v68
	ds_bpermute_b32 v81, v85, v67
	ds_bpermute_b32 v80, v85, v66
	ds_bpermute_b32 v79, v85, v65
	ds_bpermute_b32 v78, v85, v64
	ds_bpermute_b32 v77, v85, v63
	ds_bpermute_b32 v76, v85, v62
	ds_bpermute_b32 v75, v85, v61
	ds_bpermute_b32 v74, v85, v60
	ds_bpermute_b32 v73, v85, v59
	ds_bpermute_b32 v72, v85, v58
	ds_bpermute_b32 v71, v85, v57
	ds_bpermute_b32 v70, v85, v56
	ds_bpermute_b32 v51, v85, v55
	ds_bpermute_b32 v50, v85, v54
	v_mov_b32_e32 v86, 0
	v_mov_b32_e32 v87, 0
	v_mov_b32_e32 v88, 0
	v_mov_b32_e32 v89, 0
	v_mov_b32_e32 v90, 0
	v_mov_b32_e32 v91, 0
	v_mov_b32_e32 v92, 0
	v_mov_b32_e32 v93, 0
	v_mov_b32_e32 v94, 0
	v_mov_b32_e32 v95, 0
	v_mov_b32_e32 v96, 0
	v_mov_b32_e32 v97, 0
	v_mov_b32_e32 v98, 0
	v_mov_b32_e32 v99, 0
	v_mov_b32_e32 v100, 0
	v_mov_b32_e32 v83, 0
.LBB0_2503:
	global_load_dwordx4 v[190:193], v[48:49], off offset:-128
	global_load_dwordx4 v[194:197], v[48:49], off offset:-96
	global_load_dwordx4 v[198:201], v[48:49], off offset:-64
	global_load_dwordx4 v[202:205], v[48:49], off offset:-32
	global_load_dwordx4 v[206:209], v[48:49], off
	global_load_dwordx4 v[216:219], v[48:49], off offset:32
	global_load_dwordx4 v[220:223], v[48:49], off offset:64
	global_load_dwordx4 v[224:227], v[48:49], off offset:96
	v_lshl_add_u64 v[48:49], v[48:49], 0, s[16:17]
	s_waitcnt vmcnt(7) lgkmcnt(14)
	v_mfma_f32_32x32x16_bf16 v[0:15], v[190:193], v[16:19], 0
	s_waitcnt vmcnt(6)
	v_mfma_f32_32x32x16_bf16 v[0:15], v[194:197], v[20:23], v[0:15]
	s_waitcnt vmcnt(5)
	v_mfma_f32_32x32x16_bf16 v[0:15], v[198:201], v[24:27], v[0:15]
	s_waitcnt vmcnt(4)
	v_mfma_f32_32x32x16_bf16 v[0:15], v[202:205], v[28:31], v[0:15]
	s_waitcnt vmcnt(3)
	v_mfma_f32_32x32x16_bf16 v[0:15], v[206:209], v[32:35], v[0:15]
	s_waitcnt vmcnt(2)
	v_mfma_f32_32x32x16_bf16 v[0:15], v[216:219], v[36:39], v[0:15]
	s_waitcnt vmcnt(1)
	v_mfma_f32_32x32x16_bf16 v[0:15], v[220:223], v[40:43], v[0:15]
	s_waitcnt vmcnt(0)
	v_mfma_f32_32x32x16_bf16 v[0:15], v[224:227], v[44:47], v[0:15]
	s_nop 11
	v_cmp_gt_i32_e32 vcc, 0, v0
	v_not_b32_e32 v101, v0
	v_or_b32_e32 v102, 0x80000000, v0
	v_cndmask_b32_e32 v101, v102, v101, vcc
	v_and_b32_e32 v101, 0xffffff80, v101
	v_add_u32_e32 v0, s14, v53
	s_sub_i32 s14, s14, 32
	s_cmpk_lg_i32 s14, 0xff80
	v_add3_u32 v101, v0, v101, s52
	v_med3_u32 v83, v100, v83, v101
	v_med3_u32 v100, v99, v100, v101
	v_med3_u32 v99, v98, v99, v101
	v_med3_u32 v98, v97, v98, v101
	v_med3_u32 v97, v96, v97, v101
	v_med3_u32 v96, v95, v96, v101
	v_med3_u32 v95, v94, v95, v101
	v_med3_u32 v94, v93, v94, v101
	v_med3_u32 v93, v92, v93, v101
	v_med3_u32 v92, v91, v92, v101
	v_med3_u32 v91, v90, v91, v101
	v_med3_u32 v90, v89, v90, v101
	v_med3_u32 v89, v88, v89, v101
	v_med3_u32 v88, v87, v88, v101
	v_med3_u32 v87, v86, v87, v101
	v_max_u32_e32 v86, v86, v101
	v_cmp_gt_i32_e32 vcc, 0, v1
	v_not_b32_e32 v101, v1
	v_or_b32_e32 v102, 0x80000000, v1
	v_cndmask_b32_e32 v101, v102, v101, vcc
	v_and_b32_e32 v101, 0xffffff80, v101
	v_add3_u32 v101, v0, v101, s53
	v_med3_u32 v83, v100, v83, v101
	v_med3_u32 v100, v99, v100, v101
	v_med3_u32 v99, v98, v99, v101
	v_med3_u32 v98, v97, v98, v101
	v_med3_u32 v97, v96, v97, v101
	v_med3_u32 v96, v95, v96, v101
	v_med3_u32 v95, v94, v95, v101
	v_med3_u32 v94, v93, v94, v101
	v_med3_u32 v93, v92, v93, v101
	v_med3_u32 v92, v91, v92, v101
	v_med3_u32 v91, v90, v91, v101
	v_med3_u32 v90, v89, v90, v101
	v_med3_u32 v89, v88, v89, v101
	v_med3_u32 v88, v87, v88, v101
	v_med3_u32 v87, v86, v87, v101
	v_max_u32_e32 v86, v86, v101
	v_cmp_gt_i32_e32 vcc, 0, v2
	v_not_b32_e32 v101, v2
	v_or_b32_e32 v102, 0x80000000, v2
	v_cndmask_b32_e32 v101, v102, v101, vcc
	v_and_b32_e32 v101, 0xffffff80, v101
	v_add3_u32 v101, v0, v101, s54
	v_med3_u32 v83, v100, v83, v101
	v_med3_u32 v100, v99, v100, v101
	v_med3_u32 v99, v98, v99, v101
	v_med3_u32 v98, v97, v98, v101
	v_med3_u32 v97, v96, v97, v101
	v_med3_u32 v96, v95, v96, v101
	v_med3_u32 v95, v94, v95, v101
	v_med3_u32 v94, v93, v94, v101
	v_med3_u32 v93, v92, v93, v101
	v_med3_u32 v92, v91, v92, v101
	v_med3_u32 v91, v90, v91, v101
	v_med3_u32 v90, v89, v90, v101
	v_med3_u32 v89, v88, v89, v101
	v_med3_u32 v88, v87, v88, v101
	v_med3_u32 v87, v86, v87, v101
	v_max_u32_e32 v86, v86, v101
	v_cmp_gt_i32_e32 vcc, 0, v3
	v_not_b32_e32 v101, v3
	v_or_b32_e32 v102, 0x80000000, v3
	v_cndmask_b32_e32 v101, v102, v101, vcc
	v_and_b32_e32 v101, 0xffffff80, v101
	v_add3_u32 v101, v0, v101, s55
	v_med3_u32 v83, v100, v83, v101
	v_med3_u32 v100, v99, v100, v101
	v_med3_u32 v99, v98, v99, v101
	v_med3_u32 v98, v97, v98, v101
	v_med3_u32 v97, v96, v97, v101
	v_med3_u32 v96, v95, v96, v101
	v_med3_u32 v95, v94, v95, v101
	v_med3_u32 v94, v93, v94, v101
	v_med3_u32 v93, v92, v93, v101
	v_med3_u32 v92, v91, v92, v101
	v_med3_u32 v91, v90, v91, v101
	v_med3_u32 v90, v89, v90, v101
	v_med3_u32 v89, v88, v89, v101
	v_med3_u32 v88, v87, v88, v101
	v_med3_u32 v87, v86, v87, v101
	v_max_u32_e32 v86, v86, v101
	v_cmp_gt_i32_e32 vcc, 0, v4
	v_not_b32_e32 v101, v4
	v_or_b32_e32 v102, 0x80000000, v4
; #define MFMA32(a, b, c) __builtin_amdgcn_mfma_f32_32x32x16_bf16((a), (b), (c), 0, 0, 0)
; DI int crow(int i, int h) { return (i & 3) + 8 * (i >> 2) + 4 * h; }
; DI unsigned f2ord(float f) { unsigned u = __float_as_uint(f); return (u & 0x80000000u) ? ~u : (u | 0x80000000u); }
; #define INS32(T, X) { _Pragma("unroll") for (int jj = 0; jj < 16; ++jj) { unsigned t_ = max(T[jj], X); X = min(T[jj], X); T[jj] = t_; } }
; __device__ __forceinline__ void route_task(const Params& p, int layer, const u16* qg, int rb, int hd, int r, int h) {
;     ...
;     for (int n = 0; n < 4; ++n) {
;       f32x16 acc;
; #pragma unroll
;       for (int e = 0; e < 16; ++e) acc[e] = 0.f;
; #pragma unroll
;       for (int s = 0; s < 8; ++s) {
;         bf16x8 kf = *(const bf16x8*)(kg + (size_t)n * 32 * 128 + 16 * s);
;         acc = MFMA32(kf, qf[s], acc);
;       }
; #pragma unroll
;       for (int e = 0; e < 16; ++e) {
;         unsigned key = (f2ord(acc[e]) & ~127u) | (unsigned)(127 - (n * 32 + crow(e, h)));
;         INS32(tp, key);
;       }
	v_cndmask_b32_e32 v101, v102, v101, vcc
	v_and_b32_e32 v101, 0xffffff80, v101
	v_add3_u32 v101, v0, v101, s56
	v_med3_u32 v83, v100, v83, v101
	v_med3_u32 v100, v99, v100, v101
	v_med3_u32 v99, v98, v99, v101
	v_med3_u32 v98, v97, v98, v101
	v_med3_u32 v97, v96, v97, v101
	v_med3_u32 v96, v95, v96, v101
	v_med3_u32 v95, v94, v95, v101
	v_med3_u32 v94, v93, v94, v101
	v_med3_u32 v93, v92, v93, v101
	v_med3_u32 v92, v91, v92, v101
	v_med3_u32 v91, v90, v91, v101
	v_med3_u32 v90, v89, v90, v101
	v_med3_u32 v89, v88, v89, v101
	v_med3_u32 v88, v87, v88, v101
	v_med3_u32 v87, v86, v87, v101
	v_max_u32_e32 v86, v86, v101
	v_cmp_gt_i32_e32 vcc, 0, v5
	v_not_b32_e32 v101, v5
	v_or_b32_e32 v102, 0x80000000, v5
	v_cndmask_b32_e32 v101, v102, v101, vcc
	v_and_b32_e32 v101, 0xffffff80, v101
	v_add3_u32 v101, v0, v101, s57
	v_med3_u32 v83, v100, v83, v101
	v_med3_u32 v100, v99, v100, v101
	v_med3_u32 v99, v98, v99, v101
	v_med3_u32 v98, v97, v98, v101
	v_med3_u32 v97, v96, v97, v101
	v_med3_u32 v96, v95, v96, v101
	v_med3_u32 v95, v94, v95, v101
	v_med3_u32 v94, v93, v94, v101
	v_med3_u32 v93, v92, v93, v101
	v_med3_u32 v92, v91, v92, v101
	v_med3_u32 v91, v90, v91, v101
	v_med3_u32 v90, v89, v90, v101
	v_med3_u32 v89, v88, v89, v101
	v_med3_u32 v88, v87, v88, v101
	v_med3_u32 v87, v86, v87, v101
	v_max_u32_e32 v86, v86, v101
	v_cmp_gt_i32_e32 vcc, 0, v6
	v_not_b32_e32 v101, v6
	v_or_b32_e32 v102, 0x80000000, v6
	v_cndmask_b32_e32 v101, v102, v101, vcc
	v_and_b32_e32 v101, 0xffffff80, v101
	v_add3_u32 v101, v0, v101, s58
	v_med3_u32 v83, v100, v83, v101
	v_med3_u32 v100, v99, v100, v101
	v_med3_u32 v99, v98, v99, v101
	v_med3_u32 v98, v97, v98, v101
	v_med3_u32 v97, v96, v97, v101
	v_med3_u32 v96, v95, v96, v101
	v_med3_u32 v95, v94, v95, v101
	v_med3_u32 v94, v93, v94, v101
	v_med3_u32 v93, v92, v93, v101
	v_med3_u32 v92, v91, v92, v101
	v_med3_u32 v91, v90, v91, v101
	v_med3_u32 v90, v89, v90, v101
	v_med3_u32 v89, v88, v89, v101
	v_med3_u32 v88, v87, v88, v101
	v_med3_u32 v87, v86, v87, v101
	v_max_u32_e32 v86, v86, v101
	v_cmp_gt_i32_e32 vcc, 0, v7
	v_not_b32_e32 v101, v7
	v_or_b32_e32 v102, 0x80000000, v7
	v_cndmask_b32_e32 v101, v102, v101, vcc
	v_and_b32_e32 v101, 0xffffff80, v101
	v_add3_u32 v101, v0, v101, s59
	v_med3_u32 v83, v100, v83, v101
	v_med3_u32 v100, v99, v100, v101
	v_med3_u32 v99, v98, v99, v101
	v_med3_u32 v98, v97, v98, v101
	v_med3_u32 v97, v96, v97, v101
	v_med3_u32 v96, v95, v96, v101
	v_med3_u32 v95, v94, v95, v101
	v_med3_u32 v94, v93, v94, v101
	v_med3_u32 v93, v92, v93, v101
	v_med3_u32 v92, v91, v92, v101
	v_med3_u32 v91, v90, v91, v101
	v_med3_u32 v90, v89, v90, v101
	v_med3_u32 v89, v88, v89, v101
	v_med3_u32 v88, v87, v88, v101
	v_med3_u32 v87, v86, v87, v101
	v_max_u32_e32 v86, v86, v101
	v_cmp_gt_i32_e32 vcc, 0, v8
	v_not_b32_e32 v101, v8
	v_or_b32_e32 v102, 0x80000000, v8
	v_cndmask_b32_e32 v101, v102, v101, vcc
	v_and_b32_e32 v101, 0xffffff80, v101
	v_add3_u32 v101, v0, v101, s60
	v_med3_u32 v83, v100, v83, v101
	v_med3_u32 v100, v99, v100, v101
	v_med3_u32 v99, v98, v99, v101
	v_med3_u32 v98, v97, v98, v101
	v_med3_u32 v97, v96, v97, v101
	v_med3_u32 v96, v95, v96, v101
	v_med3_u32 v95, v94, v95, v101
	v_med3_u32 v94, v93, v94, v101
	v_med3_u32 v93, v92, v93, v101
	v_med3_u32 v92, v91, v92, v101
	v_med3_u32 v91, v90, v91, v101
	v_med3_u32 v90, v89, v90, v101
	v_med3_u32 v89, v88, v89, v101
	v_med3_u32 v88, v87, v88, v101
	v_med3_u32 v87, v86, v87, v101
	v_max_u32_e32 v86, v86, v101
	v_cmp_gt_i32_e32 vcc, 0, v9
	v_not_b32_e32 v101, v9
	v_or_b32_e32 v102, 0x80000000, v9
	v_cndmask_b32_e32 v101, v102, v101, vcc
	v_and_b32_e32 v101, 0xffffff80, v101
	v_add3_u32 v101, v0, v101, s61
	v_med3_u32 v83, v100, v83, v101
	v_med3_u32 v100, v99, v100, v101
	v_med3_u32 v99, v98, v99, v101
	v_med3_u32 v98, v97, v98, v101
	v_med3_u32 v97, v96, v97, v101
	v_med3_u32 v96, v95, v96, v101
	v_med3_u32 v95, v94, v95, v101
	v_med3_u32 v94, v93, v94, v101
	v_med3_u32 v93, v92, v93, v101
	v_med3_u32 v92, v91, v92, v101
	v_med3_u32 v91, v90, v91, v101
	v_med3_u32 v90, v89, v90, v101
	v_med3_u32 v89, v88, v89, v101
	v_med3_u32 v88, v87, v88, v101
	v_med3_u32 v87, v86, v87, v101
	v_max_u32_e32 v86, v86, v101
	v_cmp_gt_i32_e32 vcc, 0, v10
	v_not_b32_e32 v101, v10
	v_or_b32_e32 v102, 0x80000000, v10
	v_cndmask_b32_e32 v101, v102, v101, vcc
	v_and_b32_e32 v101, 0xffffff80, v101
	v_add3_u32 v101, v0, v101, s62
	v_med3_u32 v83, v100, v83, v101
	v_med3_u32 v100, v99, v100, v101
	v_med3_u32 v99, v98, v99, v101
	v_med3_u32 v98, v97, v98, v101
	v_med3_u32 v97, v96, v97, v101
	v_med3_u32 v96, v95, v96, v101
	v_med3_u32 v95, v94, v95, v101
	v_med3_u32 v94, v93, v94, v101
	v_med3_u32 v93, v92, v93, v101
	v_med3_u32 v92, v91, v92, v101
	v_med3_u32 v91, v90, v91, v101
	v_med3_u32 v90, v89, v90, v101
	v_med3_u32 v89, v88, v89, v101
	v_med3_u32 v88, v87, v88, v101
	v_med3_u32 v87, v86, v87, v101
	v_max_u32_e32 v86, v86, v101
	v_cmp_gt_i32_e32 vcc, 0, v11
	v_not_b32_e32 v101, v11
	v_or_b32_e32 v102, 0x80000000, v11
	v_cndmask_b32_e32 v101, v102, v101, vcc
	v_and_b32_e32 v101, 0xffffff80, v101
	v_add3_u32 v101, v0, v101, s63
	v_med3_u32 v83, v100, v83, v101
	v_med3_u32 v100, v99, v100, v101
	v_med3_u32 v99, v98, v99, v101
	v_med3_u32 v98, v97, v98, v101
	v_med3_u32 v97, v96, v97, v101
	v_med3_u32 v96, v95, v96, v101
	v_med3_u32 v95, v94, v95, v101
	v_med3_u32 v94, v93, v94, v101
	v_med3_u32 v93, v92, v93, v101
	v_med3_u32 v92, v91, v92, v101
	v_med3_u32 v91, v90, v91, v101
	v_med3_u32 v90, v89, v90, v101
	v_med3_u32 v89, v88, v89, v101
	v_med3_u32 v88, v87, v88, v101
	v_med3_u32 v87, v86, v87, v101
	v_max_u32_e32 v86, v86, v101
	v_cmp_gt_i32_e32 vcc, 0, v12
; DI int crow(int i, int h) { return (i & 3) + 8 * (i >> 2) + 4 * h; }
; DI unsigned f2ord(float f) { unsigned u = __float_as_uint(f); return (u & 0x80000000u) ? ~u : (u | 0x80000000u); }
; #define INS32(T, X) { _Pragma("unroll") for (int jj = 0; jj < 16; ++jj) { unsigned t_ = max(T[jj], X); X = min(T[jj], X); T[jj] = t_; } }
; __device__ __forceinline__ void route_task(const Params& p, int layer, const u16* qg, int rb, int hd, int r, int h) {
;     ...
;       for (int e = 0; e < 16; ++e) {
;         unsigned key = (f2ord(acc[e]) & ~127u) | (unsigned)(127 - (n * 32 + crow(e, h)));
;         INS32(tp, key);
;       }
;     }
;     unsigned ot[16];
; #pragma unroll
;     for (int jj = 0; jj < 16; ++jj) ot[jj] = (unsigned)__shfl_xor((int)tp[jj], 32);
; #pragma unroll
;     for (int jj = 0; jj < 16; ++jj) { unsigned key = ot[jj]; INS32(tp, key); }
;     ...
;   if (h == 0) {
	v_not_b32_e32 v101, v12
	v_or_b32_e32 v102, 0x80000000, v12
	v_cndmask_b32_e32 v101, v102, v101, vcc
	v_and_b32_e32 v101, 0xffffff80, v101
	v_add3_u32 v101, v0, v101, s64
	v_med3_u32 v83, v100, v83, v101
	v_med3_u32 v100, v99, v100, v101
	v_med3_u32 v99, v98, v99, v101
	v_med3_u32 v98, v97, v98, v101
	v_med3_u32 v97, v96, v97, v101
	v_med3_u32 v96, v95, v96, v101
	v_med3_u32 v95, v94, v95, v101
	v_med3_u32 v94, v93, v94, v101
	v_med3_u32 v93, v92, v93, v101
	v_med3_u32 v92, v91, v92, v101
	v_med3_u32 v91, v90, v91, v101
	v_med3_u32 v90, v89, v90, v101
	v_med3_u32 v89, v88, v89, v101
	v_med3_u32 v88, v87, v88, v101
	v_med3_u32 v87, v86, v87, v101
	v_max_u32_e32 v86, v86, v101
	v_cmp_gt_i32_e32 vcc, 0, v13
	v_not_b32_e32 v101, v13
	v_or_b32_e32 v102, 0x80000000, v13
	v_cndmask_b32_e32 v101, v102, v101, vcc
	v_and_b32_e32 v101, 0xffffff80, v101
	v_add3_u32 v101, v0, v101, s65
	v_med3_u32 v83, v100, v83, v101
	v_med3_u32 v100, v99, v100, v101
	v_med3_u32 v99, v98, v99, v101
	v_med3_u32 v98, v97, v98, v101
	v_med3_u32 v97, v96, v97, v101
	v_med3_u32 v96, v95, v96, v101
	v_med3_u32 v95, v94, v95, v101
	v_med3_u32 v94, v93, v94, v101
	v_med3_u32 v93, v92, v93, v101
	v_med3_u32 v92, v91, v92, v101
	v_med3_u32 v91, v90, v91, v101
	v_med3_u32 v90, v89, v90, v101
	v_med3_u32 v89, v88, v89, v101
	v_med3_u32 v88, v87, v88, v101
	v_med3_u32 v87, v86, v87, v101
	v_max_u32_e32 v86, v86, v101
	v_cmp_gt_i32_e32 vcc, 0, v14
	v_not_b32_e32 v101, v14
	v_or_b32_e32 v102, 0x80000000, v14
	v_cndmask_b32_e32 v101, v102, v101, vcc
	v_and_b32_e32 v101, 0xffffff80, v101
	v_add3_u32 v101, v0, v101, s66
	v_med3_u32 v83, v100, v83, v101
	v_med3_u32 v100, v99, v100, v101
	v_med3_u32 v99, v98, v99, v101
	v_med3_u32 v98, v97, v98, v101
	v_med3_u32 v97, v96, v97, v101
	v_med3_u32 v96, v95, v96, v101
	v_med3_u32 v95, v94, v95, v101
	v_med3_u32 v94, v93, v94, v101
	v_med3_u32 v93, v92, v93, v101
	v_med3_u32 v92, v91, v92, v101
	v_med3_u32 v91, v90, v91, v101
	v_med3_u32 v90, v89, v90, v101
	v_med3_u32 v89, v88, v89, v101
	v_med3_u32 v88, v87, v88, v101
	v_med3_u32 v87, v86, v87, v101
	v_max_u32_e32 v86, v86, v101
	v_cmp_gt_i32_e32 vcc, 0, v15
	v_not_b32_e32 v101, v15
	v_or_b32_e32 v102, 0x80000000, v15
	v_cndmask_b32_e32 v101, v102, v101, vcc
	v_and_b32_e32 v101, 0xffffff80, v101
	v_add3_u32 v101, v0, v101, s67
	v_med3_u32 v83, v100, v83, v101
	v_med3_u32 v100, v99, v100, v101
	v_med3_u32 v99, v98, v99, v101
	v_med3_u32 v98, v97, v98, v101
	v_med3_u32 v97, v96, v97, v101
	v_med3_u32 v96, v95, v96, v101
	v_med3_u32 v95, v94, v95, v101
	v_med3_u32 v94, v93, v94, v101
	v_med3_u32 v93, v92, v93, v101
	v_med3_u32 v92, v91, v92, v101
	v_med3_u32 v91, v90, v91, v101
	v_med3_u32 v90, v89, v90, v101
	v_med3_u32 v89, v88, v89, v101
	v_med3_u32 v88, v87, v88, v101
	v_med3_u32 v87, v86, v87, v101
	v_max_u32_e32 v86, v86, v101
	s_cbranch_scc1 .LBB0_2503
	ds_bpermute_b32 v17, v85, v86
	ds_bpermute_b32 v16, v85, v87
	ds_bpermute_b32 v13, v85, v88
	ds_bpermute_b32 v12, v85, v89
	ds_bpermute_b32 v11, v85, v90
	ds_bpermute_b32 v10, v85, v91
	ds_bpermute_b32 v9, v85, v92
	ds_bpermute_b32 v8, v85, v93
	ds_bpermute_b32 v7, v85, v94
	ds_bpermute_b32 v6, v85, v95
	ds_bpermute_b32 v5, v85, v96
	ds_bpermute_b32 v4, v85, v97
	ds_bpermute_b32 v3, v85, v98
	ds_bpermute_b32 v2, v85, v99
	ds_bpermute_b32 v1, v85, v100
	ds_bpermute_b32 v0, v85, v83
	v_cmp_eq_u32_e32 vcc, 0, v139
	s_and_saveexec_b64 s[18:19], vcc
	s_cbranch_execz .LBB0_2495
	v_max_u32_e32 v14, v69, v84
	v_min_u32_e32 v15, v69, v84
	v_max_u32_e32 v18, v68, v15
	v_min_u32_e32 v15, v68, v15
	v_max_u32_e32 v31, v14, v82
	v_min_u32_e32 v14, v14, v82
	v_max_u32_e32 v19, v67, v15
	v_min_u32_e32 v15, v67, v15
	v_max_u32_e32 v32, v18, v14
	v_min_u32_e32 v14, v18, v14
	v_max_u32_e32 v20, v66, v15
	v_min_u32_e32 v15, v66, v15
	v_max_u32_e32 v18, v19, v14
	v_min_u32_e32 v14, v19, v14
	v_max_u32_e32 v21, v65, v15
	v_min_u32_e32 v15, v65, v15
	v_max_u32_e32 v19, v20, v14
	v_min_u32_e32 v14, v20, v14
	v_max_u32_e32 v22, v64, v15
	v_min_u32_e32 v15, v64, v15
	v_max_u32_e32 v20, v21, v14
	v_min_u32_e32 v14, v21, v14
	v_max_u32_e32 v23, v63, v15
	v_min_u32_e32 v15, v63, v15
	v_max_u32_e32 v21, v22, v14
	v_min_u32_e32 v14, v22, v14
	v_max_u32_e32 v24, v62, v15
	v_min_u32_e32 v15, v62, v15
	v_max_u32_e32 v22, v23, v14
	v_min_u32_e32 v14, v23, v14
	v_max_u32_e32 v25, v61, v15
	v_min_u32_e32 v15, v61, v15
	v_max_u32_e32 v23, v24, v14
	v_min_u32_e32 v14, v24, v14
	v_max_u32_e32 v26, v60, v15
	v_min_u32_e32 v15, v60, v15
	v_max_u32_e32 v24, v25, v14
	v_min_u32_e32 v14, v25, v14
	v_max_u32_e32 v27, v59, v15
	v_min_u32_e32 v15, v59, v15
	v_max_u32_e32 v25, v26, v14
	v_min_u32_e32 v14, v26, v14
	v_max_u32_e32 v28, v58, v15
	v_min_u32_e32 v15, v58, v15
	v_max_u32_e32 v26, v27, v14
	v_min_u32_e32 v14, v27, v14
	v_max_u32_e32 v29, v57, v15
	v_min_u32_e32 v15, v57, v15
	v_max_u32_e32 v27, v28, v14
	v_min_u32_e32 v14, v28, v14
	v_max_u32_e32 v30, v56, v15
	v_max_u32_e32 v28, v29, v14
	v_min_u32_e32 v14, v29, v14
	v_max_u32_e32 v29, v30, v14
	v_min_u32_e32 v30, v30, v14
	s_waitcnt lgkmcnt(14)
; #define INS32(T, X) { _Pragma("unroll") for (int jj = 0; jj < 16; ++jj) { unsigned t_ = max(T[jj], X); X = min(T[jj], X); T[jj] = t_; } }
; __device__ __forceinline__ void route_task(const Params& p, int layer, const u16* qg, int rb, int hd, int r, int h) {
;     ...
;     for (int jj = 0; jj < 16; ++jj) ot[jj] = (unsigned)__shfl_xor((int)tp[jj], 32);
; #pragma unroll
;     for (int jj = 0; jj < 16; ++jj) { unsigned key = ot[jj]; INS32(tp, key); }
; #pragma unroll
;     for (int jj = 0; jj < 16; ++jj) top[ph][jj] = tp[jj];
	v_max_u32_e32 v14, v31, v81
	v_min_u32_e32 v31, v31, v81
	v_max_u32_e32 v33, v32, v31
	v_min_u32_e32 v31, v32, v31
	v_max_u32_e32 v32, v18, v31
	v_min_u32_e32 v18, v18, v31
	v_max_u32_e32 v31, v19, v18
	v_min_u32_e32 v18, v19, v18
	v_max_u32_e32 v19, v20, v18
	v_min_u32_e32 v18, v20, v18
	v_max_u32_e32 v20, v21, v18
	v_min_u32_e32 v18, v21, v18
	v_max_u32_e32 v21, v22, v18
	v_min_u32_e32 v18, v22, v18
	v_max_u32_e32 v22, v23, v18
	v_min_u32_e32 v18, v23, v18
	v_max_u32_e32 v23, v24, v18
	v_min_u32_e32 v18, v24, v18
	v_max_u32_e32 v24, v25, v18
	v_min_u32_e32 v18, v25, v18
	v_max_u32_e32 v25, v26, v18
	v_min_u32_e32 v18, v26, v18
	v_max_u32_e32 v26, v27, v18
	v_min_u32_e32 v18, v27, v18
	v_max_u32_e32 v27, v28, v18
	v_min_u32_e32 v18, v28, v18
	v_max_u32_e32 v28, v29, v18
	v_min_u32_e32 v18, v29, v18
	v_max_u32_e32 v29, v14, v80
	v_min_u32_e32 v14, v14, v80
	v_max_u32_e32 v34, v33, v14
	v_min_u32_e32 v14, v33, v14
	v_max_u32_e32 v33, v32, v14
	v_min_u32_e32 v14, v32, v14
	v_max_u32_e32 v32, v31, v14
	v_min_u32_e32 v14, v31, v14
	v_max_u32_e32 v31, v19, v14
	v_min_u32_e32 v14, v19, v14
	v_max_u32_e32 v19, v20, v14
	v_min_u32_e32 v14, v20, v14
	v_max_u32_e32 v20, v21, v14
	v_min_u32_e32 v14, v21, v14
	v_max_u32_e32 v21, v22, v14
	v_min_u32_e32 v14, v22, v14
	v_max_u32_e32 v22, v23, v14
	v_min_u32_e32 v14, v23, v14
	v_max_u32_e32 v23, v24, v14
	v_min_u32_e32 v14, v24, v14
	v_max_u32_e32 v24, v25, v14
	v_min_u32_e32 v14, v25, v14
	v_max_u32_e32 v25, v26, v14
	v_min_u32_e32 v14, v26, v14
	v_max_u32_e32 v26, v27, v14
	v_min_u32_e32 v14, v27, v14
	v_max_u32_e32 v27, v28, v14
	v_min_u32_e32 v28, v28, v14
	v_max_u32_e32 v14, v29, v79
	v_min_u32_e32 v29, v29, v79
	v_max_u32_e32 v35, v34, v29
	v_min_u32_e32 v29, v34, v29
	v_max_u32_e32 v34, v33, v29
	v_min_u32_e32 v29, v33, v29
	v_max_u32_e32 v33, v32, v29
	v_min_u32_e32 v29, v32, v29
	v_max_u32_e32 v32, v31, v29
	v_min_u32_e32 v29, v31, v29
	v_max_u32_e32 v31, v19, v29
	v_min_u32_e32 v19, v19, v29
	v_max_u32_e32 v29, v20, v19
	v_min_u32_e32 v19, v20, v19
	v_max_u32_e32 v20, v21, v19
	v_min_u32_e32 v19, v21, v19
	v_max_u32_e32 v21, v22, v19
	v_min_u32_e32 v19, v22, v19
	v_max_u32_e32 v22, v23, v19
	v_min_u32_e32 v19, v23, v19
	v_max_u32_e32 v23, v24, v19
	v_min_u32_e32 v19, v24, v19
	v_max_u32_e32 v24, v25, v19
	v_min_u32_e32 v19, v25, v19
	v_max_u32_e32 v25, v26, v19
	v_min_u32_e32 v19, v26, v19
	v_max_u32_e32 v26, v27, v19
	v_min_u32_e32 v19, v27, v19
	v_max_u32_e32 v27, v14, v78
	v_min_u32_e32 v14, v14, v78
	v_max_u32_e32 v36, v35, v14
	v_min_u32_e32 v14, v35, v14
	v_max_u32_e32 v35, v34, v14
	v_min_u32_e32 v14, v34, v14
	v_max_u32_e32 v34, v33, v14
	v_min_u32_e32 v14, v33, v14
	v_max_u32_e32 v33, v32, v14
	v_min_u32_e32 v14, v32, v14
	v_max_u32_e32 v32, v31, v14
	v_min_u32_e32 v14, v31, v14
	v_max_u32_e32 v31, v29, v14
	v_min_u32_e32 v14, v29, v14
	v_max_u32_e32 v29, v20, v14
	v_min_u32_e32 v14, v20, v14
	v_max_u32_e32 v20, v21, v14
	v_min_u32_e32 v14, v21, v14
	v_max_u32_e32 v21, v22, v14
	v_min_u32_e32 v14, v22, v14
	v_max_u32_e32 v22, v23, v14
	v_min_u32_e32 v14, v23, v14
	v_max_u32_e32 v23, v24, v14
	v_min_u32_e32 v14, v24, v14
	v_max_u32_e32 v24, v25, v14
	v_min_u32_e32 v14, v25, v14
	v_max_u32_e32 v25, v26, v14
	v_min_u32_e32 v26, v26, v14
	v_max_u32_e32 v14, v27, v77
	v_min_u32_e32 v27, v27, v77
	v_max_u32_e32 v37, v36, v27
	v_min_u32_e32 v27, v36, v27
	v_max_u32_e32 v36, v35, v27
	v_min_u32_e32 v27, v35, v27
	v_max_u32_e32 v35, v34, v27
	v_min_u32_e32 v27, v34, v27
	v_max_u32_e32 v34, v33, v27
	v_min_u32_e32 v27, v33, v27
	v_max_u32_e32 v33, v32, v27
	v_min_u32_e32 v27, v32, v27
	v_max_u32_e32 v32, v31, v27
	v_min_u32_e32 v27, v31, v27
	v_max_u32_e32 v31, v29, v27
	v_min_u32_e32 v27, v29, v27
	v_max_u32_e32 v29, v20, v27
	v_min_u32_e32 v20, v20, v27
	v_max_u32_e32 v27, v21, v20
	v_min_u32_e32 v20, v21, v20
	v_max_u32_e32 v21, v22, v20
	v_min_u32_e32 v20, v22, v20
	v_max_u32_e32 v22, v23, v20
	v_min_u32_e32 v20, v23, v20
	v_max_u32_e32 v23, v24, v20
	v_min_u32_e32 v20, v24, v20
	v_max_u32_e32 v24, v25, v20
	v_min_u32_e32 v20, v25, v20
	v_max_u32_e32 v25, v14, v76
	v_min_u32_e32 v14, v14, v76
	v_max_u32_e32 v38, v37, v14
	v_min_u32_e32 v14, v37, v14
	v_max_u32_e32 v37, v36, v14
	v_min_u32_e32 v14, v36, v14
	v_max_u32_e32 v36, v35, v14
	v_min_u32_e32 v14, v35, v14
	v_max_u32_e32 v35, v34, v14
	v_min_u32_e32 v14, v34, v14
	v_max_u32_e32 v34, v33, v14
	v_min_u32_e32 v14, v33, v14
	v_max_u32_e32 v33, v32, v14
	v_min_u32_e32 v14, v32, v14
	v_max_u32_e32 v32, v31, v14
	v_min_u32_e32 v14, v31, v14
	v_max_u32_e32 v31, v29, v14
	v_min_u32_e32 v14, v29, v14
	v_max_u32_e32 v29, v27, v14
	v_min_u32_e32 v14, v27, v14
	v_max_u32_e32 v27, v21, v14
	v_min_u32_e32 v14, v21, v14
	v_max_u32_e32 v21, v22, v14
	v_min_u32_e32 v14, v22, v14
	v_max_u32_e32 v22, v23, v14
	v_min_u32_e32 v14, v23, v14
	v_max_u32_e32 v23, v24, v14
	v_min_u32_e32 v24, v24, v14
	v_max_u32_e32 v14, v25, v75
	v_min_u32_e32 v25, v25, v75
	v_max_u32_e32 v39, v38, v25
	v_min_u32_e32 v25, v38, v25
	v_max_u32_e32 v38, v37, v25
	v_min_u32_e32 v25, v37, v25
	v_max_u32_e32 v37, v36, v25
	v_min_u32_e32 v25, v36, v25
	v_max_u32_e32 v36, v35, v25
	v_min_u32_e32 v25, v35, v25
	v_max_u32_e32 v35, v34, v25
	v_min_u32_e32 v25, v34, v25
	v_max_u32_e32 v34, v33, v25
	v_min_u32_e32 v25, v33, v25
	v_max_u32_e32 v33, v32, v25
	v_min_u32_e32 v25, v32, v25
	v_max_u32_e32 v32, v31, v25
	v_min_u32_e32 v25, v31, v25
	v_max_u32_e32 v31, v29, v25
	v_min_u32_e32 v25, v29, v25
	v_max_u32_e32 v29, v27, v25
	v_min_u32_e32 v25, v27, v25
	v_max_u32_e32 v27, v21, v25
	v_min_u32_e32 v21, v21, v25
	v_max_u32_e32 v25, v22, v21
	v_min_u32_e32 v21, v22, v21
; #define INS32(T, X) { _Pragma("unroll") for (int jj = 0; jj < 16; ++jj) { unsigned t_ = max(T[jj], X); X = min(T[jj], X); T[jj] = t_; } }
; __device__ __forceinline__ void route_task(const Params& p, int layer, const u16* qg, int rb, int hd, int r, int h) {
;     ...
;     for (int jj = 0; jj < 16; ++jj) ot[jj] = (unsigned)__shfl_xor((int)tp[jj], 32);
; #pragma unroll
;     for (int jj = 0; jj < 16; ++jj) { unsigned key = ot[jj]; INS32(tp, key); }
; #pragma unroll
;     for (int jj = 0; jj < 16; ++jj) top[ph][jj] = tp[jj];
	v_max_u32_e32 v22, v23, v21
	v_min_u32_e32 v21, v23, v21
	v_max_u32_e32 v23, v14, v74
	v_min_u32_e32 v14, v14, v74
	v_max_u32_e32 v40, v39, v14
	v_min_u32_e32 v14, v39, v14
	v_max_u32_e32 v39, v38, v14
	v_min_u32_e32 v14, v38, v14
	v_max_u32_e32 v38, v37, v14
	v_min_u32_e32 v14, v37, v14
	v_max_u32_e32 v37, v36, v14
	v_min_u32_e32 v14, v36, v14
	v_max_u32_e32 v36, v35, v14
	v_min_u32_e32 v14, v35, v14
	v_max_u32_e32 v35, v34, v14
	v_min_u32_e32 v14, v34, v14
	v_max_u32_e32 v34, v33, v14
	v_min_u32_e32 v14, v33, v14
	v_max_u32_e32 v33, v32, v14
	v_min_u32_e32 v14, v32, v14
	v_max_u32_e32 v32, v31, v14
	v_min_u32_e32 v14, v31, v14
	v_max_u32_e32 v31, v29, v14
	v_min_u32_e32 v14, v29, v14
	v_max_u32_e32 v29, v27, v14
	v_min_u32_e32 v14, v27, v14
	v_max_u32_e32 v27, v25, v14
	v_min_u32_e32 v14, v25, v14
	v_max_u32_e32 v25, v22, v14
	v_min_u32_e32 v22, v22, v14
	v_max_u32_e32 v14, v23, v73
	v_min_u32_e32 v23, v23, v73
	v_max_u32_e32 v41, v40, v23
	v_min_u32_e32 v23, v40, v23
	v_max_u32_e32 v40, v39, v23
	v_min_u32_e32 v23, v39, v23
	v_max_u32_e32 v39, v38, v23
	v_min_u32_e32 v23, v38, v23
	v_max_u32_e32 v38, v37, v23
	v_min_u32_e32 v23, v37, v23
	v_max_u32_e32 v37, v36, v23
	v_min_u32_e32 v23, v36, v23
	v_max_u32_e32 v36, v35, v23
	v_min_u32_e32 v23, v35, v23
	v_max_u32_e32 v35, v34, v23
	v_min_u32_e32 v23, v34, v23
	v_max_u32_e32 v34, v33, v23
	v_min_u32_e32 v23, v33, v23
	v_max_u32_e32 v33, v32, v23
	v_min_u32_e32 v23, v32, v23
	v_max_u32_e32 v32, v31, v23
	v_min_u32_e32 v23, v31, v23
	v_max_u32_e32 v31, v29, v23
	v_min_u32_e32 v23, v29, v23
	v_max_u32_e32 v29, v27, v23
	v_min_u32_e32 v23, v27, v23
	v_max_u32_e32 v27, v25, v23
	v_min_u32_e32 v23, v25, v23
	v_max_u32_e32 v25, v14, v72
	v_min_u32_e32 v14, v14, v72
	v_max_u32_e32 v42, v41, v14
	v_min_u32_e32 v14, v41, v14
	v_max_u32_e32 v41, v40, v14
	v_min_u32_e32 v14, v40, v14
	v_max_u32_e32 v40, v39, v14
	v_min_u32_e32 v14, v39, v14
	v_max_u32_e32 v39, v38, v14
	v_min_u32_e32 v14, v38, v14
	v_max_u32_e32 v38, v37, v14
	v_min_u32_e32 v14, v37, v14
	v_max_u32_e32 v37, v36, v14
	v_min_u32_e32 v14, v36, v14
	v_max_u32_e32 v36, v35, v14
	v_min_u32_e32 v14, v35, v14
	v_max_u32_e32 v35, v34, v14
	v_min_u32_e32 v14, v34, v14
	v_max_u32_e32 v34, v33, v14
	v_min_u32_e32 v14, v33, v14
	v_max_u32_e32 v33, v32, v14
	v_min_u32_e32 v14, v32, v14
	v_max_u32_e32 v32, v31, v14
	v_min_u32_e32 v14, v31, v14
	v_max_u32_e32 v31, v29, v14
	v_min_u32_e32 v14, v29, v14
	v_max_u32_e32 v29, v27, v14
	v_min_u32_e32 v27, v27, v14
	v_max_u32_e32 v14, v25, v71
	v_min_u32_e32 v25, v25, v71
	v_max_u32_e32 v43, v42, v25
	v_min_u32_e32 v25, v42, v25
	v_max_u32_e32 v42, v41, v25
	v_min_u32_e32 v25, v41, v25
	v_max_u32_e32 v41, v40, v25
	v_min_u32_e32 v25, v40, v25
	v_max_u32_e32 v40, v39, v25
	v_min_u32_e32 v25, v39, v25
	v_max_u32_e32 v39, v38, v25
	v_min_u32_e32 v25, v38, v25
	v_max_u32_e32 v38, v37, v25
	v_min_u32_e32 v25, v37, v25
	v_max_u32_e32 v37, v36, v25
	v_min_u32_e32 v25, v36, v25
	v_max_u32_e32 v36, v35, v25
	v_min_u32_e32 v25, v35, v25
	v_max_u32_e32 v35, v34, v25
	v_min_u32_e32 v25, v34, v25
	v_max_u32_e32 v34, v33, v25
	v_min_u32_e32 v25, v33, v25
	v_max_u32_e32 v33, v32, v25
	v_min_u32_e32 v25, v32, v25
	v_max_u32_e32 v32, v31, v25
	v_min_u32_e32 v25, v31, v25
	v_max_u32_e32 v31, v29, v25
	v_min_u32_e32 v25, v29, v25
	v_max_u32_e32 v29, v14, v70
	v_min_u32_e32 v14, v14, v70
	v_max_u32_e32 v44, v43, v14
	v_min_u32_e32 v14, v43, v14
	v_max_u32_e32 v43, v42, v14
	v_min_u32_e32 v14, v42, v14
	v_max_u32_e32 v42, v41, v14
	v_min_u32_e32 v14, v41, v14
	v_max_u32_e32 v41, v40, v14
	v_min_u32_e32 v14, v40, v14
	v_max_u32_e32 v40, v39, v14
	v_min_u32_e32 v14, v39, v14
	v_max_u32_e32 v39, v38, v14
	v_min_u32_e32 v14, v38, v14
	v_max_u32_e32 v38, v37, v14
	v_min_u32_e32 v14, v37, v14
	v_max_u32_e32 v37, v36, v14
	v_min_u32_e32 v14, v36, v14
	v_max_u32_e32 v36, v35, v14
	v_min_u32_e32 v14, v35, v14
	v_max_u32_e32 v35, v34, v14
	v_min_u32_e32 v14, v34, v14
	v_max_u32_e32 v34, v33, v14
	v_min_u32_e32 v14, v33, v14
	v_min_u32_e32 v15, v56, v15
	v_max_u32_e32 v33, v32, v14
	v_min_u32_e32 v14, v32, v14
	v_max_u32_e32 v32, v31, v14
	v_min_u32_e32 v31, v31, v14
	v_max_u32_e32 v14, v29, v51
	v_min_u32_e32 v29, v29, v51
	v_max_u32_e32 v63, v55, v15
	v_max_u32_e32 v46, v44, v29
	v_min_u32_e32 v29, v44, v29
	v_min_u32_e32 v47, v14, v50
	v_max_u32_e32 v64, v63, v30
	v_max_u32_e32 v45, v43, v29
	v_min_u32_e32 v29, v43, v29
	v_min_u32_e32 v48, v46, v47
	v_max_u32_e32 v65, v64, v18
	v_max_u32_e32 v44, v42, v29
	v_min_u32_e32 v29, v42, v29
	v_min_u32_e32 v49, v45, v48
	v_max_u32_e32 v66, v65, v28
	v_max_u32_e32 v43, v41, v29
	v_min_u32_e32 v29, v41, v29
	v_min_u32_e32 v51, v44, v49
	v_max_u32_e32 v67, v66, v19
	v_max_u32_e32 v42, v40, v29
	v_min_u32_e32 v29, v40, v29
	v_min_u32_e32 v53, v43, v51
	v_max_u32_e32 v68, v67, v26
	v_max_u32_e32 v41, v39, v29
	v_min_u32_e32 v29, v39, v29
	v_min_u32_e32 v56, v42, v53
	v_max_u32_e32 v69, v68, v20
	v_max_u32_e32 v40, v38, v29
	v_min_u32_e32 v29, v38, v29
	v_min_u32_e32 v57, v41, v56
	v_max_u32_e32 v70, v69, v24
	v_max_u32_e32 v39, v37, v29
	v_min_u32_e32 v29, v37, v29
	v_min_u32_e32 v58, v40, v57
	v_max_u32_e32 v71, v70, v21
	v_min_u32_e32 v30, v63, v30
	v_min_u32_e32 v15, v55, v15
	v_max_u32_e32 v38, v36, v29
	v_min_u32_e32 v29, v36, v29
	v_min_u32_e32 v59, v39, v58
	v_max_u32_e32 v72, v71, v22
	v_min_u32_e32 v28, v65, v28
	v_min_u32_e32 v18, v64, v18
	v_max3_u32 v15, v54, v15, v30
	v_max_u32_e32 v37, v35, v29
	v_min_u32_e32 v29, v35, v29
	v_min_u32_e32 v60, v38, v59
	v_max_u32_e32 v73, v72, v23
	v_min_u32_e32 v26, v67, v26
	v_min_u32_e32 v19, v66, v19
	v_max3_u32 v15, v15, v18, v28
	v_max_u32_e32 v36, v34, v29
	v_min_u32_e32 v29, v34, v29
	v_min_u32_e32 v61, v37, v60
	v_max_u32_e32 v74, v73, v27
	v_min_u32_e32 v24, v69, v24
	v_min_u32_e32 v20, v68, v20
	v_max3_u32 v15, v15, v19, v26
	v_max_u32_e32 v35, v33, v29
	v_min_u32_e32 v29, v33, v29
	v_min_u32_e32 v62, v36, v61
	v_max_u32_e32 v75, v74, v25
	v_min_u32_e32 v22, v71, v22
	v_min_u32_e32 v21, v70, v21
	v_max3_u32 v15, v15, v20, v24
	v_min_u32_e32 v18, v86, v17
	v_max_u32_e32 v17, v86, v17
	v_min_u32_e32 v33, v32, v29
	v_min_u32_e32 v34, v35, v62
	v_max_u32_e32 v29, v32, v29
	v_max_u32_e32 v76, v75, v31
	v_min_u32_e32 v27, v73, v27
	v_min_u32_e32 v23, v72, v23
	v_max3_u32 v15, v15, v21, v22
	v_max_u32_e32 v45, v45, v48
	v_min_u32_e32 v19, v87, v18
	v_max_u32_e32 v18, v87, v18
	v_min_u32_e32 v48, v17, v16
	v_max_u32_e32 v16, v17, v16
	v_min_u32_e32 v32, v29, v34
	v_max_u32_e32 v77, v76, v33
	v_min_u32_e32 v31, v75, v31
	v_min_u32_e32 v25, v74, v25
	v_max3_u32 v15, v15, v23, v27
	v_max_u32_e32 v44, v44, v49
	v_min_u32_e32 v20, v88, v19
	v_max_u32_e32 v19, v88, v19
	v_min_u32_e32 v49, v18, v48
	v_max_u32_e32 v18, v18, v48
	s_waitcnt lgkmcnt(13)
; #define INS32(T, X) { _Pragma("unroll") for (int jj = 0; jj < 16; ++jj) { unsigned t_ = max(T[jj], X); X = min(T[jj], X); T[jj] = t_; } }
; __device__ __forceinline__ void route_task(const Params& p, int layer, const u16* qg, int rb, int hd, int r, int h) {
;     ...
;     for (int jj = 0; jj < 16; ++jj) ot[jj] = (unsigned)__shfl_xor((int)tp[jj], 32);
; #pragma unroll
;     for (int jj = 0; jj < 16; ++jj) { unsigned key = ot[jj]; INS32(tp, key); }
; #pragma unroll
;     for (int jj = 0; jj < 16; ++jj) top[ph][jj] = tp[jj];
	v_min_u32_e32 v17, v16, v13
	v_max_u32_e32 v13, v16, v13
	v_min_u32_e32 v78, v77, v32
	v_min_u32_e32 v33, v76, v33
	v_max3_u32 v15, v15, v25, v31
	v_max_u32_e32 v43, v43, v51
	v_min_u32_e32 v21, v89, v20
	v_max_u32_e32 v20, v89, v20
	v_min_u32_e32 v51, v19, v49
	v_max_u32_e32 v19, v19, v49
	v_min_u32_e32 v48, v18, v17
	v_max_u32_e32 v17, v18, v17
	s_waitcnt lgkmcnt(12)
	v_min_u32_e32 v16, v13, v12
	v_max3_u32 v15, v15, v33, v78
	v_max_u32_e32 v33, v77, v32
	v_add_u32_e32 v32, s34, v52
	v_min_u32_e32 v22, v90, v21
	v_max_u32_e32 v21, v90, v21
	v_min_u32_e32 v52, v20, v51
	v_max_u32_e32 v20, v20, v51
	v_min_u32_e32 v49, v19, v48
	v_max_u32_e32 v19, v19, v48
	v_min_u32_e32 v18, v17, v16
	v_max_u32_e32 v42, v42, v53
	v_min_u32_e32 v23, v91, v22
	v_max_u32_e32 v22, v91, v22
	v_min_u32_e32 v53, v21, v52
	v_max_u32_e32 v21, v21, v52
	v_min_u32_e32 v51, v20, v49
	v_max_u32_e32 v20, v20, v49
	v_min_u32_e32 v48, v19, v18
	v_max_u32_e32 v12, v13, v12
	v_min_u32_e32 v24, v92, v23
	v_max_u32_e32 v23, v92, v23
	v_min_u32_e32 v54, v22, v53
	v_max_u32_e32 v22, v22, v53
	v_min_u32_e32 v52, v21, v51
	v_max_u32_e32 v21, v21, v51
	v_min_u32_e32 v49, v20, v48
	v_max_u32_e32 v16, v17, v16
	s_waitcnt lgkmcnt(11)
	v_min_u32_e32 v13, v12, v11
	v_max_u32_e32 v11, v12, v11
	v_min_u32_e32 v25, v93, v24
	v_max_u32_e32 v24, v93, v24
	v_min_u32_e32 v55, v23, v54
	v_max_u32_e32 v23, v23, v54
	v_min_u32_e32 v53, v22, v52
	v_max_u32_e32 v22, v22, v52
	v_min_u32_e32 v51, v21, v49
	v_min_u32_e32 v17, v16, v13
	v_max_u32_e32 v13, v16, v13
	s_waitcnt lgkmcnt(10)
	v_min_u32_e32 v12, v11, v10
	v_max_u32_e32 v10, v11, v10
	v_max_u32_e32 v41, v41, v56
	v_min_u32_e32 v26, v94, v25
	v_max_u32_e32 v25, v94, v25
	v_min_u32_e32 v56, v24, v55
	v_max_u32_e32 v24, v24, v55
	v_min_u32_e32 v54, v23, v53
	v_max_u32_e32 v23, v23, v53
	v_min_u32_e32 v52, v22, v51
	v_max_u32_e32 v18, v19, v18
	v_min_u32_e32 v16, v13, v12
	v_max_u32_e32 v12, v13, v12
	s_waitcnt lgkmcnt(9)
	v_min_u32_e32 v11, v10, v9
	v_max_u32_e32 v9, v10, v9
	v_max_u32_e32 v40, v40, v57
	v_min_u32_e32 v27, v95, v26
	v_max_u32_e32 v26, v95, v26
	v_min_u32_e32 v57, v25, v56
	v_max_u32_e32 v25, v25, v56
	v_min_u32_e32 v55, v24, v54
	v_max_u32_e32 v24, v24, v54
	v_min_u32_e32 v53, v23, v52
	v_max_u32_e32 v20, v20, v48
	v_min_u32_e32 v19, v18, v17
	v_max_u32_e32 v17, v18, v17
	v_min_u32_e32 v13, v12, v11
	v_max_u32_e32 v11, v12, v11
	s_waitcnt lgkmcnt(8)
	v_min_u32_e32 v10, v9, v8
	v_max_u32_e32 v8, v9, v8
	v_max_u32_e32 v39, v39, v58
	v_min_u32_e32 v28, v96, v27
	v_max_u32_e32 v27, v96, v27
	v_min_u32_e32 v58, v26, v57
	v_max_u32_e32 v26, v26, v57
	v_min_u32_e32 v56, v25, v55
	v_max_u32_e32 v25, v25, v55
	v_min_u32_e32 v54, v24, v53
	v_max_u32_e32 v21, v21, v49
	v_min_u32_e32 v48, v20, v19
	v_max_u32_e32 v19, v20, v19
	v_min_u32_e32 v18, v17, v16
	v_min_u32_e32 v12, v11, v10
	v_max_u32_e32 v10, v11, v10
	s_waitcnt lgkmcnt(7)
	v_min_u32_e32 v9, v8, v7
	v_max_u32_e32 v7, v8, v7
	v_max_u32_e32 v34, v29, v34
	v_max_u32_e32 v38, v38, v59
	v_min_u32_e32 v29, v97, v28
	v_max_u32_e32 v28, v97, v28
	v_min_u32_e32 v59, v27, v58
	v_max_u32_e32 v27, v27, v58
	v_min_u32_e32 v57, v26, v56
	v_max_u32_e32 v26, v26, v56
	v_min_u32_e32 v55, v25, v54
	v_max_u32_e32 v22, v22, v51
	v_min_u32_e32 v49, v21, v48
	v_max_u32_e32 v21, v21, v48
	v_min_u32_e32 v20, v19, v18
	v_min_u32_e32 v11, v10, v9
	v_max_u32_e32 v9, v10, v9
	s_waitcnt lgkmcnt(6)
	v_min_u32_e32 v8, v7, v6
	v_max_u32_e32 v6, v7, v6
	v_max_u32_e32 v37, v37, v60
	v_min_u32_e32 v30, v98, v29
	v_max_u32_e32 v29, v98, v29
	v_min_u32_e32 v60, v28, v59
	v_max_u32_e32 v28, v28, v59
	v_min_u32_e32 v58, v27, v57
	v_max_u32_e32 v27, v27, v57
	v_min_u32_e32 v56, v26, v55
	v_max_u32_e32 v23, v23, v52
	v_min_u32_e32 v51, v22, v49
	v_max_u32_e32 v22, v22, v49
	v_min_u32_e32 v48, v21, v20
	v_max_u32_e32 v16, v17, v16
	v_min_u32_e32 v10, v9, v8
	v_max_u32_e32 v8, v9, v8
	s_waitcnt lgkmcnt(5)
	v_min_u32_e32 v7, v6, v5
	v_max_u32_e32 v5, v6, v5
	v_max_u32_e32 v36, v36, v61
	v_min_u32_e32 v31, v99, v30
	v_max_u32_e32 v30, v99, v30
	v_min_u32_e32 v61, v29, v60
	v_max_u32_e32 v29, v29, v60
	v_min_u32_e32 v59, v28, v58
	v_max_u32_e32 v28, v28, v58
	v_min_u32_e32 v57, v27, v56
	v_max_u32_e32 v24, v24, v53
	v_min_u32_e32 v52, v23, v51
	v_max_u32_e32 v23, v23, v51
	v_min_u32_e32 v49, v22, v48
	v_max_u32_e32 v18, v19, v18
	v_min_u32_e32 v17, v16, v13
	v_max_u32_e32 v13, v16, v13
	v_min_u32_e32 v9, v8, v7
	v_max_u32_e32 v7, v8, v7
	s_waitcnt lgkmcnt(4)
	v_min_u32_e32 v6, v5, v4
	v_max_u32_e32 v4, v5, v4
	v_max_u32_e32 v35, v35, v62
	v_max_u32_e32 v46, v46, v47
	v_min_u32_e32 v47, v100, v31
	v_max_u32_e32 v31, v100, v31
	v_min_u32_e32 v62, v30, v61
	v_max_u32_e32 v30, v30, v61
	v_min_u32_e32 v60, v29, v59
	v_max_u32_e32 v29, v29, v59
	v_min_u32_e32 v58, v28, v57
	v_max_u32_e32 v25, v25, v54
	v_min_u32_e32 v53, v24, v52
	v_max_u32_e32 v24, v24, v52
	v_min_u32_e32 v51, v23, v49
	v_min_u32_e32 v19, v18, v17
	v_max_u32_e32 v17, v18, v17
	v_min_u32_e32 v16, v13, v12
	v_max_u32_e32 v12, v13, v12
	v_min_u32_e32 v8, v7, v6
	v_max_u32_e32 v6, v7, v6
	s_waitcnt lgkmcnt(3)
	v_min_u32_e32 v5, v4, v3
	v_max_u32_e32 v3, v4, v3
	v_min_u32_e32 v63, v31, v62
	v_max_u32_e32 v31, v31, v62
	v_min_u32_e32 v61, v30, v60
	v_max_u32_e32 v30, v30, v60
	v_min_u32_e32 v59, v29, v58
	v_max_u32_e32 v26, v26, v55
	v_min_u32_e32 v54, v25, v53
	v_max_u32_e32 v25, v25, v53
	v_min_u32_e32 v52, v24, v51
	v_min_u32_e32 v18, v17, v16
	v_max_u32_e32 v16, v17, v16
	v_min_u32_e32 v13, v12, v11
	v_max_u32_e32 v11, v12, v11
	v_min_u32_e32 v7, v6, v5
	v_max_u32_e32 v5, v6, v5
	s_waitcnt lgkmcnt(2)
; DI unsigned f2ord(float f) { unsigned u = __float_as_uint(f); return (u & 0x80000000u) ? ~u : (u | 0x80000000u); }
; DI float ord2f(unsigned u) { return __uint_as_float((u & 0x80000000u) ? (u & 0x7fffffffu) : ~u); }
; #define INS32(T, X) { _Pragma("unroll") for (int jj = 0; jj < 16; ++jj) { unsigned t_ = max(T[jj], X); X = min(T[jj], X); T[jj] = t_; } }
; __device__ __forceinline__ void route_task(const Params& p, int layer, const u16* qg, int rb, int hd, int r, int h) {
;     ...
;     for (int jj = 0; jj < 16; ++jj) { unsigned key = ot[jj]; INS32(tp, key); }
;     ...
;     for (int a = 0; a < 16; ++a) {
;       const float va = ord2f(top[0][a] & ~127u);
; #pragma unroll
;       for (int b = 0; b < 16; ++b) {
;         if ((a + 1) * (b + 1) <= 16) {
;           const float vb = ord2f(top[1][b] & ~127u);
;           unsigned key = (f2ord(va + vb) & ~255u) | (unsigned)(255 - (a * 16 + b));
;           INS32(ct, key);
	v_min_u32_e32 v4, v3, v2
	v_max_u32_e32 v2, v3, v2
	v_min_u32_e32 v62, v31, v61
	v_max_u32_e32 v31, v31, v61
	v_min_u32_e32 v60, v30, v59
	v_max_u32_e32 v27, v27, v56
	v_min_u32_e32 v55, v26, v54
	v_max_u32_e32 v26, v26, v54
	v_min_u32_e32 v53, v25, v52
	v_min_u32_e32 v17, v16, v13
	v_max_u32_e32 v13, v16, v13
	v_min_u32_e32 v12, v11, v10
	v_max_u32_e32 v10, v11, v10
	v_min_u32_e32 v6, v5, v4
	v_max_u32_e32 v4, v5, v4
	s_waitcnt lgkmcnt(1)
	v_min_u32_e32 v3, v2, v1
	v_max_u32_e32 v1, v2, v1
	v_max3_u32 v47, v83, v47, v63
	v_min_u32_e32 v61, v31, v60
	v_max_u32_e32 v28, v28, v57
	v_min_u32_e32 v56, v27, v55
	v_max_u32_e32 v27, v27, v55
	v_min_u32_e32 v54, v26, v53
	v_min_u32_e32 v16, v13, v12
	v_max_u32_e32 v12, v13, v12
	v_min_u32_e32 v11, v10, v9
	v_max_u32_e32 v9, v10, v9
	v_min_u32_e32 v5, v4, v3
	v_max_u32_e32 v3, v4, v3
	s_waitcnt lgkmcnt(0)
	v_min_u32_e32 v2, v1, v0
	v_max_u32_e32 v63, v1, v0
	v_max3_u32 v47, v47, v62, v61
	v_max_u32_e32 v29, v29, v58
	v_min_u32_e32 v57, v28, v56
	v_max_u32_e32 v28, v28, v56
	v_min_u32_e32 v55, v27, v54
	v_max_u32_e32 v20, v21, v20
	v_min_u32_e32 v13, v12, v11
	v_max_u32_e32 v11, v12, v11
	v_min_u32_e32 v10, v9, v8
	v_max_u32_e32 v8, v9, v8
	v_max_u32_e32 v62, v3, v2
	v_and_b32_e32 v0, 0x7fffff80, v63
	v_bitop3_b32 v1, v63, s52, v63 bitop3:0xcf
	v_cmp_gt_i32_e32 vcc, 0, v63
	v_max_u32_e32 v30, v30, v59
	v_min_u32_e32 v58, v29, v57
	v_max_u32_e32 v29, v29, v57
	v_min_u32_e32 v56, v28, v55
	v_max_u32_e32 v22, v22, v48
	v_min_u32_e32 v21, v20, v19
	v_max_u32_e32 v19, v20, v19
	v_min_u32_e32 v12, v11, v10
	v_max_u32_e32 v10, v11, v10
	v_min_u32_e32 v9, v8, v7
	v_max_u32_e32 v7, v8, v7
	v_min_u32_e32 v4, v3, v2
	v_max_u32_e32 v50, v14, v50
	v_cndmask_b32_e32 v1, v1, v0, vcc
	v_and_b32_e32 v0, 0x7fffff80, v62
	v_bitop3_b32 v2, v62, s52, v62 bitop3:0xcf
	v_cmp_gt_i32_e32 vcc, 0, v62
	v_max_u32_e32 v31, v31, v60
	v_min_u32_e32 v59, v30, v58
	v_max_u32_e32 v30, v30, v58
	v_min_u32_e32 v57, v29, v56
	v_max_u32_e32 v23, v23, v49
	v_min_u32_e32 v48, v22, v21
	v_max_u32_e32 v21, v22, v21
	v_min_u32_e32 v20, v19, v18
	v_max_u32_e32 v18, v19, v18
	v_min_u32_e32 v11, v10, v9
	v_max_u32_e32 v9, v10, v9
	v_min_u32_e32 v8, v7, v6
	v_max_u32_e32 v6, v7, v6
	v_cndmask_b32_e32 v0, v2, v0, vcc
	v_and_b32_e32 v2, 0x7fffff80, v50
	v_bitop3_b32 v3, v50, s52, v50 bitop3:0xcf
	v_cmp_gt_i32_e32 vcc, 0, v50
	v_min_u32_e32 v60, v31, v59
	v_max_u32_e32 v31, v31, v59
	v_min_u32_e32 v58, v30, v57
	v_max_u32_e32 v24, v24, v51
	v_min_u32_e32 v49, v23, v48
	v_max_u32_e32 v23, v23, v48
	v_min_u32_e32 v22, v21, v20
	v_min_u32_e32 v19, v18, v17
	v_max_u32_e32 v17, v18, v17
	v_min_u32_e32 v10, v9, v8
	v_max_u32_e32 v8, v9, v8
	v_min_u32_e32 v7, v6, v5
	v_max_u32_e32 v5, v6, v5
	v_cndmask_b32_e32 v2, v3, v2, vcc
	v_min_u32_e32 v59, v31, v58
	v_max_u32_e32 v25, v25, v52
	v_min_u32_e32 v51, v24, v49
	v_max_u32_e32 v24, v24, v49
	v_min_u32_e32 v48, v23, v22
	v_min_u32_e32 v18, v17, v16
	v_max_u32_e32 v16, v17, v16
	v_min_u32_e32 v9, v8, v7
	v_max_u32_e32 v7, v8, v7
	v_min_u32_e32 v6, v5, v4
	v_max_u32_e32 v61, v5, v4
	v_pk_add_f32 v[4:5], v[2:3], v[0:1] op_sel_hi:[0,1]
	v_max3_u32 v47, v47, v60, v59
	v_max_u32_e32 v26, v26, v53
	v_min_u32_e32 v52, v25, v51
	v_max_u32_e32 v25, v25, v51
	v_min_u32_e32 v49, v24, v48
	v_max_u32_e32 v20, v21, v20
	v_min_u32_e32 v17, v16, v13
	v_max_u32_e32 v13, v16, v13
	v_min_u32_e32 v8, v7, v6
	v_max_u32_e32 v60, v7, v6
	v_not_b32_e32 v3, v5
	v_or_b32_e32 v6, 0x80000000, v5
	v_cmp_gt_i32_e32 vcc, 0, v5
	v_max_u32_e32 v27, v27, v54
	v_min_u32_e32 v53, v26, v52
	v_max_u32_e32 v26, v26, v52
	v_min_u32_e32 v51, v25, v49
	v_min_u32_e32 v21, v20, v19
	v_max_u32_e32 v19, v20, v19
	v_min_u32_e32 v16, v13, v12
	v_max_u32_e32 v12, v13, v12
	v_cndmask_b32_e32 v3, v6, v3, vcc
	v_max_u32_e32 v28, v28, v55
	v_min_u32_e32 v54, v27, v53
	v_max_u32_e32 v27, v27, v53
	v_min_u32_e32 v52, v26, v51
	v_min_u32_e32 v20, v19, v18
	v_max_u32_e32 v18, v19, v18
	v_min_u32_e32 v13, v12, v11
	v_max_u32_e32 v11, v12, v11
	v_or_b32_e32 v5, 0xff, v3
	v_not_b32_e32 v3, v4
	v_or_b32_e32 v6, 0x80000000, v4
	v_cmp_gt_i32_e32 vcc, 0, v4
	v_max_u32_e32 v29, v29, v56
	v_min_u32_e32 v55, v28, v54
	v_max_u32_e32 v28, v28, v54
	v_min_u32_e32 v53, v27, v52
	v_min_u32_e32 v19, v18, v17
	v_max_u32_e32 v17, v18, v17
	v_min_u32_e32 v12, v11, v10
	v_max_u32_e32 v10, v11, v10
	v_cndmask_b32_e32 v3, v6, v3, vcc
	v_max_u32_e32 v30, v30, v57
	v_min_u32_e32 v56, v29, v55
	v_max_u32_e32 v29, v29, v55
	v_min_u32_e32 v54, v28, v53
	v_min_u32_e32 v18, v17, v16
	v_max_u32_e32 v16, v17, v16
	v_min_u32_e32 v11, v10, v9
	v_max_u32_e32 v9, v10, v9
	v_and_b32_e32 v3, 0xffffff00, v3
	v_max_u32_e32 v31, v31, v58
	v_min_u32_e32 v57, v30, v56
	v_max_u32_e32 v30, v30, v56
	v_min_u32_e32 v55, v29, v54
	v_min_u32_e32 v17, v16, v13
	v_max_u32_e32 v13, v16, v13
	v_min_u32_e32 v10, v9, v8
	v_max_u32_e32 v59, v9, v8
	v_or_b32_e32 v4, 0xfe, v3
	v_and_b32_e32 v3, 0x7fffff80, v61
	v_bitop3_b32 v8, v61, s52, v61 bitop3:0xcf
	v_cmp_gt_i32_e32 vcc, 0, v61
	v_min_u32_e32 v58, v31, v57
	v_max_u32_e32 v31, v31, v57
	v_min_u32_e32 v56, v30, v55
	v_min_u32_e32 v16, v13, v12
	v_max_u32_e32 v12, v13, v12
	v_cndmask_b32_e32 v3, v8, v3, vcc
	v_min_u32_e32 v57, v31, v56
	v_max_u32_e32 v22, v23, v22
	v_min_u32_e32 v13, v12, v11
	v_max_u32_e32 v11, v12, v11
	v_add_f32_e32 v8, v2, v3
	v_max3_u32 v47, v47, v58, v57
	v_min_u32_e32 v23, v22, v21
	v_max_u32_e32 v21, v22, v21
	v_min_u32_e32 v12, v11, v10
	v_max_u32_e32 v58, v11, v10
	v_not_b32_e32 v9, v8
	v_or_b32_e32 v10, 0x80000000, v8
	v_cmp_gt_i32_e32 vcc, 0, v8
	v_min_u32_e32 v22, v21, v20
	v_max_u32_e32 v20, v21, v20
	v_cndmask_b32_e32 v8, v10, v9, vcc
; DI unsigned f2ord(float f) { unsigned u = __float_as_uint(f); return (u & 0x80000000u) ? ~u : (u | 0x80000000u); }
; DI float ord2f(unsigned u) { return __uint_as_float((u & 0x80000000u) ? (u & 0x7fffffffu) : ~u); }
; #define INS32(T, X) { _Pragma("unroll") for (int jj = 0; jj < 16; ++jj) { unsigned t_ = max(T[jj], X); X = min(T[jj], X); T[jj] = t_; } }
; __device__ __forceinline__ void route_task(const Params& p, int layer, const u16* qg, int rb, int hd, int r, int h) {
;     ...
;     for (int a = 0; a < 16; ++a) {
;       const float va = ord2f(top[0][a] & ~127u);
; #pragma unroll
;       for (int b = 0; b < 16; ++b) {
;         if ((a + 1) * (b + 1) <= 16) {
;           const float vb = ord2f(top[1][b] & ~127u);
;           unsigned key = (f2ord(va + vb) & ~255u) | (unsigned)(255 - (a * 16 + b));
;           INS32(ct, key);
;         }
;       }
;     }
	v_min_u32_e32 v21, v20, v19
	v_max_u32_e32 v19, v20, v19
	v_and_b32_e32 v8, 0xffffff00, v8
	v_min_u32_e32 v20, v19, v18
	v_max_u32_e32 v18, v19, v18
	v_max_u32_e32 v7, v5, v4
	v_or_b32_e32 v8, 0xfd, v8
	v_min_u32_e32 v19, v18, v17
	v_max_u32_e32 v17, v18, v17
	v_min_u32_e32 v6, v5, v4
	v_min_u32_e32 v9, v7, v8
	v_med3_u32 v5, v5, v4, v8
	v_max_u32_e32 v7, v7, v8
	v_and_b32_e32 v4, 0x7fffff80, v60
	v_bitop3_b32 v8, v60, s52, v60 bitop3:0xcf
	v_cmp_gt_i32_e32 vcc, 0, v60
	v_min_u32_e32 v18, v17, v16
	v_max_u32_e32 v16, v17, v16
	v_cndmask_b32_e32 v4, v8, v4, vcc
	v_min_u32_e32 v17, v16, v13
	v_max_u32_e32 v13, v16, v13
	v_add_f32_e32 v8, v2, v4
	v_min_u32_e32 v16, v13, v12
	v_max_u32_e32 v57, v13, v12
	v_not_b32_e32 v11, v8
	v_or_b32_e32 v12, 0x80000000, v8
	v_cmp_gt_i32_e32 vcc, 0, v8
	v_min_u32_e32 v10, v6, v9
	v_max_u32_e32 v24, v24, v48
	v_cndmask_b32_e32 v8, v12, v11, vcc
	v_and_b32_e32 v8, 0xffffff00, v8
	v_or_b32_e32 v8, 0xfc, v8
	v_min_u32_e32 v11, v7, v8
	v_min_u32_e32 v12, v5, v11
	v_med3_u32 v6, v6, v9, v11
	v_max_u32_e32 v9, v5, v11
	v_max_u32_e32 v7, v7, v8
	v_and_b32_e32 v5, 0x7fffff80, v59
	v_bitop3_b32 v8, v59, s52, v59 bitop3:0xcf
	v_cmp_gt_i32_e32 vcc, 0, v59
	v_max_u32_e32 v25, v25, v49
	v_min_u32_e32 v48, v24, v23
	v_cndmask_b32_e32 v5, v8, v5, vcc
	v_max_u32_e32 v23, v24, v23
	v_add_f32_e32 v8, v2, v5
	v_max_u32_e32 v26, v26, v51
	v_min_u32_e32 v49, v25, v48
	v_max_u32_e32 v25, v25, v48
	v_min_u32_e32 v24, v23, v22
	v_not_b32_e32 v11, v8
	v_or_b32_e32 v14, 0x80000000, v8
	v_cmp_gt_i32_e32 vcc, 0, v8
	v_max_u32_e32 v27, v27, v52
	v_min_u32_e32 v51, v26, v49
	v_max_u32_e32 v26, v26, v49
	v_min_u32_e32 v48, v25, v24
	v_cndmask_b32_e32 v8, v14, v11, vcc
	v_max_u32_e32 v28, v28, v53
	v_min_u32_e32 v52, v27, v51
	v_max_u32_e32 v27, v27, v51
	v_min_u32_e32 v49, v26, v48
	v_max_u32_e32 v22, v23, v22
	v_and_b32_e32 v8, 0xffffff00, v8
	v_max_u32_e32 v29, v29, v54
	v_min_u32_e32 v53, v28, v52
	v_max_u32_e32 v28, v28, v52
	v_min_u32_e32 v51, v27, v49
	v_min_u32_e32 v23, v22, v21
	v_max_u32_e32 v21, v22, v21
	v_or_b32_e32 v8, 0xfb, v8
	v_max_u32_e32 v30, v30, v55
	v_min_u32_e32 v54, v29, v53
	v_max_u32_e32 v29, v29, v53
	v_min_u32_e32 v52, v28, v51
	v_min_u32_e32 v22, v21, v20
	v_max_u32_e32 v20, v21, v20
	v_min_u32_e32 v11, v7, v8
	v_max_u32_e32 v31, v31, v56
	v_min_u32_e32 v55, v30, v54
	v_max_u32_e32 v30, v30, v54
	v_min_u32_e32 v53, v29, v52
	v_min_u32_e32 v21, v20, v19
	v_max_u32_e32 v19, v20, v19
	v_min_u32_e32 v14, v9, v11
	v_max_u32_e32 v9, v9, v11
	v_max_u32_e32 v7, v7, v8
	v_and_b32_e32 v8, 0x7fffff80, v58
	v_bitop3_b32 v11, v58, s52, v58 bitop3:0xcf
	v_cmp_gt_i32_e32 vcc, 0, v58
	v_min_u32_e32 v56, v31, v55
	v_max_u32_e32 v31, v31, v55
	v_min_u32_e32 v54, v30, v53
	v_min_u32_e32 v20, v19, v18
	v_max_u32_e32 v18, v19, v18
	v_cndmask_b32_e32 v8, v11, v8, vcc
	v_min_u32_e32 v55, v31, v54
	v_min_u32_e32 v19, v18, v17
	v_max_u32_e32 v17, v18, v17
	v_add_f32_e32 v11, v2, v8
	v_max3_u32 v47, v47, v56, v55
	v_min_u32_e32 v18, v17, v16
	v_max_u32_e32 v56, v17, v16
	v_min_u32_e32 v13, v10, v12
	v_min_u32_e32 v16, v6, v14
	v_med3_u32 v10, v10, v12, v14
	v_max_u32_e32 v6, v6, v14
	v_not_b32_e32 v12, v11
	v_or_b32_e32 v14, 0x80000000, v11
	v_cmp_gt_i32_e32 vcc, 0, v11
	v_max_u32_e32 v24, v25, v24
	v_min_u32_e32 v25, v24, v23
	v_cndmask_b32_e32 v11, v14, v12, vcc
	v_max_u32_e32 v23, v24, v23
	v_and_b32_e32 v11, 0xffffff00, v11
	v_min_u32_e32 v24, v23, v22
	v_max_u32_e32 v22, v23, v22
	v_or_b32_e32 v11, 0xfa, v11
	v_min_u32_e32 v23, v22, v21
	v_max_u32_e32 v21, v22, v21
	v_min_u32_e32 v12, v7, v11
	v_min_u32_e32 v22, v21, v20
	v_max_u32_e32 v20, v21, v20
	v_min_u32_e32 v14, v9, v12
	v_max_u32_e32 v9, v9, v12
	v_max_u32_e32 v11, v7, v11
	v_and_b32_e32 v7, 0x7fffff80, v57
	v_bitop3_b32 v12, v57, s52, v57 bitop3:0xcf
	v_cmp_gt_i32_e32 vcc, 0, v57
	v_min_u32_e32 v21, v20, v19
	v_max_u32_e32 v19, v20, v19
	v_cndmask_b32_e32 v7, v12, v7, vcc
	v_min_u32_e32 v20, v19, v18
	v_max_u32_e32 v55, v19, v18
	v_min_u32_e32 v18, v6, v14
	v_add_f32_e32 v12, v2, v7
	v_min_u32_e32 v17, v13, v16
	v_med3_u32 v13, v13, v16, v18
	v_max_u32_e32 v6, v6, v14
	v_not_b32_e32 v14, v12
	v_or_b32_e32 v16, 0x80000000, v12
	v_cmp_gt_i32_e32 vcc, 0, v12
	v_max_u32_e32 v26, v26, v48
	v_max_u32_e32 v27, v27, v49
	v_cndmask_b32_e32 v12, v16, v14, vcc
	v_min_u32_e32 v48, v26, v25
	v_max_u32_e32 v25, v26, v25
	v_and_b32_e32 v12, 0xffffff00, v12
	v_max_u32_e32 v28, v28, v51
	v_min_u32_e32 v49, v27, v48
	v_max_u32_e32 v27, v27, v48
	v_min_u32_e32 v26, v25, v24
	v_or_b32_e32 v12, 0xf9, v12
	v_max_u32_e32 v29, v29, v52
	v_min_u32_e32 v51, v28, v49
	v_max_u32_e32 v28, v28, v49
	v_min_u32_e32 v48, v27, v26
	v_min_u32_e32 v14, v11, v12
	v_max_u32_e32 v30, v30, v53
	v_min_u32_e32 v52, v29, v51
	v_max_u32_e32 v29, v29, v51
	v_min_u32_e32 v49, v28, v48
	v_max_u32_e32 v24, v25, v24
	v_min_u32_e32 v16, v9, v14
	v_max_u32_e32 v31, v31, v54
	v_min_u32_e32 v53, v30, v52
	v_max_u32_e32 v30, v30, v52
	v_min_u32_e32 v51, v29, v49
	v_min_u32_e32 v25, v24, v23
	v_max_u32_e32 v23, v24, v23
	v_min_u32_e32 v19, v10, v18
	v_max_u32_e32 v10, v10, v18
	v_min_u32_e32 v18, v6, v16
	v_max_u32_e32 v16, v6, v16
	v_max_u32_e32 v11, v11, v12
	v_and_b32_e32 v6, 0x7fffff80, v56
	v_bitop3_b32 v12, v56, s52, v56 bitop3:0xcf
	v_cmp_gt_i32_e32 vcc, 0, v56
	v_min_u32_e32 v54, v31, v53
	v_max_u32_e32 v31, v31, v53
	v_min_u32_e32 v52, v30, v51
	v_min_u32_e32 v24, v23, v22
	v_max_u32_e32 v22, v23, v22
	v_cndmask_b32_e32 v6, v12, v6, vcc
	v_min_u32_e32 v53, v31, v52
	v_min_u32_e32 v23, v22, v21
	v_max_u32_e32 v21, v22, v21
	v_add_f32_e32 v12, v2, v6
	v_max3_u32 v47, v47, v54, v53
	v_min_u32_e32 v22, v21, v20
; DI unsigned f2ord(float f) { unsigned u = __float_as_uint(f); return (u & 0x80000000u) ? ~u : (u | 0x80000000u); }
; DI float ord2f(unsigned u) { return __uint_as_float((u & 0x80000000u) ? (u & 0x7fffffffu) : ~u); }
; #define INS32(T, X) { _Pragma("unroll") for (int jj = 0; jj < 16; ++jj) { unsigned t_ = max(T[jj], X); X = min(T[jj], X); T[jj] = t_; } }
; __device__ __forceinline__ void route_task(const Params& p, int layer, const u16* qg, int rb, int hd, int r, int h) {
;     ...
;     for (int a = 0; a < 16; ++a) {
;       const float va = ord2f(top[0][a] & ~127u);
; #pragma unroll
;       for (int b = 0; b < 16; ++b) {
;         if ((a + 1) * (b + 1) <= 16) {
;           const float vb = ord2f(top[1][b] & ~127u);
;           unsigned key = (f2ord(va + vb) & ~255u) | (unsigned)(255 - (a * 16 + b));
;           INS32(ct, key);
;         }
;       }
;     }
	v_max_u32_e32 v54, v21, v20
	v_min_u32_e32 v21, v10, v18
	v_max_u32_e32 v10, v10, v18
	v_max_u32_e32 v9, v9, v14
	v_not_b32_e32 v14, v12
	v_or_b32_e32 v18, 0x80000000, v12
	v_cmp_gt_i32_e32 vcc, 0, v12
	v_min_u32_e32 v20, v17, v19
	v_med3_u32 v17, v17, v19, v21
	v_cndmask_b32_e32 v12, v18, v14, vcc
	v_and_b32_e32 v12, 0xffffff00, v12
	v_or_b32_e32 v12, 0xf8, v12
	v_min_u32_e32 v14, v11, v12
	v_min_u32_e32 v18, v9, v14
	v_max_u32_e32 v9, v9, v14
	v_max_u32_e32 v11, v11, v12
	v_and_b32_e32 v12, 0x7fffff80, v55
	v_bitop3_b32 v14, v55, s52, v55 bitop3:0xcf
	v_cmp_gt_i32_e32 vcc, 0, v55
	v_min_u32_e32 v19, v16, v18
	v_max_u32_e32 v16, v16, v18
	v_cndmask_b32_e32 v12, v14, v12, vcc
	v_add_f32_e32 v12, v2, v12
	v_not_b32_e32 v14, v12
	v_or_b32_e32 v18, 0x80000000, v12
	v_cmp_gt_i32_e32 vcc, 0, v12
	v_max_u32_e32 v26, v27, v26
	v_min_u32_e32 v27, v26, v25
	v_cndmask_b32_e32 v12, v18, v14, vcc
	v_and_b32_e32 v12, 0xffffff00, v12
	v_or_b32_e32 v12, 0xf7, v12
	v_min_u32_e32 v14, v11, v12
	v_max_u32_e32 v25, v26, v25
	v_min_u32_e32 v18, v9, v14
	v_max_u32_e32 v9, v9, v14
	v_max_u32_e32 v11, v11, v12
	v_and_b32_e32 v12, 0x7fffff80, v54
	v_bitop3_b32 v14, v54, s52, v54 bitop3:0xcf
	v_cmp_gt_i32_e32 vcc, 0, v54
	v_min_u32_e32 v26, v25, v24
	v_max_u32_e32 v24, v25, v24
	v_cndmask_b32_e32 v12, v14, v12, vcc
	v_min_u32_e32 v25, v24, v23
	v_max_u32_e32 v23, v24, v23
	v_add_f32_e32 v12, v2, v12
	v_min_u32_e32 v24, v23, v22
	v_max_u32_e32 v53, v23, v22
	v_min_u32_e32 v22, v13, v21
	v_max_u32_e32 v13, v13, v21
	v_min_u32_e32 v21, v10, v19
	v_max_u32_e32 v10, v10, v19
	v_min_u32_e32 v19, v16, v18
	v_max_u32_e32 v16, v16, v18
	v_not_b32_e32 v14, v12
	v_or_b32_e32 v18, 0x80000000, v12
	v_cmp_gt_i32_e32 vcc, 0, v12
	v_max_u32_e32 v28, v28, v48
	v_max_u32_e32 v29, v29, v49
	v_cndmask_b32_e32 v12, v18, v14, vcc
	v_and_b32_e32 v12, 0xffffff00, v12
	v_min_u32_e32 v48, v28, v27
	v_max_u32_e32 v27, v28, v27
	v_or_b32_e32 v12, 0xf6, v12
	v_max_u32_e32 v30, v30, v51
	v_min_u32_e32 v49, v29, v48
	v_max_u32_e32 v29, v29, v48
	v_min_u32_e32 v28, v27, v26
	v_min_u32_e32 v14, v11, v12
	v_max_u32_e32 v31, v31, v52
	v_min_u32_e32 v51, v30, v49
	v_max_u32_e32 v30, v30, v49
	v_min_u32_e32 v48, v29, v28
	v_min_u32_e32 v18, v9, v14
	v_max_u32_e32 v9, v9, v14
	v_max_u32_e32 v11, v11, v12
	v_and_b32_e32 v12, 0x7fffff80, v53
	v_bitop3_b32 v14, v53, s52, v53 bitop3:0xcf
	v_cmp_gt_i32_e32 vcc, 0, v53
	v_min_u32_e32 v52, v31, v51
	v_max_u32_e32 v31, v31, v51
	v_min_u32_e32 v49, v30, v48
	v_max_u32_e32 v26, v27, v26
	v_cndmask_b32_e32 v12, v14, v12, vcc
	v_min_u32_e32 v51, v31, v49
	v_min_u32_e32 v27, v26, v25
	v_max_u32_e32 v25, v26, v25
	v_add_f32_e32 v12, v2, v12
	v_max3_u32 v47, v47, v52, v51
	v_min_u32_e32 v26, v25, v24
	v_max_u32_e32 v52, v25, v24
	v_min_u32_e32 v24, v13, v21
	v_max_u32_e32 v13, v13, v21
	v_min_u32_e32 v21, v10, v19
	v_max_u32_e32 v10, v10, v19
	v_min_u32_e32 v19, v16, v18
	v_max_u32_e32 v16, v16, v18
	v_not_b32_e32 v14, v12
	v_or_b32_e32 v18, 0x80000000, v12
	v_cmp_gt_i32_e32 vcc, 0, v12
	v_min_u32_e32 v23, v20, v22
	v_med3_u32 v20, v20, v22, v24
	v_cndmask_b32_e32 v12, v18, v14, vcc
	v_and_b32_e32 v12, 0xffffff00, v12
	v_or_b32_e32 v12, 0xf5, v12
	v_min_u32_e32 v14, v11, v12
	v_min_u32_e32 v18, v9, v14
	v_max_u32_e32 v9, v9, v14
	v_max_u32_e32 v11, v11, v12
	v_and_b32_e32 v12, 0x7fffff80, v52
	v_bitop3_b32 v14, v52, s52, v52 bitop3:0xcf
	v_cmp_gt_i32_e32 vcc, 0, v52
	v_min_u32_e32 v22, v13, v21
	v_max_u32_e32 v13, v13, v21
	v_cndmask_b32_e32 v12, v14, v12, vcc
	v_add_f32_e32 v12, v2, v12
	v_min_u32_e32 v21, v10, v19
	v_max_u32_e32 v10, v10, v19
	v_min_u32_e32 v19, v16, v18
	v_max_u32_e32 v16, v16, v18
	v_not_b32_e32 v14, v12
	v_or_b32_e32 v18, 0x80000000, v12
	v_cmp_gt_i32_e32 vcc, 0, v12
	v_max_u32_e32 v28, v29, v28
	v_min_u32_e32 v29, v28, v27
	v_cndmask_b32_e32 v12, v18, v14, vcc
	v_and_b32_e32 v12, 0xffffff00, v12
	v_max_u32_e32 v27, v28, v27
	v_or_b32_e32 v12, 0xf4, v12
	v_max_u32_e32 v51, v27, v26
	v_min_u32_e32 v14, v11, v12
	v_min_u32_e32 v18, v9, v14
	v_max_u32_e32 v9, v9, v14
	v_max_u32_e32 v11, v11, v12
	v_and_b32_e32 v12, 0x7fffff80, v51
	v_bitop3_b32 v14, v51, s52, v51 bitop3:0xcf
	v_cmp_gt_i32_e32 vcc, 0, v51
	v_min_u32_e32 v25, v17, v24
	v_max_u32_e32 v17, v17, v24
	v_cndmask_b32_e32 v12, v14, v12, vcc
	v_add_f32_e32 v12, v2, v12
	v_max_u32_e32 v30, v30, v48
	v_min_u32_e32 v24, v17, v22
	v_max_u32_e32 v17, v17, v22
	v_min_u32_e32 v22, v13, v21
	v_max_u32_e32 v13, v13, v21
	v_min_u32_e32 v21, v10, v19
	v_max_u32_e32 v10, v10, v19
	v_min_u32_e32 v19, v16, v18
	v_max_u32_e32 v16, v16, v18
	v_not_b32_e32 v14, v12
	v_or_b32_e32 v18, 0x80000000, v12
	v_cmp_gt_i32_e32 vcc, 0, v12
	v_max_u32_e32 v31, v31, v49
	v_min_u32_e32 v48, v30, v29
	v_max_u32_e32 v29, v30, v29
	v_min_u32_e32 v28, v27, v26
	v_cndmask_b32_e32 v12, v18, v14, vcc
	v_min_u32_e32 v49, v31, v48
	v_max_u32_e32 v31, v31, v48
	v_min_u32_e32 v30, v29, v28
	v_and_b32_e32 v12, 0xffffff00, v12
	v_min_u32_e32 v48, v31, v30
	v_or_b32_e32 v12, 0xf3, v12
	v_max3_u32 v47, v47, v49, v48
	v_max_u32_e32 v49, v29, v28
	v_min_u32_e32 v14, v11, v12
	v_min_u32_e32 v18, v9, v14
	v_max_u32_e32 v9, v9, v14
	v_max_u32_e32 v11, v11, v12
	v_and_b32_e32 v12, 0x7fffff80, v49
	v_bitop3_b32 v14, v49, s52, v49 bitop3:0xcf
	v_cmp_gt_i32_e32 vcc, 0, v49
	v_min_u32_e32 v26, v23, v25
	v_min_u32_e32 v27, v20, v24
	v_cndmask_b32_e32 v12, v14, v12, vcc
	v_add_f32_e32 v12, v2, v12
	v_med3_u32 v23, v23, v25, v24
	v_max_u32_e32 v20, v20, v24
	v_min_u32_e32 v24, v17, v22
	v_max_u32_e32 v17, v17, v22
	v_min_u32_e32 v22, v13, v21
	v_max_u32_e32 v13, v13, v21
	v_min_u32_e32 v21, v10, v19
	v_max_u32_e32 v10, v10, v19
; DI unsigned f2ord(float f) { unsigned u = __float_as_uint(f); return (u & 0x80000000u) ? ~u : (u | 0x80000000u); }
; DI float ord2f(unsigned u) { return __uint_as_float((u & 0x80000000u) ? (u & 0x7fffffffu) : ~u); }
; #define INS32(T, X) { _Pragma("unroll") for (int jj = 0; jj < 16; ++jj) { unsigned t_ = max(T[jj], X); X = min(T[jj], X); T[jj] = t_; } }
; __device__ __forceinline__ void route_task(const Params& p, int layer, const u16* qg, int rb, int hd, int r, int h) {
;     ...
;     for (int a = 0; a < 16; ++a) {
;       const float va = ord2f(top[0][a] & ~127u);
; #pragma unroll
;       for (int b = 0; b < 16; ++b) {
;         if ((a + 1) * (b + 1) <= 16) {
;           const float vb = ord2f(top[1][b] & ~127u);
;           unsigned key = (f2ord(va + vb) & ~255u) | (unsigned)(255 - (a * 16 + b));
;           INS32(ct, key);
;         }
;       }
;     }
	v_min_u32_e32 v19, v16, v18
	v_max_u32_e32 v16, v16, v18
	v_not_b32_e32 v14, v12
	v_or_b32_e32 v18, 0x80000000, v12
	v_cmp_gt_i32_e32 vcc, 0, v12
	v_max_u32_e32 v48, v31, v30
	v_min_u32_e32 v25, v20, v24
	v_cndmask_b32_e32 v12, v18, v14, vcc
	v_and_b32_e32 v12, 0xffffff00, v12
	v_or_b32_e32 v12, 0xf2, v12
	v_min_u32_e32 v14, v11, v12
	v_min_u32_e32 v18, v9, v14
	v_max_u32_e32 v9, v9, v14
	v_max_u32_e32 v11, v11, v12
	v_and_b32_e32 v12, 0x7fffff80, v48
	v_bitop3_b32 v14, v48, s52, v48 bitop3:0xcf
	v_cmp_gt_i32_e32 vcc, 0, v48
	v_max_u32_e32 v20, v20, v24
	v_min_u32_e32 v24, v17, v22
	v_cndmask_b32_e32 v12, v14, v12, vcc
	v_add_f32_e32 v12, v2, v12
	v_max_u32_e32 v17, v17, v22
	v_min_u32_e32 v22, v13, v21
	v_max_u32_e32 v13, v13, v21
	v_min_u32_e32 v21, v10, v19
	v_max_u32_e32 v10, v10, v19
	v_min_u32_e32 v19, v16, v18
	v_max_u32_e32 v16, v16, v18
	v_not_b32_e32 v14, v12
	v_or_b32_e32 v18, 0x80000000, v12
	v_cmp_gt_i32_e32 vcc, 0, v12
	v_min_u32_e32 v28, v26, v27
	v_min_u32_e32 v29, v23, v25
	v_cndmask_b32_e32 v12, v18, v14, vcc
	v_and_b32_e32 v12, 0xffffff00, v12
	v_or_b32_e32 v12, 0xf1, v12
	v_min_u32_e32 v14, v11, v12
	v_min_u32_e32 v18, v9, v14
	v_max_u32_e32 v9, v9, v14
	v_max_u32_e32 v11, v11, v12
	v_and_b32_e32 v12, 0x7fffff80, v47
	v_bitop3_b32 v14, v47, s52, v47 bitop3:0xcf
	v_cmp_gt_i32_e32 vcc, 0, v47
	v_med3_u32 v26, v26, v27, v25
	v_max_u32_e32 v23, v23, v25
	v_cndmask_b32_e32 v12, v14, v12, vcc
	v_add_f32_e32 v2, v2, v12
	v_not_b32_e32 v12, v2
	v_or_b32_e32 v14, 0x80000000, v2
	v_cmp_gt_i32_e32 vcc, 0, v2
	v_min_u32_e32 v25, v20, v24
	v_max_u32_e32 v20, v20, v24
	v_cndmask_b32_e32 v2, v14, v12, vcc
	v_and_b32_e32 v2, 0xffffff00, v2
	v_or_b32_e32 v2, 0xf0, v2
	v_min_u32_e32 v12, v11, v2
	v_min_u32_e32 v14, v9, v12
	v_max_u32_e32 v9, v9, v12
	v_max_u32_e32 v2, v11, v2
	v_and_b32_e32 v11, 0x7fffff80, v46
	v_bitop3_b32 v12, v46, s52, v46 bitop3:0xcf
	v_cmp_gt_i32_e32 vcc, 0, v46
	v_min_u32_e32 v24, v17, v22
	v_max_u32_e32 v17, v17, v22
	v_min_u32_e32 v22, v13, v21
	v_max_u32_e32 v13, v13, v21
	v_min_u32_e32 v21, v10, v19
	v_max_u32_e32 v10, v10, v19
	v_min_u32_e32 v19, v16, v18
	v_max_u32_e32 v16, v16, v18
	v_cndmask_b32_e32 v11, v12, v11, vcc
	v_min_u32_e32 v27, v23, v25
	v_max_u32_e32 v23, v23, v25
	v_min_u32_e32 v25, v20, v24
	v_max_u32_e32 v20, v20, v24
	v_min_u32_e32 v24, v17, v22
	v_max_u32_e32 v17, v17, v22
	v_min_u32_e32 v22, v13, v21
	v_max_u32_e32 v13, v13, v21
	v_min_u32_e32 v21, v10, v19
	v_max_u32_e32 v10, v10, v19
	v_min_u32_e32 v18, v16, v14
	v_add_f32_e32 v12, v11, v1
	v_min_u32_e32 v19, v10, v18
	v_max_u32_e32 v10, v10, v18
	v_max_u32_e32 v14, v16, v14
	v_not_b32_e32 v16, v12
	v_or_b32_e32 v18, 0x80000000, v12
	v_cmp_gt_i32_e32 vcc, 0, v12
	v_min_u32_e32 v30, v28, v29
	v_min_u32_e32 v31, v26, v27
	v_cndmask_b32_e32 v12, v18, v16, vcc
	v_and_b32_e32 v12, 0xffffff00, v12
	v_or_b32_e32 v12, 0xef, v12
	v_min_u32_e32 v16, v2, v12
	v_med3_u32 v28, v28, v29, v27
	v_max_u32_e32 v26, v26, v27
	v_min_u32_e32 v27, v23, v25
	v_max_u32_e32 v23, v23, v25
	v_min_u32_e32 v25, v20, v24
	v_max_u32_e32 v20, v20, v24
	v_min_u32_e32 v24, v17, v22
	v_max_u32_e32 v17, v17, v22
	v_min_u32_e32 v22, v13, v21
	v_max_u32_e32 v13, v13, v21
	v_min_u32_e32 v18, v9, v16
	v_max_u32_e32 v2, v2, v12
	v_add_f32_e32 v12, v11, v0
	v_min_u32_e32 v21, v13, v19
	v_max_u32_e32 v13, v13, v19
	v_min_u32_e32 v19, v14, v18
	v_max_u32_e32 v14, v14, v18
	v_max_u32_e32 v9, v9, v16
	v_not_b32_e32 v16, v12
	v_or_b32_e32 v18, 0x80000000, v12
	v_cmp_gt_i32_e32 vcc, 0, v12
	v_min_u32_e32 v29, v26, v27
	v_max_u32_e32 v26, v26, v27
	v_cndmask_b32_e32 v12, v18, v16, vcc
	v_and_b32_e32 v12, 0xffffff00, v12
	v_or_b32_e32 v12, 0xee, v12
	v_min_u32_e32 v16, v2, v12
	v_min_u32_e32 v27, v23, v25
	v_max_u32_e32 v23, v23, v25
	v_min_u32_e32 v25, v20, v24
	v_max_u32_e32 v20, v20, v24
	v_min_u32_e32 v24, v17, v22
	v_max_u32_e32 v17, v17, v22
	v_min_u32_e32 v18, v9, v16
	v_max_u32_e32 v2, v2, v12
	v_add_f32_e32 v12, v11, v3
	v_min_u32_e32 v22, v17, v21
	v_max_u32_e32 v17, v17, v21
	v_min_u32_e32 v21, v10, v19
	v_max_u32_e32 v10, v10, v19
	v_min_u32_e32 v19, v14, v18
	v_max_u32_e32 v14, v14, v18
	v_max_u32_e32 v9, v9, v16
	v_not_b32_e32 v16, v12
	v_or_b32_e32 v18, 0x80000000, v12
	v_cmp_gt_i32_e32 vcc, 0, v12
	v_min_u32_e32 v64, v30, v31
	v_min_u32_e32 v65, v28, v29
	v_cndmask_b32_e32 v12, v18, v16, vcc
	v_and_b32_e32 v12, 0xffffff00, v12
	v_or_b32_e32 v12, 0xed, v12
	v_min_u32_e32 v16, v2, v12
	v_med3_u32 v30, v30, v31, v29
	v_max_u32_e32 v28, v28, v29
	v_min_u32_e32 v29, v26, v27
	v_max_u32_e32 v26, v26, v27
	v_min_u32_e32 v27, v23, v25
	v_max_u32_e32 v23, v23, v25
	v_min_u32_e32 v25, v20, v24
	v_max_u32_e32 v20, v20, v24
	v_min_u32_e32 v18, v9, v16
	v_max_u32_e32 v2, v2, v12
	v_add_f32_e32 v12, v11, v4
	v_min_u32_e32 v24, v20, v22
	v_max_u32_e32 v20, v20, v22
	v_min_u32_e32 v22, v13, v21
	v_max_u32_e32 v13, v13, v21
	v_min_u32_e32 v21, v10, v19
	v_max_u32_e32 v10, v10, v19
	v_min_u32_e32 v19, v14, v18
	v_max_u32_e32 v14, v14, v18
	v_max_u32_e32 v9, v9, v16
	v_not_b32_e32 v16, v12
	v_or_b32_e32 v18, 0x80000000, v12
	v_cmp_gt_i32_e32 vcc, 0, v12
	v_min_u32_e32 v31, v28, v29
	v_max_u32_e32 v28, v28, v29
	v_cndmask_b32_e32 v12, v18, v16, vcc
	v_and_b32_e32 v12, 0xffffff00, v12
	v_or_b32_e32 v12, 0xec, v12
	v_min_u32_e32 v16, v2, v12
	v_min_u32_e32 v29, v26, v27
	v_max_u32_e32 v26, v26, v27
	v_min_u32_e32 v27, v23, v25
	v_max_u32_e32 v23, v23, v25
	v_min_u32_e32 v18, v9, v16
	v_max_u32_e32 v2, v2, v12
	v_add_f32_e32 v12, v11, v5
	v_min_u32_e32 v25, v23, v24
	v_max_u32_e32 v23, v23, v24
	v_min_u32_e32 v24, v17, v22
	v_max_u32_e32 v17, v17, v22
	v_min_u32_e32 v22, v13, v21
; DI unsigned f2ord(float f) { unsigned u = __float_as_uint(f); return (u & 0x80000000u) ? ~u : (u | 0x80000000u); }
; DI float ord2f(unsigned u) { return __uint_as_float((u & 0x80000000u) ? (u & 0x7fffffffu) : ~u); }
; #define INS32(T, X) { _Pragma("unroll") for (int jj = 0; jj < 16; ++jj) { unsigned t_ = max(T[jj], X); X = min(T[jj], X); T[jj] = t_; } }
; __device__ __forceinline__ void route_task(const Params& p, int layer, const u16* qg, int rb, int hd, int r, int h) {
;     ...
;     for (int a = 0; a < 16; ++a) {
;       const float va = ord2f(top[0][a] & ~127u);
; #pragma unroll
;       for (int b = 0; b < 16; ++b) {
;         if ((a + 1) * (b + 1) <= 16) {
;           const float vb = ord2f(top[1][b] & ~127u);
;           unsigned key = (f2ord(va + vb) & ~255u) | (unsigned)(255 - (a * 16 + b));
;           INS32(ct, key);
;         }
;       }
;     }
	v_max_u32_e32 v13, v13, v21
	v_min_u32_e32 v21, v10, v19
	v_max_u32_e32 v10, v10, v19
	v_min_u32_e32 v19, v14, v18
	v_max_u32_e32 v14, v14, v18
	v_max_u32_e32 v9, v9, v16
	v_not_b32_e32 v16, v12
	v_or_b32_e32 v18, 0x80000000, v12
	v_cmp_gt_i32_e32 vcc, 0, v12
	v_add_f32_e32 v8, v11, v8
	v_add_f32_e32 v7, v11, v7
	v_cndmask_b32_e32 v12, v18, v16, vcc
	v_and_b32_e32 v12, 0xffffff00, v12
	v_or_b32_e32 v12, 0xeb, v12
	v_min_u32_e32 v16, v2, v12
	v_min_u32_e32 v18, v9, v16
	v_max_u32_e32 v9, v9, v16
	v_max_u32_e32 v2, v2, v12
	v_not_b32_e32 v12, v8
	v_or_b32_e32 v16, 0x80000000, v8
	v_cmp_gt_i32_e32 vcc, 0, v8
	v_add_f32_e32 v6, v11, v6
	v_min_u32_e32 v66, v64, v65
	v_cndmask_b32_e32 v8, v16, v12, vcc
	v_and_b32_e32 v8, 0xffffff00, v8
	v_or_b32_e32 v8, 0xea, v8
	v_min_u32_e32 v12, v2, v8
	v_min_u32_e32 v16, v9, v12
	v_max_u32_e32 v9, v9, v12
	v_max_u32_e32 v2, v2, v8
	v_not_b32_e32 v8, v7
	v_or_b32_e32 v12, 0x80000000, v7
	v_cmp_gt_i32_e32 vcc, 0, v7
	v_min_u32_e32 v67, v30, v31
	v_med3_u32 v64, v64, v65, v31
	v_cndmask_b32_e32 v7, v12, v8, vcc
	v_and_b32_e32 v7, 0xffffff00, v7
	v_or_b32_e32 v7, 0xe9, v7
	v_min_u32_e32 v8, v2, v7
	v_min_u32_e32 v12, v9, v8
	v_max_u32_e32 v8, v9, v8
	v_max_u32_e32 v2, v2, v7
	v_not_b32_e32 v7, v6
	v_or_b32_e32 v9, 0x80000000, v6
	v_cmp_gt_i32_e32 vcc, 0, v6
	v_max_u32_e32 v30, v30, v31
	v_min_u32_e32 v31, v28, v29
	v_cndmask_b32_e32 v6, v9, v7, vcc
	v_and_b32_e32 v6, 0xffffff00, v6
	v_max_u32_e32 v28, v28, v29
	v_min_u32_e32 v29, v26, v27
	v_max_u32_e32 v26, v26, v27
	v_or_b32_e32 v6, 0xe8, v6
	v_min_u32_e32 v65, v30, v31
	v_max_u32_e32 v30, v30, v31
	v_min_u32_e32 v31, v28, v29
	v_max_u32_e32 v28, v28, v29
	v_min_u32_e32 v27, v26, v25
	v_max_u32_e32 v25, v26, v25
	v_min_u32_e32 v26, v20, v24
	v_max_u32_e32 v20, v20, v24
	v_min_u32_e32 v24, v17, v22
	v_max_u32_e32 v17, v17, v22
	v_min_u32_e32 v22, v13, v21
	v_max_u32_e32 v13, v13, v21
	v_min_u32_e32 v21, v10, v19
	v_max_u32_e32 v10, v10, v19
	v_min_u32_e32 v19, v14, v18
	v_max_u32_e32 v14, v14, v18
	v_min_u32_e32 v7, v2, v6
	v_min_u32_e32 v29, v28, v27
	v_max_u32_e32 v27, v28, v27
	v_min_u32_e32 v28, v23, v26
	v_max_u32_e32 v23, v23, v26
	v_min_u32_e32 v26, v20, v24
	v_max_u32_e32 v20, v20, v24
	v_min_u32_e32 v24, v17, v22
	v_max_u32_e32 v17, v17, v22
	v_min_u32_e32 v22, v13, v21
	v_max_u32_e32 v13, v13, v21
	v_min_u32_e32 v21, v10, v19
	v_max_u32_e32 v10, v10, v19
	v_min_u32_e32 v18, v14, v16
	v_max_u32_e32 v14, v14, v16
	v_min_u32_e32 v9, v8, v7
	v_max_u32_e32 v7, v8, v7
	v_max_u32_e32 v2, v2, v6
	v_and_b32_e32 v6, 0x7fffff80, v45
	v_bitop3_b32 v8, v45, s52, v45 bitop3:0xcf
	v_cmp_gt_i32_e32 vcc, 0, v45
	v_min_u32_e32 v19, v10, v18
	v_max_u32_e32 v10, v10, v18
	v_min_u32_e32 v16, v14, v12
	v_max_u32_e32 v12, v14, v12
	v_cndmask_b32_e32 v6, v8, v6, vcc
	v_min_u32_e32 v18, v10, v16
	v_max_u32_e32 v10, v10, v16
	v_min_u32_e32 v11, v12, v9
	v_add_f32_e32 v8, v6, v1
	v_min_u32_e32 v14, v10, v11
	v_max_u32_e32 v10, v10, v11
	v_max_u32_e32 v9, v12, v9
	v_not_b32_e32 v11, v8
	v_or_b32_e32 v12, 0x80000000, v8
	v_cmp_gt_i32_e32 vcc, 0, v8
	v_min_u32_e32 v68, v66, v67
	v_min_u32_e32 v69, v64, v65
	v_cndmask_b32_e32 v8, v12, v11, vcc
	v_med3_u32 v66, v66, v67, v65
	v_max_u32_e32 v64, v64, v65
	v_min_u32_e32 v65, v30, v31
	v_max_u32_e32 v30, v30, v31
	v_and_b32_e32 v8, 0xffffff00, v8
	v_min_u32_e32 v31, v30, v29
	v_max_u32_e32 v29, v30, v29
	v_min_u32_e32 v30, v25, v28
	v_max_u32_e32 v25, v25, v28
	v_min_u32_e32 v28, v23, v26
	v_max_u32_e32 v23, v23, v26
	v_min_u32_e32 v26, v20, v24
	v_max_u32_e32 v20, v20, v24
	v_min_u32_e32 v24, v17, v22
	v_max_u32_e32 v17, v17, v22
	v_min_u32_e32 v22, v13, v21
	v_max_u32_e32 v13, v13, v21
	v_or_b32_e32 v8, 0xdf, v8
	v_min_u32_e32 v21, v13, v19
	v_max_u32_e32 v13, v13, v19
	v_min_u32_e32 v11, v2, v8
	v_min_u32_e32 v19, v13, v18
	v_max_u32_e32 v13, v13, v18
	v_min_u32_e32 v12, v7, v11
	v_max_u32_e32 v2, v2, v8
	v_add_f32_e32 v8, v6, v0
	v_min_u32_e32 v16, v13, v14
	v_max_u32_e32 v13, v13, v14
	v_min_u32_e32 v14, v9, v12
	v_max_u32_e32 v9, v9, v12
	v_max_u32_e32 v7, v7, v11
	v_not_b32_e32 v11, v8
	v_or_b32_e32 v12, 0x80000000, v8
	v_cmp_gt_i32_e32 vcc, 0, v8
	v_min_u32_e32 v67, v64, v65
	v_max_u32_e32 v64, v64, v65
	v_cndmask_b32_e32 v8, v12, v11, vcc
	v_and_b32_e32 v8, 0xffffff00, v8
	v_min_u32_e32 v65, v64, v31
	v_max_u32_e32 v31, v64, v31
	v_min_u32_e32 v64, v27, v30
	v_max_u32_e32 v27, v27, v30
	v_min_u32_e32 v30, v25, v28
	v_max_u32_e32 v25, v25, v28
	v_min_u32_e32 v28, v23, v26
	v_max_u32_e32 v23, v23, v26
	v_min_u32_e32 v26, v20, v24
	v_max_u32_e32 v20, v20, v24
	v_min_u32_e32 v24, v17, v22
	v_max_u32_e32 v17, v17, v22
	v_or_b32_e32 v8, 0xde, v8
	v_min_u32_e32 v22, v17, v21
	v_max_u32_e32 v17, v17, v21
	v_min_u32_e32 v11, v2, v8
	v_min_u32_e32 v21, v17, v19
	v_max_u32_e32 v17, v17, v19
	v_min_u32_e32 v12, v7, v11
	v_max_u32_e32 v2, v2, v8
	v_add_f32_e32 v8, v6, v3
	v_min_u32_e32 v18, v17, v16
	v_max_u32_e32 v16, v17, v16
	v_min_u32_e32 v17, v10, v14
	v_max_u32_e32 v10, v10, v14
	v_min_u32_e32 v14, v9, v12
	v_max_u32_e32 v9, v9, v12
	v_max_u32_e32 v7, v7, v11
	v_not_b32_e32 v11, v8
	v_or_b32_e32 v12, 0x80000000, v8
	v_cmp_gt_i32_e32 vcc, 0, v8
	v_min_u32_e32 v71, v66, v67
	v_max_u32_e32 v66, v66, v67
	v_cndmask_b32_e32 v8, v12, v11, vcc
	v_and_b32_e32 v8, 0xffffff00, v8
	v_min_u32_e32 v70, v68, v69
	v_med3_u32 v68, v68, v69, v67
	v_min_u32_e32 v67, v66, v65
	v_max_u32_e32 v65, v66, v65
	v_min_u32_e32 v66, v29, v64
	v_max_u32_e32 v29, v29, v64
	v_min_u32_e32 v64, v27, v30
	v_max_u32_e32 v27, v27, v30
	v_min_u32_e32 v30, v25, v28
	v_max_u32_e32 v25, v25, v28
	v_min_u32_e32 v28, v23, v26
	v_max_u32_e32 v23, v23, v26
; DI unsigned f2ord(float f) { unsigned u = __float_as_uint(f); return (u & 0x80000000u) ? ~u : (u | 0x80000000u); }
; DI float ord2f(unsigned u) { return __uint_as_float((u & 0x80000000u) ? (u & 0x7fffffffu) : ~u); }
; #define INS32(T, X) { _Pragma("unroll") for (int jj = 0; jj < 16; ++jj) { unsigned t_ = max(T[jj], X); X = min(T[jj], X); T[jj] = t_; } }
; __device__ __forceinline__ void route_task(const Params& p, int layer, const u16* qg, int rb, int hd, int r, int h) {
;     ...
;     for (int a = 0; a < 16; ++a) {
;       const float va = ord2f(top[0][a] & ~127u);
; #pragma unroll
;       for (int b = 0; b < 16; ++b) {
;         if ((a + 1) * (b + 1) <= 16) {
;           const float vb = ord2f(top[1][b] & ~127u);
;           unsigned key = (f2ord(va + vb) & ~255u) | (unsigned)(255 - (a * 16 + b));
;           INS32(ct, key);
;         }
;       }
;     }
	v_min_u32_e32 v26, v20, v24
	v_max_u32_e32 v20, v20, v24
	v_or_b32_e32 v8, 0xdd, v8
	v_min_u32_e32 v24, v20, v22
	v_max_u32_e32 v20, v20, v22
	v_min_u32_e32 v11, v2, v8
	v_min_u32_e32 v22, v20, v21
	v_max_u32_e32 v20, v20, v21
	v_min_u32_e32 v12, v7, v11
	v_max_u32_e32 v2, v2, v8
	v_add_f32_e32 v8, v6, v4
	v_min_u32_e32 v19, v20, v18
	v_max_u32_e32 v18, v20, v18
	v_min_u32_e32 v20, v13, v17
	v_max_u32_e32 v13, v13, v17
	v_min_u32_e32 v17, v10, v14
	v_max_u32_e32 v10, v10, v14
	v_min_u32_e32 v14, v9, v12
	v_max_u32_e32 v9, v9, v12
	v_max_u32_e32 v7, v7, v11
	v_not_b32_e32 v11, v8
	v_or_b32_e32 v12, 0x80000000, v8
	v_cmp_gt_i32_e32 vcc, 0, v8
	v_add_f32_e32 v5, v6, v5
	v_not_b32_e32 v6, v5
	v_cndmask_b32_e32 v8, v12, v11, vcc
	v_and_b32_e32 v8, 0xffffff00, v8
	v_or_b32_e32 v8, 0xdc, v8
	v_min_u32_e32 v11, v2, v8
	v_max_u32_e32 v2, v2, v8
	v_or_b32_e32 v8, 0x80000000, v5
	v_cmp_gt_i32_e32 vcc, 0, v5
	v_min_u32_e32 v72, v70, v71
	v_min_u32_e32 v69, v68, v67
	v_cndmask_b32_e32 v5, v8, v6, vcc
	v_and_b32_e32 v5, 0xffffff00, v5
	v_med3_u32 v70, v70, v71, v67
	v_max_u32_e32 v67, v68, v67
	v_min_u32_e32 v68, v31, v66
	v_max_u32_e32 v31, v31, v66
	v_min_u32_e32 v66, v29, v64
	v_max_u32_e32 v29, v29, v64
	v_min_u32_e32 v64, v27, v30
	v_max_u32_e32 v27, v27, v30
	v_min_u32_e32 v30, v25, v28
	v_max_u32_e32 v25, v25, v28
	v_min_u32_e32 v28, v23, v26
	v_max_u32_e32 v23, v23, v26
	v_or_b32_e32 v5, 0xdb, v5
	v_min_u32_e32 v71, v65, v68
	v_max_u32_e32 v65, v65, v68
	v_min_u32_e32 v68, v31, v66
	v_max_u32_e32 v31, v31, v66
	v_min_u32_e32 v66, v29, v64
	v_max_u32_e32 v29, v29, v64
	v_min_u32_e32 v64, v27, v30
	v_max_u32_e32 v27, v27, v30
	v_min_u32_e32 v30, v25, v28
	v_max_u32_e32 v25, v25, v28
	v_min_u32_e32 v26, v23, v24
	v_max_u32_e32 v23, v23, v24
	v_min_u32_e32 v12, v7, v11
	v_max_u32_e32 v7, v7, v11
	v_min_u32_e32 v6, v2, v5
	v_min_u32_e32 v28, v25, v26
	v_max_u32_e32 v25, v25, v26
	v_min_u32_e32 v24, v23, v22
	v_max_u32_e32 v22, v23, v22
	v_min_u32_e32 v8, v7, v6
	v_max_u32_e32 v6, v7, v6
	v_max_u32_e32 v2, v2, v5
	v_and_b32_e32 v5, 0x7fffff80, v44
	v_bitop3_b32 v7, v44, s52, v44 bitop3:0xcf
	v_cmp_gt_i32_e32 vcc, 0, v44
	v_min_u32_e32 v26, v25, v24
	v_max_u32_e32 v24, v25, v24
	v_min_u32_e32 v21, v22, v19
	v_max_u32_e32 v19, v22, v19
	v_min_u32_e32 v22, v16, v20
	v_max_u32_e32 v16, v16, v20
	v_min_u32_e32 v20, v13, v17
	v_max_u32_e32 v13, v13, v17
	v_min_u32_e32 v17, v10, v14
	v_max_u32_e32 v10, v10, v14
	v_min_u32_e32 v14, v9, v12
	v_max_u32_e32 v9, v9, v12
	v_cndmask_b32_e32 v5, v7, v5, vcc
	v_min_u32_e32 v23, v24, v21
	v_max_u32_e32 v21, v24, v21
	v_min_u32_e32 v24, v18, v22
	v_max_u32_e32 v18, v18, v22
	v_min_u32_e32 v22, v16, v20
	v_max_u32_e32 v16, v16, v20
	v_min_u32_e32 v20, v13, v17
	v_max_u32_e32 v13, v13, v17
	v_min_u32_e32 v17, v10, v14
	v_max_u32_e32 v10, v10, v14
	v_min_u32_e32 v11, v9, v8
	v_add_f32_e32 v7, v5, v1
	v_min_u32_e32 v12, v10, v11
	v_max_u32_e32 v10, v10, v11
	v_max_u32_e32 v8, v9, v8
	v_not_b32_e32 v9, v7
	v_or_b32_e32 v11, 0x80000000, v7
	v_cmp_gt_i32_e32 vcc, 0, v7
	v_min_u32_e32 v69, v72, v69
	v_min_u32_e32 v72, v67, v71
	v_cndmask_b32_e32 v7, v11, v9, vcc
	v_max_u32_e32 v67, v67, v71
	v_min_u32_e32 v71, v65, v68
	v_max_u32_e32 v65, v65, v68
	v_min_u32_e32 v68, v31, v66
	v_max_u32_e32 v31, v31, v66
	v_min_u32_e32 v66, v29, v64
	v_max_u32_e32 v29, v29, v64
	v_min_u32_e32 v64, v27, v30
	v_max_u32_e32 v27, v27, v30
	v_and_b32_e32 v7, 0xffffff00, v7
	v_min_u32_e32 v30, v27, v28
	v_max_u32_e32 v27, v27, v28
	v_or_b32_e32 v7, 0xcf, v7
	v_min_u32_e32 v28, v27, v26
	v_max_u32_e32 v26, v27, v26
	v_min_u32_e32 v9, v2, v7
	v_min_u32_e32 v25, v26, v23
	v_max_u32_e32 v23, v26, v23
	v_min_u32_e32 v26, v19, v24
	v_max_u32_e32 v19, v19, v24
	v_min_u32_e32 v24, v18, v22
	v_max_u32_e32 v18, v18, v22
	v_min_u32_e32 v22, v16, v20
	v_max_u32_e32 v16, v16, v20
	v_min_u32_e32 v20, v13, v17
	v_max_u32_e32 v13, v13, v17
	v_min_u32_e32 v11, v6, v9
	v_max_u32_e32 v2, v2, v7
	v_add_f32_e32 v7, v5, v0
	v_min_u32_e32 v14, v13, v12
	v_max_u32_e32 v12, v13, v12
	v_min_u32_e32 v13, v8, v11
	v_max_u32_e32 v8, v8, v11
	v_max_u32_e32 v6, v6, v9
	v_not_b32_e32 v9, v7
	v_or_b32_e32 v11, 0x80000000, v7
	v_cmp_gt_i32_e32 vcc, 0, v7
	v_min_u32_e32 v73, v70, v72
	v_max_u32_e32 v70, v70, v72
	v_cndmask_b32_e32 v7, v11, v9, vcc
	v_min_u32_e32 v72, v67, v71
	v_max_u32_e32 v67, v67, v71
	v_min_u32_e32 v71, v65, v68
	v_max_u32_e32 v65, v65, v68
	v_min_u32_e32 v68, v31, v66
	v_max_u32_e32 v31, v31, v66
	v_min_u32_e32 v66, v29, v64
	v_max_u32_e32 v29, v29, v64
	v_and_b32_e32 v7, 0xffffff00, v7
	v_min_u32_e32 v64, v29, v30
	v_max_u32_e32 v29, v29, v30
	v_or_b32_e32 v7, 0xce, v7
	v_min_u32_e32 v30, v29, v28
	v_max_u32_e32 v28, v29, v28
	v_min_u32_e32 v9, v2, v7
	v_min_u32_e32 v27, v28, v25
	v_max_u32_e32 v25, v28, v25
	v_min_u32_e32 v28, v21, v26
	v_max_u32_e32 v21, v21, v26
	v_min_u32_e32 v26, v19, v24
	v_max_u32_e32 v19, v19, v24
	v_min_u32_e32 v24, v18, v22
	v_max_u32_e32 v18, v18, v22
	v_min_u32_e32 v22, v16, v20
	v_max_u32_e32 v16, v16, v20
	v_min_u32_e32 v11, v6, v9
	v_max_u32_e32 v2, v2, v7
	v_add_f32_e32 v7, v5, v3
	v_min_u32_e32 v17, v16, v14
	v_max_u32_e32 v14, v16, v14
	v_min_u32_e32 v16, v10, v13
	v_max_u32_e32 v10, v10, v13
	v_min_u32_e32 v13, v8, v11
	v_max_u32_e32 v8, v8, v11
	v_max_u32_e32 v6, v6, v9
	v_not_b32_e32 v9, v7
	v_or_b32_e32 v11, 0x80000000, v7
	v_cmp_gt_i32_e32 vcc, 0, v7
	v_add_f32_e32 v4, v5, v4
	v_not_b32_e32 v5, v4
	v_cndmask_b32_e32 v7, v11, v9, vcc
	v_and_b32_e32 v7, 0xffffff00, v7
	v_or_b32_e32 v7, 0xcd, v7
	v_min_u32_e32 v9, v2, v7
	v_max_u32_e32 v2, v2, v7
	v_or_b32_e32 v7, 0x80000000, v4
	v_cmp_gt_i32_e32 vcc, 0, v4
; DI unsigned f2ord(float f) { unsigned u = __float_as_uint(f); return (u & 0x80000000u) ? ~u : (u | 0x80000000u); }
; DI float ord2f(unsigned u) { return __uint_as_float((u & 0x80000000u) ? (u & 0x7fffffffu) : ~u); }
; #define INS32(T, X) { _Pragma("unroll") for (int jj = 0; jj < 16; ++jj) { unsigned t_ = max(T[jj], X); X = min(T[jj], X); T[jj] = t_; } }
; __device__ __forceinline__ void route_task(const Params& p, int layer, const u16* qg, int rb, int hd, int r, int h) {
;     ...
;     for (int a = 0; a < 16; ++a) {
;       const float va = ord2f(top[0][a] & ~127u);
; #pragma unroll
;       for (int b = 0; b < 16; ++b) {
;         if ((a + 1) * (b + 1) <= 16) {
;           const float vb = ord2f(top[1][b] & ~127u);
;           unsigned key = (f2ord(va + vb) & ~255u) | (unsigned)(255 - (a * 16 + b));
;           INS32(ct, key);
;         }
;       }
;     }
	v_min_u32_e32 v74, v70, v72
	v_max_u32_e32 v70, v70, v72
	v_cndmask_b32_e32 v4, v7, v5, vcc
	v_min_u32_e32 v72, v67, v71
	v_max_u32_e32 v67, v67, v71
	v_min_u32_e32 v71, v65, v68
	v_max_u32_e32 v65, v65, v68
	v_min_u32_e32 v68, v31, v66
	v_max_u32_e32 v31, v31, v66
	v_and_b32_e32 v4, 0xffffff00, v4
	v_max3_u32 v69, v69, v73, v74
	v_min_u32_e32 v73, v70, v72
	v_max_u32_e32 v70, v70, v72
	v_min_u32_e32 v72, v67, v71
	v_max_u32_e32 v67, v67, v71
	v_min_u32_e32 v71, v65, v68
	v_max_u32_e32 v65, v65, v68
	v_min_u32_e32 v66, v31, v64
	v_max_u32_e32 v31, v31, v64
	v_or_b32_e32 v4, 0xcc, v4
	v_min_u32_e32 v68, v65, v66
	v_max_u32_e32 v65, v65, v66
	v_min_u32_e32 v64, v31, v30
	v_max_u32_e32 v30, v31, v30
	v_min_u32_e32 v11, v6, v9
	v_max_u32_e32 v6, v6, v9
	v_min_u32_e32 v5, v2, v4
	v_min_u32_e32 v66, v65, v64
	v_max_u32_e32 v64, v65, v64
	v_min_u32_e32 v29, v30, v27
	v_max_u32_e32 v27, v30, v27
	v_min_u32_e32 v30, v23, v28
	v_max_u32_e32 v23, v23, v28
	v_min_u32_e32 v28, v21, v26
	v_max_u32_e32 v21, v21, v26
	v_min_u32_e32 v26, v19, v24
	v_max_u32_e32 v19, v19, v24
	v_min_u32_e32 v24, v18, v22
	v_max_u32_e32 v18, v18, v22
	v_min_u32_e32 v7, v6, v5
	v_max_u32_e32 v5, v6, v5
	v_max_u32_e32 v2, v2, v4
	v_and_b32_e32 v4, 0x7fffff80, v43
	v_bitop3_b32 v6, v43, s52, v43 bitop3:0xcf
	v_cmp_gt_i32_e32 vcc, 0, v43
	v_min_u32_e32 v31, v64, v29
	v_max_u32_e32 v29, v64, v29
	v_min_u32_e32 v64, v25, v30
	v_max_u32_e32 v25, v25, v30
	v_min_u32_e32 v30, v23, v28
	v_max_u32_e32 v23, v23, v28
	v_min_u32_e32 v28, v21, v26
	v_max_u32_e32 v21, v21, v26
	v_min_u32_e32 v26, v19, v24
	v_max_u32_e32 v19, v19, v24
	v_min_u32_e32 v20, v18, v17
	v_max_u32_e32 v17, v18, v17
	v_min_u32_e32 v18, v12, v16
	v_max_u32_e32 v12, v12, v16
	v_min_u32_e32 v16, v10, v13
	v_max_u32_e32 v10, v10, v13
	v_min_u32_e32 v13, v8, v11
	v_max_u32_e32 v8, v8, v11
	v_cndmask_b32_e32 v4, v6, v4, vcc
	v_min_u32_e32 v22, v19, v20
	v_max_u32_e32 v19, v19, v20
	v_min_u32_e32 v20, v14, v18
	v_max_u32_e32 v14, v14, v18
	v_min_u32_e32 v18, v12, v16
	v_max_u32_e32 v12, v12, v16
	v_min_u32_e32 v16, v10, v13
	v_max_u32_e32 v10, v10, v13
	v_min_u32_e32 v9, v8, v7
	v_add_f32_e32 v6, v4, v1
	v_min_u32_e32 v11, v10, v9
	v_max_u32_e32 v9, v10, v9
	v_max_u32_e32 v7, v8, v7
	v_not_b32_e32 v8, v6
	v_or_b32_e32 v10, 0x80000000, v6
	v_cmp_gt_i32_e32 vcc, 0, v6
	v_min_u32_e32 v74, v70, v72
	v_max_u32_e32 v70, v70, v72
	v_min_u32_e32 v72, v67, v71
	v_max_u32_e32 v67, v67, v71
	v_cndmask_b32_e32 v6, v10, v8, vcc
	v_min_u32_e32 v71, v67, v68
	v_max_u32_e32 v67, v67, v68
	v_and_b32_e32 v6, 0xffffff00, v6
	v_min_u32_e32 v68, v67, v66
	v_max_u32_e32 v66, v67, v66
	v_or_b32_e32 v6, 0xbf, v6
	v_min_u32_e32 v65, v66, v31
	v_max_u32_e32 v31, v66, v31
	v_min_u32_e32 v66, v27, v64
	v_max_u32_e32 v27, v27, v64
	v_min_u32_e32 v64, v25, v30
	v_max_u32_e32 v25, v25, v30
	v_min_u32_e32 v30, v23, v28
	v_max_u32_e32 v23, v23, v28
	v_min_u32_e32 v28, v21, v26
	v_max_u32_e32 v21, v21, v26
	v_min_u32_e32 v8, v2, v6
	v_min_u32_e32 v24, v21, v22
	v_max_u32_e32 v21, v21, v22
	v_min_u32_e32 v22, v17, v20
	v_max_u32_e32 v17, v17, v20
	v_min_u32_e32 v20, v14, v18
	v_max_u32_e32 v14, v14, v18
	v_min_u32_e32 v18, v12, v16
	v_max_u32_e32 v12, v12, v16
	v_min_u32_e32 v10, v5, v8
	v_max_u32_e32 v2, v2, v6
	v_add_f32_e32 v6, v4, v0
	v_min_u32_e32 v13, v12, v11
	v_max_u32_e32 v11, v12, v11
	v_min_u32_e32 v12, v7, v10
	v_max_u32_e32 v7, v7, v10
	v_max_u32_e32 v5, v5, v8
	v_not_b32_e32 v8, v6
	v_or_b32_e32 v10, 0x80000000, v6
	v_cmp_gt_i32_e32 vcc, 0, v6
	v_add_f32_e32 v3, v4, v3
	v_not_b32_e32 v4, v3
	v_cndmask_b32_e32 v6, v10, v8, vcc
	v_and_b32_e32 v6, 0xffffff00, v6
	v_or_b32_e32 v6, 0xbe, v6
	v_min_u32_e32 v8, v2, v6
	v_max_u32_e32 v2, v2, v6
	v_or_b32_e32 v6, 0x80000000, v3
	v_cmp_gt_i32_e32 vcc, 0, v3
	v_max3_u32 v69, v69, v73, v74
	v_min_u32_e32 v73, v70, v72
	v_max_u32_e32 v70, v70, v72
	v_cndmask_b32_e32 v3, v6, v4, vcc
	v_min_u32_e32 v72, v70, v71
	v_max_u32_e32 v70, v70, v71
	v_and_b32_e32 v3, 0xffffff00, v3
	v_min_u32_e32 v71, v70, v68
	v_max_u32_e32 v68, v70, v68
	v_or_b32_e32 v3, 0xbd, v3
	v_max3_u32 v69, v69, v73, v72
	v_min_u32_e32 v67, v68, v65
	v_max_u32_e32 v65, v68, v65
	v_min_u32_e32 v68, v29, v66
	v_max_u32_e32 v29, v29, v66
	v_min_u32_e32 v66, v27, v64
	v_max_u32_e32 v27, v27, v64
	v_min_u32_e32 v64, v25, v30
	v_max_u32_e32 v25, v25, v30
	v_min_u32_e32 v30, v23, v28
	v_max_u32_e32 v23, v23, v28
	v_min_u32_e32 v10, v5, v8
	v_max_u32_e32 v5, v5, v8
	v_min_u32_e32 v4, v2, v3
	v_max3_u32 v67, v69, v71, v67
	v_min_u32_e32 v69, v31, v68
	v_max_u32_e32 v31, v31, v68
	v_min_u32_e32 v68, v29, v66
	v_max_u32_e32 v29, v29, v66
	v_min_u32_e32 v66, v27, v64
	v_max_u32_e32 v27, v27, v64
	v_min_u32_e32 v64, v25, v30
	v_max_u32_e32 v25, v25, v30
	v_min_u32_e32 v26, v23, v24
	v_max_u32_e32 v23, v23, v24
	v_min_u32_e32 v24, v19, v22
	v_max_u32_e32 v19, v19, v22
	v_min_u32_e32 v22, v17, v20
	v_max_u32_e32 v17, v17, v20
	v_min_u32_e32 v20, v14, v18
	v_max_u32_e32 v14, v14, v18
	v_min_u32_e32 v6, v5, v4
	v_max_u32_e32 v4, v5, v4
	v_max_u32_e32 v2, v2, v3
	v_and_b32_e32 v3, 0x7fffff80, v42
	v_bitop3_b32 v5, v42, s52, v42 bitop3:0xcf
	v_cmp_gt_i32_e32 vcc, 0, v42
	v_min_u32_e32 v28, v25, v26
	v_max_u32_e32 v25, v25, v26
	v_min_u32_e32 v26, v21, v24
	v_max_u32_e32 v21, v21, v24
	v_min_u32_e32 v24, v19, v22
	v_max_u32_e32 v19, v19, v22
	v_min_u32_e32 v22, v17, v20
	v_max_u32_e32 v17, v17, v20
	v_min_u32_e32 v16, v14, v13
	v_max_u32_e32 v13, v14, v13
	v_min_u32_e32 v14, v9, v12
	v_max_u32_e32 v9, v9, v12
	v_min_u32_e32 v12, v7, v10
	v_max_u32_e32 v7, v7, v10
	v_cndmask_b32_e32 v3, v5, v3, vcc
	v_min_u32_e32 v18, v17, v16
	v_max_u32_e32 v16, v17, v16
; DI unsigned f2ord(float f) { unsigned u = __float_as_uint(f); return (u & 0x80000000u) ? ~u : (u | 0x80000000u); }
; DI float ord2f(unsigned u) { return __uint_as_float((u & 0x80000000u) ? (u & 0x7fffffffu) : ~u); }
; #define INS32(T, X) { _Pragma("unroll") for (int jj = 0; jj < 16; ++jj) { unsigned t_ = max(T[jj], X); X = min(T[jj], X); T[jj] = t_; } }
; __device__ __forceinline__ void route_task(const Params& p, int layer, const u16* qg, int rb, int hd, int r, int h) {
;     ...
;     for (int a = 0; a < 16; ++a) {
;       const float va = ord2f(top[0][a] & ~127u);
; #pragma unroll
;       for (int b = 0; b < 16; ++b) {
;         if ((a + 1) * (b + 1) <= 16) {
;           const float vb = ord2f(top[1][b] & ~127u);
;           unsigned key = (f2ord(va + vb) & ~255u) | (unsigned)(255 - (a * 16 + b));
;           INS32(ct, key);
;         }
;       }
;     }
	v_min_u32_e32 v17, v11, v14
	v_max_u32_e32 v11, v11, v14
	v_min_u32_e32 v14, v9, v12
	v_max_u32_e32 v9, v9, v12
	v_min_u32_e32 v8, v7, v6
	v_add_f32_e32 v5, v3, v1
	v_min_u32_e32 v10, v9, v8
	v_max_u32_e32 v8, v9, v8
	v_max_u32_e32 v6, v7, v6
	v_not_b32_e32 v7, v5
	v_or_b32_e32 v9, 0x80000000, v5
	v_cmp_gt_i32_e32 vcc, 0, v5
	v_add_f32_e32 v3, v3, v0
	v_min_u32_e32 v70, v65, v69
	v_cndmask_b32_e32 v5, v9, v7, vcc
	v_and_b32_e32 v5, 0xffffff00, v5
	v_or_b32_e32 v5, 0xaf, v5
	v_min_u32_e32 v7, v2, v5
	v_min_u32_e32 v9, v4, v7
	v_max_u32_e32 v4, v4, v7
	v_max_u32_e32 v2, v2, v5
	v_not_b32_e32 v5, v3
	v_or_b32_e32 v7, 0x80000000, v3
	v_cmp_gt_i32_e32 vcc, 0, v3
	v_max_u32_e32 v65, v65, v69
	v_min_u32_e32 v69, v31, v68
	v_cndmask_b32_e32 v3, v7, v5, vcc
	v_and_b32_e32 v3, 0xffffff00, v3
	v_max_u32_e32 v31, v31, v68
	v_min_u32_e32 v68, v29, v66
	v_max_u32_e32 v29, v29, v66
	v_min_u32_e32 v66, v27, v64
	v_max_u32_e32 v27, v27, v64
	v_or_b32_e32 v3, 0xae, v3
	v_min_u32_e32 v71, v65, v69
	v_max_u32_e32 v65, v65, v69
	v_min_u32_e32 v69, v31, v68
	v_max_u32_e32 v31, v31, v68
	v_min_u32_e32 v68, v29, v66
	v_max_u32_e32 v29, v29, v66
	v_min_u32_e32 v30, v27, v28
	v_max_u32_e32 v27, v27, v28
	v_min_u32_e32 v28, v23, v26
	v_max_u32_e32 v23, v23, v26
	v_min_u32_e32 v26, v21, v24
	v_max_u32_e32 v21, v21, v24
	v_min_u32_e32 v24, v19, v22
	v_max_u32_e32 v19, v19, v22
	v_min_u32_e32 v5, v2, v3
	v_min_u32_e32 v64, v29, v30
	v_max_u32_e32 v29, v29, v30
	v_min_u32_e32 v30, v25, v28
	v_max_u32_e32 v25, v25, v28
	v_min_u32_e32 v28, v23, v26
	v_max_u32_e32 v23, v23, v26
	v_min_u32_e32 v26, v21, v24
	v_max_u32_e32 v21, v21, v24
	v_min_u32_e32 v20, v19, v18
	v_max_u32_e32 v18, v19, v18
	v_min_u32_e32 v19, v13, v17
	v_max_u32_e32 v13, v13, v17
	v_min_u32_e32 v17, v11, v14
	v_max_u32_e32 v11, v11, v14
	v_min_u32_e32 v7, v4, v5
	v_max_u32_e32 v4, v4, v5
	v_max_u32_e32 v2, v2, v3
	v_and_b32_e32 v3, 0x7fffff80, v41
	v_bitop3_b32 v5, v41, s52, v41 bitop3:0xcf
	v_cmp_gt_i32_e32 vcc, 0, v41
	v_min_u32_e32 v22, v21, v20
	v_max_u32_e32 v20, v21, v20
	v_min_u32_e32 v21, v16, v19
	v_max_u32_e32 v16, v16, v19
	v_min_u32_e32 v19, v13, v17
	v_max_u32_e32 v13, v13, v17
	v_min_u32_e32 v12, v11, v10
	v_max_u32_e32 v10, v11, v10
	v_min_u32_e32 v11, v6, v9
	v_max_u32_e32 v6, v6, v9
	v_cndmask_b32_e32 v3, v5, v3, vcc
	v_min_u32_e32 v14, v13, v12
	v_max_u32_e32 v12, v13, v12
	v_min_u32_e32 v13, v8, v11
	v_max_u32_e32 v8, v8, v11
	v_min_u32_e32 v9, v6, v7
	v_add_f32_e32 v5, v3, v1
	v_min_u32_e32 v11, v8, v9
	v_max_u32_e32 v8, v8, v9
	v_max_u32_e32 v6, v6, v7
	v_not_b32_e32 v7, v5
	v_or_b32_e32 v9, 0x80000000, v5
	v_cmp_gt_i32_e32 vcc, 0, v5
	v_add_f32_e32 v3, v3, v0
	v_max3_u32 v67, v67, v70, v71
	v_cndmask_b32_e32 v5, v9, v7, vcc
	v_and_b32_e32 v5, 0xffffff00, v5
	v_or_b32_e32 v5, 0x9f, v5
	v_min_u32_e32 v7, v2, v5
	v_min_u32_e32 v9, v4, v7
	v_max_u32_e32 v4, v4, v7
	v_max_u32_e32 v2, v2, v5
	v_not_b32_e32 v5, v3
	v_or_b32_e32 v7, 0x80000000, v3
	v_cmp_gt_i32_e32 vcc, 0, v3
	v_min_u32_e32 v70, v65, v69
	v_max_u32_e32 v65, v65, v69
	v_cndmask_b32_e32 v3, v7, v5, vcc
	v_min_u32_e32 v69, v31, v68
	v_max_u32_e32 v31, v31, v68
	v_and_b32_e32 v3, 0xffffff00, v3
	v_min_u32_e32 v71, v65, v69
	v_max_u32_e32 v65, v65, v69
	v_min_u32_e32 v66, v31, v64
	v_max_u32_e32 v31, v31, v64
	v_min_u32_e32 v64, v27, v30
	v_max_u32_e32 v27, v27, v30
	v_min_u32_e32 v30, v25, v28
	v_max_u32_e32 v25, v25, v28
	v_min_u32_e32 v28, v23, v26
	v_max_u32_e32 v23, v23, v26
	v_or_b32_e32 v3, 0x9e, v3
	v_min_u32_e32 v68, v65, v66
	v_max_u32_e32 v65, v65, v66
	v_min_u32_e32 v66, v29, v64
	v_max_u32_e32 v29, v29, v64
	v_min_u32_e32 v64, v27, v30
	v_max_u32_e32 v27, v27, v30
	v_min_u32_e32 v30, v25, v28
	v_max_u32_e32 v25, v25, v28
	v_min_u32_e32 v24, v23, v22
	v_max_u32_e32 v22, v23, v22
	v_min_u32_e32 v23, v18, v21
	v_max_u32_e32 v18, v18, v21
	v_min_u32_e32 v21, v16, v19
	v_max_u32_e32 v16, v16, v19
	v_min_u32_e32 v5, v2, v3
	v_min_u32_e32 v26, v25, v24
	v_max_u32_e32 v24, v25, v24
	v_min_u32_e32 v25, v20, v23
	v_max_u32_e32 v20, v20, v23
	v_min_u32_e32 v23, v18, v21
	v_max_u32_e32 v18, v18, v21
	v_min_u32_e32 v17, v16, v14
	v_max_u32_e32 v14, v16, v14
	v_min_u32_e32 v16, v10, v13
	v_max_u32_e32 v10, v10, v13
	v_min_u32_e32 v7, v4, v5
	v_max_u32_e32 v4, v4, v5
	v_max_u32_e32 v2, v2, v3
	v_and_b32_e32 v3, 0x7fffff80, v40
	v_bitop3_b32 v5, v40, s52, v40 bitop3:0xcf
	v_cmp_gt_i32_e32 vcc, 0, v40
	v_min_u32_e32 v19, v18, v17
	v_max_u32_e32 v17, v18, v17
	v_min_u32_e32 v18, v12, v16
	v_max_u32_e32 v12, v12, v16
	v_min_u32_e32 v13, v10, v11
	v_max_u32_e32 v10, v10, v11
	v_min_u32_e32 v11, v6, v9
	v_max_u32_e32 v6, v6, v9
	v_cndmask_b32_e32 v3, v5, v3, vcc
	v_min_u32_e32 v16, v12, v13
	v_max_u32_e32 v12, v12, v13
	v_min_u32_e32 v13, v8, v11
	v_max_u32_e32 v8, v8, v11
	v_min_u32_e32 v9, v6, v7
	v_add_f32_e32 v5, v3, v1
	v_min_u32_e32 v11, v8, v9
	v_max_u32_e32 v8, v8, v9
	v_max_u32_e32 v6, v6, v7
	v_not_b32_e32 v7, v5
	v_or_b32_e32 v9, 0x80000000, v5
	v_cmp_gt_i32_e32 vcc, 0, v5
	v_add_f32_e32 v0, v3, v0
	v_not_b32_e32 v3, v0
	v_cndmask_b32_e32 v5, v9, v7, vcc
	v_and_b32_e32 v5, 0xffffff00, v5
	v_or_b32_e32 v5, 0x8f, v5
	v_min_u32_e32 v7, v2, v5
	v_max_u32_e32 v2, v2, v5
	v_or_b32_e32 v5, 0x80000000, v0
	v_cmp_gt_i32_e32 vcc, 0, v0
	v_min_u32_e32 v69, v31, v66
	v_max_u32_e32 v31, v31, v66
	v_cndmask_b32_e32 v0, v5, v3, vcc
	v_and_b32_e32 v0, 0xffffff00, v0
	v_min_u32_e32 v66, v29, v64
	v_max_u32_e32 v29, v29, v64
	v_min_u32_e32 v64, v27, v30
	v_max_u32_e32 v27, v27, v30
	v_or_b32_e32 v0, 0x8e, v0
	v_min_u32_e32 v28, v27, v26
	v_max_u32_e32 v26, v27, v26
	v_min_u32_e32 v27, v22, v25
	v_max_u32_e32 v22, v22, v25
	v_min_u32_e32 v25, v20, v23
; DI unsigned f2ord(float f) { unsigned u = __float_as_uint(f); return (u & 0x80000000u) ? ~u : (u | 0x80000000u); }
; DI float ord2f(unsigned u) { return __uint_as_float((u & 0x80000000u) ? (u & 0x7fffffffu) : ~u); }
; #define INS32(T, X) { _Pragma("unroll") for (int jj = 0; jj < 16; ++jj) { unsigned t_ = max(T[jj], X); X = min(T[jj], X); T[jj] = t_; } }
; __device__ __forceinline__ void route_task(const Params& p, int layer, const u16* qg, int rb, int hd, int r, int h) {
;     ...
;     for (int a = 0; a < 16; ++a) {
;       const float va = ord2f(top[0][a] & ~127u);
; #pragma unroll
;       for (int b = 0; b < 16; ++b) {
;         if ((a + 1) * (b + 1) <= 16) {
;           const float vb = ord2f(top[1][b] & ~127u);
;           unsigned key = (f2ord(va + vb) & ~255u) | (unsigned)(255 - (a * 16 + b));
;           INS32(ct, key);
;         }
;       }
;     }
	v_max_u32_e32 v20, v20, v23
	v_min_u32_e32 v9, v4, v7
	v_max_u32_e32 v4, v4, v7
	v_min_u32_e32 v3, v2, v0
	v_min_u32_e32 v21, v20, v19
	v_max_u32_e32 v19, v20, v19
	v_min_u32_e32 v20, v14, v18
	v_max_u32_e32 v14, v14, v18
	v_min_u32_e32 v5, v4, v3
	v_max_u32_e32 v3, v4, v3
	v_max_u32_e32 v0, v2, v0
	v_and_b32_e32 v2, 0x7fffff80, v39
	v_bitop3_b32 v4, v39, s52, v39 bitop3:0xcf
	v_cmp_gt_i32_e32 vcc, 0, v39
	v_min_u32_e32 v18, v14, v16
	v_max_u32_e32 v14, v14, v16
	v_min_u32_e32 v16, v10, v13
	v_max_u32_e32 v10, v10, v13
	v_cndmask_b32_e32 v2, v4, v2, vcc
	v_min_u32_e32 v13, v10, v11
	v_max_u32_e32 v10, v10, v11
	v_min_u32_e32 v11, v6, v9
	v_max_u32_e32 v6, v6, v9
	v_add_f32_e32 v2, v2, v1
	v_min_u32_e32 v7, v6, v5
	v_max_u32_e32 v5, v6, v5
	v_not_b32_e32 v4, v2
	v_or_b32_e32 v6, 0x80000000, v2
	v_cmp_gt_i32_e32 vcc, 0, v2
	v_max3_u32 v67, v67, v70, v71
	v_min_u32_e32 v70, v65, v69
	v_cndmask_b32_e32 v2, v6, v4, vcc
	v_and_b32_e32 v2, 0xffffff00, v2
	v_max3_u32 v67, v67, v68, v70
	v_min_u32_e32 v68, v31, v66
	v_max_u32_e32 v31, v31, v66
	v_min_u32_e32 v66, v29, v64
	v_max_u32_e32 v29, v29, v64
	v_or_b32_e32 v2, 0x7f, v2
	v_min_u32_e32 v30, v29, v28
	v_max_u32_e32 v28, v29, v28
	v_min_u32_e32 v29, v24, v27
	v_max_u32_e32 v24, v24, v27
	v_min_u32_e32 v27, v22, v25
	v_max_u32_e32 v22, v22, v25
	v_min_u32_e32 v4, v0, v2
	v_min_u32_e32 v23, v22, v21
	v_max_u32_e32 v21, v22, v21
	v_min_u32_e32 v22, v17, v20
	v_max_u32_e32 v17, v17, v20
	v_min_u32_e32 v6, v3, v4
	v_max_u32_e32 v3, v3, v4
	v_max_u32_e32 v0, v0, v2
	v_and_b32_e32 v2, 0x7fffff80, v38
	v_bitop3_b32 v4, v38, s52, v38 bitop3:0xcf
	v_cmp_gt_i32_e32 vcc, 0, v38
	v_min_u32_e32 v20, v17, v18
	v_max_u32_e32 v17, v17, v18
	v_min_u32_e32 v18, v12, v16
	v_max_u32_e32 v12, v12, v16
	v_cndmask_b32_e32 v2, v4, v2, vcc
	v_min_u32_e32 v16, v12, v13
	v_max_u32_e32 v12, v12, v13
	v_min_u32_e32 v13, v8, v11
	v_max_u32_e32 v8, v8, v11
	v_add_f32_e32 v2, v2, v1
	v_min_u32_e32 v9, v8, v7
	v_max_u32_e32 v7, v8, v7
	v_min_u32_e32 v8, v5, v6
	v_max_u32_e32 v5, v5, v6
	v_not_b32_e32 v4, v2
	v_or_b32_e32 v6, 0x80000000, v2
	v_cmp_gt_i32_e32 vcc, 0, v2
	v_max_u32_e32 v65, v65, v69
	v_min_u32_e32 v69, v65, v68
	v_cndmask_b32_e32 v2, v6, v4, vcc
	v_and_b32_e32 v2, 0xffffff00, v2
	v_max_u32_e32 v65, v65, v68
	v_min_u32_e32 v68, v31, v66
	v_max_u32_e32 v31, v31, v66
	v_or_b32_e32 v2, 0x6f, v2
	v_min_u32_e32 v64, v31, v30
	v_max_u32_e32 v30, v31, v30
	v_min_u32_e32 v31, v26, v29
	v_max_u32_e32 v26, v26, v29
	v_min_u32_e32 v29, v24, v27
	v_max_u32_e32 v24, v24, v27
	v_min_u32_e32 v4, v0, v2
	v_min_u32_e32 v25, v24, v23
	v_max_u32_e32 v23, v24, v23
	v_min_u32_e32 v24, v19, v22
	v_max_u32_e32 v19, v19, v22
	v_min_u32_e32 v6, v3, v4
	v_max_u32_e32 v3, v3, v4
	v_max_u32_e32 v0, v0, v2
	v_and_b32_e32 v2, 0x7fffff80, v37
	v_bitop3_b32 v4, v37, s52, v37 bitop3:0xcf
	v_cmp_gt_i32_e32 vcc, 0, v37
	v_min_u32_e32 v22, v19, v20
	v_max_u32_e32 v19, v19, v20
	v_min_u32_e32 v20, v14, v18
	v_max_u32_e32 v14, v14, v18
	v_cndmask_b32_e32 v2, v4, v2, vcc
	v_min_u32_e32 v18, v14, v16
	v_max_u32_e32 v14, v14, v16
	v_min_u32_e32 v16, v10, v13
	v_max_u32_e32 v10, v10, v13
	v_add_f32_e32 v2, v2, v1
	v_min_u32_e32 v11, v10, v9
	v_max_u32_e32 v9, v10, v9
	v_min_u32_e32 v10, v7, v8
	v_max_u32_e32 v7, v7, v8
	v_min_u32_e32 v8, v5, v6
	v_max_u32_e32 v5, v5, v6
	v_not_b32_e32 v4, v2
	v_or_b32_e32 v6, 0x80000000, v2
	v_cmp_gt_i32_e32 vcc, 0, v2
	v_min_u32_e32 v70, v65, v68
	v_max_u32_e32 v65, v65, v68
	v_cndmask_b32_e32 v2, v6, v4, vcc
	v_and_b32_e32 v2, 0xffffff00, v2
	v_or_b32_e32 v2, 0x5f, v2
	v_min_u32_e32 v66, v65, v64
	v_max_u32_e32 v64, v65, v64
	v_min_u32_e32 v65, v28, v31
	v_max_u32_e32 v28, v28, v31
	v_min_u32_e32 v31, v26, v29
	v_max_u32_e32 v26, v26, v29
	v_min_u32_e32 v4, v0, v2
	v_min_u32_e32 v27, v26, v25
	v_max_u32_e32 v25, v26, v25
	v_min_u32_e32 v26, v21, v24
	v_max_u32_e32 v21, v21, v24
	v_min_u32_e32 v6, v3, v4
	v_max_u32_e32 v3, v3, v4
	v_max_u32_e32 v0, v0, v2
	v_and_b32_e32 v2, 0x7fffff80, v36
	v_bitop3_b32 v4, v36, s52, v36 bitop3:0xcf
	v_cmp_gt_i32_e32 vcc, 0, v36
	v_min_u32_e32 v24, v21, v22
	v_max_u32_e32 v21, v21, v22
	v_min_u32_e32 v22, v17, v20
	v_max_u32_e32 v17, v17, v20
	v_cndmask_b32_e32 v2, v4, v2, vcc
	v_min_u32_e32 v20, v17, v18
	v_max_u32_e32 v17, v17, v18
	v_min_u32_e32 v18, v12, v16
	v_max_u32_e32 v12, v12, v16
	v_add_f32_e32 v2, v2, v1
	v_min_u32_e32 v13, v12, v11
	v_max_u32_e32 v11, v12, v11
	v_min_u32_e32 v12, v9, v10
	v_max_u32_e32 v9, v9, v10
	v_min_u32_e32 v10, v7, v8
	v_max_u32_e32 v7, v7, v8
	v_min_u32_e32 v8, v5, v6
	v_max_u32_e32 v5, v5, v6
	v_not_b32_e32 v4, v2
	v_or_b32_e32 v6, 0x80000000, v2
	v_cmp_gt_i32_e32 vcc, 0, v2
	v_min_u32_e32 v68, v30, v65
	v_max_u32_e32 v30, v30, v65
	v_cndmask_b32_e32 v2, v6, v4, vcc
	v_and_b32_e32 v2, 0xffffff00, v2
	v_or_b32_e32 v2, 0x4f, v2
	v_min_u32_e32 v65, v28, v31
	v_max_u32_e32 v28, v28, v31
	v_min_u32_e32 v4, v0, v2
	v_min_u32_e32 v29, v28, v27
	v_max_u32_e32 v27, v28, v27
	v_min_u32_e32 v28, v23, v26
	v_max_u32_e32 v23, v23, v26
	v_min_u32_e32 v6, v3, v4
	v_max_u32_e32 v3, v3, v4
	v_max_u32_e32 v0, v0, v2
	v_and_b32_e32 v2, 0x7fffff80, v35
	v_bitop3_b32 v4, v35, s52, v35 bitop3:0xcf
	v_cmp_gt_i32_e32 vcc, 0, v35
	v_min_u32_e32 v26, v23, v24
	v_max_u32_e32 v23, v23, v24
	v_min_u32_e32 v24, v19, v22
	v_max_u32_e32 v19, v19, v22
	v_cndmask_b32_e32 v2, v4, v2, vcc
	v_min_u32_e32 v22, v19, v20
	v_max_u32_e32 v19, v19, v20
	v_min_u32_e32 v20, v14, v18
	v_max_u32_e32 v14, v14, v18
	v_add_f32_e32 v2, v2, v1
	v_min_u32_e32 v16, v14, v13
	v_max_u32_e32 v13, v14, v13
	v_min_u32_e32 v14, v11, v12
	v_max_u32_e32 v11, v11, v12
	v_min_u32_e32 v12, v9, v10
; DI unsigned f2ord(float f) { unsigned u = __float_as_uint(f); return (u & 0x80000000u) ? ~u : (u | 0x80000000u); }
; DI float ord2f(unsigned u) { return __uint_as_float((u & 0x80000000u) ? (u & 0x7fffffffu) : ~u); }
; #define INS32(T, X) { _Pragma("unroll") for (int jj = 0; jj < 16; ++jj) { unsigned t_ = max(T[jj], X); X = min(T[jj], X); T[jj] = t_; } }
; __device__ __forceinline__ void route_task(const Params& p, int layer, const u16* qg, int rb, int hd, int r, int h) {
;     ...
;     for (int a = 0; a < 16; ++a) {
;       const float va = ord2f(top[0][a] & ~127u);
; #pragma unroll
;       for (int b = 0; b < 16; ++b) {
;         if ((a + 1) * (b + 1) <= 16) {
;           const float vb = ord2f(top[1][b] & ~127u);
;           unsigned key = (f2ord(va + vb) & ~255u) | (unsigned)(255 - (a * 16 + b));
;           INS32(ct, key);
;         }
;       }
;     }
	v_max_u32_e32 v9, v9, v10
	v_min_u32_e32 v10, v7, v8
	v_max_u32_e32 v7, v7, v8
	v_min_u32_e32 v8, v5, v6
	v_max_u32_e32 v5, v5, v6
	v_not_b32_e32 v4, v2
	v_or_b32_e32 v6, 0x80000000, v2
	v_cmp_gt_i32_e32 vcc, 0, v2
	v_max3_u32 v67, v67, v69, v70
	v_min_u32_e32 v69, v64, v68
	v_cndmask_b32_e32 v2, v6, v4, vcc
	v_and_or_b32 v2, v2, s69, 63
	v_max3_u32 v66, v67, v66, v69
	v_min_u32_e32 v67, v30, v65
	v_max_u32_e32 v30, v30, v65
	v_min_u32_e32 v4, v0, v2
	v_min_u32_e32 v31, v30, v29
	v_max_u32_e32 v29, v30, v29
	v_min_u32_e32 v30, v25, v28
	v_max_u32_e32 v25, v25, v28
	v_min_u32_e32 v6, v3, v4
	v_max_u32_e32 v3, v3, v4
	v_max_u32_e32 v0, v0, v2
	v_and_b32_e32 v2, 0x7fffff80, v34
	v_bitop3_b32 v4, v34, s52, v34 bitop3:0xcf
	v_cmp_gt_i32_e32 vcc, 0, v34
	v_min_u32_e32 v28, v25, v26
	v_max_u32_e32 v25, v25, v26
	v_min_u32_e32 v26, v21, v24
	v_max_u32_e32 v21, v21, v24
	v_cndmask_b32_e32 v2, v4, v2, vcc
	v_min_u32_e32 v24, v21, v22
	v_max_u32_e32 v21, v21, v22
	v_min_u32_e32 v22, v17, v20
	v_max_u32_e32 v17, v17, v20
	v_add_f32_e32 v2, v2, v1
	v_min_u32_e32 v18, v17, v16
	v_max_u32_e32 v16, v17, v16
	v_min_u32_e32 v17, v13, v14
	v_max_u32_e32 v13, v13, v14
	v_min_u32_e32 v14, v11, v12
	v_max_u32_e32 v11, v11, v12
	v_min_u32_e32 v12, v9, v10
	v_max_u32_e32 v9, v9, v10
	v_min_u32_e32 v10, v7, v8
	v_max_u32_e32 v7, v7, v8
	v_min_u32_e32 v8, v5, v6
	v_max_u32_e32 v5, v5, v6
	v_not_b32_e32 v4, v2
	v_or_b32_e32 v6, 0x80000000, v2
	v_cmp_gt_i32_e32 vcc, 0, v2
	v_max_u32_e32 v64, v64, v68
	v_min_u32_e32 v68, v64, v67
	v_cndmask_b32_e32 v2, v6, v4, vcc
	v_and_or_b32 v2, v2, s69, 47
	v_max_u32_e32 v64, v64, v67
	v_min_u32_e32 v4, v0, v2
	v_min_u32_e32 v65, v64, v31
	v_max_u32_e32 v31, v64, v31
	v_min_u32_e32 v64, v27, v30
	v_max_u32_e32 v27, v27, v30
	v_min_u32_e32 v6, v3, v4
	v_max_u32_e32 v3, v3, v4
	v_max_u32_e32 v0, v0, v2
	v_and_b32_e32 v2, 0x7fffff80, v33
	v_bitop3_b32 v4, v33, s52, v33 bitop3:0xcf
	v_cmp_gt_i32_e32 vcc, 0, v33
	v_min_u32_e32 v30, v27, v28
	v_max_u32_e32 v27, v27, v28
	v_min_u32_e32 v28, v23, v26
	v_max_u32_e32 v23, v23, v26
	v_cndmask_b32_e32 v2, v4, v2, vcc
	v_min_u32_e32 v26, v23, v24
	v_max_u32_e32 v23, v23, v24
	v_min_u32_e32 v24, v19, v22
	v_max_u32_e32 v19, v19, v22
	v_add_f32_e32 v2, v2, v1
	v_min_u32_e32 v20, v19, v18
	v_max_u32_e32 v18, v19, v18
	v_min_u32_e32 v19, v16, v17
	v_max_u32_e32 v16, v16, v17
	v_min_u32_e32 v17, v13, v14
	v_max_u32_e32 v13, v13, v14
	v_min_u32_e32 v14, v11, v12
	v_max_u32_e32 v11, v11, v12
	v_min_u32_e32 v12, v9, v10
	v_max_u32_e32 v9, v9, v10
	v_min_u32_e32 v10, v7, v8
	v_max_u32_e32 v7, v7, v8
	v_min_u32_e32 v8, v5, v6
	v_max_u32_e32 v5, v5, v6
	v_not_b32_e32 v4, v2
	v_or_b32_e32 v6, 0x80000000, v2
	v_cmp_gt_i32_e32 vcc, 0, v2
	v_max3_u32 v65, v66, v68, v65
	v_min_u32_e32 v66, v29, v64
	v_cndmask_b32_e32 v2, v6, v4, vcc
	v_max_u32_e32 v29, v29, v64
	v_and_or_b32 v2, v2, s69, 31
	v_min_u32_e32 v67, v31, v66
	v_max_u32_e32 v31, v31, v66
	v_min_u32_e32 v64, v29, v30
	v_max_u32_e32 v29, v29, v30
	v_min_u32_e32 v30, v25, v28
	v_max_u32_e32 v25, v25, v28
	v_min_u32_e32 v4, v0, v2
	v_min_u32_e32 v66, v31, v64
	v_max_u32_e32 v31, v31, v64
	v_min_u32_e32 v64, v27, v30
	v_max_u32_e32 v27, v27, v30
	v_min_u32_e32 v28, v25, v26
	v_max_u32_e32 v25, v25, v26
	v_min_u32_e32 v26, v21, v24
	v_max_u32_e32 v21, v21, v24
	v_min_u32_e32 v6, v3, v4
	v_max3_u32 v65, v65, v67, v66
	v_min_u32_e32 v66, v29, v64
	v_max_u32_e32 v29, v29, v64
	v_min_u32_e32 v30, v27, v28
	v_max_u32_e32 v27, v27, v28
	v_min_u32_e32 v28, v23, v26
	v_max_u32_e32 v23, v23, v26
	v_min_u32_e32 v22, v21, v20
	v_max_u32_e32 v20, v21, v20
	v_min_u32_e32 v21, v18, v19
	v_max_u32_e32 v18, v18, v19
	v_min_u32_e32 v19, v16, v17
	v_max_u32_e32 v16, v16, v17
	v_min_u32_e32 v17, v13, v14
	v_max_u32_e32 v13, v13, v14
	v_min_u32_e32 v14, v11, v12
	v_max_u32_e32 v11, v11, v12
	v_min_u32_e32 v12, v9, v10
	v_max_u32_e32 v9, v9, v10
	v_min_u32_e32 v10, v7, v8
	v_max_u32_e32 v7, v7, v8
	v_min_u32_e32 v8, v5, v6
	v_min_u32_e32 v67, v31, v66
	v_max_u32_e32 v31, v31, v66
	v_min_u32_e32 v64, v29, v30
	v_max_u32_e32 v29, v29, v30
	v_min_u32_e32 v30, v25, v28
	v_max_u32_e32 v25, v25, v28
	v_min_u32_e32 v24, v23, v22
	v_max_u32_e32 v22, v23, v22
	v_min_u32_e32 v23, v20, v21
	v_max_u32_e32 v20, v20, v21
	v_min_u32_e32 v21, v18, v19
	v_max_u32_e32 v18, v18, v19
	v_min_u32_e32 v19, v16, v17
	v_max_u32_e32 v16, v16, v17
	v_min_u32_e32 v17, v13, v14
	v_max_u32_e32 v13, v13, v14
	v_min_u32_e32 v14, v11, v12
	v_max_u32_e32 v11, v11, v12
	v_min_u32_e32 v12, v9, v10
	v_max_u32_e32 v9, v9, v10
	v_min_u32_e32 v10, v7, v8
	v_max_u32_e32 v3, v3, v4
	v_max_u32_e32 v0, v0, v2
	v_and_b32_e32 v2, 0x7fffff80, v15
	v_bitop3_b32 v4, v15, s52, v15 bitop3:0xcf
	v_cmp_gt_i32_e32 vcc, 0, v15
	v_min_u32_e32 v66, v31, v64
	v_max_u32_e32 v31, v31, v64
	v_min_u32_e32 v64, v27, v30
	v_max_u32_e32 v27, v27, v30
	v_min_u32_e32 v26, v25, v24
	v_max_u32_e32 v24, v25, v24
	v_min_u32_e32 v25, v22, v23
	v_max_u32_e32 v22, v22, v23
	v_min_u32_e32 v23, v20, v21
	v_max_u32_e32 v20, v20, v21
	v_min_u32_e32 v21, v18, v19
	v_max_u32_e32 v18, v18, v19
	v_min_u32_e32 v19, v16, v17
	v_max_u32_e32 v16, v16, v17
	v_min_u32_e32 v17, v13, v14
	v_max_u32_e32 v13, v13, v14
	v_min_u32_e32 v14, v11, v12
	v_max_u32_e32 v11, v11, v12
	v_min_u32_e32 v12, v9, v10
	v_cndmask_b32_e32 v2, v4, v2, vcc
	v_max3_u32 v65, v65, v67, v66
	v_min_u32_e32 v66, v29, v64
	v_max_u32_e32 v29, v29, v64
	v_min_u32_e32 v28, v27, v26
	v_max_u32_e32 v26, v27, v26
	v_min_u32_e32 v27, v24, v25
	v_max_u32_e32 v24, v24, v25
	v_min_u32_e32 v25, v22, v23
	v_max_u32_e32 v22, v22, v23
	v_min_u32_e32 v23, v20, v21
	v_max_u32_e32 v20, v20, v21
; DI float ord2f(unsigned u) { return __uint_as_float((u & 0x80000000u) ? (u & 0x7fffffffu) : ~u); }
; #define INS32(T, X) { _Pragma("unroll") for (int jj = 0; jj < 16; ++jj) { unsigned t_ = max(T[jj], X); X = min(T[jj], X); T[jj] = t_; } }
; __device__ __forceinline__ void route_task(const Params& p, int layer, const u16* qg, int rb, int hd, int r, int h) {
;     ...
;           INS32(ct, key);
;         }
;       }
;     }
;     const float v0 = ord2f(ct[0] & ~255u);
;     float vs[16];
;     float den = 0.f;
; #pragma unroll
;     for (int jj = 0; jj < 16; ++jj) { vs[jj] = __expf(ord2f(ct[jj] & ~255u) - v0); den += vs[jj]; }
	v_min_u32_e32 v21, v18, v19
	v_max_u32_e32 v18, v18, v19
	v_min_u32_e32 v19, v16, v17
	v_max_u32_e32 v16, v16, v17
	v_min_u32_e32 v17, v13, v14
	v_max_u32_e32 v13, v13, v14
	v_min_u32_e32 v14, v11, v12
	v_add_f32_e32 v1, v2, v1
	v_min_u32_e32 v67, v31, v66
	v_max_u32_e32 v31, v31, v66
	v_min_u32_e32 v30, v29, v28
	v_max_u32_e32 v28, v29, v28
	v_min_u32_e32 v29, v26, v27
	v_max_u32_e32 v26, v26, v27
	v_min_u32_e32 v27, v24, v25
	v_max_u32_e32 v24, v24, v25
	v_min_u32_e32 v25, v22, v23
	v_max_u32_e32 v22, v22, v23
	v_min_u32_e32 v23, v20, v21
	v_max_u32_e32 v20, v20, v21
	v_min_u32_e32 v21, v18, v19
	v_max_u32_e32 v18, v18, v19
	v_min_u32_e32 v19, v16, v17
	v_max_u32_e32 v16, v16, v17
	v_min_u32_e32 v17, v13, v14
	v_not_b32_e32 v2, v1
	v_or_b32_e32 v4, 0x80000000, v1
	v_cmp_gt_i32_e32 vcc, 0, v1
	v_min_u32_e32 v64, v31, v30
	v_max_u32_e32 v30, v31, v30
	v_min_u32_e32 v31, v28, v29
	v_max_u32_e32 v28, v28, v29
	v_min_u32_e32 v29, v26, v27
	v_max_u32_e32 v26, v26, v27
	v_min_u32_e32 v27, v24, v25
	v_max_u32_e32 v24, v24, v25
	v_min_u32_e32 v25, v22, v23
	v_max_u32_e32 v22, v22, v23
	v_min_u32_e32 v23, v20, v21
	v_max_u32_e32 v20, v20, v21
	v_min_u32_e32 v21, v18, v19
	v_max_u32_e32 v18, v18, v19
	v_min_u32_e32 v19, v16, v17
	v_cndmask_b32_e32 v1, v4, v2, vcc
	v_max3_u32 v64, v65, v67, v64
	v_min_u32_e32 v65, v30, v31
	v_max_u32_e32 v30, v30, v31
	v_min_u32_e32 v31, v28, v29
	v_max_u32_e32 v28, v28, v29
	v_min_u32_e32 v29, v26, v27
	v_max_u32_e32 v26, v26, v27
	v_min_u32_e32 v27, v24, v25
	v_max_u32_e32 v24, v24, v25
	v_min_u32_e32 v25, v22, v23
	v_max_u32_e32 v22, v22, v23
	v_min_u32_e32 v23, v20, v21
	v_max_u32_e32 v20, v20, v21
	v_min_u32_e32 v21, v18, v19
	v_and_or_b32 v1, v1, s69, 15
	v_min_u32_e32 v66, v30, v31
	v_max_u32_e32 v30, v30, v31
	v_min_u32_e32 v31, v28, v29
	v_max_u32_e32 v28, v28, v29
	v_min_u32_e32 v29, v26, v27
	v_max_u32_e32 v26, v26, v27
	v_min_u32_e32 v27, v24, v25
	v_max_u32_e32 v24, v24, v25
	v_min_u32_e32 v25, v22, v23
	v_max_u32_e32 v22, v22, v23
	v_min_u32_e32 v23, v20, v21
	v_min_u32_e32 v2, v0, v1
	v_max3_u32 v64, v64, v65, v66
	v_min_u32_e32 v65, v30, v31
	v_max_u32_e32 v30, v30, v31
	v_min_u32_e32 v31, v28, v29
	v_max_u32_e32 v28, v28, v29
	v_min_u32_e32 v29, v26, v27
	v_max_u32_e32 v26, v26, v27
	v_min_u32_e32 v27, v24, v25
	v_max_u32_e32 v24, v24, v25
	v_min_u32_e32 v25, v22, v23
	v_max_u32_e32 v5, v5, v6
	v_min_u32_e32 v4, v3, v2
	v_min_u32_e32 v66, v30, v31
	v_max_u32_e32 v30, v30, v31
	v_min_u32_e32 v31, v28, v29
	v_max_u32_e32 v28, v28, v29
	v_min_u32_e32 v29, v26, v27
	v_max_u32_e32 v26, v26, v27
	v_min_u32_e32 v27, v24, v25
	v_max_u32_e32 v24, v24, v25
	v_max_u32_e32 v22, v22, v23
	v_max_u32_e32 v23, v7, v8
	v_min_u32_e32 v25, v5, v4
	v_max3_u32 v64, v64, v65, v66
	v_min_u32_e32 v65, v30, v31
	v_max_u32_e32 v30, v30, v31
	v_min_u32_e32 v31, v28, v29
	v_max_u32_e32 v28, v28, v29
	v_min_u32_e32 v29, v26, v27
	v_max_u32_e32 v26, v26, v27
	v_max_u32_e32 v20, v20, v21
	v_max_u32_e32 v21, v9, v10
	v_min_u32_e32 v27, v23, v25
	v_min_u32_e32 v66, v30, v31
	v_max_u32_e32 v30, v30, v31
	v_min_u32_e32 v31, v28, v29
	v_max_u32_e32 v28, v28, v29
	v_max_u32_e32 v18, v18, v19
	v_max_u32_e32 v19, v11, v12
	v_min_u32_e32 v29, v21, v27
	v_max_u32_e32 v16, v16, v17
	v_max_u32_e32 v17, v13, v14
	v_min_u32_e32 v6, v19, v29
	v_min_u32_e32 v7, v17, v6
	v_min_u32_e32 v8, v16, v7
	v_min_u32_e32 v9, v18, v8
	v_min_u32_e32 v10, v20, v9
	v_min_u32_e32 v11, v22, v10
	v_min_u32_e32 v12, v24, v11
	v_min_u32_e32 v13, v26, v12
	v_max3_u32 v64, v64, v65, v66
	v_min_u32_e32 v65, v30, v31
	v_max_u32_e32 v30, v30, v31
	v_min_u32_e32 v14, v28, v13
	v_max_u32_e32 v0, v0, v1
	v_min_u32_e32 v31, v30, v14
	v_max_u32_e32 v7, v16, v7
	v_max_u32_e32 v6, v17, v6
	v_max_u32_e32 v2, v3, v2
	v_and_b32_e32 v16, 0x7fffff00, v0
	v_bitop3_b32 v17, v0, s68, v0 bitop3:0xcf
	v_cmp_gt_i32_e32 vcc, 0, v0
	v_max3_u32 v64, v64, v65, v31
	v_max_u32_e32 v8, v18, v8
	v_max_u32_e32 v4, v5, v4
	v_cndmask_b32_e32 v31, v17, v16, vcc
	v_and_b32_e32 v17, 0x7fffff00, v2
	v_bitop3_b32 v18, v2, s68, v2 bitop3:0xcf
	v_cmp_gt_i32_e32 vcc, 0, v2
	v_max_u32_e32 v76, v19, v29
	v_max_u32_e32 v80, v23, v25
	v_sub_f32_e32 v16, v31, v31
	v_cndmask_b32_e32 v17, v18, v17, vcc
	v_and_b32_e32 v18, 0x7fffff00, v4
	v_bitop3_b32 v19, v4, s68, v4 bitop3:0xcf
	v_cmp_gt_i32_e32 vcc, 0, v4
	v_max_u32_e32 v9, v20, v9
	v_mul_f32_e32 v16, 0x3fb8aa3b, v16
	v_sub_f32_e32 v17, v17, v31
	v_cndmask_b32_e32 v18, v19, v18, vcc
	v_and_b32_e32 v19, 0x7fffff00, v80
	v_bitop3_b32 v20, v80, s68, v80 bitop3:0xcf
	v_cmp_gt_i32_e32 vcc, 0, v80
	v_exp_f32_e32 v16, v16
	v_mul_f32_e32 v17, 0x3fb8aa3b, v17
	v_sub_f32_e32 v18, v18, v31
	v_cndmask_b32_e32 v19, v20, v19, vcc
	v_exp_f32_e32 v17, v17
	v_mul_f32_e32 v18, 0x3fb8aa3b, v18
	v_sub_f32_e32 v19, v19, v31
	v_exp_f32_e32 v18, v18
	v_mul_f32_e32 v19, 0x3fb8aa3b, v19
	v_exp_f32_e32 v19, v19
	v_add_f32_e32 v20, 0, v16
	v_add_f32_e32 v20, v17, v20
	v_max_u32_e32 v78, v21, v27
	v_add_f32_e32 v20, v18, v20
	v_max_u32_e32 v11, v24, v11
	v_add_f32_e32 v24, v19, v20
	v_and_b32_e32 v20, 0x7fffff00, v78
	v_bitop3_b32 v21, v78, s68, v78 bitop3:0xcf
	v_cmp_gt_i32_e32 vcc, 0, v78
	v_max_u32_e32 v10, v22, v10
	v_bitop3_b32 v22, v76, s68, v76 bitop3:0xcf
	v_cndmask_b32_e32 v20, v21, v20, vcc
	v_and_b32_e32 v21, 0x7fffff00, v76
	v_cmp_gt_i32_e32 vcc, 0, v76
	v_sub_f32_e32 v20, v20, v31
	v_bitop3_b32 v23, v6, s68, v6 bitop3:0xcf
	v_cndmask_b32_e32 v21, v22, v21, vcc
	v_and_b32_e32 v22, 0x7fffff00, v6
	v_cmp_gt_i32_e32 vcc, 0, v6
	v_mul_f32_e32 v20, 0x3fb8aa3b, v20
	v_sub_f32_e32 v21, v21, v31
	v_cndmask_b32_e32 v22, v23, v22, vcc
	v_and_b32_e32 v23, 0x7fffff00, v7
; DI float ord2f(unsigned u) { return __uint_as_float((u & 0x80000000u) ? (u & 0x7fffffffu) : ~u); }
; __device__ __forceinline__ void route_task(const Params& p, int layer, const u16* qg, int rb, int hd, int r, int h) {
;     ...
;     for (int jj = 0; jj < 16; ++jj) { vs[jj] = __expf(ord2f(ct[jj] & ~255u) - v0); den += vs[jj]; }
;     const float inv = 1.f / den;
;     unsigned eo[16];
; #pragma unroll
;     for (int jj = 0; jj < 16; ++jj) {
;       const unsigned flat = 255u - (ct[jj] & 255u);
;       const unsigned a = flat >> 4, b = flat & 15u;
;       unsigned ka = top[0][0], kb = top[1][0];
; #pragma unroll
;       for (int k = 1; k < 16; ++k) { ka = (a == (unsigned)k) ? top[0][k] : ka; kb = (b == (unsigned)k) ? top[1][k] : kb; }
	v_bitop3_b32 v25, v7, s68, v7 bitop3:0xcf
	v_cmp_gt_i32_e32 vcc, 0, v7
	v_exp_f32_e32 v20, v20
	v_mul_f32_e32 v21, 0x3fb8aa3b, v21
	v_sub_f32_e32 v22, v22, v31
	v_cndmask_b32_e32 v23, v25, v23, vcc
	v_exp_f32_e32 v21, v21
	v_mul_f32_e32 v22, 0x3fb8aa3b, v22
	v_sub_f32_e32 v23, v23, v31
	v_exp_f32_e32 v22, v22
	v_mul_f32_e32 v23, 0x3fb8aa3b, v23
	v_exp_f32_e32 v23, v23
	v_add_f32_e32 v24, v20, v24
	v_add_f32_e32 v24, v21, v24
	v_add_f32_e32 v24, v22, v24
	v_max_u32_e32 v13, v28, v13
	v_add_f32_e32 v28, v23, v24
	v_and_b32_e32 v24, 0x7fffff00, v8
	v_bitop3_b32 v25, v8, s68, v8 bitop3:0xcf
	v_cmp_gt_i32_e32 vcc, 0, v8
	v_max_u32_e32 v12, v26, v12
	v_bitop3_b32 v26, v9, s68, v9 bitop3:0xcf
	v_cndmask_b32_e32 v24, v25, v24, vcc
	v_and_b32_e32 v25, 0x7fffff00, v9
	v_cmp_gt_i32_e32 vcc, 0, v9
	v_sub_f32_e32 v24, v24, v31
	v_bitop3_b32 v27, v10, s68, v10 bitop3:0xcf
	v_cndmask_b32_e32 v25, v26, v25, vcc
	v_and_b32_e32 v26, 0x7fffff00, v10
	v_cmp_gt_i32_e32 vcc, 0, v10
	v_mul_f32_e32 v24, 0x3fb8aa3b, v24
	v_sub_f32_e32 v25, v25, v31
	v_cndmask_b32_e32 v26, v27, v26, vcc
	v_and_b32_e32 v27, 0x7fffff00, v11
	v_bitop3_b32 v29, v11, s68, v11 bitop3:0xcf
	v_cmp_gt_i32_e32 vcc, 0, v11
	v_exp_f32_e32 v24, v24
	v_mul_f32_e32 v25, 0x3fb8aa3b, v25
	v_sub_f32_e32 v26, v26, v31
	v_cndmask_b32_e32 v27, v29, v27, vcc
	v_exp_f32_e32 v25, v25
	v_mul_f32_e32 v26, 0x3fb8aa3b, v26
	v_sub_f32_e32 v27, v27, v31
	v_exp_f32_e32 v26, v26
	v_mul_f32_e32 v27, 0x3fb8aa3b, v27
	v_exp_f32_e32 v27, v27
	v_add_f32_e32 v28, v24, v28
	v_add_f32_e32 v28, v25, v28
	v_add_f32_e32 v28, v26, v28
	v_add_f32_e32 v67, v27, v28
	v_and_b32_e32 v28, 0x7fffff00, v12
	v_bitop3_b32 v29, v12, s68, v12 bitop3:0xcf
	v_cmp_gt_i32_e32 vcc, 0, v12
	v_max_u32_e32 v14, v30, v14
	v_bitop3_b32 v30, v13, s68, v13 bitop3:0xcf
	v_cndmask_b32_e32 v28, v29, v28, vcc
	v_and_b32_e32 v29, 0x7fffff00, v13
	v_cmp_gt_i32_e32 vcc, 0, v13
	v_not_b32_e32 v1, v0
	v_bitop3_b32 v82, v14, s68, v14 bitop3:0xcf
	v_cndmask_b32_e32 v29, v30, v29, vcc
	v_and_b32_e32 v30, 0x7fffff00, v14
	v_cmp_gt_i32_e32 vcc, 0, v14
	v_bitop3_b32 v83, v64, s68, v64 bitop3:0xcf
	v_bfe_u32 v1, v1, 4, 4
	v_cndmask_b32_e32 v30, v82, v30, vcc
	v_and_b32_e32 v82, 0x7fffff00, v64
	v_cmp_gt_i32_e32 vcc, 0, v64
	v_bitop3_b32 v0, v0, 15, v0 bitop3:0xc
	v_sub_f32_e32 v28, v28, v31
	v_cndmask_b32_e32 v82, v83, v82, vcc
	v_cmp_eq_u32_e32 vcc, 1, v1
	v_sub_f32_e32 v29, v29, v31
	v_sub_f32_e32 v30, v30, v31
	v_sub_f32_e32 v31, v82, v31
	v_cndmask_b32_e32 v82, v50, v46, vcc
	v_cmp_eq_u32_e32 vcc, 1, v0
	v_not_b32_e32 v3, v2
	v_bitop3_b32 v2, v2, 15, v2 bitop3:0xc
	v_cndmask_b32_e32 v83, v63, v62, vcc
	v_cmp_eq_u32_e32 vcc, 2, v1
	v_not_b32_e32 v5, v4
	v_not_b32_e32 v81, v80
	v_cndmask_b32_e32 v82, v82, v45, vcc
	v_cmp_eq_u32_e32 vcc, 2, v0
	v_not_b32_e32 v79, v78
	v_not_b32_e32 v77, v76
	v_cndmask_b32_e32 v83, v83, v61, vcc
	v_cmp_eq_u32_e32 vcc, 3, v1
	v_bitop3_b32 v76, v76, 15, v76 bitop3:0xc
	v_not_b32_e32 v75, v6
	v_cndmask_b32_e32 v82, v82, v44, vcc
	v_cmp_eq_u32_e32 vcc, 3, v0
	v_bfe_u32 v75, v75, 4, 4
	v_bitop3_b32 v6, v6, 15, v6 bitop3:0xc
	v_cndmask_b32_e32 v83, v83, v60, vcc
	v_cmp_eq_u32_e32 vcc, 4, v1
	v_not_b32_e32 v74, v7
	v_bfe_u32 v74, v74, 4, 4
	v_cndmask_b32_e32 v82, v82, v43, vcc
	v_cmp_eq_u32_e32 vcc, 4, v0
	v_bitop3_b32 v7, v7, 15, v7 bitop3:0xc
	v_not_b32_e32 v73, v8
	v_cndmask_b32_e32 v83, v83, v59, vcc
	v_cmp_eq_u32_e32 vcc, 5, v1
	v_bfe_u32 v73, v73, 4, 4
	v_bitop3_b32 v8, v8, 15, v8 bitop3:0xc
	v_cndmask_b32_e32 v82, v82, v42, vcc
	v_cmp_eq_u32_e32 vcc, 5, v0
	v_not_b32_e32 v72, v9
	v_bfe_u32 v72, v72, 4, 4
	v_cndmask_b32_e32 v83, v83, v58, vcc
	v_cmp_eq_u32_e32 vcc, 6, v1
	v_bitop3_b32 v9, v9, 15, v9 bitop3:0xc
	v_not_b32_e32 v71, v10
	v_cndmask_b32_e32 v82, v82, v41, vcc
	v_cmp_eq_u32_e32 vcc, 6, v0
	v_bfe_u32 v71, v71, 4, 4
	v_bitop3_b32 v10, v10, 15, v10 bitop3:0xc
	v_cndmask_b32_e32 v83, v83, v57, vcc
	v_cmp_eq_u32_e32 vcc, 7, v1
	v_not_b32_e32 v70, v11
	v_bfe_u32 v70, v70, 4, 4
	v_cndmask_b32_e32 v82, v82, v40, vcc
	v_cmp_eq_u32_e32 vcc, 7, v0
	v_bitop3_b32 v11, v11, 15, v11 bitop3:0xc
	v_not_b32_e32 v69, v12
	v_cndmask_b32_e32 v83, v83, v56, vcc
	v_cmp_eq_u32_e32 vcc, 8, v1
	v_bfe_u32 v69, v69, 4, 4
	v_bitop3_b32 v12, v12, 15, v12 bitop3:0xc
	v_cndmask_b32_e32 v82, v82, v39, vcc
	v_cmp_eq_u32_e32 vcc, 8, v0
	v_not_b32_e32 v68, v13
	v_bfe_u32 v68, v68, 4, 4
	v_cndmask_b32_e32 v83, v83, v55, vcc
	v_cmp_eq_u32_e32 vcc, 9, v1
	v_bitop3_b32 v13, v13, 15, v13 bitop3:0xc
	v_not_b32_e32 v66, v14
	v_cndmask_b32_e32 v82, v82, v38, vcc
	v_cmp_eq_u32_e32 vcc, 9, v0
	v_bfe_u32 v66, v66, 4, 4
	v_bitop3_b32 v14, v14, 15, v14 bitop3:0xc
	v_cndmask_b32_e32 v83, v83, v54, vcc
	v_cmp_eq_u32_e32 vcc, 10, v1
	v_not_b32_e32 v65, v64
	v_bfe_u32 v65, v65, 4, 4
	v_cndmask_b32_e32 v82, v82, v37, vcc
	v_cmp_eq_u32_e32 vcc, 10, v0
	v_bitop3_b32 v64, v64, 15, v64 bitop3:0xc
	v_mul_f32_e32 v28, 0x3fb8aa3b, v28
	v_cndmask_b32_e32 v83, v83, v53, vcc
	v_cmp_eq_u32_e32 vcc, 11, v1
	v_exp_f32_e32 v28, v28
	v_mul_f32_e32 v29, 0x3fb8aa3b, v29
	v_cndmask_b32_e32 v82, v82, v36, vcc
	v_cmp_eq_u32_e32 vcc, 11, v0
	v_exp_f32_e32 v29, v29
	v_mul_f32_e32 v30, 0x3fb8aa3b, v30
	v_cndmask_b32_e32 v83, v83, v52, vcc
	v_cmp_eq_u32_e32 vcc, 12, v1
	v_exp_f32_e32 v30, v30
	v_mul_f32_e32 v31, 0x3fb8aa3b, v31
	v_cndmask_b32_e32 v82, v82, v35, vcc
	v_cmp_eq_u32_e32 vcc, 12, v0
	v_exp_f32_e32 v31, v31
	v_add_f32_e32 v67, v28, v67
	v_cndmask_b32_e32 v83, v83, v51, vcc
	v_cmp_eq_u32_e32 vcc, 13, v1
	v_add_f32_e32 v67, v29, v67
	v_add_f32_e32 v67, v30, v67
	v_cndmask_b32_e32 v82, v82, v34, vcc
	v_cmp_eq_u32_e32 vcc, 13, v0
	v_add_f32_e32 v67, v31, v67
	v_or_b32_e32 v32, v32, v138
; __device__ __forceinline__ void route_task(const Params& p, int layer, const u16* qg, int rb, int hd, int r, int h) {
;     ...
;     for (int jj = 0; jj < 16; ++jj) {
;       const unsigned flat = 255u - (ct[jj] & 255u);
;       const unsigned a = flat >> 4, b = flat & 15u;
;       unsigned ka = top[0][0], kb = top[1][0];
; #pragma unroll
;       for (int k = 1; k < 16; ++k) { ka = (a == (unsigned)k) ? top[0][k] : ka; kb = (b == (unsigned)k) ? top[1][k] : kb; }
;       eo[jj] = (127u - (ka & 127u)) * 128u + (127u - (kb & 127u));
	v_cndmask_b32_e32 v83, v83, v49, vcc
	v_cmp_eq_u32_e32 vcc, 14, v1
	s_nop 1
	v_cndmask_b32_e32 v82, v82, v33, vcc
	v_cmp_eq_u32_e32 vcc, 14, v0
	s_nop 1
	v_cndmask_b32_e32 v83, v83, v48, vcc
	v_cmp_eq_u32_e32 vcc, 15, v1
	s_nop 1
	v_cndmask_b32_e32 v1, v82, v15, vcc
	v_cmp_eq_u32_e32 vcc, 15, v0
	v_lshlrev_b32_e32 v1, 7, v1
	v_and_b32_e32 v1, 0x3f80, v1
	v_cndmask_b32_e32 v0, v83, v47, vcc
	v_and_b32_e32 v0, 0x7f, v0
	v_bitop3_b32 v0, v1, s70, v0 bitop3:0x36
	v_bfe_u32 v1, v3, 4, 4
	v_cmp_eq_u32_e32 vcc, 1, v1
	s_nop 1
	v_cndmask_b32_e32 v3, v50, v46, vcc
	v_cmp_eq_u32_e32 vcc, 1, v2
	s_nop 1
	v_cndmask_b32_e32 v82, v63, v62, vcc
	v_cmp_eq_u32_e32 vcc, 2, v1
	s_nop 1
	v_cndmask_b32_e32 v3, v3, v45, vcc
	v_cmp_eq_u32_e32 vcc, 2, v2
	s_nop 1
	v_cndmask_b32_e32 v82, v82, v61, vcc
	v_cmp_eq_u32_e32 vcc, 3, v1
	s_nop 1
	v_cndmask_b32_e32 v3, v3, v44, vcc
	v_cmp_eq_u32_e32 vcc, 3, v2
	s_nop 1
	v_cndmask_b32_e32 v82, v82, v60, vcc
	v_cmp_eq_u32_e32 vcc, 4, v1
	s_nop 1
	v_cndmask_b32_e32 v3, v3, v43, vcc
	v_cmp_eq_u32_e32 vcc, 4, v2
	s_nop 1
	v_cndmask_b32_e32 v82, v82, v59, vcc
	v_cmp_eq_u32_e32 vcc, 5, v1
	s_nop 1
	v_cndmask_b32_e32 v3, v3, v42, vcc
	v_cmp_eq_u32_e32 vcc, 5, v2
	s_nop 1
	v_cndmask_b32_e32 v82, v82, v58, vcc
	v_cmp_eq_u32_e32 vcc, 6, v1
	s_nop 1
	v_cndmask_b32_e32 v3, v3, v41, vcc
	v_cmp_eq_u32_e32 vcc, 6, v2
	s_nop 1
	v_cndmask_b32_e32 v82, v82, v57, vcc
	v_cmp_eq_u32_e32 vcc, 7, v1
	s_nop 1
	v_cndmask_b32_e32 v3, v3, v40, vcc
	v_cmp_eq_u32_e32 vcc, 7, v2
	s_nop 1
	v_cndmask_b32_e32 v82, v82, v56, vcc
	v_cmp_eq_u32_e32 vcc, 8, v1
	s_nop 1
	v_cndmask_b32_e32 v3, v3, v39, vcc
	v_cmp_eq_u32_e32 vcc, 8, v2
	s_nop 1
	v_cndmask_b32_e32 v82, v82, v55, vcc
	v_cmp_eq_u32_e32 vcc, 9, v1
	s_nop 1
	v_cndmask_b32_e32 v3, v3, v38, vcc
	v_cmp_eq_u32_e32 vcc, 9, v2
	s_nop 1
	v_cndmask_b32_e32 v82, v82, v54, vcc
	v_cmp_eq_u32_e32 vcc, 10, v1
	s_nop 1
	v_cndmask_b32_e32 v3, v3, v37, vcc
	v_cmp_eq_u32_e32 vcc, 10, v2
	s_nop 1
	v_cndmask_b32_e32 v82, v82, v53, vcc
	v_cmp_eq_u32_e32 vcc, 11, v1
	s_nop 1
	v_cndmask_b32_e32 v3, v3, v36, vcc
	v_cmp_eq_u32_e32 vcc, 11, v2
	s_nop 1
	v_cndmask_b32_e32 v82, v82, v52, vcc
	v_cmp_eq_u32_e32 vcc, 12, v1
	s_nop 1
	v_cndmask_b32_e32 v3, v3, v35, vcc
	v_cmp_eq_u32_e32 vcc, 12, v2
	s_nop 1
	v_cndmask_b32_e32 v82, v82, v51, vcc
	v_cmp_eq_u32_e32 vcc, 13, v1
	s_nop 1
	v_cndmask_b32_e32 v3, v3, v34, vcc
	v_cmp_eq_u32_e32 vcc, 13, v2
	s_nop 1
	v_cndmask_b32_e32 v82, v82, v49, vcc
	v_cmp_eq_u32_e32 vcc, 14, v1
	s_nop 1
	v_cndmask_b32_e32 v3, v3, v33, vcc
	v_cmp_eq_u32_e32 vcc, 14, v2
	s_nop 1
	v_cndmask_b32_e32 v82, v82, v48, vcc
	v_cmp_eq_u32_e32 vcc, 15, v1
	s_nop 1
	v_cndmask_b32_e32 v1, v3, v15, vcc
	v_cmp_eq_u32_e32 vcc, 15, v2
	v_lshlrev_b32_e32 v1, 7, v1
	v_and_b32_e32 v1, 0x3f80, v1
	v_cndmask_b32_e32 v2, v82, v47, vcc
	v_and_b32_e32 v2, 0x7f, v2
	v_bitop3_b32 v1, v1, s70, v2 bitop3:0x36
	v_bfe_u32 v2, v5, 4, 4
	v_bitop3_b32 v3, v4, 15, v4 bitop3:0xc
	v_cmp_eq_u32_e32 vcc, 1, v2
	s_nop 1
	v_cndmask_b32_e32 v4, v50, v46, vcc
	v_cmp_eq_u32_e32 vcc, 1, v3
	s_nop 1
	v_cndmask_b32_e32 v5, v63, v62, vcc
	v_cmp_eq_u32_e32 vcc, 2, v2
	s_nop 1
	v_cndmask_b32_e32 v4, v4, v45, vcc
	v_cmp_eq_u32_e32 vcc, 2, v3
	s_nop 1
	v_cndmask_b32_e32 v5, v5, v61, vcc
	v_cmp_eq_u32_e32 vcc, 3, v2
	s_nop 1
	v_cndmask_b32_e32 v4, v4, v44, vcc
	v_cmp_eq_u32_e32 vcc, 3, v3
	s_nop 1
	v_cndmask_b32_e32 v5, v5, v60, vcc
	v_cmp_eq_u32_e32 vcc, 4, v2
	s_nop 1
	v_cndmask_b32_e32 v4, v4, v43, vcc
	v_cmp_eq_u32_e32 vcc, 4, v3
	s_nop 1
	v_cndmask_b32_e32 v5, v5, v59, vcc
	v_cmp_eq_u32_e32 vcc, 5, v2
	s_nop 1
	v_cndmask_b32_e32 v4, v4, v42, vcc
	v_cmp_eq_u32_e32 vcc, 5, v3
	s_nop 1
	v_cndmask_b32_e32 v5, v5, v58, vcc
	v_cmp_eq_u32_e32 vcc, 6, v2
	s_nop 1
	v_cndmask_b32_e32 v4, v4, v41, vcc
	v_cmp_eq_u32_e32 vcc, 6, v3
	s_nop 1
	v_cndmask_b32_e32 v5, v5, v57, vcc
	v_cmp_eq_u32_e32 vcc, 7, v2
	s_nop 1
	v_cndmask_b32_e32 v4, v4, v40, vcc
	v_cmp_eq_u32_e32 vcc, 7, v3
	s_nop 1
	v_cndmask_b32_e32 v5, v5, v56, vcc
	v_cmp_eq_u32_e32 vcc, 8, v2
	s_nop 1
	v_cndmask_b32_e32 v4, v4, v39, vcc
	v_cmp_eq_u32_e32 vcc, 8, v3
	s_nop 1
	v_cndmask_b32_e32 v5, v5, v55, vcc
	v_cmp_eq_u32_e32 vcc, 9, v2
	s_nop 1
	v_cndmask_b32_e32 v4, v4, v38, vcc
	v_cmp_eq_u32_e32 vcc, 9, v3
	s_nop 1
	v_cndmask_b32_e32 v5, v5, v54, vcc
	v_cmp_eq_u32_e32 vcc, 10, v2
	s_nop 1
	v_cndmask_b32_e32 v4, v4, v37, vcc
	v_cmp_eq_u32_e32 vcc, 10, v3
	s_nop 1
	v_cndmask_b32_e32 v5, v5, v53, vcc
	v_cmp_eq_u32_e32 vcc, 11, v2
	s_nop 1
	v_cndmask_b32_e32 v4, v4, v36, vcc
	v_cmp_eq_u32_e32 vcc, 11, v3
	s_nop 1
	v_cndmask_b32_e32 v5, v5, v52, vcc
	v_cmp_eq_u32_e32 vcc, 12, v2
	s_nop 1
	v_cndmask_b32_e32 v4, v4, v35, vcc
	v_cmp_eq_u32_e32 vcc, 12, v3
	s_nop 1
	v_cndmask_b32_e32 v5, v5, v51, vcc
	v_cmp_eq_u32_e32 vcc, 13, v2
	s_nop 1
	v_cndmask_b32_e32 v4, v4, v34, vcc
	v_cmp_eq_u32_e32 vcc, 13, v3
	s_nop 1
	v_cndmask_b32_e32 v5, v5, v49, vcc
	v_cmp_eq_u32_e32 vcc, 14, v2
	s_nop 1
	v_cndmask_b32_e32 v4, v4, v33, vcc
	v_cmp_eq_u32_e32 vcc, 14, v3
	s_nop 1
	v_cndmask_b32_e32 v5, v5, v48, vcc
	v_cmp_eq_u32_e32 vcc, 15, v2
	s_nop 1
	v_cndmask_b32_e32 v2, v4, v15, vcc
	v_cmp_eq_u32_e32 vcc, 15, v3
	v_lshlrev_b32_e32 v2, 7, v2
	v_and_b32_e32 v2, 0x3f80, v2
	v_cndmask_b32_e32 v3, v5, v47, vcc
	v_and_b32_e32 v3, 0x7f, v3
	v_bitop3_b32 v2, v2, s70, v3 bitop3:0x36
	v_bfe_u32 v3, v81, 4, 4
	v_bitop3_b32 v4, v80, 15, v80 bitop3:0xc
	v_cmp_eq_u32_e32 vcc, 1, v3
	s_nop 1
	v_cndmask_b32_e32 v5, v50, v46, vcc
	v_cmp_eq_u32_e32 vcc, 1, v4
	s_nop 1
	v_cndmask_b32_e32 v80, v63, v62, vcc
	v_cmp_eq_u32_e32 vcc, 2, v3
	s_nop 1
	v_cndmask_b32_e32 v5, v5, v45, vcc
	v_cmp_eq_u32_e32 vcc, 2, v4
	s_nop 1
	v_cndmask_b32_e32 v80, v80, v61, vcc
; __device__ __forceinline__ void route_task(const Params& p, int layer, const u16* qg, int rb, int hd, int r, int h) {
;     ...
;     for (int jj = 0; jj < 16; ++jj) {
;       const unsigned flat = 255u - (ct[jj] & 255u);
;       const unsigned a = flat >> 4, b = flat & 15u;
;       unsigned ka = top[0][0], kb = top[1][0];
; #pragma unroll
;       for (int k = 1; k < 16; ++k) { ka = (a == (unsigned)k) ? top[0][k] : ka; kb = (b == (unsigned)k) ? top[1][k] : kb; }
;       eo[jj] = (127u - (ka & 127u)) * 128u + (127u - (kb & 127u));
	v_cmp_eq_u32_e32 vcc, 3, v3
	s_nop 1
	v_cndmask_b32_e32 v5, v5, v44, vcc
	v_cmp_eq_u32_e32 vcc, 3, v4
	s_nop 1
	v_cndmask_b32_e32 v80, v80, v60, vcc
	v_cmp_eq_u32_e32 vcc, 4, v3
	s_nop 1
	v_cndmask_b32_e32 v5, v5, v43, vcc
	v_cmp_eq_u32_e32 vcc, 4, v4
	s_nop 1
	v_cndmask_b32_e32 v80, v80, v59, vcc
	v_cmp_eq_u32_e32 vcc, 5, v3
	s_nop 1
	v_cndmask_b32_e32 v5, v5, v42, vcc
	v_cmp_eq_u32_e32 vcc, 5, v4
	s_nop 1
	v_cndmask_b32_e32 v80, v80, v58, vcc
	v_cmp_eq_u32_e32 vcc, 6, v3
	s_nop 1
	v_cndmask_b32_e32 v5, v5, v41, vcc
	v_cmp_eq_u32_e32 vcc, 6, v4
	s_nop 1
	v_cndmask_b32_e32 v80, v80, v57, vcc
	v_cmp_eq_u32_e32 vcc, 7, v3
	s_nop 1
	v_cndmask_b32_e32 v5, v5, v40, vcc
	v_cmp_eq_u32_e32 vcc, 7, v4
	s_nop 1
	v_cndmask_b32_e32 v80, v80, v56, vcc
	v_cmp_eq_u32_e32 vcc, 8, v3
	s_nop 1
	v_cndmask_b32_e32 v5, v5, v39, vcc
	v_cmp_eq_u32_e32 vcc, 8, v4
	s_nop 1
	v_cndmask_b32_e32 v80, v80, v55, vcc
	v_cmp_eq_u32_e32 vcc, 9, v3
	s_nop 1
	v_cndmask_b32_e32 v5, v5, v38, vcc
	v_cmp_eq_u32_e32 vcc, 9, v4
	s_nop 1
	v_cndmask_b32_e32 v80, v80, v54, vcc
	v_cmp_eq_u32_e32 vcc, 10, v3
	s_nop 1
	v_cndmask_b32_e32 v5, v5, v37, vcc
	v_cmp_eq_u32_e32 vcc, 10, v4
	s_nop 1
	v_cndmask_b32_e32 v80, v80, v53, vcc
	v_cmp_eq_u32_e32 vcc, 11, v3
	s_nop 1
	v_cndmask_b32_e32 v5, v5, v36, vcc
	v_cmp_eq_u32_e32 vcc, 11, v4
	s_nop 1
	v_cndmask_b32_e32 v80, v80, v52, vcc
	v_cmp_eq_u32_e32 vcc, 12, v3
	s_nop 1
	v_cndmask_b32_e32 v5, v5, v35, vcc
	v_cmp_eq_u32_e32 vcc, 12, v4
	s_nop 1
	v_cndmask_b32_e32 v80, v80, v51, vcc
	v_cmp_eq_u32_e32 vcc, 13, v3
	s_nop 1
	v_cndmask_b32_e32 v5, v5, v34, vcc
	v_cmp_eq_u32_e32 vcc, 13, v4
	s_nop 1
	v_cndmask_b32_e32 v80, v80, v49, vcc
	v_cmp_eq_u32_e32 vcc, 14, v3
	s_nop 1
	v_cndmask_b32_e32 v5, v5, v33, vcc
	v_cmp_eq_u32_e32 vcc, 14, v4
	s_nop 1
	v_cndmask_b32_e32 v80, v80, v48, vcc
	v_cmp_eq_u32_e32 vcc, 15, v3
	s_nop 1
	v_cndmask_b32_e32 v3, v5, v15, vcc
	v_cmp_eq_u32_e32 vcc, 15, v4
	v_lshlrev_b32_e32 v3, 7, v3
	v_and_b32_e32 v3, 0x3f80, v3
	v_cndmask_b32_e32 v4, v80, v47, vcc
	v_and_b32_e32 v4, 0x7f, v4
	v_bitop3_b32 v3, v3, s70, v4 bitop3:0x36
	v_bfe_u32 v4, v79, 4, 4
	v_bitop3_b32 v5, v78, 15, v78 bitop3:0xc
	v_cmp_eq_u32_e32 vcc, 1, v4
	s_nop 1
	v_cndmask_b32_e32 v78, v50, v46, vcc
	v_cmp_eq_u32_e32 vcc, 1, v5
	s_nop 1
	v_cndmask_b32_e32 v79, v63, v62, vcc
	v_cmp_eq_u32_e32 vcc, 2, v4
	s_nop 1
	v_cndmask_b32_e32 v78, v78, v45, vcc
	v_cmp_eq_u32_e32 vcc, 2, v5
	s_nop 1
	v_cndmask_b32_e32 v79, v79, v61, vcc
	v_cmp_eq_u32_e32 vcc, 3, v4
	s_nop 1
	v_cndmask_b32_e32 v78, v78, v44, vcc
	v_cmp_eq_u32_e32 vcc, 3, v5
	s_nop 1
	v_cndmask_b32_e32 v79, v79, v60, vcc
	v_cmp_eq_u32_e32 vcc, 4, v4
	s_nop 1
	v_cndmask_b32_e32 v78, v78, v43, vcc
	v_cmp_eq_u32_e32 vcc, 4, v5
	s_nop 1
	v_cndmask_b32_e32 v79, v79, v59, vcc
	v_cmp_eq_u32_e32 vcc, 5, v4
	s_nop 1
	v_cndmask_b32_e32 v78, v78, v42, vcc
	v_cmp_eq_u32_e32 vcc, 5, v5
	s_nop 1
	v_cndmask_b32_e32 v79, v79, v58, vcc
	v_cmp_eq_u32_e32 vcc, 6, v4
	s_nop 1
	v_cndmask_b32_e32 v78, v78, v41, vcc
	v_cmp_eq_u32_e32 vcc, 6, v5
	s_nop 1
	v_cndmask_b32_e32 v79, v79, v57, vcc
	v_cmp_eq_u32_e32 vcc, 7, v4
	s_nop 1
	v_cndmask_b32_e32 v78, v78, v40, vcc
	v_cmp_eq_u32_e32 vcc, 7, v5
	s_nop 1
	v_cndmask_b32_e32 v79, v79, v56, vcc
	v_cmp_eq_u32_e32 vcc, 8, v4
	s_nop 1
	v_cndmask_b32_e32 v78, v78, v39, vcc
	v_cmp_eq_u32_e32 vcc, 8, v5
	s_nop 1
	v_cndmask_b32_e32 v79, v79, v55, vcc
	v_cmp_eq_u32_e32 vcc, 9, v4
	s_nop 1
	v_cndmask_b32_e32 v78, v78, v38, vcc
	v_cmp_eq_u32_e32 vcc, 9, v5
	s_nop 1
	v_cndmask_b32_e32 v79, v79, v54, vcc
	v_cmp_eq_u32_e32 vcc, 10, v4
	s_nop 1
	v_cndmask_b32_e32 v78, v78, v37, vcc
	v_cmp_eq_u32_e32 vcc, 10, v5
	s_nop 1
	v_cndmask_b32_e32 v79, v79, v53, vcc
	v_cmp_eq_u32_e32 vcc, 11, v4
	s_nop 1
	v_cndmask_b32_e32 v78, v78, v36, vcc
	v_cmp_eq_u32_e32 vcc, 11, v5
	s_nop 1
	v_cndmask_b32_e32 v79, v79, v52, vcc
	v_cmp_eq_u32_e32 vcc, 12, v4
	s_nop 1
	v_cndmask_b32_e32 v78, v78, v35, vcc
	v_cmp_eq_u32_e32 vcc, 12, v5
	s_nop 1
	v_cndmask_b32_e32 v79, v79, v51, vcc
	v_cmp_eq_u32_e32 vcc, 13, v4
	s_nop 1
	v_cndmask_b32_e32 v78, v78, v34, vcc
	v_cmp_eq_u32_e32 vcc, 13, v5
	s_nop 1
	v_cndmask_b32_e32 v79, v79, v49, vcc
	v_cmp_eq_u32_e32 vcc, 14, v4
	s_nop 1
	v_cndmask_b32_e32 v78, v78, v33, vcc
	v_cmp_eq_u32_e32 vcc, 14, v5
	s_nop 1
	v_cndmask_b32_e32 v79, v79, v48, vcc
	v_cmp_eq_u32_e32 vcc, 15, v4
	s_nop 1
	v_cndmask_b32_e32 v4, v78, v15, vcc
	v_cmp_eq_u32_e32 vcc, 15, v5
	v_lshlrev_b32_e32 v4, 7, v4
	v_and_b32_e32 v4, 0x3f80, v4
	v_cndmask_b32_e32 v5, v79, v47, vcc
	v_and_b32_e32 v5, 0x7f, v5
	v_bitop3_b32 v4, v4, s70, v5 bitop3:0x36
	v_bfe_u32 v5, v77, 4, 4
	v_cmp_eq_u32_e32 vcc, 1, v5
	s_nop 1
	v_cndmask_b32_e32 v77, v50, v46, vcc
	v_cmp_eq_u32_e32 vcc, 1, v76
	s_nop 1
	v_cndmask_b32_e32 v78, v63, v62, vcc
	v_cmp_eq_u32_e32 vcc, 2, v5
	s_nop 1
	v_cndmask_b32_e32 v77, v77, v45, vcc
	v_cmp_eq_u32_e32 vcc, 2, v76
	s_nop 1
	v_cndmask_b32_e32 v78, v78, v61, vcc
	v_cmp_eq_u32_e32 vcc, 3, v5
	s_nop 1
	v_cndmask_b32_e32 v77, v77, v44, vcc
	v_cmp_eq_u32_e32 vcc, 3, v76
	s_nop 1
	v_cndmask_b32_e32 v78, v78, v60, vcc
	v_cmp_eq_u32_e32 vcc, 4, v5
	s_nop 1
	v_cndmask_b32_e32 v77, v77, v43, vcc
	v_cmp_eq_u32_e32 vcc, 4, v76
	s_nop 1
	v_cndmask_b32_e32 v78, v78, v59, vcc
	v_cmp_eq_u32_e32 vcc, 5, v5
	s_nop 1
	v_cndmask_b32_e32 v77, v77, v42, vcc
	v_cmp_eq_u32_e32 vcc, 5, v76
	s_nop 1
	v_cndmask_b32_e32 v78, v78, v58, vcc
	v_cmp_eq_u32_e32 vcc, 6, v5
	s_nop 1
	v_cndmask_b32_e32 v77, v77, v41, vcc
	v_cmp_eq_u32_e32 vcc, 6, v76
	s_nop 1
	v_cndmask_b32_e32 v78, v78, v57, vcc
	v_cmp_eq_u32_e32 vcc, 7, v5
	s_nop 1
	v_cndmask_b32_e32 v77, v77, v40, vcc
	v_cmp_eq_u32_e32 vcc, 7, v76
	s_nop 1
	v_cndmask_b32_e32 v78, v78, v56, vcc
; __device__ __forceinline__ void route_task(const Params& p, int layer, const u16* qg, int rb, int hd, int r, int h) {
;     ...
;     for (int jj = 0; jj < 16; ++jj) {
;       const unsigned flat = 255u - (ct[jj] & 255u);
;       const unsigned a = flat >> 4, b = flat & 15u;
;       unsigned ka = top[0][0], kb = top[1][0];
; #pragma unroll
;       for (int k = 1; k < 16; ++k) { ka = (a == (unsigned)k) ? top[0][k] : ka; kb = (b == (unsigned)k) ? top[1][k] : kb; }
;       eo[jj] = (127u - (ka & 127u)) * 128u + (127u - (kb & 127u));
	v_cmp_eq_u32_e32 vcc, 8, v5
	s_nop 1
	v_cndmask_b32_e32 v77, v77, v39, vcc
	v_cmp_eq_u32_e32 vcc, 8, v76
	s_nop 1
	v_cndmask_b32_e32 v78, v78, v55, vcc
	v_cmp_eq_u32_e32 vcc, 9, v5
	s_nop 1
	v_cndmask_b32_e32 v77, v77, v38, vcc
	v_cmp_eq_u32_e32 vcc, 9, v76
	s_nop 1
	v_cndmask_b32_e32 v78, v78, v54, vcc
	v_cmp_eq_u32_e32 vcc, 10, v5
	s_nop 1
	v_cndmask_b32_e32 v77, v77, v37, vcc
	v_cmp_eq_u32_e32 vcc, 10, v76
	s_nop 1
	v_cndmask_b32_e32 v78, v78, v53, vcc
	v_cmp_eq_u32_e32 vcc, 11, v5
	s_nop 1
	v_cndmask_b32_e32 v77, v77, v36, vcc
	v_cmp_eq_u32_e32 vcc, 11, v76
	s_nop 1
	v_cndmask_b32_e32 v78, v78, v52, vcc
	v_cmp_eq_u32_e32 vcc, 12, v5
	s_nop 1
	v_cndmask_b32_e32 v77, v77, v35, vcc
	v_cmp_eq_u32_e32 vcc, 12, v76
	s_nop 1
	v_cndmask_b32_e32 v78, v78, v51, vcc
	v_cmp_eq_u32_e32 vcc, 13, v5
	s_nop 1
	v_cndmask_b32_e32 v77, v77, v34, vcc
	v_cmp_eq_u32_e32 vcc, 13, v76
	s_nop 1
	v_cndmask_b32_e32 v78, v78, v49, vcc
	v_cmp_eq_u32_e32 vcc, 14, v5
	s_nop 1
	v_cndmask_b32_e32 v77, v77, v33, vcc
	v_cmp_eq_u32_e32 vcc, 14, v76
	s_nop 1
	v_cndmask_b32_e32 v78, v78, v48, vcc
	v_cmp_eq_u32_e32 vcc, 15, v5
	s_nop 1
	v_cndmask_b32_e32 v5, v77, v15, vcc
	v_cmp_eq_u32_e32 vcc, 15, v76
	v_lshlrev_b32_e32 v5, 7, v5
	v_and_b32_e32 v5, 0x3f80, v5
	v_cndmask_b32_e32 v76, v78, v47, vcc
	v_and_b32_e32 v76, 0x7f, v76
	v_cmp_eq_u32_e32 vcc, 1, v75
	v_bitop3_b32 v5, v5, s70, v76 bitop3:0x36
	s_nop 0
	v_cndmask_b32_e32 v76, v50, v46, vcc
	v_cmp_eq_u32_e32 vcc, 1, v6
	s_nop 1
	v_cndmask_b32_e32 v77, v63, v62, vcc
	v_cmp_eq_u32_e32 vcc, 2, v75
	s_nop 1
	v_cndmask_b32_e32 v76, v76, v45, vcc
	v_cmp_eq_u32_e32 vcc, 2, v6
	s_nop 1
	v_cndmask_b32_e32 v77, v77, v61, vcc
	v_cmp_eq_u32_e32 vcc, 3, v75
	s_nop 1
	v_cndmask_b32_e32 v76, v76, v44, vcc
	v_cmp_eq_u32_e32 vcc, 3, v6
	s_nop 1
	v_cndmask_b32_e32 v77, v77, v60, vcc
	v_cmp_eq_u32_e32 vcc, 4, v75
	s_nop 1
	v_cndmask_b32_e32 v76, v76, v43, vcc
	v_cmp_eq_u32_e32 vcc, 4, v6
	s_nop 1
	v_cndmask_b32_e32 v77, v77, v59, vcc
	v_cmp_eq_u32_e32 vcc, 5, v75
	s_nop 1
	v_cndmask_b32_e32 v76, v76, v42, vcc
	v_cmp_eq_u32_e32 vcc, 5, v6
	s_nop 1
	v_cndmask_b32_e32 v77, v77, v58, vcc
	v_cmp_eq_u32_e32 vcc, 6, v75
	s_nop 1
	v_cndmask_b32_e32 v76, v76, v41, vcc
	v_cmp_eq_u32_e32 vcc, 6, v6
	s_nop 1
	v_cndmask_b32_e32 v77, v77, v57, vcc
	v_cmp_eq_u32_e32 vcc, 7, v75
	s_nop 1
	v_cndmask_b32_e32 v76, v76, v40, vcc
	v_cmp_eq_u32_e32 vcc, 7, v6
	s_nop 1
	v_cndmask_b32_e32 v77, v77, v56, vcc
	v_cmp_eq_u32_e32 vcc, 8, v75
	s_nop 1
	v_cndmask_b32_e32 v76, v76, v39, vcc
	v_cmp_eq_u32_e32 vcc, 8, v6
	s_nop 1
	v_cndmask_b32_e32 v77, v77, v55, vcc
	v_cmp_eq_u32_e32 vcc, 9, v75
	s_nop 1
	v_cndmask_b32_e32 v76, v76, v38, vcc
	v_cmp_eq_u32_e32 vcc, 9, v6
	s_nop 1
	v_cndmask_b32_e32 v77, v77, v54, vcc
	v_cmp_eq_u32_e32 vcc, 10, v75
	s_nop 1
	v_cndmask_b32_e32 v76, v76, v37, vcc
	v_cmp_eq_u32_e32 vcc, 10, v6
	s_nop 1
	v_cndmask_b32_e32 v77, v77, v53, vcc
	v_cmp_eq_u32_e32 vcc, 11, v75
	s_nop 1
	v_cndmask_b32_e32 v76, v76, v36, vcc
	v_cmp_eq_u32_e32 vcc, 11, v6
	s_nop 1
	v_cndmask_b32_e32 v77, v77, v52, vcc
	v_cmp_eq_u32_e32 vcc, 12, v75
	s_nop 1
	v_cndmask_b32_e32 v76, v76, v35, vcc
	v_cmp_eq_u32_e32 vcc, 12, v6
	s_nop 1
	v_cndmask_b32_e32 v77, v77, v51, vcc
	v_cmp_eq_u32_e32 vcc, 13, v75
	s_nop 1
	v_cndmask_b32_e32 v76, v76, v34, vcc
	v_cmp_eq_u32_e32 vcc, 13, v6
	s_nop 1
	v_cndmask_b32_e32 v77, v77, v49, vcc
	v_cmp_eq_u32_e32 vcc, 14, v75
	s_nop 1
	v_cndmask_b32_e32 v76, v76, v33, vcc
	v_cmp_eq_u32_e32 vcc, 14, v6
	s_nop 1
	v_cndmask_b32_e32 v77, v77, v48, vcc
	v_cmp_eq_u32_e32 vcc, 15, v75
	s_nop 1
	v_cndmask_b32_e32 v75, v76, v15, vcc
	v_cmp_eq_u32_e32 vcc, 15, v6
	v_lshlrev_b32_e32 v75, 7, v75
	v_and_b32_e32 v75, 0x3f80, v75
	v_cndmask_b32_e32 v6, v77, v47, vcc
	v_and_b32_e32 v6, 0x7f, v6
	v_cmp_eq_u32_e32 vcc, 1, v74
	v_bitop3_b32 v6, v75, s70, v6 bitop3:0x36
	s_nop 0
	v_cndmask_b32_e32 v75, v50, v46, vcc
	v_cmp_eq_u32_e32 vcc, 1, v7
	s_nop 1
	v_cndmask_b32_e32 v76, v63, v62, vcc
	v_cmp_eq_u32_e32 vcc, 2, v74
	s_nop 1
	v_cndmask_b32_e32 v75, v75, v45, vcc
	v_cmp_eq_u32_e32 vcc, 2, v7
	s_nop 1
	v_cndmask_b32_e32 v76, v76, v61, vcc
	v_cmp_eq_u32_e32 vcc, 3, v74
	s_nop 1
	v_cndmask_b32_e32 v75, v75, v44, vcc
	v_cmp_eq_u32_e32 vcc, 3, v7
	s_nop 1
	v_cndmask_b32_e32 v76, v76, v60, vcc
	v_cmp_eq_u32_e32 vcc, 4, v74
	s_nop 1
	v_cndmask_b32_e32 v75, v75, v43, vcc
	v_cmp_eq_u32_e32 vcc, 4, v7
	s_nop 1
	v_cndmask_b32_e32 v76, v76, v59, vcc
	v_cmp_eq_u32_e32 vcc, 5, v74
	s_nop 1
	v_cndmask_b32_e32 v75, v75, v42, vcc
	v_cmp_eq_u32_e32 vcc, 5, v7
	s_nop 1
	v_cndmask_b32_e32 v76, v76, v58, vcc
	v_cmp_eq_u32_e32 vcc, 6, v74
	s_nop 1
	v_cndmask_b32_e32 v75, v75, v41, vcc
	v_cmp_eq_u32_e32 vcc, 6, v7
	s_nop 1
	v_cndmask_b32_e32 v76, v76, v57, vcc
	v_cmp_eq_u32_e32 vcc, 7, v74
	s_nop 1
	v_cndmask_b32_e32 v75, v75, v40, vcc
	v_cmp_eq_u32_e32 vcc, 7, v7
	s_nop 1
	v_cndmask_b32_e32 v76, v76, v56, vcc
	v_cmp_eq_u32_e32 vcc, 8, v74
	s_nop 1
	v_cndmask_b32_e32 v75, v75, v39, vcc
	v_cmp_eq_u32_e32 vcc, 8, v7
	s_nop 1
	v_cndmask_b32_e32 v76, v76, v55, vcc
	v_cmp_eq_u32_e32 vcc, 9, v74
	s_nop 1
	v_cndmask_b32_e32 v75, v75, v38, vcc
	v_cmp_eq_u32_e32 vcc, 9, v7
	s_nop 1
	v_cndmask_b32_e32 v76, v76, v54, vcc
	v_cmp_eq_u32_e32 vcc, 10, v74
	s_nop 1
	v_cndmask_b32_e32 v75, v75, v37, vcc
	v_cmp_eq_u32_e32 vcc, 10, v7
	s_nop 1
	v_cndmask_b32_e32 v76, v76, v53, vcc
	v_cmp_eq_u32_e32 vcc, 11, v74
	s_nop 1
	v_cndmask_b32_e32 v75, v75, v36, vcc
	v_cmp_eq_u32_e32 vcc, 11, v7
	s_nop 1
	v_cndmask_b32_e32 v76, v76, v52, vcc
	v_cmp_eq_u32_e32 vcc, 12, v74
	s_nop 1
	v_cndmask_b32_e32 v75, v75, v35, vcc
	v_cmp_eq_u32_e32 vcc, 12, v7
	s_nop 1
	v_cndmask_b32_e32 v76, v76, v51, vcc
; __device__ __forceinline__ void route_task(const Params& p, int layer, const u16* qg, int rb, int hd, int r, int h) {
;     ...
;     for (int jj = 0; jj < 16; ++jj) {
;       const unsigned flat = 255u - (ct[jj] & 255u);
;       const unsigned a = flat >> 4, b = flat & 15u;
;       unsigned ka = top[0][0], kb = top[1][0];
; #pragma unroll
;       for (int k = 1; k < 16; ++k) { ka = (a == (unsigned)k) ? top[0][k] : ka; kb = (b == (unsigned)k) ? top[1][k] : kb; }
;       eo[jj] = (127u - (ka & 127u)) * 128u + (127u - (kb & 127u));
;     }
	v_cmp_eq_u32_e32 vcc, 13, v74
	s_nop 1
	v_cndmask_b32_e32 v75, v75, v34, vcc
	v_cmp_eq_u32_e32 vcc, 13, v7
	s_nop 1
	v_cndmask_b32_e32 v76, v76, v49, vcc
	v_cmp_eq_u32_e32 vcc, 14, v74
	s_nop 1
	v_cndmask_b32_e32 v75, v75, v33, vcc
	v_cmp_eq_u32_e32 vcc, 14, v7
	s_nop 1
	v_cndmask_b32_e32 v76, v76, v48, vcc
	v_cmp_eq_u32_e32 vcc, 15, v74
	s_nop 1
	v_cndmask_b32_e32 v74, v75, v15, vcc
	v_cmp_eq_u32_e32 vcc, 15, v7
	v_lshlrev_b32_e32 v74, 7, v74
	v_and_b32_e32 v74, 0x3f80, v74
	v_cndmask_b32_e32 v7, v76, v47, vcc
	v_and_b32_e32 v7, 0x7f, v7
	v_cmp_eq_u32_e32 vcc, 1, v73
	v_bitop3_b32 v7, v74, s70, v7 bitop3:0x36
	s_nop 0
	v_cndmask_b32_e32 v74, v50, v46, vcc
	v_cmp_eq_u32_e32 vcc, 1, v8
	s_nop 1
	v_cndmask_b32_e32 v75, v63, v62, vcc
	v_cmp_eq_u32_e32 vcc, 2, v73
	s_nop 1
	v_cndmask_b32_e32 v74, v74, v45, vcc
	v_cmp_eq_u32_e32 vcc, 2, v8
	s_nop 1
	v_cndmask_b32_e32 v75, v75, v61, vcc
	v_cmp_eq_u32_e32 vcc, 3, v73
	s_nop 1
	v_cndmask_b32_e32 v74, v74, v44, vcc
	v_cmp_eq_u32_e32 vcc, 3, v8
	s_nop 1
	v_cndmask_b32_e32 v75, v75, v60, vcc
	v_cmp_eq_u32_e32 vcc, 4, v73
	s_nop 1
	v_cndmask_b32_e32 v74, v74, v43, vcc
	v_cmp_eq_u32_e32 vcc, 4, v8
	s_nop 1
	v_cndmask_b32_e32 v75, v75, v59, vcc
	v_cmp_eq_u32_e32 vcc, 5, v73
	s_nop 1
	v_cndmask_b32_e32 v74, v74, v42, vcc
	v_cmp_eq_u32_e32 vcc, 5, v8
	s_nop 1
	v_cndmask_b32_e32 v75, v75, v58, vcc
	v_cmp_eq_u32_e32 vcc, 6, v73
	s_nop 1
	v_cndmask_b32_e32 v74, v74, v41, vcc
	v_cmp_eq_u32_e32 vcc, 6, v8
	s_nop 1
	v_cndmask_b32_e32 v75, v75, v57, vcc
	v_cmp_eq_u32_e32 vcc, 7, v73
	s_nop 1
	v_cndmask_b32_e32 v74, v74, v40, vcc
	v_cmp_eq_u32_e32 vcc, 7, v8
	s_nop 1
	v_cndmask_b32_e32 v75, v75, v56, vcc
	v_cmp_eq_u32_e32 vcc, 8, v73
	s_nop 1
	v_cndmask_b32_e32 v74, v74, v39, vcc
	v_cmp_eq_u32_e32 vcc, 8, v8
	s_nop 1
	v_cndmask_b32_e32 v75, v75, v55, vcc
	v_cmp_eq_u32_e32 vcc, 9, v73
	s_nop 1
	v_cndmask_b32_e32 v74, v74, v38, vcc
	v_cmp_eq_u32_e32 vcc, 9, v8
	s_nop 1
	v_cndmask_b32_e32 v75, v75, v54, vcc
	v_cmp_eq_u32_e32 vcc, 10, v73
	s_nop 1
	v_cndmask_b32_e32 v74, v74, v37, vcc
	v_cmp_eq_u32_e32 vcc, 10, v8
	s_nop 1
	v_cndmask_b32_e32 v75, v75, v53, vcc
	v_cmp_eq_u32_e32 vcc, 11, v73
	s_nop 1
	v_cndmask_b32_e32 v74, v74, v36, vcc
	v_cmp_eq_u32_e32 vcc, 11, v8
	s_nop 1
	v_cndmask_b32_e32 v75, v75, v52, vcc
	v_cmp_eq_u32_e32 vcc, 12, v73
	s_nop 1
	v_cndmask_b32_e32 v74, v74, v35, vcc
	v_cmp_eq_u32_e32 vcc, 12, v8
	s_nop 1
	v_cndmask_b32_e32 v75, v75, v51, vcc
	v_cmp_eq_u32_e32 vcc, 13, v73
	s_nop 1
	v_cndmask_b32_e32 v74, v74, v34, vcc
	v_cmp_eq_u32_e32 vcc, 13, v8
	s_nop 1
	v_cndmask_b32_e32 v75, v75, v49, vcc
	v_cmp_eq_u32_e32 vcc, 14, v73
	s_nop 1
	v_cndmask_b32_e32 v74, v74, v33, vcc
	v_cmp_eq_u32_e32 vcc, 14, v8
	s_nop 1
	v_cndmask_b32_e32 v75, v75, v48, vcc
	v_cmp_eq_u32_e32 vcc, 15, v73
	s_nop 1
	v_cndmask_b32_e32 v73, v74, v15, vcc
	v_cmp_eq_u32_e32 vcc, 15, v8
	v_lshlrev_b32_e32 v73, 7, v73
	v_and_b32_e32 v73, 0x3f80, v73
	v_cndmask_b32_e32 v8, v75, v47, vcc
	v_and_b32_e32 v8, 0x7f, v8
	v_cmp_eq_u32_e32 vcc, 1, v72
	v_bitop3_b32 v8, v73, s70, v8 bitop3:0x36
	s_nop 0
	v_cndmask_b32_e32 v73, v50, v46, vcc
	v_cmp_eq_u32_e32 vcc, 1, v9
	s_nop 1
	v_cndmask_b32_e32 v74, v63, v62, vcc
	v_cmp_eq_u32_e32 vcc, 2, v72
	s_nop 1
	v_cndmask_b32_e32 v73, v73, v45, vcc
	v_cmp_eq_u32_e32 vcc, 2, v9
	s_nop 1
	v_cndmask_b32_e32 v74, v74, v61, vcc
	v_cmp_eq_u32_e32 vcc, 3, v72
	s_nop 1
	v_cndmask_b32_e32 v73, v73, v44, vcc
	v_cmp_eq_u32_e32 vcc, 3, v9
	s_nop 1
	v_cndmask_b32_e32 v74, v74, v60, vcc
	v_cmp_eq_u32_e32 vcc, 4, v72
	s_nop 1
	v_cndmask_b32_e32 v73, v73, v43, vcc
	v_cmp_eq_u32_e32 vcc, 4, v9
	s_nop 1
	v_cndmask_b32_e32 v74, v74, v59, vcc
	v_cmp_eq_u32_e32 vcc, 5, v72
	s_nop 1
	v_cndmask_b32_e32 v73, v73, v42, vcc
	v_cmp_eq_u32_e32 vcc, 5, v9
	s_nop 1
	v_cndmask_b32_e32 v74, v74, v58, vcc
	v_cmp_eq_u32_e32 vcc, 6, v72
	s_nop 1
	v_cndmask_b32_e32 v73, v73, v41, vcc
	v_cmp_eq_u32_e32 vcc, 6, v9
	s_nop 1
	v_cndmask_b32_e32 v74, v74, v57, vcc
	v_cmp_eq_u32_e32 vcc, 7, v72
	s_nop 1
	v_cndmask_b32_e32 v73, v73, v40, vcc
	v_cmp_eq_u32_e32 vcc, 7, v9
	s_nop 1
	v_cndmask_b32_e32 v74, v74, v56, vcc
	v_cmp_eq_u32_e32 vcc, 8, v72
	s_nop 1
	v_cndmask_b32_e32 v73, v73, v39, vcc
	v_cmp_eq_u32_e32 vcc, 8, v9
	s_nop 1
	v_cndmask_b32_e32 v74, v74, v55, vcc
	v_cmp_eq_u32_e32 vcc, 9, v72
	s_nop 1
	v_cndmask_b32_e32 v73, v73, v38, vcc
	v_cmp_eq_u32_e32 vcc, 9, v9
	s_nop 1
	v_cndmask_b32_e32 v74, v74, v54, vcc
	v_cmp_eq_u32_e32 vcc, 10, v72
	s_nop 1
	v_cndmask_b32_e32 v73, v73, v37, vcc
	v_cmp_eq_u32_e32 vcc, 10, v9
	s_nop 1
	v_cndmask_b32_e32 v74, v74, v53, vcc
	v_cmp_eq_u32_e32 vcc, 11, v72
	s_nop 1
	v_cndmask_b32_e32 v73, v73, v36, vcc
	v_cmp_eq_u32_e32 vcc, 11, v9
	s_nop 1
	v_cndmask_b32_e32 v74, v74, v52, vcc
	v_cmp_eq_u32_e32 vcc, 12, v72
	s_nop 1
	v_cndmask_b32_e32 v73, v73, v35, vcc
	v_cmp_eq_u32_e32 vcc, 12, v9
	s_nop 1
	v_cndmask_b32_e32 v74, v74, v51, vcc
	v_cmp_eq_u32_e32 vcc, 13, v72
	s_nop 1
	v_cndmask_b32_e32 v73, v73, v34, vcc
	v_cmp_eq_u32_e32 vcc, 13, v9
	s_nop 1
	v_cndmask_b32_e32 v74, v74, v49, vcc
	v_cmp_eq_u32_e32 vcc, 14, v72
	s_nop 1
	v_cndmask_b32_e32 v73, v73, v33, vcc
	v_cmp_eq_u32_e32 vcc, 14, v9
	s_nop 1
	v_cndmask_b32_e32 v74, v74, v48, vcc
	v_cmp_eq_u32_e32 vcc, 15, v72
	s_nop 1
	v_cndmask_b32_e32 v72, v73, v15, vcc
	v_cmp_eq_u32_e32 vcc, 15, v9
	v_lshlrev_b32_e32 v72, 7, v72
	v_and_b32_e32 v72, 0x3f80, v72
	v_cndmask_b32_e32 v9, v74, v47, vcc
	v_and_b32_e32 v9, 0x7f, v9
	v_cmp_eq_u32_e32 vcc, 1, v71
	v_bitop3_b32 v9, v72, s70, v9 bitop3:0x36
	s_nop 0
	v_cndmask_b32_e32 v72, v50, v46, vcc
	v_cmp_eq_u32_e32 vcc, 1, v10
	s_nop 1
	v_cndmask_b32_e32 v73, v63, v62, vcc
	v_cmp_eq_u32_e32 vcc, 2, v71
	s_nop 1
; __device__ __forceinline__ void route_task(const Params& p, int layer, const u16* qg, int rb, int hd, int r, int h) {
;     ...
;     for (int jj = 0; jj < 16; ++jj) {
;       const unsigned flat = 255u - (ct[jj] & 255u);
;       const unsigned a = flat >> 4, b = flat & 15u;
;       unsigned ka = top[0][0], kb = top[1][0];
; #pragma unroll
;       for (int k = 1; k < 16; ++k) { ka = (a == (unsigned)k) ? top[0][k] : ka; kb = (b == (unsigned)k) ? top[1][k] : kb; }
;       eo[jj] = (127u - (ka & 127u)) * 128u + (127u - (kb & 127u));
;     }
	v_cndmask_b32_e32 v72, v72, v45, vcc
	v_cmp_eq_u32_e32 vcc, 2, v10
	s_nop 1
	v_cndmask_b32_e32 v73, v73, v61, vcc
	v_cmp_eq_u32_e32 vcc, 3, v71
	s_nop 1
	v_cndmask_b32_e32 v72, v72, v44, vcc
	v_cmp_eq_u32_e32 vcc, 3, v10
	s_nop 1
	v_cndmask_b32_e32 v73, v73, v60, vcc
	v_cmp_eq_u32_e32 vcc, 4, v71
	s_nop 1
	v_cndmask_b32_e32 v72, v72, v43, vcc
	v_cmp_eq_u32_e32 vcc, 4, v10
	s_nop 1
	v_cndmask_b32_e32 v73, v73, v59, vcc
	v_cmp_eq_u32_e32 vcc, 5, v71
	s_nop 1
	v_cndmask_b32_e32 v72, v72, v42, vcc
	v_cmp_eq_u32_e32 vcc, 5, v10
	s_nop 1
	v_cndmask_b32_e32 v73, v73, v58, vcc
	v_cmp_eq_u32_e32 vcc, 6, v71
	s_nop 1
	v_cndmask_b32_e32 v72, v72, v41, vcc
	v_cmp_eq_u32_e32 vcc, 6, v10
	s_nop 1
	v_cndmask_b32_e32 v73, v73, v57, vcc
	v_cmp_eq_u32_e32 vcc, 7, v71
	s_nop 1
	v_cndmask_b32_e32 v72, v72, v40, vcc
	v_cmp_eq_u32_e32 vcc, 7, v10
	s_nop 1
	v_cndmask_b32_e32 v73, v73, v56, vcc
	v_cmp_eq_u32_e32 vcc, 8, v71
	s_nop 1
	v_cndmask_b32_e32 v72, v72, v39, vcc
	v_cmp_eq_u32_e32 vcc, 8, v10
	s_nop 1
	v_cndmask_b32_e32 v73, v73, v55, vcc
	v_cmp_eq_u32_e32 vcc, 9, v71
	s_nop 1
	v_cndmask_b32_e32 v72, v72, v38, vcc
	v_cmp_eq_u32_e32 vcc, 9, v10
	s_nop 1
	v_cndmask_b32_e32 v73, v73, v54, vcc
	v_cmp_eq_u32_e32 vcc, 10, v71
	s_nop 1
	v_cndmask_b32_e32 v72, v72, v37, vcc
	v_cmp_eq_u32_e32 vcc, 10, v10
	s_nop 1
	v_cndmask_b32_e32 v73, v73, v53, vcc
	v_cmp_eq_u32_e32 vcc, 11, v71
	s_nop 1
	v_cndmask_b32_e32 v72, v72, v36, vcc
	v_cmp_eq_u32_e32 vcc, 11, v10
	s_nop 1
	v_cndmask_b32_e32 v73, v73, v52, vcc
	v_cmp_eq_u32_e32 vcc, 12, v71
	s_nop 1
	v_cndmask_b32_e32 v72, v72, v35, vcc
	v_cmp_eq_u32_e32 vcc, 12, v10
	s_nop 1
	v_cndmask_b32_e32 v73, v73, v51, vcc
	v_cmp_eq_u32_e32 vcc, 13, v71
	s_nop 1
	v_cndmask_b32_e32 v72, v72, v34, vcc
	v_cmp_eq_u32_e32 vcc, 13, v10
	s_nop 1
	v_cndmask_b32_e32 v73, v73, v49, vcc
	v_cmp_eq_u32_e32 vcc, 14, v71
	s_nop 1
	v_cndmask_b32_e32 v72, v72, v33, vcc
	v_cmp_eq_u32_e32 vcc, 14, v10
	s_nop 1
	v_cndmask_b32_e32 v73, v73, v48, vcc
	v_cmp_eq_u32_e32 vcc, 15, v71
	s_nop 1
	v_cndmask_b32_e32 v71, v72, v15, vcc
	v_cmp_eq_u32_e32 vcc, 15, v10
	v_lshlrev_b32_e32 v71, 7, v71
	v_and_b32_e32 v71, 0x3f80, v71
	v_cndmask_b32_e32 v10, v73, v47, vcc
	v_and_b32_e32 v10, 0x7f, v10
	v_cmp_eq_u32_e32 vcc, 1, v70
	v_bitop3_b32 v10, v71, s70, v10 bitop3:0x36
	s_nop 0
	v_cndmask_b32_e32 v71, v50, v46, vcc
	v_cmp_eq_u32_e32 vcc, 1, v11
	s_nop 1
	v_cndmask_b32_e32 v72, v63, v62, vcc
	v_cmp_eq_u32_e32 vcc, 2, v70
	s_nop 1
	v_cndmask_b32_e32 v71, v71, v45, vcc
	v_cmp_eq_u32_e32 vcc, 2, v11
	s_nop 1
	v_cndmask_b32_e32 v72, v72, v61, vcc
	v_cmp_eq_u32_e32 vcc, 3, v70
	s_nop 1
	v_cndmask_b32_e32 v71, v71, v44, vcc
	v_cmp_eq_u32_e32 vcc, 3, v11
	s_nop 1
	v_cndmask_b32_e32 v72, v72, v60, vcc
	v_cmp_eq_u32_e32 vcc, 4, v70
	s_nop 1
	v_cndmask_b32_e32 v71, v71, v43, vcc
	v_cmp_eq_u32_e32 vcc, 4, v11
	s_nop 1
	v_cndmask_b32_e32 v72, v72, v59, vcc
	v_cmp_eq_u32_e32 vcc, 5, v70
	s_nop 1
	v_cndmask_b32_e32 v71, v71, v42, vcc
	v_cmp_eq_u32_e32 vcc, 5, v11
	s_nop 1
	v_cndmask_b32_e32 v72, v72, v58, vcc
	v_cmp_eq_u32_e32 vcc, 6, v70
	s_nop 1
	v_cndmask_b32_e32 v71, v71, v41, vcc
	v_cmp_eq_u32_e32 vcc, 6, v11
	s_nop 1
	v_cndmask_b32_e32 v72, v72, v57, vcc
	v_cmp_eq_u32_e32 vcc, 7, v70
	s_nop 1
	v_cndmask_b32_e32 v71, v71, v40, vcc
	v_cmp_eq_u32_e32 vcc, 7, v11
	s_nop 1
	v_cndmask_b32_e32 v72, v72, v56, vcc
	v_cmp_eq_u32_e32 vcc, 8, v70
	s_nop 1
	v_cndmask_b32_e32 v71, v71, v39, vcc
	v_cmp_eq_u32_e32 vcc, 8, v11
	s_nop 1
	v_cndmask_b32_e32 v72, v72, v55, vcc
	v_cmp_eq_u32_e32 vcc, 9, v70
	s_nop 1
	v_cndmask_b32_e32 v71, v71, v38, vcc
	v_cmp_eq_u32_e32 vcc, 9, v11
	s_nop 1
	v_cndmask_b32_e32 v72, v72, v54, vcc
	v_cmp_eq_u32_e32 vcc, 10, v70
	s_nop 1
	v_cndmask_b32_e32 v71, v71, v37, vcc
	v_cmp_eq_u32_e32 vcc, 10, v11
	s_nop 1
	v_cndmask_b32_e32 v72, v72, v53, vcc
	v_cmp_eq_u32_e32 vcc, 11, v70
	s_nop 1
	v_cndmask_b32_e32 v71, v71, v36, vcc
	v_cmp_eq_u32_e32 vcc, 11, v11
	s_nop 1
	v_cndmask_b32_e32 v72, v72, v52, vcc
	v_cmp_eq_u32_e32 vcc, 12, v70
	s_nop 1
	v_cndmask_b32_e32 v71, v71, v35, vcc
	v_cmp_eq_u32_e32 vcc, 12, v11
	s_nop 1
	v_cndmask_b32_e32 v72, v72, v51, vcc
	v_cmp_eq_u32_e32 vcc, 13, v70
	s_nop 1
	v_cndmask_b32_e32 v71, v71, v34, vcc
	v_cmp_eq_u32_e32 vcc, 13, v11
	s_nop 1
	v_cndmask_b32_e32 v72, v72, v49, vcc
	v_cmp_eq_u32_e32 vcc, 14, v70
	s_nop 1
	v_cndmask_b32_e32 v71, v71, v33, vcc
	v_cmp_eq_u32_e32 vcc, 14, v11
	s_nop 1
	v_cndmask_b32_e32 v72, v72, v48, vcc
	v_cmp_eq_u32_e32 vcc, 15, v70
	s_nop 1
	v_cndmask_b32_e32 v70, v71, v15, vcc
	v_cmp_eq_u32_e32 vcc, 15, v11
	v_lshlrev_b32_e32 v70, 7, v70
	v_and_b32_e32 v70, 0x3f80, v70
	v_cndmask_b32_e32 v11, v72, v47, vcc
	v_and_b32_e32 v11, 0x7f, v11
	v_cmp_eq_u32_e32 vcc, 1, v69
	v_bitop3_b32 v11, v70, s70, v11 bitop3:0x36
	s_nop 0
	v_cndmask_b32_e32 v70, v50, v46, vcc
	v_cmp_eq_u32_e32 vcc, 1, v12
	s_nop 1
	v_cndmask_b32_e32 v71, v63, v62, vcc
	v_cmp_eq_u32_e32 vcc, 2, v69
	s_nop 1
	v_cndmask_b32_e32 v70, v70, v45, vcc
	v_cmp_eq_u32_e32 vcc, 2, v12
	s_nop 1
	v_cndmask_b32_e32 v71, v71, v61, vcc
	v_cmp_eq_u32_e32 vcc, 3, v69
	s_nop 1
	v_cndmask_b32_e32 v70, v70, v44, vcc
	v_cmp_eq_u32_e32 vcc, 3, v12
	s_nop 1
	v_cndmask_b32_e32 v71, v71, v60, vcc
	v_cmp_eq_u32_e32 vcc, 4, v69
	s_nop 1
	v_cndmask_b32_e32 v70, v70, v43, vcc
	v_cmp_eq_u32_e32 vcc, 4, v12
	s_nop 1
	v_cndmask_b32_e32 v71, v71, v59, vcc
	v_cmp_eq_u32_e32 vcc, 5, v69
	s_nop 1
	v_cndmask_b32_e32 v70, v70, v42, vcc
	v_cmp_eq_u32_e32 vcc, 5, v12
	s_nop 1
	v_cndmask_b32_e32 v71, v71, v58, vcc
	v_cmp_eq_u32_e32 vcc, 6, v69
	s_nop 1
	v_cndmask_b32_e32 v70, v70, v41, vcc
	v_cmp_eq_u32_e32 vcc, 6, v12
	s_nop 1
	v_cndmask_b32_e32 v71, v71, v57, vcc
; __device__ __forceinline__ void route_task(const Params& p, int layer, const u16* qg, int rb, int hd, int r, int h) {
;     ...
;     for (int jj = 0; jj < 16; ++jj) {
;       const unsigned flat = 255u - (ct[jj] & 255u);
;       const unsigned a = flat >> 4, b = flat & 15u;
;       unsigned ka = top[0][0], kb = top[1][0];
; #pragma unroll
;       for (int k = 1; k < 16; ++k) { ka = (a == (unsigned)k) ? top[0][k] : ka; kb = (b == (unsigned)k) ? top[1][k] : kb; }
;       eo[jj] = (127u - (ka & 127u)) * 128u + (127u - (kb & 127u));
;     }
	v_cmp_eq_u32_e32 vcc, 7, v69
	s_nop 1
	v_cndmask_b32_e32 v70, v70, v40, vcc
	v_cmp_eq_u32_e32 vcc, 7, v12
	s_nop 1
	v_cndmask_b32_e32 v71, v71, v56, vcc
	v_cmp_eq_u32_e32 vcc, 8, v69
	s_nop 1
	v_cndmask_b32_e32 v70, v70, v39, vcc
	v_cmp_eq_u32_e32 vcc, 8, v12
	s_nop 1
	v_cndmask_b32_e32 v71, v71, v55, vcc
	v_cmp_eq_u32_e32 vcc, 9, v69
	s_nop 1
	v_cndmask_b32_e32 v70, v70, v38, vcc
	v_cmp_eq_u32_e32 vcc, 9, v12
	s_nop 1
	v_cndmask_b32_e32 v71, v71, v54, vcc
	v_cmp_eq_u32_e32 vcc, 10, v69
	s_nop 1
	v_cndmask_b32_e32 v70, v70, v37, vcc
	v_cmp_eq_u32_e32 vcc, 10, v12
	s_nop 1
	v_cndmask_b32_e32 v71, v71, v53, vcc
	v_cmp_eq_u32_e32 vcc, 11, v69
	s_nop 1
	v_cndmask_b32_e32 v70, v70, v36, vcc
	v_cmp_eq_u32_e32 vcc, 11, v12
	s_nop 1
	v_cndmask_b32_e32 v71, v71, v52, vcc
	v_cmp_eq_u32_e32 vcc, 12, v69
	s_nop 1
	v_cndmask_b32_e32 v70, v70, v35, vcc
	v_cmp_eq_u32_e32 vcc, 12, v12
	s_nop 1
	v_cndmask_b32_e32 v71, v71, v51, vcc
	v_cmp_eq_u32_e32 vcc, 13, v69
	s_nop 1
	v_cndmask_b32_e32 v70, v70, v34, vcc
	v_cmp_eq_u32_e32 vcc, 13, v12
	s_nop 1
	v_cndmask_b32_e32 v71, v71, v49, vcc
	v_cmp_eq_u32_e32 vcc, 14, v69
	s_nop 1
	v_cndmask_b32_e32 v70, v70, v33, vcc
	v_cmp_eq_u32_e32 vcc, 14, v12
	s_nop 1
	v_cndmask_b32_e32 v71, v71, v48, vcc
	v_cmp_eq_u32_e32 vcc, 15, v69
	s_nop 1
	v_cndmask_b32_e32 v69, v70, v15, vcc
	v_cmp_eq_u32_e32 vcc, 15, v12
	v_lshlrev_b32_e32 v69, 7, v69
	v_and_b32_e32 v69, 0x3f80, v69
	v_cndmask_b32_e32 v12, v71, v47, vcc
	v_and_b32_e32 v12, 0x7f, v12
	v_cmp_eq_u32_e32 vcc, 1, v68
	v_bitop3_b32 v12, v69, s70, v12 bitop3:0x36
	s_nop 0
	v_cndmask_b32_e32 v69, v50, v46, vcc
	v_cmp_eq_u32_e32 vcc, 1, v13
	s_nop 1
	v_cndmask_b32_e32 v70, v63, v62, vcc
	v_cmp_eq_u32_e32 vcc, 2, v68
	s_nop 1
	v_cndmask_b32_e32 v69, v69, v45, vcc
	v_cmp_eq_u32_e32 vcc, 2, v13
	s_nop 1
	v_cndmask_b32_e32 v70, v70, v61, vcc
	v_cmp_eq_u32_e32 vcc, 3, v68
	s_nop 1
	v_cndmask_b32_e32 v69, v69, v44, vcc
	v_cmp_eq_u32_e32 vcc, 3, v13
	s_nop 1
	v_cndmask_b32_e32 v70, v70, v60, vcc
	v_cmp_eq_u32_e32 vcc, 4, v68
	s_nop 1
	v_cndmask_b32_e32 v69, v69, v43, vcc
	v_cmp_eq_u32_e32 vcc, 4, v13
	s_nop 1
	v_cndmask_b32_e32 v70, v70, v59, vcc
	v_cmp_eq_u32_e32 vcc, 5, v68
	s_nop 1
	v_cndmask_b32_e32 v69, v69, v42, vcc
	v_cmp_eq_u32_e32 vcc, 5, v13
	s_nop 1
	v_cndmask_b32_e32 v70, v70, v58, vcc
	v_cmp_eq_u32_e32 vcc, 6, v68
	s_nop 1
	v_cndmask_b32_e32 v69, v69, v41, vcc
	v_cmp_eq_u32_e32 vcc, 6, v13
	s_nop 1
	v_cndmask_b32_e32 v70, v70, v57, vcc
	v_cmp_eq_u32_e32 vcc, 7, v68
	s_nop 1
	v_cndmask_b32_e32 v69, v69, v40, vcc
	v_cmp_eq_u32_e32 vcc, 7, v13
	s_nop 1
	v_cndmask_b32_e32 v70, v70, v56, vcc
	v_cmp_eq_u32_e32 vcc, 8, v68
	s_nop 1
	v_cndmask_b32_e32 v69, v69, v39, vcc
	v_cmp_eq_u32_e32 vcc, 8, v13
	s_nop 1
	v_cndmask_b32_e32 v70, v70, v55, vcc
	v_cmp_eq_u32_e32 vcc, 9, v68
	s_nop 1
	v_cndmask_b32_e32 v69, v69, v38, vcc
	v_cmp_eq_u32_e32 vcc, 9, v13
	s_nop 1
	v_cndmask_b32_e32 v70, v70, v54, vcc
	v_cmp_eq_u32_e32 vcc, 10, v68
	s_nop 1
	v_cndmask_b32_e32 v69, v69, v37, vcc
	v_cmp_eq_u32_e32 vcc, 10, v13
	s_nop 1
	v_cndmask_b32_e32 v70, v70, v53, vcc
	v_cmp_eq_u32_e32 vcc, 11, v68
	s_nop 1
	v_cndmask_b32_e32 v69, v69, v36, vcc
	v_cmp_eq_u32_e32 vcc, 11, v13
	s_nop 1
	v_cndmask_b32_e32 v70, v70, v52, vcc
	v_cmp_eq_u32_e32 vcc, 12, v68
	s_nop 1
	v_cndmask_b32_e32 v69, v69, v35, vcc
	v_cmp_eq_u32_e32 vcc, 12, v13
	s_nop 1
	v_cndmask_b32_e32 v70, v70, v51, vcc
	v_cmp_eq_u32_e32 vcc, 13, v68
	s_nop 1
	v_cndmask_b32_e32 v69, v69, v34, vcc
	v_cmp_eq_u32_e32 vcc, 13, v13
	s_nop 1
	v_cndmask_b32_e32 v70, v70, v49, vcc
	v_cmp_eq_u32_e32 vcc, 14, v68
	s_nop 1
	v_cndmask_b32_e32 v69, v69, v33, vcc
	v_cmp_eq_u32_e32 vcc, 14, v13
	s_nop 1
	v_cndmask_b32_e32 v70, v70, v48, vcc
	v_cmp_eq_u32_e32 vcc, 15, v68
	s_nop 1
	v_cndmask_b32_e32 v68, v69, v15, vcc
	v_cmp_eq_u32_e32 vcc, 15, v13
	v_lshlrev_b32_e32 v68, 7, v68
	v_and_b32_e32 v68, 0x3f80, v68
	v_cndmask_b32_e32 v13, v70, v47, vcc
	v_and_b32_e32 v13, 0x7f, v13
	v_cmp_eq_u32_e32 vcc, 1, v66
	v_bitop3_b32 v13, v68, s70, v13 bitop3:0x36
	s_nop 0
	v_cndmask_b32_e32 v68, v50, v46, vcc
	v_cmp_eq_u32_e32 vcc, 1, v14
	s_nop 1
	v_cndmask_b32_e32 v69, v63, v62, vcc
	v_cmp_eq_u32_e32 vcc, 2, v66
	s_nop 1
	v_cndmask_b32_e32 v68, v68, v45, vcc
	v_cmp_eq_u32_e32 vcc, 2, v14
	s_nop 1
	v_cndmask_b32_e32 v69, v69, v61, vcc
	v_cmp_eq_u32_e32 vcc, 3, v66
	s_nop 1
	v_cndmask_b32_e32 v68, v68, v44, vcc
	v_cmp_eq_u32_e32 vcc, 3, v14
	s_nop 1
	v_cndmask_b32_e32 v69, v69, v60, vcc
	v_cmp_eq_u32_e32 vcc, 4, v66
	s_nop 1
	v_cndmask_b32_e32 v68, v68, v43, vcc
	v_cmp_eq_u32_e32 vcc, 4, v14
	s_nop 1
	v_cndmask_b32_e32 v69, v69, v59, vcc
	v_cmp_eq_u32_e32 vcc, 5, v66
	s_nop 1
	v_cndmask_b32_e32 v68, v68, v42, vcc
	v_cmp_eq_u32_e32 vcc, 5, v14
	s_nop 1
	v_cndmask_b32_e32 v69, v69, v58, vcc
	v_cmp_eq_u32_e32 vcc, 6, v66
	s_nop 1
	v_cndmask_b32_e32 v68, v68, v41, vcc
	v_cmp_eq_u32_e32 vcc, 6, v14
	s_nop 1
	v_cndmask_b32_e32 v69, v69, v57, vcc
	v_cmp_eq_u32_e32 vcc, 7, v66
	s_nop 1
	v_cndmask_b32_e32 v68, v68, v40, vcc
	v_cmp_eq_u32_e32 vcc, 7, v14
	s_nop 1
	v_cndmask_b32_e32 v69, v69, v56, vcc
	v_cmp_eq_u32_e32 vcc, 8, v66
	s_nop 1
	v_cndmask_b32_e32 v68, v68, v39, vcc
	v_cmp_eq_u32_e32 vcc, 8, v14
	s_nop 1
	v_cndmask_b32_e32 v69, v69, v55, vcc
	v_cmp_eq_u32_e32 vcc, 9, v66
; __device__ __forceinline__ void route_task(const Params& p, int layer, const u16* qg, int rb, int hd, int r, int h) {
;     ...
;     const float inv = 1.f / den;
;     unsigned eo[16];
; #pragma unroll
;     for (int jj = 0; jj < 16; ++jj) {
;       const unsigned flat = 255u - (ct[jj] & 255u);
;       const unsigned a = flat >> 4, b = flat & 15u;
;       unsigned ka = top[0][0], kb = top[1][0];
; #pragma unroll
;       for (int k = 1; k < 16; ++k) { ka = (a == (unsigned)k) ? top[0][k] : ka; kb = (b == (unsigned)k) ? top[1][k] : kb; }
;       eo[jj] = (127u - (ka & 127u)) * 128u + (127u - (kb & 127u));
;     }
;     const size_t ob = (size_t)(rb + r) * 128 + hd * 16;
; #pragma unroll
;     for (int g4 = 0; g4 < 4; ++g4) {
;       *(u32x4*)(EX + ob + g4 * 4) = u32x4{eo[g4 * 4], eo[g4 * 4 + 1], eo[g4 * 4 + 2], eo[g4 * 4 + 3]};
;       *(f32x4*)(GT + ob + g4 * 4) = f32x4{vs[g4 * 4] * inv, vs[g4 * 4 + 1] * inv, vs[g4 * 4 + 2] * inv, vs[g4 * 4 + 3] * inv};
;     }
	s_nop 1
	v_cndmask_b32_e32 v68, v68, v38, vcc
	v_cmp_eq_u32_e32 vcc, 9, v14
	s_nop 1
	v_cndmask_b32_e32 v69, v69, v54, vcc
	v_cmp_eq_u32_e32 vcc, 10, v66
	s_nop 1
	v_cndmask_b32_e32 v68, v68, v37, vcc
	v_cmp_eq_u32_e32 vcc, 10, v14
	s_nop 1
	v_cndmask_b32_e32 v69, v69, v53, vcc
	v_cmp_eq_u32_e32 vcc, 11, v66
	s_nop 1
	v_cndmask_b32_e32 v68, v68, v36, vcc
	v_cmp_eq_u32_e32 vcc, 11, v14
	s_nop 1
	v_cndmask_b32_e32 v69, v69, v52, vcc
	v_cmp_eq_u32_e32 vcc, 12, v66
	s_nop 1
	v_cndmask_b32_e32 v68, v68, v35, vcc
	v_cmp_eq_u32_e32 vcc, 12, v14
	s_nop 1
	v_cndmask_b32_e32 v69, v69, v51, vcc
	v_cmp_eq_u32_e32 vcc, 13, v66
	s_nop 1
	v_cndmask_b32_e32 v68, v68, v34, vcc
	v_cmp_eq_u32_e32 vcc, 13, v14
	s_nop 1
	v_cndmask_b32_e32 v69, v69, v49, vcc
	v_cmp_eq_u32_e32 vcc, 14, v66
	s_nop 1
	v_cndmask_b32_e32 v68, v68, v33, vcc
	v_cmp_eq_u32_e32 vcc, 14, v14
	s_nop 1
	v_cndmask_b32_e32 v69, v69, v48, vcc
	v_cmp_eq_u32_e32 vcc, 15, v66
	s_nop 1
	v_cndmask_b32_e32 v66, v68, v15, vcc
	v_cmp_eq_u32_e32 vcc, 15, v14
	v_lshlrev_b32_e32 v66, 7, v66
	v_and_b32_e32 v66, 0x3f80, v66
	v_cndmask_b32_e32 v14, v69, v47, vcc
	v_cmp_eq_u32_e32 vcc, 1, v65
	v_and_b32_e32 v14, 0x7f, v14
	v_bitop3_b32 v14, v66, s70, v14 bitop3:0x36
	v_cndmask_b32_e32 v46, v50, v46, vcc
	v_cmp_eq_u32_e32 vcc, 1, v64
	s_nop 1
	v_cndmask_b32_e32 v50, v63, v62, vcc
	v_cmp_eq_u32_e32 vcc, 2, v65
	s_nop 1
	v_cndmask_b32_e32 v45, v46, v45, vcc
	v_cmp_eq_u32_e32 vcc, 2, v64
	s_nop 1
	v_cndmask_b32_e32 v46, v50, v61, vcc
	v_cmp_eq_u32_e32 vcc, 3, v65
	s_nop 1
	v_cndmask_b32_e32 v44, v45, v44, vcc
	v_cmp_eq_u32_e32 vcc, 3, v64
	s_nop 1
	v_cndmask_b32_e32 v45, v46, v60, vcc
	v_cmp_eq_u32_e32 vcc, 4, v65
	s_nop 1
	v_cndmask_b32_e32 v43, v44, v43, vcc
	v_cmp_eq_u32_e32 vcc, 4, v64
	s_nop 1
	v_cndmask_b32_e32 v44, v45, v59, vcc
	v_cmp_eq_u32_e32 vcc, 5, v65
	s_nop 1
	v_cndmask_b32_e32 v42, v43, v42, vcc
	v_cmp_eq_u32_e32 vcc, 5, v64
	s_nop 1
	v_cndmask_b32_e32 v43, v44, v58, vcc
	v_cmp_eq_u32_e32 vcc, 6, v65
	s_nop 1
	v_cndmask_b32_e32 v41, v42, v41, vcc
	v_cmp_eq_u32_e32 vcc, 6, v64
	s_nop 1
	v_cndmask_b32_e32 v42, v43, v57, vcc
	v_cmp_eq_u32_e32 vcc, 7, v65
	s_nop 1
	v_cndmask_b32_e32 v40, v41, v40, vcc
	v_cmp_eq_u32_e32 vcc, 7, v64
	s_nop 1
	v_cndmask_b32_e32 v41, v42, v56, vcc
	v_cmp_eq_u32_e32 vcc, 8, v65
	s_nop 1
	v_cndmask_b32_e32 v39, v40, v39, vcc
	v_cmp_eq_u32_e32 vcc, 8, v64
	s_nop 1
	v_cndmask_b32_e32 v40, v41, v55, vcc
	v_cmp_eq_u32_e32 vcc, 9, v65
	s_nop 1
	v_cndmask_b32_e32 v38, v39, v38, vcc
	v_cmp_eq_u32_e32 vcc, 9, v64
	s_nop 1
	v_cndmask_b32_e32 v39, v40, v54, vcc
	v_cmp_eq_u32_e32 vcc, 10, v65
	s_nop 1
	v_cndmask_b32_e32 v37, v38, v37, vcc
	v_cmp_eq_u32_e32 vcc, 10, v64
	s_nop 1
	v_cndmask_b32_e32 v38, v39, v53, vcc
	v_cmp_eq_u32_e32 vcc, 11, v65
	s_nop 1
	v_cndmask_b32_e32 v36, v37, v36, vcc
	v_cmp_eq_u32_e32 vcc, 11, v64
	s_nop 1
	v_cndmask_b32_e32 v37, v38, v52, vcc
	v_cmp_eq_u32_e32 vcc, 12, v65
	s_nop 1
	v_cndmask_b32_e32 v35, v36, v35, vcc
	v_cmp_eq_u32_e32 vcc, 12, v64
	s_nop 1
	v_cndmask_b32_e32 v36, v37, v51, vcc
	v_cmp_eq_u32_e32 vcc, 13, v65
	s_nop 1
	v_cndmask_b32_e32 v34, v35, v34, vcc
	v_cmp_eq_u32_e32 vcc, 13, v64
	s_nop 1
	v_cndmask_b32_e32 v35, v36, v49, vcc
	v_cmp_eq_u32_e32 vcc, 14, v65
	s_nop 1
	v_cndmask_b32_e32 v33, v34, v33, vcc
	v_cmp_eq_u32_e32 vcc, 14, v64
	s_nop 1
	v_cndmask_b32_e32 v34, v35, v48, vcc
	v_cmp_eq_u32_e32 vcc, 15, v65
	s_nop 1
	v_cndmask_b32_e32 v15, v33, v15, vcc
	v_cmp_eq_u32_e32 vcc, 15, v64
	v_lshlrev_b32_e32 v15, 7, v15
	v_and_b32_e32 v15, 0x3f80, v15
	v_cndmask_b32_e32 v33, v34, v47, vcc
	v_div_scale_f32 v34, s[34:35], v67, v67, 1.0
	v_rcp_f32_e32 v35, v34
	v_and_b32_e32 v33, 0x7f, v33
	v_bitop3_b32 v15, v15, s70, v33 bitop3:0x36
	s_lshl_b32 s34, s72, 4
	v_fma_f32 v33, -v34, v35, 1.0
	v_fmac_f32_e32 v35, v33, v35
	v_div_scale_f32 v33, vcc, 1.0, v67, 1.0
	v_mul_f32_e32 v36, v33, v35
	v_fma_f32 v37, -v34, v36, v33
	v_fmac_f32_e32 v36, v37, v35
	v_fma_f32 v33, -v34, v36, v33
	v_div_fmas_f32 v33, v33, v35, v36
	v_div_fixup_f32 v34, v33, v67, 1.0
	v_ashrrev_i32_e32 v33, 31, v32
	v_lshlrev_b64 v[32:33], 7, v[32:33]
	s_ashr_i32 s35, s34, 31
	v_lshl_add_u64 v[32:33], v[32:33], 0, s[34:35]
	v_lshlrev_b64 v[32:33], 2, v[32:33]
	v_lshl_add_u64 v[36:37], s[8:9], 0, v[32:33]
	v_lshl_add_u64 v[32:33], s[6:7], 0, v[32:33]
	global_store_dwordx4 v[36:37], v[0:3], off
	s_nop 1
	v_pk_mul_f32 v[2:3], v[18:19], v[34:35] op_sel_hi:[1,0]
	v_pk_mul_f32 v[0:1], v[16:17], v[34:35] op_sel_hi:[1,0]
	global_store_dwordx4 v[32:33], v[0:3], off
	global_store_dwordx4 v[36:37], v[4:7], off offset:16
	s_nop 0
	v_pk_mul_f32 v[2:3], v[22:23], v[34:35] op_sel_hi:[1,0]
	v_pk_mul_f32 v[0:1], v[20:21], v[34:35] op_sel_hi:[1,0]
	global_store_dwordx4 v[32:33], v[0:3], off offset:16
	global_store_dwordx4 v[36:37], v[8:11], off offset:32
	s_nop 0
	v_pk_mul_f32 v[2:3], v[26:27], v[34:35] op_sel_hi:[1,0]
	v_pk_mul_f32 v[0:1], v[24:25], v[34:35] op_sel_hi:[1,0]
	global_store_dwordx4 v[32:33], v[0:3], off offset:32
	global_store_dwordx4 v[36:37], v[12:15], off offset:48
	s_nop 0
	v_pk_mul_f32 v[2:3], v[30:31], v[34:35] op_sel_hi:[1,0]
	v_pk_mul_f32 v[0:1], v[28:29], v[34:35] op_sel_hi:[1,0]
	global_store_dwordx4 v[32:33], v[0:3], off offset:48
	s_branch .LBB0_2495
